# cache policy: GEMM output stores nt instead of write-through (transposes stay write-through); compare with v70
# speedup vs baseline: 1.0122x; 1.0122x over previous
; #define PG8_STAGE(bufoff, gbase, voff) do { _Pragma("unroll") for (int _i = 0; _i < 2; ++_i) \
;         __builtin_amdgcn_global_load_lds((const unsigned*)((const char*)(gbase) + (voff)[_i]), (LAS unsigned*)(lds + (bufoff) + ldsw + _i * 8192), 16, 0, 0); } while (0)
; #define PG8_LDA(dst, b, h) do { _Pragma("unroll") for (int m = 0; m < 4; ++m) _Pragma("unroll") for (int k = 0; k < 2; ++k) dst[m][k] = *(const LAS bf16x8*)(lds + PG8_SA(b, h) + aoff + m * 2048 + k * 1024); } while (0)
; #define PG8_LDB(dst, b, h) do { _Pragma("unroll") for (int n = 0; n < 2; ++n) _Pragma("unroll") for (int k = 0; k < 2; ++k) dst[n][k] = *(const LAS bf16x8*)(lds + PG8_SB(b, h) + boff + n * 2048 + k * 1024); } while (0)
; #define PG8_MMA(ai, bj, At, Bt) do { __builtin_amdgcn_s_setprio(1); _Pragma("unroll") for (int m = 0; m < 4; ++m) _Pragma("unroll") for (int n = 0; n < 2; ++n) _Pragma("unroll") for (int k = 0; k < 2; ++k) \
;         acc[ai][bj][m][n] = __builtin_amdgcn_mfma_f32_16x16x32_bf16(Bt[n][k], At[m][k], acc[ai][bj][m][n], 0, 0, 0); __builtin_amdgcn_s_setprio(0); } while (0)
; #define PG8_WAIT_V(n) asm volatile("s_waitcnt vmcnt(" #n ")" ::: "memory")
; #define PG8_WAIT_L(n) asm volatile("s_waitcnt lgkmcnt(" #n ")" ::: "memory")
; #define PG8_BAR __builtin_amdgcn_s_barrier()
; #define PG8_SCHED __builtin_amdgcn_sched_barrier(0)
; template <class Epi>
; __device__ __forceinline__ void gemm_phase(LAS unsigned char* lds, const Gemm g, const Order& S, const Epi& E, const int tid) {
;     ...
;             PG8_LDB(B0, 0, 0); PG8_SCHED; PG8_LDA(At, 0, 0); PG8_STAGE(PG8_SA(1, 1), a1 + hstepA, voffA);
;             PG8_WAIT_L(8); PG8_BAR; PG8_WAIT_L(0); PG8_MMA(0, 0, At, B0); PG8_BAR; PG8_SCHED;
;             PG8_LDB(B1, 0, 1); PG8_STAGE(PG8_SB(0, 0), b2, voffB);
;             PG8_BAR; PG8_WAIT_L(0); PG8_MMA(0, 1, At, B1); PG8_BAR;
;             PG8_LDA(At, 0, 1); PG8_STAGE(PG8_SA(0, 0), a2, voffA);
;             PG8_BAR; PG8_WAIT_L(0); PG8_MMA(1, 0, At, B0); PG8_BAR; PG8_SCHED;
;             PG8_STAGE(PG8_SB(0, 1), b2 + hstepB, voffB);
;             PG8_WAIT_V(6); PG8_BAR; PG8_MMA(1, 1, At, B1); PG8_BAR;
.LBB0_68:
	ds_read_b128 v[150:153], v147
	ds_read_b128 v[154:157], v147 offset:1024
	ds_read_b128 v[158:161], v147 offset:2048
	ds_read_b128 v[162:165], v147 offset:3072
	s_add_u32 s22, s20, 0xfff80080
	s_addc_u32 s23, s21, -1
	s_cmp_eq_u32 s47, 28
	s_cselect_b32 s25, s9, s23
	s_cselect_b32 s24, s43, s22
	s_cselect_b32 s23, s11, s46
	s_cselect_b32 s22, s44, s45
	v_lshl_add_u64 v[198:199], s[20:21], 0, v[136:137]
	s_add_i32 m0, s7, 0xc000
	ds_read_b128 v[166:169], v148
	ds_read_b128 v[170:173], v148 offset:1024
	ds_read_b128 v[174:177], v148 offset:2048
	ds_read_b128 v[178:181], v148 offset:3072
	ds_read_b128 v[182:185], v148 offset:4096
	ds_read_b128 v[186:189], v148 offset:5120
	ds_read_b128 v[190:193], v148 offset:6144
	ds_read_b128 v[194:197], v148 offset:7168
	global_load_lds_dwordx4 v[198:199], off
	v_lshl_add_u64 v[198:199], s[20:21], 0, v[138:139]
	s_add_i32 m0, s7, 0xe000
	s_nop 0
	global_load_lds_dwordx4 v[198:199], off
	s_waitcnt lgkmcnt(8)
	s_barrier
	s_waitcnt lgkmcnt(0)
	s_setprio 1
	s_waitcnt lgkmcnt(0)
	v_mfma_f32_16x16x32_bf16 v[124:127], v[150:153], v[166:169], v[124:127]
	v_mfma_f32_16x16x32_bf16 v[120:123], v[158:161], v[166:169], v[120:123]
	v_mfma_f32_16x16x32_bf16 v[116:119], v[150:153], v[174:177], v[116:119]
	v_mfma_f32_16x16x32_bf16 v[112:115], v[158:161], v[174:177], v[112:115]
	v_mfma_f32_16x16x32_bf16 v[100:103], v[150:153], v[182:185], v[100:103]
	v_mfma_f32_16x16x32_bf16 v[96:99], v[158:161], v[182:185], v[96:99]
	v_mfma_f32_16x16x32_bf16 v[84:87], v[150:153], v[190:193], v[84:87]
	v_mfma_f32_16x16x32_bf16 v[80:83], v[158:161], v[190:193], v[80:83]
	v_mfma_f32_16x16x32_bf16 v[124:127], v[154:157], v[170:173], v[124:127]
	v_mfma_f32_16x16x32_bf16 v[120:123], v[162:165], v[170:173], v[120:123]
	v_mfma_f32_16x16x32_bf16 v[116:119], v[154:157], v[178:181], v[116:119]
	v_mfma_f32_16x16x32_bf16 v[112:115], v[162:165], v[178:181], v[112:115]
	v_mfma_f32_16x16x32_bf16 v[100:103], v[154:157], v[186:189], v[100:103]
	v_mfma_f32_16x16x32_bf16 v[96:99], v[162:165], v[186:189], v[96:99]
	v_mfma_f32_16x16x32_bf16 v[84:87], v[154:157], v[194:197], v[84:87]
	v_mfma_f32_16x16x32_bf16 v[80:83], v[162:165], v[194:197], v[80:83]
	s_setprio 0
	s_barrier
	s_add_i32 s48, s39, s26
	v_lshl_add_u64 v[214:215], s[22:23], 0, v[132:133]
	s_mov_b32 m0, s48
	ds_read_b128 v[198:201], v149
	ds_read_b128 v[202:205], v149 offset:1024
	ds_read_b128 v[206:209], v149 offset:2048
	ds_read_b128 v[210:213], v149 offset:3072
	global_load_lds_dwordx4 v[214:215], off
	v_lshl_add_u64 v[216:217], s[22:23], 0, v[128:129]
	s_add_i32 m0, s48, 0x2000
	s_nop 0
	global_load_lds_dwordx4 v[216:217], off
	s_barrier
	s_waitcnt lgkmcnt(0)
	s_setprio 1
	s_waitcnt lgkmcnt(0)
	v_mfma_f32_16x16x32_bf16 v[108:111], v[198:201], v[166:169], v[108:111]
	v_mfma_f32_16x16x32_bf16 v[104:107], v[206:209], v[166:169], v[104:107]
	v_mfma_f32_16x16x32_bf16 v[92:95], v[198:201], v[174:177], v[92:95]
	v_mfma_f32_16x16x32_bf16 v[88:91], v[206:209], v[174:177], v[88:91]
	v_mfma_f32_16x16x32_bf16 v[76:79], v[198:201], v[182:185], v[76:79]
	v_mfma_f32_16x16x32_bf16 v[72:75], v[206:209], v[182:185], v[72:75]
	v_mfma_f32_16x16x32_bf16 v[68:71], v[198:201], v[190:193], v[68:71]
	v_mfma_f32_16x16x32_bf16 v[64:67], v[206:209], v[190:193], v[64:67]
	v_mfma_f32_16x16x32_bf16 v[108:111], v[202:205], v[170:173], v[108:111]
	v_mfma_f32_16x16x32_bf16 v[104:107], v[210:213], v[170:173], v[104:107]
	v_mfma_f32_16x16x32_bf16 v[92:95], v[202:205], v[178:181], v[92:95]
	v_mfma_f32_16x16x32_bf16 v[88:91], v[210:213], v[178:181], v[88:91]
	v_mfma_f32_16x16x32_bf16 v[76:79], v[202:205], v[186:189], v[76:79]
	v_mfma_f32_16x16x32_bf16 v[72:75], v[210:213], v[186:189], v[72:75]
	v_mfma_f32_16x16x32_bf16 v[68:71], v[202:205], v[194:197], v[68:71]
	v_mfma_f32_16x16x32_bf16 v[64:67], v[210:213], v[194:197], v[64:67]
	s_setprio 0
	s_mov_b32 m0, s7
	v_lshl_add_u64 v[218:219], s[24:25], 0, v[134:135]
	s_barrier
	ds_read_b128 v[166:169], v148 offset:16384
	ds_read_b128 v[170:173], v148 offset:17408
	ds_read_b128 v[174:177], v148 offset:18432
	ds_read_b128 v[178:181], v148 offset:19456
	ds_read_b128 v[182:185], v148 offset:20480
	ds_read_b128 v[186:189], v148 offset:21504
	ds_read_b128 v[190:193], v148 offset:22528
	ds_read_b128 v[194:197], v148 offset:23552
	global_load_lds_dwordx4 v[218:219], off
	v_lshl_add_u64 v[220:221], s[24:25], 0, v[130:131]
	s_mov_b32 m0, s29
	s_nop 0
	global_load_lds_dwordx4 v[220:221], off
	s_barrier
	s_waitcnt lgkmcnt(0)
	s_setprio 1
	s_waitcnt lgkmcnt(0)
	v_mfma_f32_16x16x32_bf16 v[60:63], v[150:153], v[166:169], v[60:63]
	v_mfma_f32_16x16x32_bf16 v[56:59], v[158:161], v[166:169], v[56:59]
	v_mfma_f32_16x16x32_bf16 v[52:55], v[150:153], v[174:177], v[52:55]
	v_mfma_f32_16x16x32_bf16 v[48:51], v[158:161], v[174:177], v[48:51]
	v_mfma_f32_16x16x32_bf16 v[36:39], v[150:153], v[182:185], v[36:39]
	v_mfma_f32_16x16x32_bf16 v[32:35], v[158:161], v[182:185], v[32:35]
	v_mfma_f32_16x16x32_bf16 v[20:23], v[150:153], v[190:193], v[20:23]
	v_mfma_f32_16x16x32_bf16 v[16:19], v[158:161], v[190:193], v[16:19]
	v_mfma_f32_16x16x32_bf16 v[60:63], v[154:157], v[170:173], v[60:63]
	v_mfma_f32_16x16x32_bf16 v[56:59], v[162:165], v[170:173], v[56:59]
	v_mfma_f32_16x16x32_bf16 v[52:55], v[154:157], v[178:181], v[52:55]
	v_mfma_f32_16x16x32_bf16 v[48:51], v[162:165], v[178:181], v[48:51]
	v_mfma_f32_16x16x32_bf16 v[36:39], v[154:157], v[186:189], v[36:39]
	v_mfma_f32_16x16x32_bf16 v[32:35], v[162:165], v[186:189], v[32:35]
	v_mfma_f32_16x16x32_bf16 v[20:23], v[154:157], v[194:197], v[20:23]
	v_mfma_f32_16x16x32_bf16 v[16:19], v[162:165], v[194:197], v[16:19]
	s_setprio 0
	s_barrier
; #define PG8_STAGE(bufoff, gbase, voff) do { _Pragma("unroll") for (int _i = 0; _i < 2; ++_i) \
;         __builtin_amdgcn_global_load_lds((const unsigned*)((const char*)(gbase) + (voff)[_i]), (LAS unsigned*)(lds + (bufoff) + ldsw + _i * 8192), 16, 0, 0); } while (0)
; #define PG8_LDA(dst, b, h) do { _Pragma("unroll") for (int m = 0; m < 4; ++m) _Pragma("unroll") for (int k = 0; k < 2; ++k) dst[m][k] = *(const LAS bf16x8*)(lds + PG8_SA(b, h) + aoff + m * 2048 + k * 1024); } while (0)
; #define PG8_LDB(dst, b, h) do { _Pragma("unroll") for (int n = 0; n < 2; ++n) _Pragma("unroll") for (int k = 0; k < 2; ++k) dst[n][k] = *(const LAS bf16x8*)(lds + PG8_SB(b, h) + boff + n * 2048 + k * 1024); } while (0)
; #define PG8_MMA(ai, bj, At, Bt) do { __builtin_amdgcn_s_setprio(1); _Pragma("unroll") for (int m = 0; m < 4; ++m) _Pragma("unroll") for (int n = 0; n < 2; ++n) _Pragma("unroll") for (int k = 0; k < 2; ++k) \
;         acc[ai][bj][m][n] = __builtin_amdgcn_mfma_f32_16x16x32_bf16(Bt[n][k], At[m][k], acc[ai][bj][m][n], 0, 0, 0); __builtin_amdgcn_s_setprio(0); } while (0)
; #define PG8_WAIT_V(n) asm volatile("s_waitcnt vmcnt(" #n ")" ::: "memory")
; #define PG8_WAIT_L(n) asm volatile("s_waitcnt lgkmcnt(" #n ")" ::: "memory")
; #define PG8_BAR __builtin_amdgcn_s_barrier()
; #define PG8_SCHED __builtin_amdgcn_sched_barrier(0)
; template <class Epi>
; __device__ __forceinline__ void gemm_phase(LAS unsigned char* lds, const Gemm g, const Order& S, const Epi& E, const int tid) {
;     ...
;             PG8_BAR; PG8_WAIT_L(0); PG8_MMA(1, 0, At, B0); PG8_BAR; PG8_SCHED;
;             PG8_STAGE(PG8_SB(0, 1), b2 + hstepB, voffB);
;             PG8_WAIT_V(6); PG8_BAR; PG8_MMA(1, 1, At, B1); PG8_BAR;
;             PG8_LDB(B0, 1, 0); PG8_SCHED; PG8_LDA(At, 1, 0); PG8_STAGE(PG8_SA(0, 1), a2 + hstepA, voffA);
;             PG8_WAIT_L(8); PG8_BAR; PG8_WAIT_L(0); PG8_MMA(0, 0, At, B0); PG8_BAR; PG8_SCHED;
;             PG8_LDB(B1, 1, 1); PG8_STAGE(PG8_SB(1, 0), b3, voffB);
;             PG8_BAR; PG8_WAIT_L(0); PG8_MMA(0, 1, At, B1); PG8_BAR;
;             PG8_LDA(At, 1, 1); PG8_STAGE(PG8_SA(1, 0), a3, voffA);
;             PG8_BAR; PG8_WAIT_L(0); PG8_MMA(1, 0, At, B0); PG8_BAR; PG8_SCHED;
	s_add_u32 s48, s22, 0x80000
	s_addc_u32 s49, s23, 0
	s_add_i32 s50, s40, s26
	v_lshl_add_u64 v[150:151], s[48:49], 0, v[132:133]
	s_mov_b32 m0, s50
	s_nop 0
	global_load_lds_dwordx4 v[150:151], off
	v_lshl_add_u64 v[150:151], s[48:49], 0, v[128:129]
	s_add_i32 m0, s50, 0x2000
	s_nop 0
	global_load_lds_dwordx4 v[150:151], off
	s_waitcnt vmcnt(6)
	s_barrier
	s_setprio 1
	v_mfma_f32_16x16x32_bf16 v[44:47], v[198:201], v[166:169], v[44:47]
	v_mfma_f32_16x16x32_bf16 v[40:43], v[206:209], v[166:169], v[40:43]
	v_mfma_f32_16x16x32_bf16 v[28:31], v[198:201], v[174:177], v[28:31]
	v_mfma_f32_16x16x32_bf16 v[24:27], v[206:209], v[174:177], v[24:27]
	v_mfma_f32_16x16x32_bf16 v[12:15], v[198:201], v[182:185], v[12:15]
	v_mfma_f32_16x16x32_bf16 v[8:11], v[206:209], v[182:185], v[8:11]
	v_mfma_f32_16x16x32_bf16 v[4:7], v[198:201], v[190:193], v[4:7]
	v_mfma_f32_16x16x32_bf16 v[0:3], v[206:209], v[190:193], v[0:3]
	v_mfma_f32_16x16x32_bf16 v[44:47], v[202:205], v[170:173], v[44:47]
	v_mfma_f32_16x16x32_bf16 v[40:43], v[210:213], v[170:173], v[40:43]
	v_mfma_f32_16x16x32_bf16 v[28:31], v[202:205], v[178:181], v[28:31]
	v_mfma_f32_16x16x32_bf16 v[24:27], v[210:213], v[178:181], v[24:27]
	v_mfma_f32_16x16x32_bf16 v[12:15], v[202:205], v[186:189], v[12:15]
	v_mfma_f32_16x16x32_bf16 v[8:11], v[210:213], v[186:189], v[8:11]
	v_mfma_f32_16x16x32_bf16 v[4:7], v[202:205], v[194:197], v[4:7]
	v_mfma_f32_16x16x32_bf16 v[0:3], v[210:213], v[194:197], v[0:3]
	s_setprio 0
	s_add_i32 s48, 0, 0x18000
	v_add_u32_e32 v162, s48, v145
	s_barrier
	ds_read_b128 v[150:153], v162
	ds_read_b128 v[154:157], v162 offset:1024
	ds_read_b128 v[158:161], v162 offset:2048
	ds_read_b128 v[162:165], v162 offset:3072
	s_add_u32 s24, s24, 0x80000
	s_addc_u32 s25, s25, 0
	s_mov_b32 m0, s30
	v_lshl_add_u64 v[198:199], s[24:25], 0, v[134:135]
	ds_read_b128 v[166:169], v148 offset:32768
	ds_read_b128 v[170:173], v148 offset:33792
	ds_read_b128 v[174:177], v148 offset:34816
	ds_read_b128 v[178:181], v148 offset:35840
	ds_read_b128 v[182:185], v148 offset:36864
	ds_read_b128 v[186:189], v148 offset:37888
	ds_read_b128 v[190:193], v148 offset:38912
	ds_read_b128 v[194:197], v148 offset:39936
	global_load_lds_dwordx4 v[198:199], off
	v_lshl_add_u64 v[198:199], s[24:25], 0, v[130:131]
	s_mov_b32 m0, s31
	s_nop 0
	global_load_lds_dwordx4 v[198:199], off
	s_waitcnt lgkmcnt(8)
	s_barrier
	s_waitcnt lgkmcnt(0)
	s_setprio 1
	s_waitcnt lgkmcnt(0)
	v_mfma_f32_16x16x32_bf16 v[124:127], v[150:153], v[166:169], v[124:127]
	v_mfma_f32_16x16x32_bf16 v[120:123], v[158:161], v[166:169], v[120:123]
	v_mfma_f32_16x16x32_bf16 v[116:119], v[150:153], v[174:177], v[116:119]
	v_mfma_f32_16x16x32_bf16 v[112:115], v[158:161], v[174:177], v[112:115]
	v_mfma_f32_16x16x32_bf16 v[100:103], v[150:153], v[182:185], v[100:103]
	v_mfma_f32_16x16x32_bf16 v[96:99], v[158:161], v[182:185], v[96:99]
	v_mfma_f32_16x16x32_bf16 v[84:87], v[150:153], v[190:193], v[84:87]
	v_mfma_f32_16x16x32_bf16 v[80:83], v[158:161], v[190:193], v[80:83]
	v_mfma_f32_16x16x32_bf16 v[124:127], v[154:157], v[170:173], v[124:127]
	v_mfma_f32_16x16x32_bf16 v[120:123], v[162:165], v[170:173], v[120:123]
	v_mfma_f32_16x16x32_bf16 v[116:119], v[154:157], v[178:181], v[116:119]
	v_mfma_f32_16x16x32_bf16 v[112:115], v[162:165], v[178:181], v[112:115]
	v_mfma_f32_16x16x32_bf16 v[100:103], v[154:157], v[186:189], v[100:103]
	v_mfma_f32_16x16x32_bf16 v[96:99], v[162:165], v[186:189], v[96:99]
	v_mfma_f32_16x16x32_bf16 v[84:87], v[154:157], v[194:197], v[84:87]
	v_mfma_f32_16x16x32_bf16 v[80:83], v[162:165], v[194:197], v[80:83]
	s_setprio 0
	s_barrier
	s_add_i32 s24, 0, 0x1c000
	s_add_i32 s25, s48, s26
	v_add_u32_e32 v210, s24, v145
	v_lshl_add_u64 v[214:215], v[214:215], 0, s[4:5]
	s_mov_b32 m0, s25
	ds_read_b128 v[198:201], v210
	ds_read_b128 v[202:205], v210 offset:1024
	ds_read_b128 v[206:209], v210 offset:2048
	ds_read_b128 v[210:213], v210 offset:3072
	global_load_lds_dwordx4 v[214:215], off
	v_lshl_add_u64 v[214:215], v[216:217], 0, s[4:5]
	s_add_i32 m0, s25, 0x2000
	s_nop 0
	global_load_lds_dwordx4 v[214:215], off
	s_barrier
	s_waitcnt lgkmcnt(0)
	s_setprio 1
	s_waitcnt lgkmcnt(0)
	v_mfma_f32_16x16x32_bf16 v[108:111], v[198:201], v[166:169], v[108:111]
	v_mfma_f32_16x16x32_bf16 v[104:107], v[206:209], v[166:169], v[104:107]
	v_mfma_f32_16x16x32_bf16 v[92:95], v[198:201], v[174:177], v[92:95]
	v_mfma_f32_16x16x32_bf16 v[88:91], v[206:209], v[174:177], v[88:91]
	v_mfma_f32_16x16x32_bf16 v[76:79], v[198:201], v[182:185], v[76:79]
	v_mfma_f32_16x16x32_bf16 v[72:75], v[206:209], v[182:185], v[72:75]
	v_mfma_f32_16x16x32_bf16 v[68:71], v[198:201], v[190:193], v[68:71]
	v_mfma_f32_16x16x32_bf16 v[64:67], v[206:209], v[190:193], v[64:67]
	v_mfma_f32_16x16x32_bf16 v[108:111], v[202:205], v[170:173], v[108:111]
	v_mfma_f32_16x16x32_bf16 v[104:107], v[210:213], v[170:173], v[104:107]
	v_mfma_f32_16x16x32_bf16 v[92:95], v[202:205], v[178:181], v[92:95]
	v_mfma_f32_16x16x32_bf16 v[88:91], v[210:213], v[178:181], v[88:91]
	v_mfma_f32_16x16x32_bf16 v[76:79], v[202:205], v[186:189], v[76:79]
	v_mfma_f32_16x16x32_bf16 v[72:75], v[210:213], v[186:189], v[72:75]
	v_mfma_f32_16x16x32_bf16 v[68:71], v[202:205], v[194:197], v[68:71]
	v_mfma_f32_16x16x32_bf16 v[64:67], v[210:213], v[194:197], v[64:67]
	s_setprio 0
	s_mov_b32 m0, s34
	v_lshl_add_u64 v[214:215], v[218:219], 0, s[4:5]
	s_barrier
	ds_read_b128 v[166:169], v148 offset:49152
	ds_read_b128 v[170:173], v148 offset:50176
	ds_read_b128 v[174:177], v148 offset:51200
	ds_read_b128 v[178:181], v148 offset:52224
	ds_read_b128 v[182:185], v148 offset:53248
	ds_read_b128 v[186:189], v148 offset:54272
	ds_read_b128 v[190:193], v148 offset:55296
	ds_read_b128 v[194:197], v148 offset:56320
	global_load_lds_dwordx4 v[214:215], off
	v_lshl_add_u64 v[214:215], v[220:221], 0, s[4:5]
	s_mov_b32 m0, s35
	s_nop 0
	global_load_lds_dwordx4 v[214:215], off
	s_barrier
; #define PG8_STAGE(bufoff, gbase, voff) do { _Pragma("unroll") for (int _i = 0; _i < 2; ++_i) \
;         __builtin_amdgcn_global_load_lds((const unsigned*)((const char*)(gbase) + (voff)[_i]), (LAS unsigned*)(lds + (bufoff) + ldsw + _i * 8192), 16, 0, 0); } while (0)
; #define PG8_MMA(ai, bj, At, Bt) do { __builtin_amdgcn_s_setprio(1); _Pragma("unroll") for (int m = 0; m < 4; ++m) _Pragma("unroll") for (int n = 0; n < 2; ++n) _Pragma("unroll") for (int k = 0; k < 2; ++k) \
;         acc[ai][bj][m][n] = __builtin_amdgcn_mfma_f32_16x16x32_bf16(Bt[n][k], At[m][k], acc[ai][bj][m][n], 0, 0, 0); __builtin_amdgcn_s_setprio(0); } while (0)
; #define PG8_WAIT_V(n) asm volatile("s_waitcnt vmcnt(" #n ")" ::: "memory")
; #define PG8_WAIT_L(n) asm volatile("s_waitcnt lgkmcnt(" #n ")" ::: "memory")
; #define PG8_BAR __builtin_amdgcn_s_barrier()
; #define PG8_SCHED __builtin_amdgcn_sched_barrier(0)
; template <class Epi>
; __device__ __forceinline__ void gemm_phase(LAS unsigned char* lds, const Gemm g, const Order& S, const Epi& E, const int tid) {
;     ...
;             PG8_BAR; PG8_WAIT_L(0); PG8_MMA(1, 0, At, B0); PG8_BAR; PG8_SCHED;
;             PG8_STAGE(PG8_SB(1, 1), b3 + hstepB, voffB);
;             PG8_WAIT_V(6); PG8_BAR; PG8_MMA(1, 1, At, B1); PG8_BAR;
	s_waitcnt lgkmcnt(0)
	s_setprio 1
	s_waitcnt lgkmcnt(0)
	v_mfma_f32_16x16x32_bf16 v[60:63], v[150:153], v[166:169], v[60:63]
	v_mfma_f32_16x16x32_bf16 v[56:59], v[158:161], v[166:169], v[56:59]
	v_mfma_f32_16x16x32_bf16 v[52:55], v[150:153], v[174:177], v[52:55]
	v_mfma_f32_16x16x32_bf16 v[48:51], v[158:161], v[174:177], v[48:51]
	v_mfma_f32_16x16x32_bf16 v[36:39], v[150:153], v[182:185], v[36:39]
	v_mfma_f32_16x16x32_bf16 v[32:35], v[158:161], v[182:185], v[32:35]
	v_mfma_f32_16x16x32_bf16 v[20:23], v[150:153], v[190:193], v[20:23]
	v_mfma_f32_16x16x32_bf16 v[16:19], v[158:161], v[190:193], v[16:19]
	v_mfma_f32_16x16x32_bf16 v[60:63], v[154:157], v[170:173], v[60:63]
	v_mfma_f32_16x16x32_bf16 v[56:59], v[162:165], v[170:173], v[56:59]
	v_mfma_f32_16x16x32_bf16 v[52:55], v[154:157], v[178:181], v[52:55]
	v_mfma_f32_16x16x32_bf16 v[48:51], v[162:165], v[178:181], v[48:51]
	v_mfma_f32_16x16x32_bf16 v[36:39], v[154:157], v[186:189], v[36:39]
	v_mfma_f32_16x16x32_bf16 v[32:35], v[162:165], v[186:189], v[32:35]
	v_mfma_f32_16x16x32_bf16 v[20:23], v[154:157], v[194:197], v[20:23]
	v_mfma_f32_16x16x32_bf16 v[16:19], v[162:165], v[194:197], v[16:19]
	s_setprio 0
	s_barrier
	s_add_u32 s22, s22, 0x80080
	s_addc_u32 s23, s23, 0
	s_add_i32 s24, s24, s26
	v_lshl_add_u64 v[150:151], s[22:23], 0, v[132:133]
	s_mov_b32 m0, s24
	s_nop 0
	global_load_lds_dwordx4 v[150:151], off
	v_lshl_add_u64 v[150:151], s[22:23], 0, v[128:129]
	s_add_i32 m0, s24, 0x2000
	s_nop 0
	global_load_lds_dwordx4 v[150:151], off
	s_waitcnt vmcnt(6)
	s_barrier
	s_setprio 1
	v_mfma_f32_16x16x32_bf16 v[44:47], v[198:201], v[166:169], v[44:47]
	v_mfma_f32_16x16x32_bf16 v[40:43], v[206:209], v[166:169], v[40:43]
	v_mfma_f32_16x16x32_bf16 v[28:31], v[198:201], v[174:177], v[28:31]
	v_mfma_f32_16x16x32_bf16 v[24:27], v[206:209], v[174:177], v[24:27]
	v_mfma_f32_16x16x32_bf16 v[12:15], v[198:201], v[182:185], v[12:15]
	v_mfma_f32_16x16x32_bf16 v[8:11], v[206:209], v[182:185], v[8:11]
	v_mfma_f32_16x16x32_bf16 v[4:7], v[198:201], v[190:193], v[4:7]
	v_mfma_f32_16x16x32_bf16 v[0:3], v[206:209], v[190:193], v[0:3]
	v_mfma_f32_16x16x32_bf16 v[44:47], v[202:205], v[170:173], v[44:47]
	v_mfma_f32_16x16x32_bf16 v[40:43], v[210:213], v[170:173], v[40:43]
	v_mfma_f32_16x16x32_bf16 v[28:31], v[202:205], v[178:181], v[28:31]
	v_mfma_f32_16x16x32_bf16 v[24:27], v[210:213], v[178:181], v[24:27]
	v_mfma_f32_16x16x32_bf16 v[12:15], v[202:205], v[186:189], v[12:15]
	v_mfma_f32_16x16x32_bf16 v[8:11], v[210:213], v[186:189], v[8:11]
	v_mfma_f32_16x16x32_bf16 v[4:7], v[202:205], v[194:197], v[4:7]
	v_mfma_f32_16x16x32_bf16 v[0:3], v[210:213], v[194:197], v[0:3]
	s_setprio 0
	s_add_i32 s47, s47, 2
	s_add_u32 s20, s20, 0x100
	s_addc_u32 s21, s21, 0
	s_add_u32 s45, s45, 0x100
	s_addc_u32 s46, s46, 0
	s_cmp_gt_u32 s47, 29
	s_barrier
	s_cbranch_scc0 .LBB0_68
;     __device__ __forceinline__ void operator()(const f32x4 (&acc)[2][2][4][2], const Unit& u, int wr, int wc, int fr, int fq) const {
;         const int row0 = u.pm * BM + wr * 64 + fr, col0 = u.pn * BM + wc * 32 + 8 * fq;
; #pragma unroll
;         for (int ai = 0; ai < 2; ++ai)
; #pragma unroll
;             for (int m = 0; m < 4; ++m) { bf16_t* rowp = O + (size_t)(row0 + ai * HALF + m * 16) * ldc + col0;
;                 float rs = 1.0f; if (RS) rs = rt[u.i * 256 + wr * 64 + fr + ai * HALF + m * 16];
; #pragma unroll
;                 for (int bj = 0; bj < 2; ++bj) { f32x4 v0 = acc[ai][bj][m][0], v1 = acc[ai][bj][m][1];
;                     if (RS) { v0 *= rs; v1 *= rs; }
;                     if (ACT == 1) {
; #pragma unroll
;                         for (int j = 0; j < 4; ++j) { const float a = fmaxf(v0[j], 0.f), b = fmaxf(v1[j], 0.f); v0[j] = a * a; v1[j] = b * b; } }
;                     u32x4 w; w.x = pk2(v0[0], v0[1]); w.y = pk2(v0[2], v0[3]); w.z = pk2(v1[0], v1[1]); w.w = pk2(v1[2], v1[3]);
;                     *(u32x4*)(rowp + bj * HALF) = w; } }
	v_lshl_add_u32 v156, s6, 8, v144
	v_lshl_or_b32 v150, s42, 8, v146
	v_ashrrev_i32_e32 v151, 31, v150
	v_mov_b64_e32 v[152:153], s[72:73]
	v_cvt_pk_bf16_f32 v68, v68, v69
	v_cvt_pk_bf16_f32 v69, v70, v71
	v_cvt_pk_bf16_f32 v70, v64, v65
	v_add_u32_e32 v64, 0x80, v156
	v_mad_i64_i32 v[154:155], s[20:21], v156, s41, v[152:153]
	v_lshlrev_b64 v[150:151], 1, v[150:151]
	v_cvt_pk_bf16_f32 v108, v108, v109
	v_cvt_pk_bf16_f32 v109, v110, v111
	v_cvt_pk_bf16_f32 v110, v104, v105
	v_or_b32_e32 v104, 16, v156
	v_mad_i64_i32 v[64:65], s[20:21], v64, s41, v[152:153]
	v_cvt_pk_bf16_f32 v44, v44, v45
	v_cvt_pk_bf16_f32 v45, v46, v47
	v_cvt_pk_bf16_f32 v46, v40, v41
	v_add_u32_e32 v40, 0x90, v156
	v_lshl_add_u64 v[154:155], v[154:155], 0, v[150:151]
	v_cvt_pk_bf16_f32 v111, v106, v107
	v_mad_i64_i32 v[104:105], s[20:21], v104, s41, v[152:153]
	v_cvt_pk_bf16_f32 v92, v92, v93
	v_cvt_pk_bf16_f32 v93, v94, v95
	v_cvt_pk_bf16_f32 v94, v88, v89
	v_or_b32_e32 v88, 32, v156
	v_lshl_add_u64 v[64:65], v[64:65], 0, v[150:151]
	v_cvt_pk_bf16_f32 v47, v42, v43
	v_mad_i64_i32 v[40:41], s[20:21], v40, s41, v[152:153]
	v_cvt_pk_bf16_f32 v28, v28, v29
	v_cvt_pk_bf16_f32 v29, v30, v31
	v_cvt_pk_bf16_f32 v30, v24, v25
	v_add_u32_e32 v24, 0xa0, v156
	global_store_dwordx4 v[154:155], v[108:111], off offset:256 nt
	v_cvt_pk_bf16_f32 v95, v90, v91
	v_mad_i64_i32 v[88:89], s[20:21], v88, s41, v[152:153]
	v_lshl_add_u64 v[108:109], v[104:105], 0, v[150:151]
	v_cvt_pk_bf16_f32 v76, v76, v77
	v_cvt_pk_bf16_f32 v77, v78, v79
	v_cvt_pk_bf16_f32 v78, v72, v73
	v_or_b32_e32 v72, 48, v156
	global_store_dwordx4 v[64:65], v[44:47], off offset:256 nt
	v_cvt_pk_bf16_f32 v31, v26, v27
	v_mad_i64_i32 v[24:25], s[20:21], v24, s41, v[152:153]
	v_lshl_add_u64 v[44:45], v[40:41], 0, v[150:151]
	v_cvt_pk_bf16_f32 v12, v12, v13
	v_cvt_pk_bf16_f32 v13, v14, v15
	v_cvt_pk_bf16_f32 v14, v8, v9
	v_add_u32_e32 v8, 0xb0, v156
	global_store_dwordx4 v[108:109], v[92:95], off offset:256 nt
	v_cvt_pk_bf16_f32 v79, v74, v75
	v_mad_i64_i32 v[72:73], s[20:21], v72, s41, v[152:153]
	v_lshl_add_u64 v[92:93], v[88:89], 0, v[150:151]
	global_store_dwordx4 v[44:45], v[28:31], off offset:256 nt
	v_cvt_pk_bf16_f32 v15, v10, v11
	v_mad_i64_i32 v[8:9], s[20:21], v8, s41, v[152:153]
	v_lshl_add_u64 v[28:29], v[24:25], 0, v[150:151]
	v_cvt_pk_bf16_f32 v124, v124, v125
	v_cvt_pk_bf16_f32 v125, v126, v127
	v_cvt_pk_bf16_f32 v126, v120, v121
	v_cvt_pk_bf16_f32 v127, v122, v123
	v_cvt_pk_bf16_f32 v104, v116, v117
	v_cvt_pk_bf16_f32 v105, v118, v119
	v_cvt_pk_bf16_f32 v106, v112, v113
	v_cvt_pk_bf16_f32 v107, v114, v115
	v_cvt_pk_bf16_f32 v88, v100, v101
	v_cvt_pk_bf16_f32 v89, v102, v103
	v_cvt_pk_bf16_f32 v90, v96, v97
	v_cvt_pk_bf16_f32 v91, v98, v99
	global_store_dwordx4 v[92:93], v[76:79], off offset:256 nt
	v_cvt_pk_bf16_f32 v74, v80, v81
	v_cvt_pk_bf16_f32 v75, v82, v83
	v_lshl_add_u64 v[76:77], v[72:73], 0, v[150:151]
	v_cvt_pk_bf16_f32 v72, v84, v85
	v_cvt_pk_bf16_f32 v73, v86, v87
	v_cvt_pk_bf16_f32 v71, v66, v67
	v_cvt_pk_bf16_f32 v60, v60, v61
	v_cvt_pk_bf16_f32 v61, v62, v63
	v_cvt_pk_bf16_f32 v62, v56, v57
	v_cvt_pk_bf16_f32 v63, v58, v59
	v_cvt_pk_bf16_f32 v40, v52, v53
	v_cvt_pk_bf16_f32 v41, v54, v55
	v_cvt_pk_bf16_f32 v42, v48, v49
	v_cvt_pk_bf16_f32 v43, v50, v51
	v_cvt_pk_bf16_f32 v24, v36, v37
	v_cvt_pk_bf16_f32 v25, v38, v39
	v_cvt_pk_bf16_f32 v26, v32, v33
	v_cvt_pk_bf16_f32 v27, v34, v35
	global_store_dwordx4 v[28:29], v[12:15], off offset:256 nt
	v_cvt_pk_bf16_f32 v10, v16, v17
	v_cvt_pk_bf16_f32 v11, v18, v19
	v_lshl_add_u64 v[12:13], v[8:9], 0, v[150:151]
	v_cvt_pk_bf16_f32 v8, v20, v21
	v_cvt_pk_bf16_f32 v9, v22, v23
	v_cvt_pk_bf16_f32 v4, v4, v5
	v_cvt_pk_bf16_f32 v5, v6, v7
	v_cvt_pk_bf16_f32 v6, v0, v1
	v_cvt_pk_bf16_f32 v7, v2, v3
	s_and_b64 vcc, exec, s[0:1]
	s_mov_b32 s42, s10
	s_mov_b32 s6, s8
	s_mov_b64 s[22:23], s[18:19]
	s_mov_b64 s[20:21], s[12:13]
	global_store_dwordx4 v[154:155], v[124:127], off nt
	global_store_dwordx4 v[108:109], v[104:107], off nt
	global_store_dwordx4 v[92:93], v[88:91], off nt
	global_store_dwordx4 v[76:77], v[72:75], off nt
	global_store_dwordx4 v[76:77], v[68:71], off offset:256 nt
	global_store_dwordx4 v[64:65], v[60:63], off nt
	global_store_dwordx4 v[44:45], v[40:43], off nt
	global_store_dwordx4 v[28:29], v[24:27], off nt
	global_store_dwordx4 v[12:13], v[8:11], off nt
	global_store_dwordx4 v[12:13], v[4:7], off offset:256 nt
	s_cbranch_vccz .LBB0_65
	s_waitcnt vmcnt(0)
	s_cmpk_gt_u32 s3, 0xff
	s_cbranch_scc1 .LBB0_72
	s_barrier

; #define PG8_STAGE(bufoff, gbase, voff) do { _Pragma("unroll") for (int _i = 0; _i < 2; ++_i) \
;         __builtin_amdgcn_global_load_lds((const unsigned*)((const char*)(gbase) + (voff)[_i]), (LAS unsigned*)(lds + (bufoff) + ldsw + _i * 8192), 16, 0, 0); } while (0)
; #define PG8_LDA(dst, b, h) do { _Pragma("unroll") for (int m = 0; m < 4; ++m) _Pragma("unroll") for (int k = 0; k < 2; ++k) dst[m][k] = *(const LAS bf16x8*)(lds + PG8_SA(b, h) + aoff + m * 2048 + k * 1024); } while (0)
; #define PG8_LDB(dst, b, h) do { _Pragma("unroll") for (int n = 0; n < 2; ++n) _Pragma("unroll") for (int k = 0; k < 2; ++k) dst[n][k] = *(const LAS bf16x8*)(lds + PG8_SB(b, h) + boff + n * 2048 + k * 1024); } while (0)
; #define PG8_MMA(ai, bj, At, Bt) do { __builtin_amdgcn_s_setprio(1); _Pragma("unroll") for (int m = 0; m < 4; ++m) _Pragma("unroll") for (int n = 0; n < 2; ++n) _Pragma("unroll") for (int k = 0; k < 2; ++k) \
;         acc[ai][bj][m][n] = __builtin_amdgcn_mfma_f32_16x16x32_bf16(Bt[n][k], At[m][k], acc[ai][bj][m][n], 0, 0, 0); __builtin_amdgcn_s_setprio(0); } while (0)
; #define PG8_WAIT_V(n) asm volatile("s_waitcnt vmcnt(" #n ")" ::: "memory")
; #define PG8_WAIT_L(n) asm volatile("s_waitcnt lgkmcnt(" #n ")" ::: "memory")
; #define PG8_BAR __builtin_amdgcn_s_barrier()
; #define PG8_SCHED __builtin_amdgcn_sched_barrier(0)
; template <class Epi>
; __device__ __forceinline__ void gemm_phase(LAS unsigned char* lds, const Gemm g, const Order& S, const Epi& E, const int tid) {
;     ...
;             PG8_LDB(B0, 0, 0); PG8_SCHED; PG8_LDA(At, 0, 0); PG8_STAGE(PG8_SA(1, 1), a1 + hstepA, voffA);
;             PG8_WAIT_L(8); PG8_BAR; PG8_WAIT_L(0); PG8_MMA(0, 0, At, B0); PG8_BAR; PG8_SCHED;
;             PG8_LDB(B1, 0, 1); PG8_STAGE(PG8_SB(0, 0), b2, voffB);
;             PG8_BAR; PG8_WAIT_L(0); PG8_MMA(0, 1, At, B1); PG8_BAR;
;             PG8_LDA(At, 0, 1); PG8_STAGE(PG8_SA(0, 0), a2, voffA);
;             PG8_BAR; PG8_WAIT_L(0); PG8_MMA(1, 0, At, B0); PG8_BAR; PG8_SCHED;
;             PG8_STAGE(PG8_SB(0, 1), b2 + hstepB, voffB);
;             PG8_WAIT_V(6); PG8_BAR; PG8_MMA(1, 1, At, B1); PG8_BAR;
.LBB0_592:
	ds_read_b128 v[128:131], v171
	ds_read_b128 v[132:135], v171 offset:1024
	ds_read_b128 v[136:139], v171 offset:2048
	ds_read_b128 v[140:143], v171 offset:3072
	s_add_u32 s28, s26, 0xfff80080
	s_addc_u32 s29, s27, -1
	s_cmp_eq_u32 s51, 28
	s_cselect_b32 s31, s7, s29
	s_cselect_b32 s30, s15, s28
	s_cselect_b32 s29, s17, s50
	s_cselect_b32 s28, s48, s49
	v_lshl_add_u64 v[200:201], s[26:27], 0, v[152:153]
	s_add_i32 m0, s34, 0xc000
	ds_read_b128 v[160:163], v172
	ds_read_b128 v[164:167], v172 offset:1024
	ds_read_b128 v[176:179], v172 offset:2048
	ds_read_b128 v[180:183], v172 offset:3072
	ds_read_b128 v[184:187], v172 offset:4096
	ds_read_b128 v[188:191], v172 offset:5120
	ds_read_b128 v[192:195], v172 offset:6144
	ds_read_b128 v[196:199], v172 offset:7168
	global_load_lds_dwordx4 v[200:201], off
	v_lshl_add_u64 v[200:201], s[26:27], 0, v[154:155]
	s_add_i32 m0, s34, 0xe000
	s_nop 0
	global_load_lds_dwordx4 v[200:201], off
	s_waitcnt lgkmcnt(8)
	s_barrier
	s_waitcnt lgkmcnt(0)
	s_setprio 1
	s_waitcnt lgkmcnt(0)
	v_mfma_f32_16x16x32_bf16 v[124:127], v[128:131], v[160:163], v[124:127]
	v_mfma_f32_16x16x32_bf16 v[120:123], v[136:139], v[160:163], v[120:123]
	v_mfma_f32_16x16x32_bf16 v[108:111], v[128:131], v[176:179], v[108:111]
	v_mfma_f32_16x16x32_bf16 v[104:107], v[136:139], v[176:179], v[104:107]
	v_mfma_f32_16x16x32_bf16 v[92:95], v[128:131], v[184:187], v[92:95]
	v_mfma_f32_16x16x32_bf16 v[88:91], v[136:139], v[184:187], v[88:91]
	v_mfma_f32_16x16x32_bf16 v[76:79], v[128:131], v[192:195], v[76:79]
	v_mfma_f32_16x16x32_bf16 v[72:75], v[136:139], v[192:195], v[72:75]
	v_mfma_f32_16x16x32_bf16 v[124:127], v[132:135], v[164:167], v[124:127]
	v_mfma_f32_16x16x32_bf16 v[120:123], v[140:143], v[164:167], v[120:123]
	v_mfma_f32_16x16x32_bf16 v[108:111], v[132:135], v[180:183], v[108:111]
	v_mfma_f32_16x16x32_bf16 v[104:107], v[140:143], v[180:183], v[104:107]
	v_mfma_f32_16x16x32_bf16 v[92:95], v[132:135], v[188:191], v[92:95]
	v_mfma_f32_16x16x32_bf16 v[88:91], v[140:143], v[188:191], v[88:91]
	v_mfma_f32_16x16x32_bf16 v[76:79], v[132:135], v[196:199], v[76:79]
	v_mfma_f32_16x16x32_bf16 v[72:75], v[140:143], v[196:199], v[72:75]
	s_setprio 0
	s_barrier
	s_add_i32 s52, s45, s33
	v_lshl_add_u64 v[216:217], s[28:29], 0, v[146:147]
	s_mov_b32 m0, s52
	ds_read_b128 v[200:203], v173
	ds_read_b128 v[204:207], v173 offset:1024
	ds_read_b128 v[208:211], v173 offset:2048
	ds_read_b128 v[212:215], v173 offset:3072
	global_load_lds_dwordx4 v[216:217], off
	v_lshl_add_u64 v[218:219], s[28:29], 0, v[150:151]
	s_add_i32 m0, s52, 0x2000
	s_nop 0
	global_load_lds_dwordx4 v[218:219], off
	s_barrier
	s_waitcnt lgkmcnt(0)
	s_setprio 1
	s_waitcnt lgkmcnt(0)
	v_mfma_f32_16x16x32_bf16 v[116:119], v[200:203], v[160:163], v[116:119]
	v_mfma_f32_16x16x32_bf16 v[112:115], v[208:211], v[160:163], v[112:115]
	v_mfma_f32_16x16x32_bf16 v[100:103], v[200:203], v[176:179], v[100:103]
	v_mfma_f32_16x16x32_bf16 v[96:99], v[208:211], v[176:179], v[96:99]
	v_mfma_f32_16x16x32_bf16 v[84:87], v[200:203], v[184:187], v[84:87]
	v_mfma_f32_16x16x32_bf16 v[80:83], v[208:211], v[184:187], v[80:83]
	v_mfma_f32_16x16x32_bf16 v[68:71], v[200:203], v[192:195], v[68:71]
	v_mfma_f32_16x16x32_bf16 v[64:67], v[208:211], v[192:195], v[64:67]
	v_mfma_f32_16x16x32_bf16 v[116:119], v[204:207], v[164:167], v[116:119]
	v_mfma_f32_16x16x32_bf16 v[112:115], v[212:215], v[164:167], v[112:115]
	v_mfma_f32_16x16x32_bf16 v[100:103], v[204:207], v[180:183], v[100:103]
	v_mfma_f32_16x16x32_bf16 v[96:99], v[212:215], v[180:183], v[96:99]
	v_mfma_f32_16x16x32_bf16 v[84:87], v[204:207], v[188:191], v[84:87]
	v_mfma_f32_16x16x32_bf16 v[80:83], v[212:215], v[188:191], v[80:83]
	v_mfma_f32_16x16x32_bf16 v[68:71], v[204:207], v[196:199], v[68:71]
	v_mfma_f32_16x16x32_bf16 v[64:67], v[212:215], v[196:199], v[64:67]
	s_setprio 0
	s_mov_b32 m0, s34
	v_lshl_add_u64 v[220:221], s[30:31], 0, v[144:145]
	s_barrier
	ds_read_b128 v[160:163], v172 offset:16384
	ds_read_b128 v[164:167], v172 offset:17408
	ds_read_b128 v[176:179], v172 offset:18432
	ds_read_b128 v[180:183], v172 offset:19456
	ds_read_b128 v[184:187], v172 offset:20480
	ds_read_b128 v[188:191], v172 offset:21504
	ds_read_b128 v[192:195], v172 offset:22528
	ds_read_b128 v[196:199], v172 offset:23552
	global_load_lds_dwordx4 v[220:221], off
	v_lshl_add_u64 v[222:223], s[30:31], 0, v[148:149]
	s_mov_b32 m0, s35
	s_nop 0
	global_load_lds_dwordx4 v[222:223], off
	s_barrier
	s_waitcnt lgkmcnt(0)
	s_setprio 1
	s_waitcnt lgkmcnt(0)
	v_mfma_f32_16x16x32_bf16 v[60:63], v[128:131], v[160:163], v[60:63]
	v_mfma_f32_16x16x32_bf16 v[56:59], v[136:139], v[160:163], v[56:59]
	v_mfma_f32_16x16x32_bf16 v[44:47], v[128:131], v[176:179], v[44:47]
	v_mfma_f32_16x16x32_bf16 v[40:43], v[136:139], v[176:179], v[40:43]
	v_mfma_f32_16x16x32_bf16 v[28:31], v[128:131], v[184:187], v[28:31]
	v_mfma_f32_16x16x32_bf16 v[24:27], v[136:139], v[184:187], v[24:27]
	v_mfma_f32_16x16x32_bf16 v[12:15], v[128:131], v[192:195], v[12:15]
	v_mfma_f32_16x16x32_bf16 v[8:11], v[136:139], v[192:195], v[8:11]
	v_mfma_f32_16x16x32_bf16 v[60:63], v[132:135], v[164:167], v[60:63]
	v_mfma_f32_16x16x32_bf16 v[56:59], v[140:143], v[164:167], v[56:59]
	v_mfma_f32_16x16x32_bf16 v[44:47], v[132:135], v[180:183], v[44:47]
	v_mfma_f32_16x16x32_bf16 v[40:43], v[140:143], v[180:183], v[40:43]
	v_mfma_f32_16x16x32_bf16 v[28:31], v[132:135], v[188:191], v[28:31]
	v_mfma_f32_16x16x32_bf16 v[24:27], v[140:143], v[188:191], v[24:27]
	v_mfma_f32_16x16x32_bf16 v[12:15], v[132:135], v[196:199], v[12:15]
	v_mfma_f32_16x16x32_bf16 v[8:11], v[140:143], v[196:199], v[8:11]
	s_setprio 0
	s_barrier
; #define PG8_STAGE(bufoff, gbase, voff) do { _Pragma("unroll") for (int _i = 0; _i < 2; ++_i) \
;         __builtin_amdgcn_global_load_lds((const unsigned*)((const char*)(gbase) + (voff)[_i]), (LAS unsigned*)(lds + (bufoff) + ldsw + _i * 8192), 16, 0, 0); } while (0)
; #define PG8_LDA(dst, b, h) do { _Pragma("unroll") for (int m = 0; m < 4; ++m) _Pragma("unroll") for (int k = 0; k < 2; ++k) dst[m][k] = *(const LAS bf16x8*)(lds + PG8_SA(b, h) + aoff + m * 2048 + k * 1024); } while (0)
; #define PG8_LDB(dst, b, h) do { _Pragma("unroll") for (int n = 0; n < 2; ++n) _Pragma("unroll") for (int k = 0; k < 2; ++k) dst[n][k] = *(const LAS bf16x8*)(lds + PG8_SB(b, h) + boff + n * 2048 + k * 1024); } while (0)
; #define PG8_MMA(ai, bj, At, Bt) do { __builtin_amdgcn_s_setprio(1); _Pragma("unroll") for (int m = 0; m < 4; ++m) _Pragma("unroll") for (int n = 0; n < 2; ++n) _Pragma("unroll") for (int k = 0; k < 2; ++k) \
;         acc[ai][bj][m][n] = __builtin_amdgcn_mfma_f32_16x16x32_bf16(Bt[n][k], At[m][k], acc[ai][bj][m][n], 0, 0, 0); __builtin_amdgcn_s_setprio(0); } while (0)
; #define PG8_WAIT_V(n) asm volatile("s_waitcnt vmcnt(" #n ")" ::: "memory")
; #define PG8_WAIT_L(n) asm volatile("s_waitcnt lgkmcnt(" #n ")" ::: "memory")
; #define PG8_BAR __builtin_amdgcn_s_barrier()
; #define PG8_SCHED __builtin_amdgcn_sched_barrier(0)
; template <class Epi>
; __device__ __forceinline__ void gemm_phase(LAS unsigned char* lds, const Gemm g, const Order& S, const Epi& E, const int tid) {
;     ...
;             PG8_BAR; PG8_WAIT_L(0); PG8_MMA(1, 0, At, B0); PG8_BAR; PG8_SCHED;
;             PG8_STAGE(PG8_SB(0, 1), b2 + hstepB, voffB);
;             PG8_WAIT_V(6); PG8_BAR; PG8_MMA(1, 1, At, B1); PG8_BAR;
;             PG8_LDB(B0, 1, 0); PG8_SCHED; PG8_LDA(At, 1, 0); PG8_STAGE(PG8_SA(0, 1), a2 + hstepA, voffA);
;             PG8_WAIT_L(8); PG8_BAR; PG8_WAIT_L(0); PG8_MMA(0, 0, At, B0); PG8_BAR; PG8_SCHED;
;             PG8_LDB(B1, 1, 1); PG8_STAGE(PG8_SB(1, 0), b3, voffB);
;             PG8_BAR; PG8_WAIT_L(0); PG8_MMA(0, 1, At, B1); PG8_BAR;
;             PG8_LDA(At, 1, 1); PG8_STAGE(PG8_SA(1, 0), a3, voffA);
;             PG8_BAR; PG8_WAIT_L(0); PG8_MMA(1, 0, At, B0); PG8_BAR; PG8_SCHED;
	s_add_u32 s52, s28, 0x80000
	s_addc_u32 s53, s29, 0
	s_add_i32 s55, s46, s33
	v_lshl_add_u64 v[128:129], s[52:53], 0, v[146:147]
	s_mov_b32 m0, s55
	s_nop 0
	global_load_lds_dwordx4 v[128:129], off
	v_lshl_add_u64 v[128:129], s[52:53], 0, v[150:151]
	s_add_i32 m0, s55, 0x2000
	s_nop 0
	global_load_lds_dwordx4 v[128:129], off
	s_waitcnt vmcnt(6)
	s_barrier
	s_setprio 1
	v_mfma_f32_16x16x32_bf16 v[52:55], v[200:203], v[160:163], v[52:55]
	v_mfma_f32_16x16x32_bf16 v[48:51], v[208:211], v[160:163], v[48:51]
	v_mfma_f32_16x16x32_bf16 v[36:39], v[200:203], v[176:179], v[36:39]
	v_mfma_f32_16x16x32_bf16 v[32:35], v[208:211], v[176:179], v[32:35]
	v_mfma_f32_16x16x32_bf16 v[20:23], v[200:203], v[184:187], v[20:23]
	v_mfma_f32_16x16x32_bf16 v[16:19], v[208:211], v[184:187], v[16:19]
	v_mfma_f32_16x16x32_bf16 v[4:7], v[200:203], v[192:195], v[4:7]
	v_mfma_f32_16x16x32_bf16 v[0:3], v[208:211], v[192:195], v[0:3]
	v_mfma_f32_16x16x32_bf16 v[52:55], v[204:207], v[164:167], v[52:55]
	v_mfma_f32_16x16x32_bf16 v[48:51], v[212:215], v[164:167], v[48:51]
	v_mfma_f32_16x16x32_bf16 v[36:39], v[204:207], v[180:183], v[36:39]
	v_mfma_f32_16x16x32_bf16 v[32:35], v[212:215], v[180:183], v[32:35]
	v_mfma_f32_16x16x32_bf16 v[20:23], v[204:207], v[188:191], v[20:23]
	v_mfma_f32_16x16x32_bf16 v[16:19], v[212:215], v[188:191], v[16:19]
	v_mfma_f32_16x16x32_bf16 v[4:7], v[204:207], v[196:199], v[4:7]
	v_mfma_f32_16x16x32_bf16 v[0:3], v[212:215], v[196:199], v[0:3]
	s_setprio 0
	s_add_i32 s52, 0, 0x18000
	v_add_u32_e32 v140, s52, v169
	s_barrier
	ds_read_b128 v[128:131], v140
	ds_read_b128 v[132:135], v140 offset:1024
	ds_read_b128 v[136:139], v140 offset:2048
	ds_read_b128 v[140:143], v140 offset:3072
	s_add_u32 s30, s30, 0x80000
	s_addc_u32 s31, s31, 0
	s_mov_b32 m0, s39
	v_lshl_add_u64 v[200:201], s[30:31], 0, v[144:145]
	ds_read_b128 v[160:163], v172 offset:32768
	ds_read_b128 v[164:167], v172 offset:33792
	ds_read_b128 v[176:179], v172 offset:34816
	ds_read_b128 v[180:183], v172 offset:35840
	ds_read_b128 v[184:187], v172 offset:36864
	ds_read_b128 v[188:191], v172 offset:37888
	ds_read_b128 v[192:195], v172 offset:38912
	ds_read_b128 v[196:199], v172 offset:39936
	global_load_lds_dwordx4 v[200:201], off
	v_lshl_add_u64 v[200:201], s[30:31], 0, v[148:149]
	s_mov_b32 m0, s40
	s_nop 0
	global_load_lds_dwordx4 v[200:201], off
	s_waitcnt lgkmcnt(8)
	s_barrier
	s_waitcnt lgkmcnt(0)
	s_setprio 1
	s_waitcnt lgkmcnt(0)
	v_mfma_f32_16x16x32_bf16 v[124:127], v[128:131], v[160:163], v[124:127]
	v_mfma_f32_16x16x32_bf16 v[120:123], v[136:139], v[160:163], v[120:123]
	v_mfma_f32_16x16x32_bf16 v[108:111], v[128:131], v[176:179], v[108:111]
	v_mfma_f32_16x16x32_bf16 v[104:107], v[136:139], v[176:179], v[104:107]
	v_mfma_f32_16x16x32_bf16 v[92:95], v[128:131], v[184:187], v[92:95]
	v_mfma_f32_16x16x32_bf16 v[88:91], v[136:139], v[184:187], v[88:91]
	v_mfma_f32_16x16x32_bf16 v[76:79], v[128:131], v[192:195], v[76:79]
	v_mfma_f32_16x16x32_bf16 v[72:75], v[136:139], v[192:195], v[72:75]
	v_mfma_f32_16x16x32_bf16 v[124:127], v[132:135], v[164:167], v[124:127]
	v_mfma_f32_16x16x32_bf16 v[120:123], v[140:143], v[164:167], v[120:123]
	v_mfma_f32_16x16x32_bf16 v[108:111], v[132:135], v[180:183], v[108:111]
	v_mfma_f32_16x16x32_bf16 v[104:107], v[140:143], v[180:183], v[104:107]
	v_mfma_f32_16x16x32_bf16 v[92:95], v[132:135], v[188:191], v[92:95]
	v_mfma_f32_16x16x32_bf16 v[88:91], v[140:143], v[188:191], v[88:91]
	v_mfma_f32_16x16x32_bf16 v[76:79], v[132:135], v[196:199], v[76:79]
	v_mfma_f32_16x16x32_bf16 v[72:75], v[140:143], v[196:199], v[72:75]
	s_setprio 0
	s_barrier
	s_add_i32 s30, 0, 0x1c000
	s_add_i32 s31, s52, s33
	v_add_u32_e32 v175, s30, v169
	v_lshl_add_u64 v[216:217], v[216:217], 0, s[12:13]
	s_mov_b32 m0, s31
	ds_read_b128 v[200:203], v175
	ds_read_b128 v[204:207], v175 offset:1024
	ds_read_b128 v[208:211], v175 offset:2048
	ds_read_b128 v[212:215], v175 offset:3072
	global_load_lds_dwordx4 v[216:217], off
	v_lshl_add_u64 v[216:217], v[218:219], 0, s[12:13]
	s_add_i32 m0, s31, 0x2000
	s_nop 0
	global_load_lds_dwordx4 v[216:217], off
	s_barrier
	s_waitcnt lgkmcnt(0)
	s_setprio 1
	s_waitcnt lgkmcnt(0)
	v_mfma_f32_16x16x32_bf16 v[116:119], v[200:203], v[160:163], v[116:119]
	v_mfma_f32_16x16x32_bf16 v[112:115], v[208:211], v[160:163], v[112:115]
	v_mfma_f32_16x16x32_bf16 v[100:103], v[200:203], v[176:179], v[100:103]
	v_mfma_f32_16x16x32_bf16 v[96:99], v[208:211], v[176:179], v[96:99]
	v_mfma_f32_16x16x32_bf16 v[84:87], v[200:203], v[184:187], v[84:87]
	v_mfma_f32_16x16x32_bf16 v[80:83], v[208:211], v[184:187], v[80:83]
	v_mfma_f32_16x16x32_bf16 v[68:71], v[200:203], v[192:195], v[68:71]
	v_mfma_f32_16x16x32_bf16 v[64:67], v[208:211], v[192:195], v[64:67]
	v_mfma_f32_16x16x32_bf16 v[116:119], v[204:207], v[164:167], v[116:119]
	v_mfma_f32_16x16x32_bf16 v[112:115], v[212:215], v[164:167], v[112:115]
	v_mfma_f32_16x16x32_bf16 v[100:103], v[204:207], v[180:183], v[100:103]
	v_mfma_f32_16x16x32_bf16 v[96:99], v[212:215], v[180:183], v[96:99]
	v_mfma_f32_16x16x32_bf16 v[84:87], v[204:207], v[188:191], v[84:87]
	v_mfma_f32_16x16x32_bf16 v[80:83], v[212:215], v[188:191], v[80:83]
	v_mfma_f32_16x16x32_bf16 v[68:71], v[204:207], v[196:199], v[68:71]
	v_mfma_f32_16x16x32_bf16 v[64:67], v[212:215], v[196:199], v[64:67]
	s_setprio 0
	s_mov_b32 m0, s43
	v_lshl_add_u64 v[216:217], v[220:221], 0, s[12:13]
	s_barrier
	ds_read_b128 v[160:163], v172 offset:49152
	ds_read_b128 v[164:167], v172 offset:50176
	ds_read_b128 v[176:179], v172 offset:51200
	ds_read_b128 v[180:183], v172 offset:52224
	ds_read_b128 v[184:187], v172 offset:53248
	ds_read_b128 v[188:191], v172 offset:54272
	ds_read_b128 v[192:195], v172 offset:55296
	ds_read_b128 v[196:199], v172 offset:56320
	global_load_lds_dwordx4 v[216:217], off
	v_lshl_add_u64 v[216:217], v[222:223], 0, s[12:13]
	s_mov_b32 m0, s44
	s_nop 0
	global_load_lds_dwordx4 v[216:217], off
	s_barrier
; #define PG8_STAGE(bufoff, gbase, voff) do { _Pragma("unroll") for (int _i = 0; _i < 2; ++_i) \
;         __builtin_amdgcn_global_load_lds((const unsigned*)((const char*)(gbase) + (voff)[_i]), (LAS unsigned*)(lds + (bufoff) + ldsw + _i * 8192), 16, 0, 0); } while (0)
; #define PG8_WAIT_V(n) asm volatile("s_waitcnt vmcnt(" #n ")" ::: "memory")
; #define PG8_WAIT_L(n) asm volatile("s_waitcnt lgkmcnt(" #n ")" ::: "memory")
; template <class Epi>
; __device__ __forceinline__ void gemm_phase(LAS unsigned char* lds, const Gemm g, const Order& S, const Epi& E, const int tid) {
;     ...
;             PG8_BAR; PG8_WAIT_L(0); PG8_MMA(1, 0, At, B0); PG8_BAR; PG8_SCHED;
;             PG8_STAGE(PG8_SB(1, 1), b3 + hstepB, voffB);
;             PG8_WAIT_V(6); PG8_BAR; PG8_MMA(1, 1, At, B1); PG8_BAR;
;     __device__ __forceinline__ void operator()(const f32x4 (&acc)[2][2][4][2], const Unit& u, int wr, int wc, int fr, int fq) const {
;     ...
;             if (BASE_F32) {
; #pragma unroll
;                 for (int m = 0; m < 4; m += 2) {
;                     f32x4 bs[2][2][2];
; #pragma unroll
;                     for (int mm = 0; mm < 2; ++mm) { const size_t off = (size_t)(row0 + ai * HALF + (m + mm) * 16) * DM + col0;
; #pragma unroll
;                         for (int bj = 0; bj < 2; ++bj)
; #pragma unroll
;                             for (int n = 0; n < 2; ++n) bs[mm][bj][n] = *(const f32x4*)(basef + off + bj * HALF + n * 4); }
; #pragma unroll
;                     for (int mm = 0; mm < 2; ++mm) { const size_t off = (size_t)(row0 + ai * HALF + (m + mm) * 16) * DM + col0;
;                         float ss = 0.f;
; #pragma unroll
;                         for (int bj = 0; bj < 2; ++bj) { const f32x4 v0 = bs[mm][bj][0] + acc[ai][bj][m + mm][0], v1 = bs[mm][bj][1] + acc[ai][bj][m + mm][1];
;                             ss += (v0[0] * v0[0] + v0[1] * v0[1]) + (v0[2] * v0[2] + v0[3] * v0[3]) + (v1[0] * v1[0] + v1[1] * v1[1]) + (v1[2] * v1[2] + v1[3] * v1[3]);
;                             u32x4 w; w.x = pk2(v0[0], v0[1]); w.y = pk2(v0[2], v0[3]); w.z = pk2(v1[0], v1[1]); w.w = pk2(v1[2], v1[3]);
;                             *(u32x4*)(out + off + bj * HALF) = w; }
;                         if (ssqp) { ss += __shfl_xor(ss, 16); ss += __shfl_xor(ss, 32); if (fq == 0) ssqp[(size_t)(row0 + ai * HALF + (m + mm) * 16) * 32 + u.pn * 4 + wc] = ss; } }
	s_waitcnt lgkmcnt(0)
	s_setprio 1
	s_waitcnt lgkmcnt(0)
	v_mfma_f32_16x16x32_bf16 v[60:63], v[128:131], v[160:163], v[60:63]
	v_mfma_f32_16x16x32_bf16 v[56:59], v[136:139], v[160:163], v[56:59]
	v_mfma_f32_16x16x32_bf16 v[44:47], v[128:131], v[176:179], v[44:47]
	v_mfma_f32_16x16x32_bf16 v[40:43], v[136:139], v[176:179], v[40:43]
	v_mfma_f32_16x16x32_bf16 v[28:31], v[128:131], v[184:187], v[28:31]
	v_mfma_f32_16x16x32_bf16 v[24:27], v[136:139], v[184:187], v[24:27]
	v_mfma_f32_16x16x32_bf16 v[12:15], v[128:131], v[192:195], v[12:15]
	v_mfma_f32_16x16x32_bf16 v[8:11], v[136:139], v[192:195], v[8:11]
	v_mfma_f32_16x16x32_bf16 v[60:63], v[132:135], v[164:167], v[60:63]
	v_mfma_f32_16x16x32_bf16 v[56:59], v[140:143], v[164:167], v[56:59]
	v_mfma_f32_16x16x32_bf16 v[44:47], v[132:135], v[180:183], v[44:47]
	v_mfma_f32_16x16x32_bf16 v[40:43], v[140:143], v[180:183], v[40:43]
	v_mfma_f32_16x16x32_bf16 v[28:31], v[132:135], v[188:191], v[28:31]
	v_mfma_f32_16x16x32_bf16 v[24:27], v[140:143], v[188:191], v[24:27]
	v_mfma_f32_16x16x32_bf16 v[12:15], v[132:135], v[196:199], v[12:15]
	v_mfma_f32_16x16x32_bf16 v[8:11], v[140:143], v[196:199], v[8:11]
	s_setprio 0
	s_barrier
	s_add_u32 s28, s28, 0x80080
	s_addc_u32 s29, s29, 0
	s_add_i32 s30, s30, s33
	v_lshl_add_u64 v[128:129], s[28:29], 0, v[146:147]
	s_mov_b32 m0, s30
	s_nop 0
	global_load_lds_dwordx4 v[128:129], off
	v_lshl_add_u64 v[128:129], s[28:29], 0, v[150:151]
	s_add_i32 m0, s30, 0x2000
	s_nop 0
	global_load_lds_dwordx4 v[128:129], off
	s_waitcnt vmcnt(6)
	s_barrier
	s_setprio 1
	v_mfma_f32_16x16x32_bf16 v[52:55], v[200:203], v[160:163], v[52:55]
	v_mfma_f32_16x16x32_bf16 v[48:51], v[208:211], v[160:163], v[48:51]
	v_mfma_f32_16x16x32_bf16 v[36:39], v[200:203], v[176:179], v[36:39]
	v_mfma_f32_16x16x32_bf16 v[32:35], v[208:211], v[176:179], v[32:35]
	v_mfma_f32_16x16x32_bf16 v[20:23], v[200:203], v[184:187], v[20:23]
	v_mfma_f32_16x16x32_bf16 v[16:19], v[208:211], v[184:187], v[16:19]
	v_mfma_f32_16x16x32_bf16 v[4:7], v[200:203], v[192:195], v[4:7]
	v_mfma_f32_16x16x32_bf16 v[0:3], v[208:211], v[192:195], v[0:3]
	v_mfma_f32_16x16x32_bf16 v[52:55], v[204:207], v[164:167], v[52:55]
	v_mfma_f32_16x16x32_bf16 v[48:51], v[212:215], v[164:167], v[48:51]
	v_mfma_f32_16x16x32_bf16 v[36:39], v[204:207], v[180:183], v[36:39]
	v_mfma_f32_16x16x32_bf16 v[32:35], v[212:215], v[180:183], v[32:35]
	v_mfma_f32_16x16x32_bf16 v[20:23], v[204:207], v[188:191], v[20:23]
	v_mfma_f32_16x16x32_bf16 v[16:19], v[212:215], v[188:191], v[16:19]
	v_mfma_f32_16x16x32_bf16 v[4:7], v[204:207], v[196:199], v[4:7]
	v_mfma_f32_16x16x32_bf16 v[0:3], v[212:215], v[196:199], v[0:3]
	s_setprio 0
	s_add_i32 s51, s51, 2
	s_add_u32 s26, s26, 0x100
	s_addc_u32 s27, s27, 0
	s_add_u32 s49, s49, 0x100
	s_addc_u32 s50, s50, 0
	s_cmp_gt_u32 s51, 29
	s_barrier
	s_cbranch_scc0 .LBB0_592
	v_lshl_add_u32 v162, s8, 8, v168
	v_lshl_or_b32 v160, s6, 8, v170
	v_ashrrev_i32_e32 v161, 31, v160
	v_ashrrev_i32_e32 v163, 31, v162
	v_lshl_add_u64 v[164:165], v[160:161], 2, s[56:57]
	v_lshlrev_b64 v[128:129], 13, v[162:163]
	v_or_b32_e32 v166, 16, v162
	v_lshl_add_u64 v[128:129], v[164:165], 0, v[128:129]
	v_ashrrev_i32_e32 v167, 31, v166
	global_load_dwordx4 v[176:179], v[128:129], off
	global_load_dwordx4 v[180:183], v[128:129], off offset:16
	global_load_dwordx4 v[184:187], v[128:129], off offset:512
	global_load_dwordx4 v[188:191], v[128:129], off offset:528
	v_lshlrev_b64 v[128:129], 13, v[166:167]
	v_lshl_add_u64 v[132:133], v[164:165], 0, v[128:129]
	global_load_dwordx4 v[136:139], v[132:133], off offset:16
	global_load_dwordx4 v[140:143], v[132:133], off
	global_load_dwordx4 v[128:131], v[132:133], off offset:528
	s_nop 0
	global_load_dwordx4 v[132:135], v[132:133], off offset:512
	v_lshlrev_b64 v[192:193], 12, v[162:163]
	s_lshl_b32 s26, s6, 2
	v_cndmask_b32_e64 v175, 0, 1, s[10:11]
	v_lshl_add_u64 v[192:193], s[22:23], 0, v[192:193]
	s_ashr_i32 s27, s26, 31
	v_cmp_ne_u32_e64 s[6:7], 1, v175
	s_andn2_b64 vcc, exec, s[10:11]
	v_lshl_add_u64 v[192:193], v[160:161], 1, v[192:193]
	s_waitcnt vmcnt(0)
	v_pk_add_f32 v[126:127], v[126:127], v[178:179]
	v_pk_add_f32 v[124:125], v[124:125], v[176:177]
	v_pk_add_f32 v[122:123], v[122:123], v[182:183]
	v_pk_add_f32 v[120:121], v[120:121], v[180:181]
	v_pk_add_f32 v[118:119], v[118:119], v[186:187]
	v_pk_add_f32 v[116:117], v[116:117], v[184:185]
	v_pk_add_f32 v[114:115], v[114:115], v[190:191]
	v_pk_add_f32 v[112:113], v[112:113], v[188:189]
	v_cvt_pk_bf16_f32 v176, v124, v125
	v_cvt_pk_bf16_f32 v177, v126, v127
	v_cvt_pk_bf16_f32 v178, v120, v121
	v_cvt_pk_bf16_f32 v179, v122, v123
	v_cvt_pk_bf16_f32 v180, v116, v117
	v_cvt_pk_bf16_f32 v181, v118, v119
	v_cvt_pk_bf16_f32 v182, v112, v113
	v_cvt_pk_bf16_f32 v183, v114, v115
	global_store_dwordx4 v[192:193], v[176:179], off nt
	global_store_dwordx4 v[192:193], v[180:183], off offset:256 nt
	s_cbranch_vccnz .LBB0_597
	v_mul_f32_e32 v115, v115, v115
	v_fmac_f32_e32 v115, v114, v114
	v_mul_f32_e32 v114, v117, v117
	v_mul_f32_e32 v123, v123, v123
	v_fmac_f32_e32 v114, v116, v116
	v_mul_f32_e32 v116, v119, v119
	v_fmac_f32_e32 v123, v122, v122
	v_mul_f32_e32 v122, v125, v125
	v_fmac_f32_e32 v116, v118, v118
	v_mul_f32_e32 v113, v113, v113
	v_fmac_f32_e32 v122, v124, v124
	v_mul_f32_e32 v124, v127, v127
	v_add_f32_e32 v114, v114, v116
	v_fmac_f32_e32 v113, v112, v112
	v_fmac_f32_e32 v124, v126, v126
	v_mul_f32_e32 v121, v121, v121
	v_add_f32_e32 v112, v114, v113
	v_and_b32_e32 v114, 64, v174
	v_add_f32_e32 v122, v122, v124
	v_fmac_f32_e32 v121, v120, v120
	v_xor_b32_e32 v113, 16, v174
	v_add_u32_e32 v114, 64, v114
	v_add_f32_e32 v120, v122, v121
	v_cmp_lt_i32_e32 vcc, v113, v114
	v_add_f32_e32 v120, v123, v120
	v_add_f32_e32 v112, v115, v112
	v_cndmask_b32_e32 v113, v174, v113, vcc
	v_add_f32_e32 v112, v120, v112
	v_lshlrev_b32_e32 v113, 2, v113
	ds_bpermute_b32 v113, v113, v112
	s_waitcnt lgkmcnt(0)
	v_add_f32_e32 v112, v112, v113
	v_xor_b32_e32 v113, 32, v174
	v_cmp_lt_i32_e32 vcc, v113, v114
	s_nop 1
	v_cndmask_b32_e32 v113, v174, v113, vcc
	v_lshlrev_b32_e32 v113, 2, v113
	ds_bpermute_b32 v113, v113, v112
	s_and_saveexec_b64 s[28:29], s[0:1]
	s_cbranch_execz .LBB0_596
	v_lshlrev_b64 v[114:115], 7, v[162:163]
	v_lshl_add_u64 v[114:115], s[24:25], 0, v[114:115]
	v_lshl_add_u64 v[114:115], s[26:27], 2, v[114:115]
	s_lshl_b32 s8, s41, 2
	v_lshl_add_u64 v[114:115], v[114:115], 0, s[8:9]
	s_waitcnt lgkmcnt(0)
	v_add_f32_e32 v112, v112, v113
	global_store_dword v[114:115], v112, off

;     __device__ __forceinline__ void operator()(const f32x4 (&acc)[2][2][4][2], const Unit& u, int wr, int wc, int fr, int fq) const {
;     ...
;                     for (int mm = 0; mm < 2; ++mm) { const size_t off = (size_t)(row0 + ai * HALF + (m + mm) * 16) * DM + col0;
; #pragma unroll
;                         for (int bj = 0; bj < 2; ++bj)
; #pragma unroll
;                             for (int n = 0; n < 2; ++n) bs[mm][bj][n] = *(const f32x4*)(basef + off + bj * HALF + n * 4); }
; #pragma unroll
;                     for (int mm = 0; mm < 2; ++mm) { const size_t off = (size_t)(row0 + ai * HALF + (m + mm) * 16) * DM + col0;
;                         float ss = 0.f;
; #pragma unroll
;                         for (int bj = 0; bj < 2; ++bj) { const f32x4 v0 = bs[mm][bj][0] + acc[ai][bj][m + mm][0], v1 = bs[mm][bj][1] + acc[ai][bj][m + mm][1];
;                             ss += (v0[0] * v0[0] + v0[1] * v0[1]) + (v0[2] * v0[2] + v0[3] * v0[3]) + (v1[0] * v1[0] + v1[1] * v1[1]) + (v1[2] * v1[2] + v1[3] * v1[3]);
;                             u32x4 w; w.x = pk2(v0[0], v0[1]); w.y = pk2(v0[2], v0[3]); w.z = pk2(v1[0], v1[1]); w.w = pk2(v1[2], v1[3]);
;                             *(u32x4*)(out + off + bj * HALF) = w; }
;                         if (ssqp) { ss += __shfl_xor(ss, 16); ss += __shfl_xor(ss, 32); if (fq == 0) ssqp[(size_t)(row0 + ai * HALF + (m + mm) * 16) * 32 + u.pn * 4 + wc] = ss; } }
.LBB0_597:
	v_lshlrev_b64 v[116:117], 12, v[166:167]
	v_pk_add_f32 v[110:111], v[110:111], v[142:143]
	v_pk_add_f32 v[108:109], v[108:109], v[140:141]
	v_pk_add_f32 v[106:107], v[106:107], v[138:139]
	v_pk_add_f32 v[104:105], v[104:105], v[136:137]
	v_lshl_add_u64 v[116:117], s[22:23], 0, v[116:117]
	v_cvt_pk_bf16_f32 v112, v108, v109
	s_waitcnt lgkmcnt(0)
	v_cvt_pk_bf16_f32 v113, v110, v111
	v_cvt_pk_bf16_f32 v114, v104, v105
	v_cvt_pk_bf16_f32 v115, v106, v107
	v_lshl_add_u64 v[116:117], v[160:161], 1, v[116:117]
	v_pk_add_f32 v[102:103], v[102:103], v[134:135]
	v_pk_add_f32 v[100:101], v[100:101], v[132:133]
	v_pk_add_f32 v[98:99], v[98:99], v[130:131]
	v_pk_add_f32 v[96:97], v[96:97], v[128:129]
	global_store_dwordx4 v[116:117], v[112:115], off nt
	s_and_b64 vcc, exec, s[6:7]
	s_nop 0
	v_cvt_pk_bf16_f32 v112, v100, v101
	v_cvt_pk_bf16_f32 v113, v102, v103
	v_cvt_pk_bf16_f32 v114, v96, v97
	v_cvt_pk_bf16_f32 v115, v98, v99
	global_store_dwordx4 v[116:117], v[112:115], off offset:256 nt
	s_cbranch_vccnz .LBB0_601
	v_mul_f32_e32 v99, v99, v99
	v_fmac_f32_e32 v99, v98, v98
	v_mul_f32_e32 v98, v101, v101
	v_mul_f32_e32 v107, v107, v107
	v_fmac_f32_e32 v98, v100, v100
	v_mul_f32_e32 v100, v103, v103
	v_fmac_f32_e32 v107, v106, v106
	v_mul_f32_e32 v106, v109, v109
	v_fmac_f32_e32 v100, v102, v102
	v_mul_f32_e32 v97, v97, v97
	v_fmac_f32_e32 v106, v108, v108
	v_mul_f32_e32 v108, v111, v111
	v_add_f32_e32 v98, v98, v100
	v_fmac_f32_e32 v97, v96, v96
	v_fmac_f32_e32 v108, v110, v110
	v_mul_f32_e32 v105, v105, v105
	v_add_f32_e32 v96, v98, v97
	v_and_b32_e32 v98, 64, v174
	v_add_f32_e32 v106, v106, v108
	v_fmac_f32_e32 v105, v104, v104
	v_xor_b32_e32 v97, 16, v174
	v_add_u32_e32 v98, 64, v98
	v_add_f32_e32 v104, v106, v105
	v_cmp_lt_i32_e32 vcc, v97, v98
	v_add_f32_e32 v104, v107, v104
	v_add_f32_e32 v96, v99, v96
	v_cndmask_b32_e32 v97, v174, v97, vcc
	v_add_f32_e32 v96, v104, v96
	v_lshlrev_b32_e32 v97, 2, v97
	ds_bpermute_b32 v97, v97, v96
	s_waitcnt lgkmcnt(0)
	v_add_f32_e32 v96, v96, v97
	v_xor_b32_e32 v97, 32, v174
	v_cmp_lt_i32_e32 vcc, v97, v98
	s_nop 1
	v_cndmask_b32_e32 v97, v174, v97, vcc
	v_lshlrev_b32_e32 v97, 2, v97
	ds_bpermute_b32 v97, v97, v96
	s_and_saveexec_b64 s[28:29], s[0:1]
	s_cbranch_execz .LBB0_600
	v_lshlrev_b64 v[98:99], 7, v[166:167]
	v_lshl_add_u64 v[98:99], s[24:25], 0, v[98:99]
	v_lshl_add_u64 v[98:99], s[26:27], 2, v[98:99]
	s_lshl_b32 s8, s41, 2
	v_lshl_add_u64 v[98:99], v[98:99], 0, s[8:9]
	s_waitcnt lgkmcnt(0)
	v_add_f32_e32 v96, v96, v97
	global_store_dword v[98:99], v96, off

;     __device__ __forceinline__ void operator()(const f32x4 (&acc)[2][2][4][2], const Unit& u, int wr, int wc, int fr, int fq) const {
;     ...
;                 for (int m = 0; m < 4; m += 2) {
;                     f32x4 bs[2][2][2];
; #pragma unroll
;                     for (int mm = 0; mm < 2; ++mm) { const size_t off = (size_t)(row0 + ai * HALF + (m + mm) * 16) * DM + col0;
; #pragma unroll
;                         for (int bj = 0; bj < 2; ++bj)
; #pragma unroll
;                             for (int n = 0; n < 2; ++n) bs[mm][bj][n] = *(const f32x4*)(basef + off + bj * HALF + n * 4); }
; #pragma unroll
;                     for (int mm = 0; mm < 2; ++mm) { const size_t off = (size_t)(row0 + ai * HALF + (m + mm) * 16) * DM + col0;
;                         float ss = 0.f;
; #pragma unroll
;                         for (int bj = 0; bj < 2; ++bj) { const f32x4 v0 = bs[mm][bj][0] + acc[ai][bj][m + mm][0], v1 = bs[mm][bj][1] + acc[ai][bj][m + mm][1];
;                             ss += (v0[0] * v0[0] + v0[1] * v0[1]) + (v0[2] * v0[2] + v0[3] * v0[3]) + (v1[0] * v1[0] + v1[1] * v1[1]) + (v1[2] * v1[2] + v1[3] * v1[3]);
;                             u32x4 w; w.x = pk2(v0[0], v0[1]); w.y = pk2(v0[2], v0[3]); w.z = pk2(v1[0], v1[1]); w.w = pk2(v1[2], v1[3]);
;                             *(u32x4*)(out + off + bj * HALF) = w; }
;                         if (ssqp) { ss += __shfl_xor(ss, 16); ss += __shfl_xor(ss, 32); if (fq == 0) ssqp[(size_t)(row0 + ai * HALF + (m + mm) * 16) * 32 + u.pn * 4 + wc] = ss; } }
.LBB0_601:
	s_nop 0
	v_or_b32_e32 v114, 32, v162
	v_ashrrev_i32_e32 v115, 31, v114
	s_waitcnt lgkmcnt(0)
	v_lshlrev_b64 v[96:97], 13, v[114:115]
	v_or_b32_e32 v112, 48, v162
	v_lshl_add_u64 v[96:97], v[164:165], 0, v[96:97]
	v_ashrrev_i32_e32 v113, 31, v112
	global_load_dwordx4 v[116:119], v[96:97], off
	global_load_dwordx4 v[120:123], v[96:97], off offset:16
	global_load_dwordx4 v[124:127], v[96:97], off offset:512
	global_load_dwordx4 v[128:131], v[96:97], off offset:528
	v_lshlrev_b64 v[96:97], 13, v[112:113]
	v_lshl_add_u64 v[100:101], v[164:165], 0, v[96:97]
	global_load_dwordx4 v[104:107], v[100:101], off offset:16
	global_load_dwordx4 v[108:111], v[100:101], off
	global_load_dwordx4 v[96:99], v[100:101], off offset:528
	s_nop 0
	global_load_dwordx4 v[100:103], v[100:101], off offset:512
	v_lshlrev_b64 v[132:133], 12, v[114:115]
	v_lshl_add_u64 v[132:133], s[22:23], 0, v[132:133]
	s_and_b64 vcc, exec, s[6:7]
	v_lshl_add_u64 v[132:133], v[160:161], 1, v[132:133]
	s_waitcnt vmcnt(7)
	v_pk_add_f32 v[94:95], v[94:95], v[118:119]
	v_pk_add_f32 v[92:93], v[92:93], v[116:117]
	s_waitcnt vmcnt(6)
	v_pk_add_f32 v[90:91], v[90:91], v[122:123]
	v_pk_add_f32 v[88:89], v[88:89], v[120:121]
	s_waitcnt vmcnt(5)
	v_pk_add_f32 v[86:87], v[86:87], v[126:127]
	v_pk_add_f32 v[84:85], v[84:85], v[124:125]
	s_waitcnt vmcnt(4)
	v_pk_add_f32 v[82:83], v[82:83], v[130:131]
	v_pk_add_f32 v[80:81], v[80:81], v[128:129]
	v_cvt_pk_bf16_f32 v116, v92, v93
	v_cvt_pk_bf16_f32 v117, v94, v95
	v_cvt_pk_bf16_f32 v118, v88, v89
	v_cvt_pk_bf16_f32 v119, v90, v91
	v_cvt_pk_bf16_f32 v120, v84, v85
	v_cvt_pk_bf16_f32 v121, v86, v87
	v_cvt_pk_bf16_f32 v122, v80, v81
	v_cvt_pk_bf16_f32 v123, v82, v83
	global_store_dwordx4 v[132:133], v[116:119], off nt
	global_store_dwordx4 v[132:133], v[120:123], off offset:256 nt
	s_cbranch_vccnz .LBB0_605
	v_mul_f32_e32 v83, v83, v83
	v_fmac_f32_e32 v83, v82, v82
	v_mul_f32_e32 v82, v85, v85
	v_mul_f32_e32 v91, v91, v91
	v_fmac_f32_e32 v82, v84, v84
	v_mul_f32_e32 v84, v87, v87
	v_fmac_f32_e32 v91, v90, v90
	v_mul_f32_e32 v90, v93, v93
	v_fmac_f32_e32 v84, v86, v86
	v_mul_f32_e32 v81, v81, v81
	v_fmac_f32_e32 v90, v92, v92
	v_mul_f32_e32 v92, v95, v95
	v_add_f32_e32 v82, v82, v84
	v_fmac_f32_e32 v81, v80, v80
	v_fmac_f32_e32 v92, v94, v94
	v_mul_f32_e32 v89, v89, v89
	v_add_f32_e32 v80, v82, v81
	v_and_b32_e32 v82, 64, v174
	v_add_f32_e32 v90, v90, v92
	v_fmac_f32_e32 v89, v88, v88
	v_xor_b32_e32 v81, 16, v174
	v_add_u32_e32 v82, 64, v82
	v_add_f32_e32 v88, v90, v89
	v_cmp_lt_i32_e32 vcc, v81, v82
	v_add_f32_e32 v88, v91, v88
	v_add_f32_e32 v80, v83, v80
	v_cndmask_b32_e32 v81, v174, v81, vcc
	v_add_f32_e32 v80, v88, v80
	v_lshlrev_b32_e32 v81, 2, v81
	ds_bpermute_b32 v81, v81, v80
	s_waitcnt lgkmcnt(0)
	v_add_f32_e32 v80, v80, v81
	v_xor_b32_e32 v81, 32, v174
	v_cmp_lt_i32_e32 vcc, v81, v82
	s_nop 1
	v_cndmask_b32_e32 v81, v174, v81, vcc
	v_lshlrev_b32_e32 v81, 2, v81
	ds_bpermute_b32 v81, v81, v80
	s_and_saveexec_b64 s[28:29], s[0:1]
	s_cbranch_execz .LBB0_604
	v_lshlrev_b64 v[82:83], 7, v[114:115]
	v_lshl_add_u64 v[82:83], s[24:25], 0, v[82:83]
	v_lshl_add_u64 v[82:83], s[26:27], 2, v[82:83]
	s_lshl_b32 s8, s41, 2
	v_lshl_add_u64 v[82:83], v[82:83], 0, s[8:9]
	s_waitcnt lgkmcnt(0)
	v_add_f32_e32 v80, v80, v81
	global_store_dword v[82:83], v80, off

;     __device__ __forceinline__ void operator()(const f32x4 (&acc)[2][2][4][2], const Unit& u, int wr, int wc, int fr, int fq) const {
;     ...
;                     for (int mm = 0; mm < 2; ++mm) { const size_t off = (size_t)(row0 + ai * HALF + (m + mm) * 16) * DM + col0;
;                         float ss = 0.f;
; #pragma unroll
;                         for (int bj = 0; bj < 2; ++bj) { const f32x4 v0 = bs[mm][bj][0] + acc[ai][bj][m + mm][0], v1 = bs[mm][bj][1] + acc[ai][bj][m + mm][1];
;                             ss += (v0[0] * v0[0] + v0[1] * v0[1]) + (v0[2] * v0[2] + v0[3] * v0[3]) + (v1[0] * v1[0] + v1[1] * v1[1]) + (v1[2] * v1[2] + v1[3] * v1[3]);
;                             u32x4 w; w.x = pk2(v0[0], v0[1]); w.y = pk2(v0[2], v0[3]); w.z = pk2(v1[0], v1[1]); w.w = pk2(v1[2], v1[3]);
;                             *(u32x4*)(out + off + bj * HALF) = w; }
;                         if (ssqp) { ss += __shfl_xor(ss, 16); ss += __shfl_xor(ss, 32); if (fq == 0) ssqp[(size_t)(row0 + ai * HALF + (m + mm) * 16) * 32 + u.pn * 4 + wc] = ss; } }
.LBB0_605:
	v_lshlrev_b64 v[84:85], 12, v[112:113]
	s_waitcnt vmcnt(4)
	v_pk_add_f32 v[78:79], v[78:79], v[110:111]
	v_pk_add_f32 v[76:77], v[76:77], v[108:109]
	v_pk_add_f32 v[74:75], v[74:75], v[106:107]
	v_pk_add_f32 v[72:73], v[72:73], v[104:105]
	v_lshl_add_u64 v[84:85], s[22:23], 0, v[84:85]
	v_cvt_pk_bf16_f32 v80, v76, v77
	s_waitcnt lgkmcnt(0)
	v_cvt_pk_bf16_f32 v81, v78, v79
	v_cvt_pk_bf16_f32 v82, v72, v73
	v_cvt_pk_bf16_f32 v83, v74, v75
	v_lshl_add_u64 v[84:85], v[160:161], 1, v[84:85]
	s_waitcnt vmcnt(2)
	v_pk_add_f32 v[70:71], v[70:71], v[102:103]
	v_pk_add_f32 v[68:69], v[68:69], v[100:101]
	v_pk_add_f32 v[66:67], v[66:67], v[98:99]
	v_pk_add_f32 v[64:65], v[64:65], v[96:97]
	global_store_dwordx4 v[84:85], v[80:83], off nt
	s_and_b64 vcc, exec, s[6:7]
	s_nop 0
	v_cvt_pk_bf16_f32 v80, v68, v69
	v_cvt_pk_bf16_f32 v81, v70, v71
	v_cvt_pk_bf16_f32 v82, v64, v65
	v_cvt_pk_bf16_f32 v83, v66, v67
	global_store_dwordx4 v[84:85], v[80:83], off offset:256 nt
	s_cbranch_vccnz .LBB0_609
	v_mul_f32_e32 v67, v67, v67
	v_fmac_f32_e32 v67, v66, v66
	v_mul_f32_e32 v66, v69, v69
	v_mul_f32_e32 v75, v75, v75
	v_fmac_f32_e32 v66, v68, v68
	v_mul_f32_e32 v68, v71, v71
	v_fmac_f32_e32 v75, v74, v74
	v_mul_f32_e32 v74, v77, v77
	v_fmac_f32_e32 v68, v70, v70
	v_mul_f32_e32 v65, v65, v65
	v_fmac_f32_e32 v74, v76, v76
	v_mul_f32_e32 v76, v79, v79
	v_add_f32_e32 v66, v66, v68
	v_fmac_f32_e32 v65, v64, v64
	v_fmac_f32_e32 v76, v78, v78
	v_mul_f32_e32 v73, v73, v73
	v_add_f32_e32 v64, v66, v65
	v_and_b32_e32 v66, 64, v174
	v_add_f32_e32 v74, v74, v76
	v_fmac_f32_e32 v73, v72, v72
	v_xor_b32_e32 v65, 16, v174
	v_add_u32_e32 v66, 64, v66
	v_add_f32_e32 v72, v74, v73
	v_cmp_lt_i32_e32 vcc, v65, v66
	v_add_f32_e32 v72, v75, v72
	v_add_f32_e32 v64, v67, v64
	v_cndmask_b32_e32 v65, v174, v65, vcc
	v_add_f32_e32 v64, v72, v64
	v_lshlrev_b32_e32 v65, 2, v65
	ds_bpermute_b32 v65, v65, v64
	s_waitcnt lgkmcnt(0)
	v_add_f32_e32 v64, v64, v65
	v_xor_b32_e32 v65, 32, v174
	v_cmp_lt_i32_e32 vcc, v65, v66
	s_nop 1
	v_cndmask_b32_e32 v65, v174, v65, vcc
	v_lshlrev_b32_e32 v65, 2, v65
	ds_bpermute_b32 v65, v65, v64
	s_and_saveexec_b64 s[28:29], s[0:1]
	s_cbranch_execz .LBB0_608
	v_lshlrev_b64 v[66:67], 7, v[112:113]
	v_lshl_add_u64 v[66:67], s[24:25], 0, v[66:67]
	v_lshl_add_u64 v[66:67], s[26:27], 2, v[66:67]
	s_lshl_b32 s8, s41, 2
	v_lshl_add_u64 v[66:67], v[66:67], 0, s[8:9]
	s_waitcnt lgkmcnt(0)
	v_add_f32_e32 v64, v64, v65
	global_store_dword v[66:67], v64, off

;     __device__ __forceinline__ void operator()(const f32x4 (&acc)[2][2][4][2], const Unit& u, int wr, int wc, int fr, int fq) const {
;     ...
;                 for (int m = 0; m < 4; m += 2) {
;                     f32x4 bs[2][2][2];
; #pragma unroll
;                     for (int mm = 0; mm < 2; ++mm) { const size_t off = (size_t)(row0 + ai * HALF + (m + mm) * 16) * DM + col0;
; #pragma unroll
;                         for (int bj = 0; bj < 2; ++bj)
; #pragma unroll
;                             for (int n = 0; n < 2; ++n) bs[mm][bj][n] = *(const f32x4*)(basef + off + bj * HALF + n * 4); }
; #pragma unroll
;                     for (int mm = 0; mm < 2; ++mm) { const size_t off = (size_t)(row0 + ai * HALF + (m + mm) * 16) * DM + col0;
;                         float ss = 0.f;
; #pragma unroll
;                         for (int bj = 0; bj < 2; ++bj) { const f32x4 v0 = bs[mm][bj][0] + acc[ai][bj][m + mm][0], v1 = bs[mm][bj][1] + acc[ai][bj][m + mm][1];
;                             ss += (v0[0] * v0[0] + v0[1] * v0[1]) + (v0[2] * v0[2] + v0[3] * v0[3]) + (v1[0] * v1[0] + v1[1] * v1[1]) + (v1[2] * v1[2] + v1[3] * v1[3]);
;                             u32x4 w; w.x = pk2(v0[0], v0[1]); w.y = pk2(v0[2], v0[3]); w.z = pk2(v1[0], v1[1]); w.w = pk2(v1[2], v1[3]);
;                             *(u32x4*)(out + off + bj * HALF) = w; }
;                         if (ssqp) { ss += __shfl_xor(ss, 16); ss += __shfl_xor(ss, 32); if (fq == 0) ssqp[(size_t)(row0 + ai * HALF + (m + mm) * 16) * 32 + u.pn * 4 + wc] = ss; } }
.LBB0_609:
	s_nop 0
	v_add_u32_e32 v82, 0x80, v162
	v_ashrrev_i32_e32 v83, 31, v82
	s_waitcnt lgkmcnt(0)
	v_lshlrev_b64 v[64:65], 13, v[82:83]
	v_add_u32_e32 v80, 0x90, v162
	v_lshl_add_u64 v[64:65], v[164:165], 0, v[64:65]
	v_ashrrev_i32_e32 v81, 31, v80
	global_load_dwordx4 v[84:87], v[64:65], off
	global_load_dwordx4 v[88:91], v[64:65], off offset:16
	global_load_dwordx4 v[92:95], v[64:65], off offset:512
	global_load_dwordx4 v[96:99], v[64:65], off offset:528
	v_lshlrev_b64 v[64:65], 13, v[80:81]
	v_lshl_add_u64 v[68:69], v[164:165], 0, v[64:65]
	global_load_dwordx4 v[72:75], v[68:69], off offset:16
	global_load_dwordx4 v[76:79], v[68:69], off
	global_load_dwordx4 v[64:67], v[68:69], off offset:528
	s_nop 0
	global_load_dwordx4 v[68:71], v[68:69], off offset:512
	v_lshlrev_b64 v[100:101], 12, v[82:83]
	v_lshl_add_u64 v[100:101], s[22:23], 0, v[100:101]
	s_and_b64 vcc, exec, s[6:7]
	v_lshl_add_u64 v[100:101], v[160:161], 1, v[100:101]
	s_waitcnt vmcnt(7)
	v_pk_add_f32 v[62:63], v[62:63], v[86:87]
	v_pk_add_f32 v[60:61], v[60:61], v[84:85]
	s_waitcnt vmcnt(6)
	v_pk_add_f32 v[58:59], v[58:59], v[90:91]
	v_pk_add_f32 v[56:57], v[56:57], v[88:89]
	s_waitcnt vmcnt(5)
	v_pk_add_f32 v[54:55], v[54:55], v[94:95]
	v_pk_add_f32 v[52:53], v[52:53], v[92:93]
	s_waitcnt vmcnt(4)
	v_pk_add_f32 v[50:51], v[50:51], v[98:99]
	v_pk_add_f32 v[48:49], v[48:49], v[96:97]
	v_cvt_pk_bf16_f32 v84, v60, v61
	v_cvt_pk_bf16_f32 v85, v62, v63
	v_cvt_pk_bf16_f32 v86, v56, v57
	v_cvt_pk_bf16_f32 v87, v58, v59
	v_cvt_pk_bf16_f32 v88, v52, v53
	v_cvt_pk_bf16_f32 v89, v54, v55
	v_cvt_pk_bf16_f32 v90, v48, v49
	v_cvt_pk_bf16_f32 v91, v50, v51
	global_store_dwordx4 v[100:101], v[84:87], off nt
	global_store_dwordx4 v[100:101], v[88:91], off offset:256 nt
	s_cbranch_vccnz .LBB0_613
	v_mul_f32_e32 v51, v51, v51
	v_fmac_f32_e32 v51, v50, v50
	v_mul_f32_e32 v50, v53, v53
	v_mul_f32_e32 v59, v59, v59
	v_fmac_f32_e32 v50, v52, v52
	v_mul_f32_e32 v52, v55, v55
	v_fmac_f32_e32 v59, v58, v58
	v_mul_f32_e32 v58, v61, v61
	v_fmac_f32_e32 v52, v54, v54
	v_mul_f32_e32 v49, v49, v49
	v_fmac_f32_e32 v58, v60, v60
	v_mul_f32_e32 v60, v63, v63
	v_add_f32_e32 v50, v50, v52
	v_fmac_f32_e32 v49, v48, v48
	v_fmac_f32_e32 v60, v62, v62
	v_mul_f32_e32 v57, v57, v57
	v_add_f32_e32 v48, v50, v49
	v_and_b32_e32 v50, 64, v174
	v_add_f32_e32 v58, v58, v60
	v_fmac_f32_e32 v57, v56, v56
	v_xor_b32_e32 v49, 16, v174
	v_add_u32_e32 v50, 64, v50
	v_add_f32_e32 v56, v58, v57
	v_cmp_lt_i32_e32 vcc, v49, v50
	v_add_f32_e32 v56, v59, v56
	v_add_f32_e32 v48, v51, v48
	v_cndmask_b32_e32 v49, v174, v49, vcc
	v_add_f32_e32 v48, v56, v48
	v_lshlrev_b32_e32 v49, 2, v49
	ds_bpermute_b32 v49, v49, v48
	s_waitcnt lgkmcnt(0)
	v_add_f32_e32 v48, v48, v49
	v_xor_b32_e32 v49, 32, v174
	v_cmp_lt_i32_e32 vcc, v49, v50
	s_nop 1
	v_cndmask_b32_e32 v49, v174, v49, vcc
	v_lshlrev_b32_e32 v49, 2, v49
	ds_bpermute_b32 v49, v49, v48
	s_and_saveexec_b64 s[28:29], s[0:1]
	s_cbranch_execz .LBB0_612
	v_lshlrev_b64 v[50:51], 7, v[82:83]
	v_lshl_add_u64 v[50:51], s[24:25], 0, v[50:51]
	v_lshl_add_u64 v[50:51], s[26:27], 2, v[50:51]
	s_lshl_b32 s8, s41, 2
	v_lshl_add_u64 v[50:51], v[50:51], 0, s[8:9]
	s_waitcnt lgkmcnt(0)
	v_add_f32_e32 v48, v48, v49
	global_store_dword v[50:51], v48, off

;     __device__ __forceinline__ void operator()(const f32x4 (&acc)[2][2][4][2], const Unit& u, int wr, int wc, int fr, int fq) const {
;     ...
;                     for (int mm = 0; mm < 2; ++mm) { const size_t off = (size_t)(row0 + ai * HALF + (m + mm) * 16) * DM + col0;
;                         float ss = 0.f;
; #pragma unroll
;                         for (int bj = 0; bj < 2; ++bj) { const f32x4 v0 = bs[mm][bj][0] + acc[ai][bj][m + mm][0], v1 = bs[mm][bj][1] + acc[ai][bj][m + mm][1];
;                             ss += (v0[0] * v0[0] + v0[1] * v0[1]) + (v0[2] * v0[2] + v0[3] * v0[3]) + (v1[0] * v1[0] + v1[1] * v1[1]) + (v1[2] * v1[2] + v1[3] * v1[3]);
;                             u32x4 w; w.x = pk2(v0[0], v0[1]); w.y = pk2(v0[2], v0[3]); w.z = pk2(v1[0], v1[1]); w.w = pk2(v1[2], v1[3]);
;                             *(u32x4*)(out + off + bj * HALF) = w; }
;                         if (ssqp) { ss += __shfl_xor(ss, 16); ss += __shfl_xor(ss, 32); if (fq == 0) ssqp[(size_t)(row0 + ai * HALF + (m + mm) * 16) * 32 + u.pn * 4 + wc] = ss; } }
.LBB0_613:
	v_lshlrev_b64 v[52:53], 12, v[80:81]
	s_waitcnt vmcnt(4)
	v_pk_add_f32 v[46:47], v[46:47], v[78:79]
	v_pk_add_f32 v[44:45], v[44:45], v[76:77]
	v_pk_add_f32 v[42:43], v[42:43], v[74:75]
	v_pk_add_f32 v[40:41], v[40:41], v[72:73]
	v_lshl_add_u64 v[52:53], s[22:23], 0, v[52:53]
	v_cvt_pk_bf16_f32 v48, v44, v45
	s_waitcnt lgkmcnt(0)
	v_cvt_pk_bf16_f32 v49, v46, v47
	v_cvt_pk_bf16_f32 v50, v40, v41
	v_cvt_pk_bf16_f32 v51, v42, v43
	v_lshl_add_u64 v[52:53], v[160:161], 1, v[52:53]
	s_waitcnt vmcnt(2)
	v_pk_add_f32 v[38:39], v[38:39], v[70:71]
	v_pk_add_f32 v[36:37], v[36:37], v[68:69]
	v_pk_add_f32 v[34:35], v[34:35], v[66:67]
	v_pk_add_f32 v[32:33], v[32:33], v[64:65]
	global_store_dwordx4 v[52:53], v[48:51], off nt
	s_and_b64 vcc, exec, s[6:7]
	s_nop 0
	v_cvt_pk_bf16_f32 v48, v36, v37
	v_cvt_pk_bf16_f32 v49, v38, v39
	v_cvt_pk_bf16_f32 v50, v32, v33
	v_cvt_pk_bf16_f32 v51, v34, v35
	global_store_dwordx4 v[52:53], v[48:51], off offset:256 nt
	s_cbranch_vccnz .LBB0_617
	v_mul_f32_e32 v35, v35, v35
	v_fmac_f32_e32 v35, v34, v34
	v_mul_f32_e32 v34, v37, v37
	v_mul_f32_e32 v43, v43, v43
	v_fmac_f32_e32 v34, v36, v36
	v_mul_f32_e32 v36, v39, v39
	v_fmac_f32_e32 v43, v42, v42
	v_mul_f32_e32 v42, v45, v45
	v_fmac_f32_e32 v36, v38, v38
	v_mul_f32_e32 v33, v33, v33
	v_fmac_f32_e32 v42, v44, v44
	v_mul_f32_e32 v44, v47, v47
	v_add_f32_e32 v34, v34, v36
	v_fmac_f32_e32 v33, v32, v32
	v_fmac_f32_e32 v44, v46, v46
	v_mul_f32_e32 v41, v41, v41
	v_add_f32_e32 v32, v34, v33
	v_and_b32_e32 v34, 64, v174
	v_add_f32_e32 v42, v42, v44
	v_fmac_f32_e32 v41, v40, v40
	v_xor_b32_e32 v33, 16, v174
	v_add_u32_e32 v34, 64, v34
	v_add_f32_e32 v40, v42, v41
	v_cmp_lt_i32_e32 vcc, v33, v34
	v_add_f32_e32 v40, v43, v40
	v_add_f32_e32 v32, v35, v32
	v_cndmask_b32_e32 v33, v174, v33, vcc
	v_add_f32_e32 v32, v40, v32
	v_lshlrev_b32_e32 v33, 2, v33
	ds_bpermute_b32 v33, v33, v32
	s_waitcnt lgkmcnt(0)
	v_add_f32_e32 v32, v32, v33
	v_xor_b32_e32 v33, 32, v174
	v_cmp_lt_i32_e32 vcc, v33, v34
	s_nop 1
	v_cndmask_b32_e32 v33, v174, v33, vcc
	v_lshlrev_b32_e32 v33, 2, v33
	ds_bpermute_b32 v33, v33, v32
	s_and_saveexec_b64 s[28:29], s[0:1]
	s_cbranch_execz .LBB0_616
	v_lshlrev_b64 v[34:35], 7, v[80:81]
	v_lshl_add_u64 v[34:35], s[24:25], 0, v[34:35]
	v_lshl_add_u64 v[34:35], s[26:27], 2, v[34:35]
	s_lshl_b32 s8, s41, 2
	v_lshl_add_u64 v[34:35], v[34:35], 0, s[8:9]
	s_waitcnt lgkmcnt(0)
	v_add_f32_e32 v32, v32, v33
	global_store_dword v[34:35], v32, off

;     __device__ __forceinline__ void operator()(const f32x4 (&acc)[2][2][4][2], const Unit& u, int wr, int wc, int fr, int fq) const {
;     ...
;                 for (int m = 0; m < 4; m += 2) {
;                     f32x4 bs[2][2][2];
; #pragma unroll
;                     for (int mm = 0; mm < 2; ++mm) { const size_t off = (size_t)(row0 + ai * HALF + (m + mm) * 16) * DM + col0;
; #pragma unroll
;                         for (int bj = 0; bj < 2; ++bj)
; #pragma unroll
;                             for (int n = 0; n < 2; ++n) bs[mm][bj][n] = *(const f32x4*)(basef + off + bj * HALF + n * 4); }
; #pragma unroll
;                     for (int mm = 0; mm < 2; ++mm) { const size_t off = (size_t)(row0 + ai * HALF + (m + mm) * 16) * DM + col0;
;                         float ss = 0.f;
; #pragma unroll
;                         for (int bj = 0; bj < 2; ++bj) { const f32x4 v0 = bs[mm][bj][0] + acc[ai][bj][m + mm][0], v1 = bs[mm][bj][1] + acc[ai][bj][m + mm][1];
;                             ss += (v0[0] * v0[0] + v0[1] * v0[1]) + (v0[2] * v0[2] + v0[3] * v0[3]) + (v1[0] * v1[0] + v1[1] * v1[1]) + (v1[2] * v1[2] + v1[3] * v1[3]);
;                             u32x4 w; w.x = pk2(v0[0], v0[1]); w.y = pk2(v0[2], v0[3]); w.z = pk2(v1[0], v1[1]); w.w = pk2(v1[2], v1[3]);
;                             *(u32x4*)(out + off + bj * HALF) = w; }
;                         if (ssqp) { ss += __shfl_xor(ss, 16); ss += __shfl_xor(ss, 32); if (fq == 0) ssqp[(size_t)(row0 + ai * HALF + (m + mm) * 16) * 32 + u.pn * 4 + wc] = ss; } }
.LBB0_617:
	s_nop 0
	v_add_u32_e32 v50, 0xa0, v162
	v_ashrrev_i32_e32 v51, 31, v50
	s_waitcnt lgkmcnt(0)
	v_lshlrev_b64 v[32:33], 13, v[50:51]
	v_add_u32_e32 v48, 0xb0, v162
	v_lshl_add_u64 v[32:33], v[164:165], 0, v[32:33]
	v_ashrrev_i32_e32 v49, 31, v48
	global_load_dwordx4 v[52:55], v[32:33], off
	global_load_dwordx4 v[56:59], v[32:33], off offset:16
	global_load_dwordx4 v[60:63], v[32:33], off offset:512
	global_load_dwordx4 v[64:67], v[32:33], off offset:528
	v_lshlrev_b64 v[32:33], 13, v[48:49]
	v_lshl_add_u64 v[36:37], v[164:165], 0, v[32:33]
	global_load_dwordx4 v[40:43], v[36:37], off offset:16
	global_load_dwordx4 v[44:47], v[36:37], off
	global_load_dwordx4 v[32:35], v[36:37], off offset:528
	s_nop 0
	global_load_dwordx4 v[36:39], v[36:37], off offset:512
	v_lshlrev_b64 v[68:69], 12, v[50:51]
	v_lshl_add_u64 v[68:69], s[22:23], 0, v[68:69]
	s_and_b64 vcc, exec, s[6:7]
	v_lshl_add_u64 v[68:69], v[160:161], 1, v[68:69]
	s_waitcnt vmcnt(7)
	v_pk_add_f32 v[30:31], v[30:31], v[54:55]
	v_pk_add_f32 v[28:29], v[28:29], v[52:53]
	s_waitcnt vmcnt(6)
	v_pk_add_f32 v[26:27], v[26:27], v[58:59]
	v_pk_add_f32 v[24:25], v[24:25], v[56:57]
	s_waitcnt vmcnt(5)
	v_pk_add_f32 v[22:23], v[22:23], v[62:63]
	v_pk_add_f32 v[20:21], v[20:21], v[60:61]
	s_waitcnt vmcnt(4)
	v_pk_add_f32 v[18:19], v[18:19], v[66:67]
	v_pk_add_f32 v[16:17], v[16:17], v[64:65]
	v_cvt_pk_bf16_f32 v52, v28, v29
	v_cvt_pk_bf16_f32 v53, v30, v31
	v_cvt_pk_bf16_f32 v54, v24, v25
	v_cvt_pk_bf16_f32 v55, v26, v27
	v_cvt_pk_bf16_f32 v56, v20, v21
	v_cvt_pk_bf16_f32 v57, v22, v23
	v_cvt_pk_bf16_f32 v58, v16, v17
	v_cvt_pk_bf16_f32 v59, v18, v19
	global_store_dwordx4 v[68:69], v[52:55], off nt
	global_store_dwordx4 v[68:69], v[56:59], off offset:256 nt
	s_cbranch_vccnz .LBB0_621
	v_mul_f32_e32 v19, v19, v19
	v_fmac_f32_e32 v19, v18, v18
	v_mul_f32_e32 v18, v21, v21
	v_mul_f32_e32 v27, v27, v27
	v_fmac_f32_e32 v18, v20, v20
	v_mul_f32_e32 v20, v23, v23
	v_fmac_f32_e32 v27, v26, v26
	v_mul_f32_e32 v26, v29, v29
	v_fmac_f32_e32 v20, v22, v22
	v_mul_f32_e32 v17, v17, v17
	v_fmac_f32_e32 v26, v28, v28
	v_mul_f32_e32 v28, v31, v31
	v_add_f32_e32 v18, v18, v20
	v_fmac_f32_e32 v17, v16, v16
	v_fmac_f32_e32 v28, v30, v30
	v_mul_f32_e32 v25, v25, v25
	v_add_f32_e32 v16, v18, v17
	v_and_b32_e32 v18, 64, v174
	v_add_f32_e32 v26, v26, v28
	v_fmac_f32_e32 v25, v24, v24
	v_xor_b32_e32 v17, 16, v174
	v_add_u32_e32 v18, 64, v18
	v_add_f32_e32 v24, v26, v25
	v_cmp_lt_i32_e32 vcc, v17, v18
	v_add_f32_e32 v24, v27, v24
	v_add_f32_e32 v16, v19, v16
	v_cndmask_b32_e32 v17, v174, v17, vcc
	v_add_f32_e32 v16, v24, v16
	v_lshlrev_b32_e32 v17, 2, v17
	ds_bpermute_b32 v17, v17, v16
	s_waitcnt lgkmcnt(0)
	v_add_f32_e32 v16, v16, v17
	v_xor_b32_e32 v17, 32, v174
	v_cmp_lt_i32_e32 vcc, v17, v18
	s_nop 1
	v_cndmask_b32_e32 v17, v174, v17, vcc
	v_lshlrev_b32_e32 v17, 2, v17
	ds_bpermute_b32 v17, v17, v16
	s_and_saveexec_b64 s[28:29], s[0:1]
	s_cbranch_execz .LBB0_620
	v_lshlrev_b64 v[18:19], 7, v[50:51]
	v_lshl_add_u64 v[18:19], s[24:25], 0, v[18:19]
	v_lshl_add_u64 v[18:19], s[26:27], 2, v[18:19]
	s_lshl_b32 s8, s41, 2
	v_lshl_add_u64 v[18:19], v[18:19], 0, s[8:9]
	s_waitcnt lgkmcnt(0)
	v_add_f32_e32 v16, v16, v17
	global_store_dword v[18:19], v16, off

;     __device__ __forceinline__ void operator()(const f32x4 (&acc)[2][2][4][2], const Unit& u, int wr, int wc, int fr, int fq) const {
;     ...
;                     for (int mm = 0; mm < 2; ++mm) { const size_t off = (size_t)(row0 + ai * HALF + (m + mm) * 16) * DM + col0;
;                         float ss = 0.f;
; #pragma unroll
;                         for (int bj = 0; bj < 2; ++bj) { const f32x4 v0 = bs[mm][bj][0] + acc[ai][bj][m + mm][0], v1 = bs[mm][bj][1] + acc[ai][bj][m + mm][1];
;                             ss += (v0[0] * v0[0] + v0[1] * v0[1]) + (v0[2] * v0[2] + v0[3] * v0[3]) + (v1[0] * v1[0] + v1[1] * v1[1]) + (v1[2] * v1[2] + v1[3] * v1[3]);
;                             u32x4 w; w.x = pk2(v0[0], v0[1]); w.y = pk2(v0[2], v0[3]); w.z = pk2(v1[0], v1[1]); w.w = pk2(v1[2], v1[3]);
;                             *(u32x4*)(out + off + bj * HALF) = w; }
;                         if (ssqp) { ss += __shfl_xor(ss, 16); ss += __shfl_xor(ss, 32); if (fq == 0) ssqp[(size_t)(row0 + ai * HALF + (m + mm) * 16) * 32 + u.pn * 4 + wc] = ss; } }
.LBB0_621:
	v_lshlrev_b64 v[20:21], 12, v[48:49]
	s_waitcnt vmcnt(4)
	v_pk_add_f32 v[14:15], v[14:15], v[46:47]
	v_pk_add_f32 v[12:13], v[12:13], v[44:45]
	v_pk_add_f32 v[10:11], v[10:11], v[42:43]
	v_pk_add_f32 v[8:9], v[8:9], v[40:41]
	v_lshl_add_u64 v[20:21], s[22:23], 0, v[20:21]
	v_cvt_pk_bf16_f32 v16, v12, v13
	s_waitcnt lgkmcnt(0)
	v_cvt_pk_bf16_f32 v17, v14, v15
	v_cvt_pk_bf16_f32 v18, v8, v9
	v_cvt_pk_bf16_f32 v19, v10, v11
	v_lshl_add_u64 v[20:21], v[160:161], 1, v[20:21]
	s_waitcnt vmcnt(2)
	v_pk_add_f32 v[6:7], v[6:7], v[38:39]
	v_pk_add_f32 v[4:5], v[4:5], v[36:37]
	v_pk_add_f32 v[2:3], v[2:3], v[34:35]
	v_pk_add_f32 v[0:1], v[0:1], v[32:33]
	global_store_dwordx4 v[20:21], v[16:19], off nt
	s_and_b64 vcc, exec, s[6:7]
	s_nop 0
	v_cvt_pk_bf16_f32 v16, v4, v5
	v_cvt_pk_bf16_f32 v17, v6, v7
	v_cvt_pk_bf16_f32 v18, v0, v1
	v_cvt_pk_bf16_f32 v19, v2, v3
	global_store_dwordx4 v[20:21], v[16:19], off offset:256 nt
	s_cbranch_vccnz .LBB0_584
	v_mul_f32_e32 v3, v3, v3
	v_fmac_f32_e32 v3, v2, v2
	v_mul_f32_e32 v2, v5, v5
	v_mul_f32_e32 v11, v11, v11
	v_fmac_f32_e32 v2, v4, v4
	v_mul_f32_e32 v4, v7, v7
	v_fmac_f32_e32 v11, v10, v10
	v_mul_f32_e32 v10, v13, v13
	v_fmac_f32_e32 v4, v6, v6
	v_mul_f32_e32 v1, v1, v1
	v_fmac_f32_e32 v10, v12, v12
	v_mul_f32_e32 v12, v15, v15
	v_add_f32_e32 v2, v2, v4
	v_fmac_f32_e32 v1, v0, v0
	v_fmac_f32_e32 v12, v14, v14
	v_mul_f32_e32 v9, v9, v9
	v_add_f32_e32 v0, v2, v1
	v_and_b32_e32 v2, 64, v174
	v_add_f32_e32 v10, v10, v12
	v_fmac_f32_e32 v9, v8, v8
	v_xor_b32_e32 v1, 16, v174
	v_add_u32_e32 v2, 64, v2
	v_add_f32_e32 v8, v10, v9
	v_cmp_lt_i32_e32 vcc, v1, v2
	v_add_f32_e32 v8, v11, v8
	v_add_f32_e32 v0, v3, v0
	v_cndmask_b32_e32 v1, v174, v1, vcc
	v_add_f32_e32 v0, v8, v0
	v_lshlrev_b32_e32 v1, 2, v1
	ds_bpermute_b32 v1, v1, v0
	s_waitcnt lgkmcnt(0)
	v_add_f32_e32 v0, v0, v1
	v_xor_b32_e32 v1, 32, v174
	v_cmp_lt_i32_e32 vcc, v1, v2
	s_nop 1
	v_cndmask_b32_e32 v1, v174, v1, vcc
	v_lshlrev_b32_e32 v1, 2, v1
	ds_bpermute_b32 v1, v1, v0
	s_and_saveexec_b64 s[6:7], s[0:1]
	s_cbranch_execz .LBB0_583
	v_lshlrev_b64 v[2:3], 7, v[48:49]
	v_lshl_add_u64 v[2:3], s[24:25], 0, v[2:3]
	v_lshl_add_u64 v[2:3], s[26:27], 2, v[2:3]
	s_lshl_b32 s8, s41, 2
	v_lshl_add_u64 v[2:3], v[2:3], 0, s[8:9]
	s_waitcnt lgkmcnt(0)
	v_add_f32_e32 v0, v0, v1
	global_store_dword v[2:3], v0, off
	s_branch .LBB0_583

; #define PG8_STAGE(bufoff, gbase, voff) do { _Pragma("unroll") for (int _i = 0; _i < 2; ++_i) \
;         __builtin_amdgcn_global_load_lds((const unsigned*)((const char*)(gbase) + (voff)[_i]), (LAS unsigned*)(lds + (bufoff) + ldsw + _i * 8192), 16, 0, 0); } while (0)
; #define PG8_LDA(dst, b, h) do { _Pragma("unroll") for (int m = 0; m < 4; ++m) _Pragma("unroll") for (int k = 0; k < 2; ++k) dst[m][k] = *(const LAS bf16x8*)(lds + PG8_SA(b, h) + aoff + m * 2048 + k * 1024); } while (0)
; #define PG8_LDB(dst, b, h) do { _Pragma("unroll") for (int n = 0; n < 2; ++n) _Pragma("unroll") for (int k = 0; k < 2; ++k) dst[n][k] = *(const LAS bf16x8*)(lds + PG8_SB(b, h) + boff + n * 2048 + k * 1024); } while (0)
; #define PG8_MMA(ai, bj, At, Bt) do { __builtin_amdgcn_s_setprio(1); _Pragma("unroll") for (int m = 0; m < 4; ++m) _Pragma("unroll") for (int n = 0; n < 2; ++n) _Pragma("unroll") for (int k = 0; k < 2; ++k) \
;         acc[ai][bj][m][n] = __builtin_amdgcn_mfma_f32_16x16x32_bf16(Bt[n][k], At[m][k], acc[ai][bj][m][n], 0, 0, 0); __builtin_amdgcn_s_setprio(0); } while (0)
; #define PG8_WAIT_V(n) asm volatile("s_waitcnt vmcnt(" #n ")" ::: "memory")
; #define PG8_WAIT_L(n) asm volatile("s_waitcnt lgkmcnt(" #n ")" ::: "memory")
; #define PG8_BAR __builtin_amdgcn_s_barrier()
; #define PG8_SCHED __builtin_amdgcn_sched_barrier(0)
; template <class Epi>
; __device__ __forceinline__ void gemm_phase(LAS unsigned char* lds, const Gemm g, const Order& S, const Epi& E, const int tid) {
;     ...
;             PG8_LDB(B0, 0, 0); PG8_SCHED; PG8_LDA(At, 0, 0); PG8_STAGE(PG8_SA(1, 1), a1 + hstepA, voffA);
;             PG8_WAIT_L(8); PG8_BAR; PG8_WAIT_L(0); PG8_MMA(0, 0, At, B0); PG8_BAR; PG8_SCHED;
;             PG8_LDB(B1, 0, 1); PG8_STAGE(PG8_SB(0, 0), b2, voffB);
;             PG8_BAR; PG8_WAIT_L(0); PG8_MMA(0, 1, At, B1); PG8_BAR;
;             PG8_LDA(At, 0, 1); PG8_STAGE(PG8_SA(0, 0), a2, voffA);
;             PG8_BAR; PG8_WAIT_L(0); PG8_MMA(1, 0, At, B0); PG8_BAR; PG8_SCHED;
;             PG8_STAGE(PG8_SB(0, 1), b2 + hstepB, voffB);
;             PG8_WAIT_V(6); PG8_BAR; PG8_MMA(1, 1, At, B1); PG8_BAR;
.LBB0_658:
	ds_read_b128 v[154:157], v150
	ds_read_b128 v[158:161], v150 offset:1024
	ds_read_b128 v[162:165], v150 offset:2048
	ds_read_b128 v[166:169], v150 offset:3072
	s_add_u32 s30, s28, 0xfff80080
	s_addc_u32 s31, s29, -1
	s_cmp_eq_u32 s60, 28
	s_cselect_b32 s35, s15, s31
	s_cselect_b32 s34, s56, s30
	s_cselect_b32 s31, s17, s59
	s_cselect_b32 s30, s57, s58
	v_lshl_add_u64 v[144:145], s[28:29], 0, v[136:137]
	s_add_i32 m0, s27, 0xc000
	ds_read_b128 v[170:173], v151
	ds_read_b128 v[174:177], v151 offset:1024
	ds_read_b128 v[178:181], v151 offset:2048
	ds_read_b128 v[182:185], v151 offset:3072
	ds_read_b128 v[186:189], v151 offset:4096
	ds_read_b128 v[190:193], v151 offset:5120
	ds_read_b128 v[194:197], v151 offset:6144
	ds_read_b128 v[198:201], v151 offset:7168
	global_load_lds_dwordx4 v[144:145], off
	v_lshl_add_u64 v[144:145], s[28:29], 0, v[138:139]
	s_add_i32 m0, s27, 0xe000
	s_nop 0
	global_load_lds_dwordx4 v[144:145], off
	s_waitcnt lgkmcnt(8)
	s_barrier
	s_waitcnt lgkmcnt(0)
	s_setprio 1
	s_waitcnt lgkmcnt(0)
	v_mfma_f32_16x16x32_bf16 v[124:127], v[154:157], v[170:173], v[124:127]
	v_mfma_f32_16x16x32_bf16 v[120:123], v[162:165], v[170:173], v[120:123]
	v_mfma_f32_16x16x32_bf16 v[108:111], v[154:157], v[178:181], v[108:111]
	v_mfma_f32_16x16x32_bf16 v[104:107], v[162:165], v[178:181], v[104:107]
	v_mfma_f32_16x16x32_bf16 v[92:95], v[154:157], v[186:189], v[92:95]
	v_mfma_f32_16x16x32_bf16 v[88:91], v[162:165], v[186:189], v[88:91]
	v_mfma_f32_16x16x32_bf16 v[76:79], v[154:157], v[194:197], v[76:79]
	v_mfma_f32_16x16x32_bf16 v[72:75], v[162:165], v[194:197], v[72:75]
	v_mfma_f32_16x16x32_bf16 v[124:127], v[158:161], v[174:177], v[124:127]
	v_mfma_f32_16x16x32_bf16 v[120:123], v[166:169], v[174:177], v[120:123]
	v_mfma_f32_16x16x32_bf16 v[108:111], v[158:161], v[182:185], v[108:111]
	v_mfma_f32_16x16x32_bf16 v[104:107], v[166:169], v[182:185], v[104:107]
	v_mfma_f32_16x16x32_bf16 v[92:95], v[158:161], v[190:193], v[92:95]
	v_mfma_f32_16x16x32_bf16 v[88:91], v[166:169], v[190:193], v[88:91]
	v_mfma_f32_16x16x32_bf16 v[76:79], v[158:161], v[198:201], v[76:79]
	v_mfma_f32_16x16x32_bf16 v[72:75], v[166:169], v[198:201], v[72:75]
	s_setprio 0
	s_barrier
	s_add_i32 s61, s45, s39
	v_lshl_add_u64 v[144:145], s[30:31], 0, v[132:133]
	s_mov_b32 m0, s61
	ds_read_b128 v[202:205], v152
	ds_read_b128 v[206:209], v152 offset:1024
	ds_read_b128 v[210:213], v152 offset:2048
	ds_read_b128 v[214:217], v152 offset:3072
	global_load_lds_dwordx4 v[144:145], off
	v_lshl_add_u64 v[218:219], s[30:31], 0, v[128:129]
	s_add_i32 m0, s61, 0x2000
	s_nop 0
	global_load_lds_dwordx4 v[218:219], off
	s_barrier
	s_waitcnt lgkmcnt(0)
	s_setprio 1
	s_waitcnt lgkmcnt(0)
	v_mfma_f32_16x16x32_bf16 v[116:119], v[202:205], v[170:173], v[116:119]
	v_mfma_f32_16x16x32_bf16 v[112:115], v[210:213], v[170:173], v[112:115]
	v_mfma_f32_16x16x32_bf16 v[100:103], v[202:205], v[178:181], v[100:103]
	v_mfma_f32_16x16x32_bf16 v[96:99], v[210:213], v[178:181], v[96:99]
	v_mfma_f32_16x16x32_bf16 v[84:87], v[202:205], v[186:189], v[84:87]
	v_mfma_f32_16x16x32_bf16 v[80:83], v[210:213], v[186:189], v[80:83]
	v_mfma_f32_16x16x32_bf16 v[68:71], v[202:205], v[194:197], v[68:71]
	v_mfma_f32_16x16x32_bf16 v[64:67], v[210:213], v[194:197], v[64:67]
	v_mfma_f32_16x16x32_bf16 v[116:119], v[206:209], v[174:177], v[116:119]
	v_mfma_f32_16x16x32_bf16 v[112:115], v[214:217], v[174:177], v[112:115]
	v_mfma_f32_16x16x32_bf16 v[100:103], v[206:209], v[182:185], v[100:103]
	v_mfma_f32_16x16x32_bf16 v[96:99], v[214:217], v[182:185], v[96:99]
	v_mfma_f32_16x16x32_bf16 v[84:87], v[206:209], v[190:193], v[84:87]
	v_mfma_f32_16x16x32_bf16 v[80:83], v[214:217], v[190:193], v[80:83]
	v_mfma_f32_16x16x32_bf16 v[68:71], v[206:209], v[198:201], v[68:71]
	v_mfma_f32_16x16x32_bf16 v[64:67], v[214:217], v[198:201], v[64:67]
	s_setprio 0
	s_mov_b32 m0, s27
	v_lshl_add_u64 v[220:221], s[34:35], 0, v[134:135]
	s_barrier
	ds_read_b128 v[170:173], v151 offset:16384
	ds_read_b128 v[174:177], v151 offset:17408
	ds_read_b128 v[178:181], v151 offset:18432
	ds_read_b128 v[182:185], v151 offset:19456
	ds_read_b128 v[186:189], v151 offset:20480
	ds_read_b128 v[190:193], v151 offset:21504
	ds_read_b128 v[194:197], v151 offset:22528
	ds_read_b128 v[198:201], v151 offset:23552
	global_load_lds_dwordx4 v[220:221], off
	v_lshl_add_u64 v[222:223], s[34:35], 0, v[130:131]
	s_mov_b32 m0, s40
	s_nop 0
	global_load_lds_dwordx4 v[222:223], off
	s_barrier
	s_waitcnt lgkmcnt(0)
	s_setprio 1
	s_waitcnt lgkmcnt(0)
	v_mfma_f32_16x16x32_bf16 v[60:63], v[154:157], v[170:173], v[60:63]
	v_mfma_f32_16x16x32_bf16 v[56:59], v[162:165], v[170:173], v[56:59]
	v_mfma_f32_16x16x32_bf16 v[44:47], v[154:157], v[178:181], v[44:47]
	v_mfma_f32_16x16x32_bf16 v[40:43], v[162:165], v[178:181], v[40:43]
	v_mfma_f32_16x16x32_bf16 v[28:31], v[154:157], v[186:189], v[28:31]
	v_mfma_f32_16x16x32_bf16 v[24:27], v[162:165], v[186:189], v[24:27]
	v_mfma_f32_16x16x32_bf16 v[12:15], v[154:157], v[194:197], v[12:15]
	v_mfma_f32_16x16x32_bf16 v[8:11], v[162:165], v[194:197], v[8:11]
	v_mfma_f32_16x16x32_bf16 v[60:63], v[158:161], v[174:177], v[60:63]
	v_mfma_f32_16x16x32_bf16 v[56:59], v[166:169], v[174:177], v[56:59]
	v_mfma_f32_16x16x32_bf16 v[44:47], v[158:161], v[182:185], v[44:47]
	v_mfma_f32_16x16x32_bf16 v[40:43], v[166:169], v[182:185], v[40:43]
	v_mfma_f32_16x16x32_bf16 v[28:31], v[158:161], v[190:193], v[28:31]
	v_mfma_f32_16x16x32_bf16 v[24:27], v[166:169], v[190:193], v[24:27]
	v_mfma_f32_16x16x32_bf16 v[12:15], v[158:161], v[198:201], v[12:15]
	v_mfma_f32_16x16x32_bf16 v[8:11], v[166:169], v[198:201], v[8:11]
	s_setprio 0
	s_barrier
; #define PG8_STAGE(bufoff, gbase, voff) do { _Pragma("unroll") for (int _i = 0; _i < 2; ++_i) \
;         __builtin_amdgcn_global_load_lds((const unsigned*)((const char*)(gbase) + (voff)[_i]), (LAS unsigned*)(lds + (bufoff) + ldsw + _i * 8192), 16, 0, 0); } while (0)
; #define PG8_LDA(dst, b, h) do { _Pragma("unroll") for (int m = 0; m < 4; ++m) _Pragma("unroll") for (int k = 0; k < 2; ++k) dst[m][k] = *(const LAS bf16x8*)(lds + PG8_SA(b, h) + aoff + m * 2048 + k * 1024); } while (0)
; #define PG8_LDB(dst, b, h) do { _Pragma("unroll") for (int n = 0; n < 2; ++n) _Pragma("unroll") for (int k = 0; k < 2; ++k) dst[n][k] = *(const LAS bf16x8*)(lds + PG8_SB(b, h) + boff + n * 2048 + k * 1024); } while (0)
; #define PG8_MMA(ai, bj, At, Bt) do { __builtin_amdgcn_s_setprio(1); _Pragma("unroll") for (int m = 0; m < 4; ++m) _Pragma("unroll") for (int n = 0; n < 2; ++n) _Pragma("unroll") for (int k = 0; k < 2; ++k) \
;         acc[ai][bj][m][n] = __builtin_amdgcn_mfma_f32_16x16x32_bf16(Bt[n][k], At[m][k], acc[ai][bj][m][n], 0, 0, 0); __builtin_amdgcn_s_setprio(0); } while (0)
; #define PG8_WAIT_V(n) asm volatile("s_waitcnt vmcnt(" #n ")" ::: "memory")
; #define PG8_WAIT_L(n) asm volatile("s_waitcnt lgkmcnt(" #n ")" ::: "memory")
; #define PG8_BAR __builtin_amdgcn_s_barrier()
; #define PG8_SCHED __builtin_amdgcn_sched_barrier(0)
; template <class Epi>
; __device__ __forceinline__ void gemm_phase(LAS unsigned char* lds, const Gemm g, const Order& S, const Epi& E, const int tid) {
;     ...
;             PG8_BAR; PG8_WAIT_L(0); PG8_MMA(1, 0, At, B0); PG8_BAR; PG8_SCHED;
;             PG8_STAGE(PG8_SB(0, 1), b2 + hstepB, voffB);
;             PG8_WAIT_V(6); PG8_BAR; PG8_MMA(1, 1, At, B1); PG8_BAR;
;             PG8_LDB(B0, 1, 0); PG8_SCHED; PG8_LDA(At, 1, 0); PG8_STAGE(PG8_SA(0, 1), a2 + hstepA, voffA);
;             PG8_WAIT_L(8); PG8_BAR; PG8_WAIT_L(0); PG8_MMA(0, 0, At, B0); PG8_BAR; PG8_SCHED;
;             PG8_LDB(B1, 1, 1); PG8_STAGE(PG8_SB(1, 0), b3, voffB);
;             PG8_BAR; PG8_WAIT_L(0); PG8_MMA(0, 1, At, B1); PG8_BAR;
;             PG8_LDA(At, 1, 1); PG8_STAGE(PG8_SA(1, 0), a3, voffA);
;             PG8_BAR; PG8_WAIT_L(0); PG8_MMA(1, 0, At, B0); PG8_BAR; PG8_SCHED;
	s_add_u32 s66, s30, 0x80000
	s_addc_u32 s67, s31, 0
	s_add_i32 s61, s46, s39
	v_lshl_add_u64 v[154:155], s[66:67], 0, v[132:133]
	s_mov_b32 m0, s61
	s_nop 0
	global_load_lds_dwordx4 v[154:155], off
	v_lshl_add_u64 v[154:155], s[66:67], 0, v[128:129]
	s_add_i32 m0, s61, 0x2000
	s_nop 0
	global_load_lds_dwordx4 v[154:155], off
	s_waitcnt vmcnt(6)
	s_barrier
	s_setprio 1
	v_mfma_f32_16x16x32_bf16 v[52:55], v[202:205], v[170:173], v[52:55]
	v_mfma_f32_16x16x32_bf16 v[48:51], v[210:213], v[170:173], v[48:51]
	v_mfma_f32_16x16x32_bf16 v[36:39], v[202:205], v[178:181], v[36:39]
	v_mfma_f32_16x16x32_bf16 v[32:35], v[210:213], v[178:181], v[32:35]
	v_mfma_f32_16x16x32_bf16 v[20:23], v[202:205], v[186:189], v[20:23]
	v_mfma_f32_16x16x32_bf16 v[16:19], v[210:213], v[186:189], v[16:19]
	v_mfma_f32_16x16x32_bf16 v[4:7], v[202:205], v[194:197], v[4:7]
	v_mfma_f32_16x16x32_bf16 v[0:3], v[210:213], v[194:197], v[0:3]
	v_mfma_f32_16x16x32_bf16 v[52:55], v[206:209], v[174:177], v[52:55]
	v_mfma_f32_16x16x32_bf16 v[48:51], v[214:217], v[174:177], v[48:51]
	v_mfma_f32_16x16x32_bf16 v[36:39], v[206:209], v[182:185], v[36:39]
	v_mfma_f32_16x16x32_bf16 v[32:35], v[214:217], v[182:185], v[32:35]
	v_mfma_f32_16x16x32_bf16 v[20:23], v[206:209], v[190:193], v[20:23]
	v_mfma_f32_16x16x32_bf16 v[16:19], v[214:217], v[190:193], v[16:19]
	v_mfma_f32_16x16x32_bf16 v[4:7], v[206:209], v[198:201], v[4:7]
	v_mfma_f32_16x16x32_bf16 v[0:3], v[214:217], v[198:201], v[0:3]
	s_setprio 0
	s_add_i32 s61, 0, 0x18000
	v_add_u32_e32 v153, s61, v147
	s_barrier
	ds_read_b128 v[154:157], v153
	ds_read_b128 v[158:161], v153 offset:1024
	ds_read_b128 v[162:165], v153 offset:2048
	ds_read_b128 v[166:169], v153 offset:3072
	s_add_u32 s34, s34, 0x80000
	s_addc_u32 s35, s35, 0
	s_mov_b32 m0, s41
	v_lshl_add_u64 v[202:203], s[34:35], 0, v[134:135]
	ds_read_b128 v[170:173], v151 offset:32768
	ds_read_b128 v[174:177], v151 offset:33792
	ds_read_b128 v[178:181], v151 offset:34816
	ds_read_b128 v[182:185], v151 offset:35840
	ds_read_b128 v[186:189], v151 offset:36864
	ds_read_b128 v[190:193], v151 offset:37888
	ds_read_b128 v[194:197], v151 offset:38912
	ds_read_b128 v[198:201], v151 offset:39936
	global_load_lds_dwordx4 v[202:203], off
	v_lshl_add_u64 v[202:203], s[34:35], 0, v[130:131]
	s_mov_b32 m0, s42
	s_nop 0
	global_load_lds_dwordx4 v[202:203], off
	s_waitcnt lgkmcnt(8)
	s_barrier
	s_waitcnt lgkmcnt(0)
	s_setprio 1
	s_waitcnt lgkmcnt(0)
	v_mfma_f32_16x16x32_bf16 v[124:127], v[154:157], v[170:173], v[124:127]
	v_mfma_f32_16x16x32_bf16 v[120:123], v[162:165], v[170:173], v[120:123]
	v_mfma_f32_16x16x32_bf16 v[108:111], v[154:157], v[178:181], v[108:111]
	v_mfma_f32_16x16x32_bf16 v[104:107], v[162:165], v[178:181], v[104:107]
	v_mfma_f32_16x16x32_bf16 v[92:95], v[154:157], v[186:189], v[92:95]
	v_mfma_f32_16x16x32_bf16 v[88:91], v[162:165], v[186:189], v[88:91]
	v_mfma_f32_16x16x32_bf16 v[76:79], v[154:157], v[194:197], v[76:79]
	v_mfma_f32_16x16x32_bf16 v[72:75], v[162:165], v[194:197], v[72:75]
	v_mfma_f32_16x16x32_bf16 v[124:127], v[158:161], v[174:177], v[124:127]
	v_mfma_f32_16x16x32_bf16 v[120:123], v[166:169], v[174:177], v[120:123]
	v_mfma_f32_16x16x32_bf16 v[108:111], v[158:161], v[182:185], v[108:111]
	v_mfma_f32_16x16x32_bf16 v[104:107], v[166:169], v[182:185], v[104:107]
	v_mfma_f32_16x16x32_bf16 v[92:95], v[158:161], v[190:193], v[92:95]
	v_mfma_f32_16x16x32_bf16 v[88:91], v[166:169], v[190:193], v[88:91]
	v_mfma_f32_16x16x32_bf16 v[76:79], v[158:161], v[198:201], v[76:79]
	v_mfma_f32_16x16x32_bf16 v[72:75], v[166:169], v[198:201], v[72:75]
	s_setprio 0
	s_barrier
	s_add_i32 s34, 0, 0x1c000
	s_add_i32 s35, s61, s39
	v_add_u32_e32 v153, s34, v147
	v_lshl_add_u64 v[144:145], v[144:145], 0, s[4:5]
	s_mov_b32 m0, s35
	ds_read_b128 v[202:205], v153
	ds_read_b128 v[206:209], v153 offset:1024
	ds_read_b128 v[210:213], v153 offset:2048
	ds_read_b128 v[214:217], v153 offset:3072
	global_load_lds_dwordx4 v[144:145], off
	v_lshl_add_u64 v[144:145], v[218:219], 0, s[4:5]
	s_add_i32 m0, s35, 0x2000
	s_nop 0
	global_load_lds_dwordx4 v[144:145], off
	s_barrier
	s_waitcnt lgkmcnt(0)
	s_setprio 1
	s_waitcnt lgkmcnt(0)
	v_mfma_f32_16x16x32_bf16 v[116:119], v[202:205], v[170:173], v[116:119]
	v_mfma_f32_16x16x32_bf16 v[112:115], v[210:213], v[170:173], v[112:115]
	v_mfma_f32_16x16x32_bf16 v[100:103], v[202:205], v[178:181], v[100:103]
	v_mfma_f32_16x16x32_bf16 v[96:99], v[210:213], v[178:181], v[96:99]
	v_mfma_f32_16x16x32_bf16 v[84:87], v[202:205], v[186:189], v[84:87]
	v_mfma_f32_16x16x32_bf16 v[80:83], v[210:213], v[186:189], v[80:83]
	v_mfma_f32_16x16x32_bf16 v[68:71], v[202:205], v[194:197], v[68:71]
	v_mfma_f32_16x16x32_bf16 v[64:67], v[210:213], v[194:197], v[64:67]
	v_mfma_f32_16x16x32_bf16 v[116:119], v[206:209], v[174:177], v[116:119]
	v_mfma_f32_16x16x32_bf16 v[112:115], v[214:217], v[174:177], v[112:115]
	v_mfma_f32_16x16x32_bf16 v[100:103], v[206:209], v[182:185], v[100:103]
	v_mfma_f32_16x16x32_bf16 v[96:99], v[214:217], v[182:185], v[96:99]
	v_mfma_f32_16x16x32_bf16 v[84:87], v[206:209], v[190:193], v[84:87]
	v_mfma_f32_16x16x32_bf16 v[80:83], v[214:217], v[190:193], v[80:83]
	v_mfma_f32_16x16x32_bf16 v[68:71], v[206:209], v[198:201], v[68:71]
	v_mfma_f32_16x16x32_bf16 v[64:67], v[214:217], v[198:201], v[64:67]
	s_setprio 0
	s_mov_b32 m0, s43
	v_lshl_add_u64 v[144:145], v[220:221], 0, s[4:5]
	s_barrier
	ds_read_b128 v[170:173], v151 offset:49152
	ds_read_b128 v[174:177], v151 offset:50176
	ds_read_b128 v[178:181], v151 offset:51200
	ds_read_b128 v[182:185], v151 offset:52224
	ds_read_b128 v[186:189], v151 offset:53248
	ds_read_b128 v[190:193], v151 offset:54272
	ds_read_b128 v[194:197], v151 offset:55296
	ds_read_b128 v[198:201], v151 offset:56320
	global_load_lds_dwordx4 v[144:145], off
	v_lshl_add_u64 v[144:145], v[222:223], 0, s[4:5]
	s_mov_b32 m0, s44
	s_nop 0
	global_load_lds_dwordx4 v[144:145], off
	s_barrier
; #define PG8_STAGE(bufoff, gbase, voff) do { _Pragma("unroll") for (int _i = 0; _i < 2; ++_i) \
;         __builtin_amdgcn_global_load_lds((const unsigned*)((const char*)(gbase) + (voff)[_i]), (LAS unsigned*)(lds + (bufoff) + ldsw + _i * 8192), 16, 0, 0); } while (0)
; #define PG8_MMA(ai, bj, At, Bt) do { __builtin_amdgcn_s_setprio(1); _Pragma("unroll") for (int m = 0; m < 4; ++m) _Pragma("unroll") for (int n = 0; n < 2; ++n) _Pragma("unroll") for (int k = 0; k < 2; ++k) \
;         acc[ai][bj][m][n] = __builtin_amdgcn_mfma_f32_16x16x32_bf16(Bt[n][k], At[m][k], acc[ai][bj][m][n], 0, 0, 0); __builtin_amdgcn_s_setprio(0); } while (0)
; #define PG8_WAIT_V(n) asm volatile("s_waitcnt vmcnt(" #n ")" ::: "memory")
; #define PG8_WAIT_L(n) asm volatile("s_waitcnt lgkmcnt(" #n ")" ::: "memory")
; #define PG8_BAR __builtin_amdgcn_s_barrier()
; #define PG8_SCHED __builtin_amdgcn_sched_barrier(0)
; template <class Epi>
; __device__ __forceinline__ void gemm_phase(LAS unsigned char* lds, const Gemm g, const Order& S, const Epi& E, const int tid) {
;     ...
;             PG8_BAR; PG8_WAIT_L(0); PG8_MMA(1, 0, At, B0); PG8_BAR; PG8_SCHED;
;             PG8_STAGE(PG8_SB(1, 1), b3 + hstepB, voffB);
;             PG8_WAIT_V(6); PG8_BAR; PG8_MMA(1, 1, At, B1); PG8_BAR;
;     __device__ __forceinline__ void operator()(const f32x4 (&acc)[2][2][4][2], const Unit& u, int wr, int wc, int fr, int fq) const {
;         const int row0 = u.pm * BM + wr * 64 + fr, col0 = u.pn * BM + wc * 32 + 8 * fq;
; #pragma unroll
;         for (int ai = 0; ai < 2; ++ai)
; #pragma unroll
;             for (int m = 0; m < 4; ++m) { bf16_t* rowp = O + (size_t)(row0 + ai * HALF + m * 16) * ldc + col0;
;                 float rs = 1.0f; if (RS) rs = rt[u.i * 256 + wr * 64 + fr + ai * HALF + m * 16];
; #pragma unroll
;                 for (int bj = 0; bj < 2; ++bj) { f32x4 v0 = acc[ai][bj][m][0], v1 = acc[ai][bj][m][1];
;                     if (RS) { v0 *= rs; v1 *= rs; }
;                     if (ACT == 1) {
; #pragma unroll
;                         for (int j = 0; j < 4; ++j) { const float a = fmaxf(v0[j], 0.f), b = fmaxf(v1[j], 0.f); v0[j] = a * a; v1[j] = b * b; } }
;                     u32x4 w; w.x = pk2(v0[0], v0[1]); w.y = pk2(v0[2], v0[3]); w.z = pk2(v1[0], v1[1]); w.w = pk2(v1[2], v1[3]);
;                     *(u32x4*)(rowp + bj * HALF) = w; } }
	s_waitcnt lgkmcnt(0)
	s_setprio 1
	s_waitcnt lgkmcnt(0)
	v_mfma_f32_16x16x32_bf16 v[60:63], v[154:157], v[170:173], v[60:63]
	v_mfma_f32_16x16x32_bf16 v[56:59], v[162:165], v[170:173], v[56:59]
	v_mfma_f32_16x16x32_bf16 v[44:47], v[154:157], v[178:181], v[44:47]
	v_mfma_f32_16x16x32_bf16 v[40:43], v[162:165], v[178:181], v[40:43]
	v_mfma_f32_16x16x32_bf16 v[28:31], v[154:157], v[186:189], v[28:31]
	v_mfma_f32_16x16x32_bf16 v[24:27], v[162:165], v[186:189], v[24:27]
	v_mfma_f32_16x16x32_bf16 v[12:15], v[154:157], v[194:197], v[12:15]
	v_mfma_f32_16x16x32_bf16 v[8:11], v[162:165], v[194:197], v[8:11]
	v_mfma_f32_16x16x32_bf16 v[60:63], v[158:161], v[174:177], v[60:63]
	v_mfma_f32_16x16x32_bf16 v[56:59], v[166:169], v[174:177], v[56:59]
	v_mfma_f32_16x16x32_bf16 v[44:47], v[158:161], v[182:185], v[44:47]
	v_mfma_f32_16x16x32_bf16 v[40:43], v[166:169], v[182:185], v[40:43]
	v_mfma_f32_16x16x32_bf16 v[28:31], v[158:161], v[190:193], v[28:31]
	v_mfma_f32_16x16x32_bf16 v[24:27], v[166:169], v[190:193], v[24:27]
	v_mfma_f32_16x16x32_bf16 v[12:15], v[158:161], v[198:201], v[12:15]
	v_mfma_f32_16x16x32_bf16 v[8:11], v[166:169], v[198:201], v[8:11]
	s_setprio 0
	s_barrier
	s_add_u32 s30, s30, 0x80080
	s_addc_u32 s31, s31, 0
	s_add_i32 s34, s34, s39
	v_lshl_add_u64 v[144:145], s[30:31], 0, v[132:133]
	s_mov_b32 m0, s34
	s_nop 0
	global_load_lds_dwordx4 v[144:145], off
	v_lshl_add_u64 v[144:145], s[30:31], 0, v[128:129]
	s_add_i32 m0, s34, 0x2000
	s_nop 0
	global_load_lds_dwordx4 v[144:145], off
	s_waitcnt vmcnt(6)
	s_barrier
	s_setprio 1
	v_mfma_f32_16x16x32_bf16 v[52:55], v[202:205], v[170:173], v[52:55]
	v_mfma_f32_16x16x32_bf16 v[48:51], v[210:213], v[170:173], v[48:51]
	v_mfma_f32_16x16x32_bf16 v[36:39], v[202:205], v[178:181], v[36:39]
	v_mfma_f32_16x16x32_bf16 v[32:35], v[210:213], v[178:181], v[32:35]
	v_mfma_f32_16x16x32_bf16 v[20:23], v[202:205], v[186:189], v[20:23]
	v_mfma_f32_16x16x32_bf16 v[16:19], v[210:213], v[186:189], v[16:19]
	v_mfma_f32_16x16x32_bf16 v[4:7], v[202:205], v[194:197], v[4:7]
	v_mfma_f32_16x16x32_bf16 v[0:3], v[210:213], v[194:197], v[0:3]
	v_mfma_f32_16x16x32_bf16 v[52:55], v[206:209], v[174:177], v[52:55]
	v_mfma_f32_16x16x32_bf16 v[48:51], v[214:217], v[174:177], v[48:51]
	v_mfma_f32_16x16x32_bf16 v[36:39], v[206:209], v[182:185], v[36:39]
	v_mfma_f32_16x16x32_bf16 v[32:35], v[214:217], v[182:185], v[32:35]
	v_mfma_f32_16x16x32_bf16 v[20:23], v[206:209], v[190:193], v[20:23]
	v_mfma_f32_16x16x32_bf16 v[16:19], v[214:217], v[190:193], v[16:19]
	v_mfma_f32_16x16x32_bf16 v[4:7], v[206:209], v[198:201], v[4:7]
	v_mfma_f32_16x16x32_bf16 v[0:3], v[214:217], v[198:201], v[0:3]
	s_setprio 0
	s_add_i32 s60, s60, 2
	s_add_u32 s28, s28, 0x100
	s_addc_u32 s29, s29, 0
	s_add_u32 s58, s58, 0x100
	s_addc_u32 s59, s59, 0
	s_cmp_gt_u32 s60, 29
	s_barrier
	s_cbranch_scc0 .LBB0_658
	v_lshl_add_u32 v153, s53, 10, v148
	ds_read2_b32 v[156:157], v153 offset1:16
	v_lshl_add_u32 v154, s26, 8, v146
	v_lshl_or_b32 v144, s55, 8, v149
	v_ashrrev_i32_e32 v155, 31, v154
	v_ashrrev_i32_e32 v145, 31, v144
	s_waitcnt lgkmcnt(0)
	v_pk_mul_f32 v[122:123], v[122:123], v[156:157] op_sel_hi:[1,0]
	v_pk_mul_f32 v[120:121], v[120:121], v[156:157] op_sel_hi:[1,0]
	v_pk_mul_f32 v[126:127], v[126:127], v[156:157] op_sel_hi:[1,0]
	v_pk_mul_f32 v[124:125], v[124:125], v[156:157] op_sel_hi:[1,0]
	v_max_f32_e32 v120, 0, v120
	v_max_f32_e32 v121, 0, v121
	v_max_f32_e32 v122, 0, v122
	v_lshlrev_b64 v[158:159], 14, v[154:155]
	v_max_f32_e32 v124, 0, v124
	v_mul_f32_e32 v155, v120, v120
	v_max_f32_e32 v120, 0, v125
	v_mul_f32_e32 v125, v121, v121
	v_max_f32_e32 v121, 0, v126
	v_mul_f32_e32 v126, v122, v122
	v_max_f32_e32 v122, 0, v127
	v_max_f32_e32 v123, 0, v123
	v_lshl_add_u64 v[158:159], s[72:73], 0, v[158:159]
	v_lshlrev_b64 v[160:161], 1, v[144:145]
	v_mul_f32_e32 v124, v124, v124
	v_mul_f32_e32 v120, v120, v120
	v_mul_f32_e32 v121, v121, v121
	v_mul_f32_e32 v122, v122, v122
	v_mul_f32_e32 v123, v123, v123
	v_pk_mul_f32 v[114:115], v[114:115], v[156:157] op_sel_hi:[1,0]
	v_pk_mul_f32 v[112:113], v[112:113], v[156:157] op_sel_hi:[1,0]
	v_lshl_add_u64 v[144:145], v[158:159], 0, v[160:161]
	v_cvt_pk_bf16_f32 v120, v124, v120
	v_cvt_pk_bf16_f32 v121, v121, v122
	v_cvt_pk_bf16_f32 v122, v155, v125
	v_cvt_pk_bf16_f32 v123, v126, v123
	v_pk_mul_f32 v[118:119], v[118:119], v[156:157] op_sel_hi:[1,0]
	v_pk_mul_f32 v[116:117], v[116:117], v[156:157] op_sel_hi:[1,0]
	v_max_f32_e32 v112, 0, v112
	v_max_f32_e32 v113, 0, v113
	v_max_f32_e32 v114, 0, v114
	global_store_dwordx4 v[144:145], v[120:123], off nt
	v_max_f32_e32 v116, 0, v116
	v_max_f32_e32 v115, 0, v115
	v_mul_f32_e32 v120, v112, v112
	v_max_f32_e32 v112, 0, v117
	v_mul_f32_e32 v117, v113, v113
	v_max_f32_e32 v113, 0, v118
	v_mul_f32_e32 v118, v114, v114
	v_max_f32_e32 v114, 0, v119
	v_mul_f32_e32 v116, v116, v116
	v_mul_f32_e32 v112, v112, v112
	v_mul_f32_e32 v113, v113, v113
	v_mul_f32_e32 v114, v114, v114
	v_mul_f32_e32 v115, v115, v115
	v_cvt_pk_bf16_f32 v112, v116, v112
	v_cvt_pk_bf16_f32 v113, v113, v114
	v_cvt_pk_bf16_f32 v114, v120, v117
	v_cvt_pk_bf16_f32 v115, v118, v115
	global_store_dwordx4 v[144:145], v[112:115], off offset:256 nt
	s_mov_b32 s53, s52
	s_mov_b32 s55, s16
	v_mov_b32_e32 v114, v157
	v_or_b32_e32 v112, 16, v154
	v_pk_mul_f32 v[106:107], v[106:107], v[114:115] op_sel_hi:[1,0]
	v_pk_mul_f32 v[104:105], v[104:105], v[114:115] op_sel_hi:[1,0]
	v_ashrrev_i32_e32 v113, 31, v112
	v_pk_mul_f32 v[110:111], v[110:111], v[114:115] op_sel_hi:[1,0]
	v_pk_mul_f32 v[108:109], v[108:109], v[114:115] op_sel_hi:[1,0]
	v_max_f32_e32 v104, 0, v104
	v_max_f32_e32 v105, 0, v105
	v_max_f32_e32 v106, 0, v106
;     __device__ __forceinline__ void operator()(const f32x4 (&acc)[2][2][4][2], const Unit& u, int wr, int wc, int fr, int fq) const {
;         const int row0 = u.pm * BM + wr * 64 + fr, col0 = u.pn * BM + wc * 32 + 8 * fq;
; #pragma unroll
;         for (int ai = 0; ai < 2; ++ai)
; #pragma unroll
;             for (int m = 0; m < 4; ++m) { bf16_t* rowp = O + (size_t)(row0 + ai * HALF + m * 16) * ldc + col0;
;                 float rs = 1.0f; if (RS) rs = rt[u.i * 256 + wr * 64 + fr + ai * HALF + m * 16];
; #pragma unroll
;                 for (int bj = 0; bj < 2; ++bj) { f32x4 v0 = acc[ai][bj][m][0], v1 = acc[ai][bj][m][1];
;                     if (RS) { v0 *= rs; v1 *= rs; }
;                     if (ACT == 1) {
; #pragma unroll
;                         for (int j = 0; j < 4; ++j) { const float a = fmaxf(v0[j], 0.f), b = fmaxf(v1[j], 0.f); v0[j] = a * a; v1[j] = b * b; } }
;                     u32x4 w; w.x = pk2(v0[0], v0[1]); w.y = pk2(v0[2], v0[3]); w.z = pk2(v1[0], v1[1]); w.w = pk2(v1[2], v1[3]);
;                     *(u32x4*)(rowp + bj * HALF) = w; } }
	v_lshlrev_b64 v[112:113], 14, v[112:113]
	v_max_f32_e32 v108, 0, v108
	v_mul_f32_e32 v115, v104, v104
	v_max_f32_e32 v104, 0, v109
	v_mul_f32_e32 v109, v105, v105
	v_max_f32_e32 v105, 0, v110
	v_mul_f32_e32 v110, v106, v106
	v_max_f32_e32 v106, 0, v111
	v_max_f32_e32 v107, 0, v107
	v_lshl_add_u64 v[112:113], s[72:73], 0, v[112:113]
	v_mul_f32_e32 v108, v108, v108
	v_mul_f32_e32 v104, v104, v104
	v_mul_f32_e32 v105, v105, v105
	v_mul_f32_e32 v106, v106, v106
	v_mul_f32_e32 v107, v107, v107
	v_pk_mul_f32 v[98:99], v[98:99], v[114:115] op_sel_hi:[1,0]
	v_pk_mul_f32 v[96:97], v[96:97], v[114:115] op_sel_hi:[1,0]
	v_lshl_add_u64 v[112:113], v[112:113], 0, v[160:161]
	v_cvt_pk_bf16_f32 v104, v108, v104
	v_cvt_pk_bf16_f32 v105, v105, v106
	v_cvt_pk_bf16_f32 v106, v115, v109
	v_cvt_pk_bf16_f32 v107, v110, v107
	v_pk_mul_f32 v[102:103], v[102:103], v[114:115] op_sel_hi:[1,0]
	v_pk_mul_f32 v[100:101], v[100:101], v[114:115] op_sel_hi:[1,0]
	v_max_f32_e32 v96, 0, v96
	v_max_f32_e32 v97, 0, v97
	v_max_f32_e32 v98, 0, v98
	global_store_dwordx4 v[112:113], v[104:107], off nt
	v_max_f32_e32 v100, 0, v100
	v_max_f32_e32 v99, 0, v99
	v_mul_f32_e32 v104, v96, v96
	v_max_f32_e32 v96, 0, v101
	v_mul_f32_e32 v101, v97, v97
	v_max_f32_e32 v97, 0, v102
	v_mul_f32_e32 v102, v98, v98
	v_max_f32_e32 v98, 0, v103
	v_mul_f32_e32 v100, v100, v100
	v_mul_f32_e32 v96, v96, v96
	v_mul_f32_e32 v97, v97, v97
	v_mul_f32_e32 v98, v98, v98
	v_mul_f32_e32 v99, v99, v99
	v_cvt_pk_bf16_f32 v96, v100, v96
	v_cvt_pk_bf16_f32 v97, v97, v98
	v_cvt_pk_bf16_f32 v98, v104, v101
	v_cvt_pk_bf16_f32 v99, v102, v99
	global_store_dwordx4 v[112:113], v[96:99], off offset:256 nt
	ds_read2_b32 v[98:99], v153 offset0:32 offset1:48
	s_mov_b32 s26, s14
	v_or_b32_e32 v96, 32, v154
	v_ashrrev_i32_e32 v97, 31, v96
	v_lshlrev_b64 v[96:97], 14, v[96:97]
	s_waitcnt lgkmcnt(0)
	v_pk_mul_f32 v[90:91], v[90:91], v[98:99] op_sel_hi:[1,0]
	v_pk_mul_f32 v[88:89], v[88:89], v[98:99] op_sel_hi:[1,0]
	v_pk_mul_f32 v[94:95], v[94:95], v[98:99] op_sel_hi:[1,0]
	v_pk_mul_f32 v[92:93], v[92:93], v[98:99] op_sel_hi:[1,0]
	v_max_f32_e32 v88, 0, v88
	v_max_f32_e32 v89, 0, v89
	v_max_f32_e32 v90, 0, v90
	v_max_f32_e32 v92, 0, v92
	v_mul_f32_e32 v100, v88, v88
	v_max_f32_e32 v88, 0, v93
	v_mul_f32_e32 v93, v89, v89
	v_max_f32_e32 v89, 0, v94
	v_mul_f32_e32 v94, v90, v90
	v_max_f32_e32 v90, 0, v95
	v_max_f32_e32 v91, 0, v91
	v_lshl_add_u64 v[96:97], s[72:73], 0, v[96:97]
	v_mul_f32_e32 v92, v92, v92
	v_mul_f32_e32 v88, v88, v88
	v_mul_f32_e32 v89, v89, v89
	v_mul_f32_e32 v90, v90, v90
	v_mul_f32_e32 v91, v91, v91
	v_pk_mul_f32 v[82:83], v[82:83], v[98:99] op_sel_hi:[1,0]
	v_pk_mul_f32 v[80:81], v[80:81], v[98:99] op_sel_hi:[1,0]
	v_lshl_add_u64 v[96:97], v[96:97], 0, v[160:161]
	v_cvt_pk_bf16_f32 v88, v92, v88
	v_cvt_pk_bf16_f32 v89, v89, v90
	v_cvt_pk_bf16_f32 v90, v100, v93
	v_cvt_pk_bf16_f32 v91, v94, v91
	v_pk_mul_f32 v[86:87], v[86:87], v[98:99] op_sel_hi:[1,0]
	v_pk_mul_f32 v[84:85], v[84:85], v[98:99] op_sel_hi:[1,0]
	v_max_f32_e32 v80, 0, v80
	v_max_f32_e32 v81, 0, v81
	v_max_f32_e32 v82, 0, v82
	global_store_dwordx4 v[96:97], v[88:91], off nt
	v_max_f32_e32 v84, 0, v84
	v_max_f32_e32 v83, 0, v83
	v_mul_f32_e32 v88, v80, v80
	v_max_f32_e32 v80, 0, v85
	v_mul_f32_e32 v85, v81, v81
	v_max_f32_e32 v81, 0, v86
	v_mul_f32_e32 v86, v82, v82
	v_max_f32_e32 v82, 0, v87
	v_mul_f32_e32 v84, v84, v84
	v_mul_f32_e32 v80, v80, v80
	v_mul_f32_e32 v81, v81, v81
	v_mul_f32_e32 v82, v82, v82
	v_mul_f32_e32 v83, v83, v83
	v_cvt_pk_bf16_f32 v80, v84, v80
	v_cvt_pk_bf16_f32 v81, v81, v82
	v_cvt_pk_bf16_f32 v82, v88, v85
	v_cvt_pk_bf16_f32 v83, v86, v83
	global_store_dwordx4 v[96:97], v[80:83], off offset:256 nt
	s_mov_b64 s[30:31], s[20:21]
	s_mov_b64 s[28:29], s[18:19]
	v_mov_b32_e32 v82, v99
	v_or_b32_e32 v80, 48, v154
	v_pk_mul_f32 v[74:75], v[74:75], v[82:83] op_sel_hi:[1,0]
	v_pk_mul_f32 v[72:73], v[72:73], v[82:83] op_sel_hi:[1,0]
	v_ashrrev_i32_e32 v81, 31, v80
	v_pk_mul_f32 v[78:79], v[78:79], v[82:83] op_sel_hi:[1,0]
	v_pk_mul_f32 v[76:77], v[76:77], v[82:83] op_sel_hi:[1,0]
	v_max_f32_e32 v72, 0, v72
	v_max_f32_e32 v73, 0, v73
	v_max_f32_e32 v74, 0, v74
	v_lshlrev_b64 v[80:81], 14, v[80:81]
	v_max_f32_e32 v76, 0, v76
	v_mul_f32_e32 v83, v72, v72
	v_max_f32_e32 v72, 0, v77
	v_mul_f32_e32 v77, v73, v73
	v_max_f32_e32 v73, 0, v78
	v_mul_f32_e32 v78, v74, v74
	v_max_f32_e32 v74, 0, v79
	v_max_f32_e32 v75, 0, v75
	v_lshl_add_u64 v[80:81], s[72:73], 0, v[80:81]
	v_mul_f32_e32 v76, v76, v76
	v_mul_f32_e32 v72, v72, v72
	v_mul_f32_e32 v73, v73, v73
	v_mul_f32_e32 v74, v74, v74
	v_mul_f32_e32 v75, v75, v75
	v_pk_mul_f32 v[64:65], v[64:65], v[82:83] op_sel_hi:[1,0]
	v_lshl_add_u64 v[80:81], v[80:81], 0, v[160:161]
	v_cvt_pk_bf16_f32 v72, v76, v72
	v_cvt_pk_bf16_f32 v73, v73, v74
	v_cvt_pk_bf16_f32 v74, v83, v77
	v_cvt_pk_bf16_f32 v75, v78, v75
	v_pk_mul_f32 v[68:69], v[68:69], v[82:83] op_sel_hi:[1,0]
	v_max_f32_e32 v64, 0, v64
	global_store_dwordx4 v[80:81], v[72:75], off nt
	v_max_f32_e32 v68, 0, v68
	v_mul_f32_e32 v68, v68, v68
	v_mul_f32_e32 v72, v64, v64
	v_max_f32_e32 v64, 0, v69
	v_mul_f32_e32 v64, v64, v64
	v_cvt_pk_bf16_f32 v64, v68, v64
	ds_read2_b32 v[68:69], v153 offset0:128 offset1:144
	v_pk_mul_f32 v[66:67], v[66:67], v[82:83] op_sel_hi:[1,0]
	v_pk_mul_f32 v[70:71], v[70:71], v[82:83] op_sel_hi:[1,0]
	v_max_f32_e32 v65, 0, v65
	v_max_f32_e32 v66, 0, v66
	v_mul_f32_e32 v73, v65, v65
	v_max_f32_e32 v65, 0, v70
	v_mul_f32_e32 v70, v66, v66
	v_max_f32_e32 v66, 0, v71
	v_max_f32_e32 v67, 0, v67
	v_mul_f32_e32 v65, v65, v65
	v_mul_f32_e32 v66, v66, v66
	v_mul_f32_e32 v67, v67, v67
	s_waitcnt lgkmcnt(0)
;     __device__ __forceinline__ void operator()(const f32x4 (&acc)[2][2][4][2], const Unit& u, int wr, int wc, int fr, int fq) const {
;         const int row0 = u.pm * BM + wr * 64 + fr, col0 = u.pn * BM + wc * 32 + 8 * fq;
; #pragma unroll
;         for (int ai = 0; ai < 2; ++ai)
; #pragma unroll
;             for (int m = 0; m < 4; ++m) { bf16_t* rowp = O + (size_t)(row0 + ai * HALF + m * 16) * ldc + col0;
;                 float rs = 1.0f; if (RS) rs = rt[u.i * 256 + wr * 64 + fr + ai * HALF + m * 16];
; #pragma unroll
;                 for (int bj = 0; bj < 2; ++bj) { f32x4 v0 = acc[ai][bj][m][0], v1 = acc[ai][bj][m][1];
;                     if (RS) { v0 *= rs; v1 *= rs; }
;                     if (ACT == 1) {
; #pragma unroll
;                         for (int j = 0; j < 4; ++j) { const float a = fmaxf(v0[j], 0.f), b = fmaxf(v1[j], 0.f); v0[j] = a * a; v1[j] = b * b; } }
;                     u32x4 w; w.x = pk2(v0[0], v0[1]); w.y = pk2(v0[2], v0[3]); w.z = pk2(v1[0], v1[1]); w.w = pk2(v1[2], v1[3]);
;                     *(u32x4*)(rowp + bj * HALF) = w; } }
	v_pk_mul_f32 v[56:57], v[56:57], v[68:69] op_sel_hi:[1,0]
	v_cvt_pk_bf16_f32 v65, v65, v66
	v_cvt_pk_bf16_f32 v66, v72, v73
	v_cvt_pk_bf16_f32 v67, v70, v67
	v_pk_mul_f32 v[60:61], v[60:61], v[68:69] op_sel_hi:[1,0]
	v_pk_mul_f32 v[58:59], v[58:59], v[68:69] op_sel_hi:[1,0]
	v_max_f32_e32 v56, 0, v56
	global_store_dwordx4 v[80:81], v[64:67], off offset:256 nt
	v_pk_mul_f32 v[62:63], v[62:63], v[68:69] op_sel_hi:[1,0]
	v_max_f32_e32 v60, 0, v60
	v_mul_f32_e32 v66, v56, v56
	v_max_f32_e32 v56, 0, v61
	v_max_f32_e32 v57, 0, v57
	v_max_f32_e32 v58, 0, v58
	v_mul_f32_e32 v60, v60, v60
	v_mul_f32_e32 v56, v56, v56
	v_mul_f32_e32 v61, v57, v57
	v_max_f32_e32 v57, 0, v62
	v_mul_f32_e32 v62, v58, v58
	v_max_f32_e32 v58, 0, v63
	v_max_f32_e32 v59, 0, v59
	v_mul_f32_e32 v57, v57, v57
	v_mul_f32_e32 v58, v58, v58
	v_mul_f32_e32 v59, v59, v59
	v_cvt_pk_bf16_f32 v56, v60, v56
	v_add_co_u32_e32 v60, vcc, s47, v144
	v_pk_mul_f32 v[50:51], v[50:51], v[68:69] op_sel_hi:[1,0]
	v_pk_mul_f32 v[48:49], v[48:49], v[68:69] op_sel_hi:[1,0]
	v_cvt_pk_bf16_f32 v57, v57, v58
	v_cvt_pk_bf16_f32 v58, v66, v61
	v_cvt_pk_bf16_f32 v59, v62, v59
	v_addc_co_u32_e32 v61, vcc, 0, v145, vcc
	v_pk_mul_f32 v[54:55], v[54:55], v[68:69] op_sel_hi:[1,0]
	v_pk_mul_f32 v[52:53], v[52:53], v[68:69] op_sel_hi:[1,0]
	v_max_f32_e32 v48, 0, v48
	v_max_f32_e32 v49, 0, v49
	v_max_f32_e32 v50, 0, v50
	global_store_dwordx4 v[60:61], v[56:59], off nt
	v_max_f32_e32 v52, 0, v52
	v_max_f32_e32 v51, 0, v51
	v_mul_f32_e32 v56, v48, v48
	v_max_f32_e32 v48, 0, v53
	v_mul_f32_e32 v53, v49, v49
	v_max_f32_e32 v49, 0, v54
	v_mul_f32_e32 v54, v50, v50
	v_max_f32_e32 v50, 0, v55
	v_mul_f32_e32 v52, v52, v52
	v_mul_f32_e32 v48, v48, v48
	v_mul_f32_e32 v49, v49, v49
	v_mul_f32_e32 v50, v50, v50
	v_mul_f32_e32 v51, v51, v51
	v_lshl_add_u64 v[64:65], v[144:145], 0, s[6:7]
	v_cvt_pk_bf16_f32 v48, v52, v48
	v_cvt_pk_bf16_f32 v49, v49, v50
	v_cvt_pk_bf16_f32 v50, v56, v53
	v_cvt_pk_bf16_f32 v51, v54, v51
	global_store_dwordx4 v[64:65], v[48:51], off offset:256 nt
	s_nop 1
	v_mov_b32_e32 v50, v69
	v_pk_mul_f32 v[40:41], v[40:41], v[50:51] op_sel_hi:[1,0]
	v_pk_mul_f32 v[44:45], v[44:45], v[50:51] op_sel_hi:[1,0]
	v_pk_mul_f32 v[42:43], v[42:43], v[50:51] op_sel_hi:[1,0]
	v_max_f32_e32 v40, 0, v40
	v_pk_mul_f32 v[46:47], v[46:47], v[50:51] op_sel_hi:[1,0]
	v_max_f32_e32 v44, 0, v44
	v_mul_f32_e32 v51, v40, v40
	v_max_f32_e32 v40, 0, v45
	v_max_f32_e32 v41, 0, v41
	v_max_f32_e32 v42, 0, v42
	v_mul_f32_e32 v44, v44, v44
	v_mul_f32_e32 v40, v40, v40
	v_mul_f32_e32 v45, v41, v41
	v_max_f32_e32 v41, 0, v46
	v_mul_f32_e32 v46, v42, v42
	v_max_f32_e32 v42, 0, v47
	v_max_f32_e32 v43, 0, v43
	v_mul_f32_e32 v41, v41, v41
	v_mul_f32_e32 v42, v42, v42
	v_mul_f32_e32 v43, v43, v43
	v_cvt_pk_bf16_f32 v40, v44, v40
	v_add_co_u32_e32 v44, vcc, s48, v144
	v_pk_mul_f32 v[32:33], v[32:33], v[50:51] op_sel_hi:[1,0]
	v_cvt_pk_bf16_f32 v41, v41, v42
	v_cvt_pk_bf16_f32 v42, v51, v45
	v_cvt_pk_bf16_f32 v43, v46, v43
	v_addc_co_u32_e32 v45, vcc, 0, v145, vcc
	v_pk_mul_f32 v[36:37], v[36:37], v[50:51] op_sel_hi:[1,0]
	v_max_f32_e32 v32, 0, v32
	global_store_dwordx4 v[44:45], v[40:43], off nt
	v_max_f32_e32 v36, 0, v36
	v_mul_f32_e32 v36, v36, v36
	v_mul_f32_e32 v40, v32, v32
	v_max_f32_e32 v32, 0, v37
	v_mul_f32_e32 v32, v32, v32
	v_cvt_pk_bf16_f32 v32, v36, v32
	ds_read2_b32 v[36:37], v153 offset0:160 offset1:176
	v_pk_mul_f32 v[34:35], v[34:35], v[50:51] op_sel_hi:[1,0]
	v_pk_mul_f32 v[38:39], v[38:39], v[50:51] op_sel_hi:[1,0]
	v_max_f32_e32 v33, 0, v33
	v_max_f32_e32 v34, 0, v34
	v_mul_f32_e32 v41, v33, v33
	v_max_f32_e32 v33, 0, v38
	v_mul_f32_e32 v38, v34, v34
	v_max_f32_e32 v34, 0, v39
	v_max_f32_e32 v35, 0, v35
	v_mul_f32_e32 v33, v33, v33
	v_mul_f32_e32 v34, v34, v34
	v_mul_f32_e32 v35, v35, v35
	s_waitcnt lgkmcnt(0)
;     __device__ __forceinline__ void operator()(const f32x4 (&acc)[2][2][4][2], const Unit& u, int wr, int wc, int fr, int fq) const {
;         const int row0 = u.pm * BM + wr * 64 + fr, col0 = u.pn * BM + wc * 32 + 8 * fq;
; #pragma unroll
;         for (int ai = 0; ai < 2; ++ai)
; #pragma unroll
;             for (int m = 0; m < 4; ++m) { bf16_t* rowp = O + (size_t)(row0 + ai * HALF + m * 16) * ldc + col0;
;                 float rs = 1.0f; if (RS) rs = rt[u.i * 256 + wr * 64 + fr + ai * HALF + m * 16];
; #pragma unroll
;                 for (int bj = 0; bj < 2; ++bj) { f32x4 v0 = acc[ai][bj][m][0], v1 = acc[ai][bj][m][1];
;                     if (RS) { v0 *= rs; v1 *= rs; }
;                     if (ACT == 1) {
; #pragma unroll
;                         for (int j = 0; j < 4; ++j) { const float a = fmaxf(v0[j], 0.f), b = fmaxf(v1[j], 0.f); v0[j] = a * a; v1[j] = b * b; } }
;                     u32x4 w; w.x = pk2(v0[0], v0[1]); w.y = pk2(v0[2], v0[3]); w.z = pk2(v1[0], v1[1]); w.w = pk2(v1[2], v1[3]);
;                     *(u32x4*)(rowp + bj * HALF) = w; } }
	v_pk_mul_f32 v[24:25], v[24:25], v[36:37] op_sel_hi:[1,0]
	v_lshl_add_u64 v[48:49], v[144:145], 0, s[8:9]
	v_cvt_pk_bf16_f32 v33, v33, v34
	v_cvt_pk_bf16_f32 v34, v40, v41
	v_cvt_pk_bf16_f32 v35, v38, v35
	v_pk_mul_f32 v[28:29], v[28:29], v[36:37] op_sel_hi:[1,0]
	v_pk_mul_f32 v[26:27], v[26:27], v[36:37] op_sel_hi:[1,0]
	v_max_f32_e32 v24, 0, v24
	global_store_dwordx4 v[48:49], v[32:35], off offset:256 nt
	v_pk_mul_f32 v[30:31], v[30:31], v[36:37] op_sel_hi:[1,0]
	v_max_f32_e32 v28, 0, v28
	v_mul_f32_e32 v34, v24, v24
	v_max_f32_e32 v24, 0, v29
	v_max_f32_e32 v25, 0, v25
	v_max_f32_e32 v26, 0, v26
	v_mul_f32_e32 v28, v28, v28
	v_mul_f32_e32 v24, v24, v24
	v_mul_f32_e32 v29, v25, v25
	v_max_f32_e32 v25, 0, v30
	v_mul_f32_e32 v30, v26, v26
	v_max_f32_e32 v26, 0, v31
	v_max_f32_e32 v27, 0, v27
	v_mul_f32_e32 v25, v25, v25
	v_mul_f32_e32 v26, v26, v26
	v_mul_f32_e32 v27, v27, v27
	v_cvt_pk_bf16_f32 v24, v28, v24
	v_add_co_u32_e32 v28, vcc, s49, v144
	v_pk_mul_f32 v[18:19], v[18:19], v[36:37] op_sel_hi:[1,0]
	v_pk_mul_f32 v[16:17], v[16:17], v[36:37] op_sel_hi:[1,0]
	v_cvt_pk_bf16_f32 v25, v25, v26
	v_cvt_pk_bf16_f32 v26, v34, v29
	v_cvt_pk_bf16_f32 v27, v30, v27
	v_addc_co_u32_e32 v29, vcc, 0, v145, vcc
	v_pk_mul_f32 v[22:23], v[22:23], v[36:37] op_sel_hi:[1,0]
	v_pk_mul_f32 v[20:21], v[20:21], v[36:37] op_sel_hi:[1,0]
	v_max_f32_e32 v16, 0, v16
	v_max_f32_e32 v17, 0, v17
	v_max_f32_e32 v18, 0, v18
	global_store_dwordx4 v[28:29], v[24:27], off nt
	v_max_f32_e32 v20, 0, v20
	v_max_f32_e32 v19, 0, v19
	v_mul_f32_e32 v24, v16, v16
	v_max_f32_e32 v16, 0, v21
	v_mul_f32_e32 v21, v17, v17
	v_max_f32_e32 v17, 0, v22
	v_mul_f32_e32 v22, v18, v18
	v_max_f32_e32 v18, 0, v23
	v_mul_f32_e32 v20, v20, v20
	v_mul_f32_e32 v16, v16, v16
	v_mul_f32_e32 v17, v17, v17
	v_mul_f32_e32 v18, v18, v18
	v_mul_f32_e32 v19, v19, v19
	v_lshl_add_u64 v[32:33], v[144:145], 0, s[10:11]
	v_cvt_pk_bf16_f32 v16, v20, v16
	v_cvt_pk_bf16_f32 v17, v17, v18
	v_cvt_pk_bf16_f32 v18, v24, v21
	v_cvt_pk_bf16_f32 v19, v22, v19
	global_store_dwordx4 v[32:33], v[16:19], off offset:256 nt
	s_nop 1
	v_mov_b32_e32 v18, v37
	v_pk_mul_f32 v[8:9], v[8:9], v[18:19] op_sel_hi:[1,0]
	v_pk_mul_f32 v[12:13], v[12:13], v[18:19] op_sel_hi:[1,0]
	v_pk_mul_f32 v[10:11], v[10:11], v[18:19] op_sel_hi:[1,0]
	v_max_f32_e32 v8, 0, v8
	v_pk_mul_f32 v[14:15], v[14:15], v[18:19] op_sel_hi:[1,0]
	v_max_f32_e32 v12, 0, v12
	v_mul_f32_e32 v19, v8, v8
	v_max_f32_e32 v8, 0, v13
	v_max_f32_e32 v9, 0, v9
	v_max_f32_e32 v10, 0, v10
	v_mul_f32_e32 v12, v12, v12
	v_mul_f32_e32 v8, v8, v8
	v_mul_f32_e32 v13, v9, v9
	v_max_f32_e32 v9, 0, v14
	v_mul_f32_e32 v14, v10, v10
	v_max_f32_e32 v10, 0, v15
	v_max_f32_e32 v11, 0, v11
	v_mul_f32_e32 v9, v9, v9
	v_mul_f32_e32 v10, v10, v10
	v_mul_f32_e32 v11, v11, v11
	v_cvt_pk_bf16_f32 v8, v12, v8
	v_add_co_u32_e32 v12, vcc, s50, v144
	v_pk_mul_f32 v[2:3], v[2:3], v[18:19] op_sel_hi:[1,0]
	v_pk_mul_f32 v[0:1], v[0:1], v[18:19] op_sel_hi:[1,0]
	v_cvt_pk_bf16_f32 v9, v9, v10
	v_cvt_pk_bf16_f32 v10, v19, v13
	v_cvt_pk_bf16_f32 v11, v14, v11
	v_addc_co_u32_e32 v13, vcc, 0, v145, vcc
	v_pk_mul_f32 v[6:7], v[6:7], v[18:19] op_sel_hi:[1,0]
	v_pk_mul_f32 v[4:5], v[4:5], v[18:19] op_sel_hi:[1,0]
	v_max_f32_e32 v0, 0, v0
	v_max_f32_e32 v1, 0, v1
	v_max_f32_e32 v2, 0, v2
	global_store_dwordx4 v[12:13], v[8:11], off nt
	v_max_f32_e32 v4, 0, v4
	v_max_f32_e32 v3, 0, v3
	v_mul_f32_e32 v8, v0, v0
	v_max_f32_e32 v0, 0, v5
	v_mul_f32_e32 v5, v1, v1
	v_max_f32_e32 v1, 0, v6
	v_mul_f32_e32 v6, v2, v2
	v_max_f32_e32 v2, 0, v7
	v_mul_f32_e32 v4, v4, v4
	v_mul_f32_e32 v0, v0, v0
	v_mul_f32_e32 v1, v1, v1
	v_mul_f32_e32 v2, v2, v2
	v_mul_f32_e32 v3, v3, v3
	v_lshl_add_u64 v[16:17], v[144:145], 0, s[12:13]
	v_cvt_pk_bf16_f32 v0, v4, v0
	v_cvt_pk_bf16_f32 v1, v1, v2
	v_cvt_pk_bf16_f32 v2, v8, v5
	v_cvt_pk_bf16_f32 v3, v6, v3
	s_and_b64 vcc, exec, s[0:1]
	global_store_dwordx4 v[16:17], v[0:3], off offset:256 nt
	s_cbranch_vccz .LBB0_651
	s_waitcnt vmcnt(0)
	s_cmpk_gt_u32 s33, 0xff
	s_cbranch_scc1 .LBB0_662
	s_barrier

; #define PG8_STAGE(bufoff, gbase, voff) do { _Pragma("unroll") for (int _i = 0; _i < 2; ++_i) \
;         __builtin_amdgcn_global_load_lds((const unsigned*)((const char*)(gbase) + (voff)[_i]), (LAS unsigned*)(lds + (bufoff) + ldsw + _i * 8192), 16, 0, 0); } while (0)
; #define PG8_LDA(dst, b, h) do { _Pragma("unroll") for (int m = 0; m < 4; ++m) _Pragma("unroll") for (int k = 0; k < 2; ++k) dst[m][k] = *(const LAS bf16x8*)(lds + PG8_SA(b, h) + aoff + m * 2048 + k * 1024); } while (0)
; #define PG8_LDB(dst, b, h) do { _Pragma("unroll") for (int n = 0; n < 2; ++n) _Pragma("unroll") for (int k = 0; k < 2; ++k) dst[n][k] = *(const LAS bf16x8*)(lds + PG8_SB(b, h) + boff + n * 2048 + k * 1024); } while (0)
; #define PG8_MMA(ai, bj, At, Bt) do { __builtin_amdgcn_s_setprio(1); _Pragma("unroll") for (int m = 0; m < 4; ++m) _Pragma("unroll") for (int n = 0; n < 2; ++n) _Pragma("unroll") for (int k = 0; k < 2; ++k) \
;         acc[ai][bj][m][n] = __builtin_amdgcn_mfma_f32_16x16x32_bf16(Bt[n][k], At[m][k], acc[ai][bj][m][n], 0, 0, 0); __builtin_amdgcn_s_setprio(0); } while (0)
; #define PG8_WAIT_V(n) asm volatile("s_waitcnt vmcnt(" #n ")" ::: "memory")
; #define PG8_WAIT_L(n) asm volatile("s_waitcnt lgkmcnt(" #n ")" ::: "memory")
; #define PG8_BAR __builtin_amdgcn_s_barrier()
; #define PG8_SCHED __builtin_amdgcn_sched_barrier(0)
; template <class Epi>
; __device__ __forceinline__ void gemm_phase(LAS unsigned char* lds, const Gemm g, const Order& S, const Epi& E, const int tid) {
;     ...
;             PG8_LDB(B0, 0, 0); PG8_SCHED; PG8_LDA(At, 0, 0); PG8_STAGE(PG8_SA(1, 1), a1 + hstepA, voffA);
;             PG8_WAIT_L(8); PG8_BAR; PG8_WAIT_L(0); PG8_MMA(0, 0, At, B0); PG8_BAR; PG8_SCHED;
;             PG8_LDB(B1, 0, 1); PG8_STAGE(PG8_SB(0, 0), b2, voffB);
;             PG8_BAR; PG8_WAIT_L(0); PG8_MMA(0, 1, At, B1); PG8_BAR;
;             PG8_LDA(At, 0, 1); PG8_STAGE(PG8_SA(0, 0), a2, voffA);
;             PG8_BAR; PG8_WAIT_L(0); PG8_MMA(1, 0, At, B0); PG8_BAR; PG8_SCHED;
;             PG8_STAGE(PG8_SB(0, 1), b2 + hstepB, voffB);
;             PG8_WAIT_V(6); PG8_BAR; PG8_MMA(1, 1, At, B1); PG8_BAR;
.LBB0_688:
	ds_read_b128 v[128:131], v189
	ds_read_b128 v[132:135], v189 offset:1024
	ds_read_b128 v[136:139], v189 offset:2048
	ds_read_b128 v[140:143], v189 offset:3072
	s_add_u32 s28, s26, 0xffe00080
	s_addc_u32 s29, s27, -1
	s_cmpk_eq_i32 s51, 0x7c
	s_cselect_b32 s31, s7, s29
	s_cselect_b32 s30, s15, s28
	s_cselect_b32 s29, s17, s50
	s_cselect_b32 s28, s48, s49
	v_lshl_add_u64 v[184:185], s[26:27], 0, v[160:161]
	s_add_i32 m0, s34, 0xc000
	ds_read_b128 v[144:147], v190
	ds_read_b128 v[148:151], v190 offset:1024
	ds_read_b128 v[168:171], v190 offset:2048
	ds_read_b128 v[172:175], v190 offset:3072
	ds_read_b128 v[176:179], v190 offset:4096
	ds_read_b128 v[180:183], v190 offset:5120
	ds_read_b128 v[194:197], v190 offset:6144
	ds_read_b128 v[198:201], v190 offset:7168
	global_load_lds_dwordx4 v[184:185], off
	v_lshl_add_u64 v[184:185], s[26:27], 0, v[162:163]
	s_add_i32 m0, s34, 0xe000
	s_nop 0
	global_load_lds_dwordx4 v[184:185], off
	s_waitcnt lgkmcnt(8)
	s_barrier
	s_waitcnt lgkmcnt(0)
	s_setprio 1
	s_waitcnt lgkmcnt(0)
	v_mfma_f32_16x16x32_bf16 v[124:127], v[128:131], v[144:147], v[124:127]
	v_mfma_f32_16x16x32_bf16 v[120:123], v[136:139], v[144:147], v[120:123]
	v_mfma_f32_16x16x32_bf16 v[108:111], v[128:131], v[168:171], v[108:111]
	v_mfma_f32_16x16x32_bf16 v[104:107], v[136:139], v[168:171], v[104:107]
	v_mfma_f32_16x16x32_bf16 v[92:95], v[128:131], v[176:179], v[92:95]
	v_mfma_f32_16x16x32_bf16 v[88:91], v[136:139], v[176:179], v[88:91]
	v_mfma_f32_16x16x32_bf16 v[76:79], v[128:131], v[194:197], v[76:79]
	v_mfma_f32_16x16x32_bf16 v[72:75], v[136:139], v[194:197], v[72:75]
	v_mfma_f32_16x16x32_bf16 v[124:127], v[132:135], v[148:151], v[124:127]
	v_mfma_f32_16x16x32_bf16 v[120:123], v[140:143], v[148:151], v[120:123]
	v_mfma_f32_16x16x32_bf16 v[108:111], v[132:135], v[172:175], v[108:111]
	v_mfma_f32_16x16x32_bf16 v[104:107], v[140:143], v[172:175], v[104:107]
	v_mfma_f32_16x16x32_bf16 v[92:95], v[132:135], v[180:183], v[92:95]
	v_mfma_f32_16x16x32_bf16 v[88:91], v[140:143], v[180:183], v[88:91]
	v_mfma_f32_16x16x32_bf16 v[76:79], v[132:135], v[198:201], v[76:79]
	v_mfma_f32_16x16x32_bf16 v[72:75], v[140:143], v[198:201], v[72:75]
	s_setprio 0
	s_barrier
	s_add_i32 s52, s45, s33
	v_lshl_add_u64 v[184:185], s[28:29], 0, v[154:155]
	s_mov_b32 m0, s52
	ds_read_b128 v[202:205], v191
	ds_read_b128 v[206:209], v191 offset:1024
	ds_read_b128 v[210:213], v191 offset:2048
	ds_read_b128 v[214:217], v191 offset:3072
	global_load_lds_dwordx4 v[184:185], off
	v_lshl_add_u64 v[218:219], s[28:29], 0, v[158:159]
	s_add_i32 m0, s52, 0x2000
	s_nop 0
	global_load_lds_dwordx4 v[218:219], off
	s_barrier
	s_waitcnt lgkmcnt(0)
	s_setprio 1
	s_waitcnt lgkmcnt(0)
	v_mfma_f32_16x16x32_bf16 v[116:119], v[202:205], v[144:147], v[116:119]
	v_mfma_f32_16x16x32_bf16 v[112:115], v[210:213], v[144:147], v[112:115]
	v_mfma_f32_16x16x32_bf16 v[100:103], v[202:205], v[168:171], v[100:103]
	v_mfma_f32_16x16x32_bf16 v[96:99], v[210:213], v[168:171], v[96:99]
	v_mfma_f32_16x16x32_bf16 v[84:87], v[202:205], v[176:179], v[84:87]
	v_mfma_f32_16x16x32_bf16 v[80:83], v[210:213], v[176:179], v[80:83]
	v_mfma_f32_16x16x32_bf16 v[68:71], v[202:205], v[194:197], v[68:71]
	v_mfma_f32_16x16x32_bf16 v[64:67], v[210:213], v[194:197], v[64:67]
	v_mfma_f32_16x16x32_bf16 v[116:119], v[206:209], v[148:151], v[116:119]
	v_mfma_f32_16x16x32_bf16 v[112:115], v[214:217], v[148:151], v[112:115]
	v_mfma_f32_16x16x32_bf16 v[100:103], v[206:209], v[172:175], v[100:103]
	v_mfma_f32_16x16x32_bf16 v[96:99], v[214:217], v[172:175], v[96:99]
	v_mfma_f32_16x16x32_bf16 v[84:87], v[206:209], v[180:183], v[84:87]
	v_mfma_f32_16x16x32_bf16 v[80:83], v[214:217], v[180:183], v[80:83]
	v_mfma_f32_16x16x32_bf16 v[68:71], v[206:209], v[198:201], v[68:71]
	v_mfma_f32_16x16x32_bf16 v[64:67], v[214:217], v[198:201], v[64:67]
	s_setprio 0
	s_mov_b32 m0, s34
	v_lshl_add_u64 v[220:221], s[30:31], 0, v[152:153]
	s_barrier
	ds_read_b128 v[144:147], v190 offset:16384
	ds_read_b128 v[148:151], v190 offset:17408
	ds_read_b128 v[168:171], v190 offset:18432
	ds_read_b128 v[172:175], v190 offset:19456
	ds_read_b128 v[176:179], v190 offset:20480
	ds_read_b128 v[180:183], v190 offset:21504
	ds_read_b128 v[194:197], v190 offset:22528
	ds_read_b128 v[198:201], v190 offset:23552
	global_load_lds_dwordx4 v[220:221], off
	v_lshl_add_u64 v[222:223], s[30:31], 0, v[156:157]
	s_mov_b32 m0, s35
	s_nop 0
	global_load_lds_dwordx4 v[222:223], off
	s_barrier
	s_waitcnt lgkmcnt(0)
	s_setprio 1
	s_waitcnt lgkmcnt(0)
	v_mfma_f32_16x16x32_bf16 v[60:63], v[128:131], v[144:147], v[60:63]
	v_mfma_f32_16x16x32_bf16 v[56:59], v[136:139], v[144:147], v[56:59]
	v_mfma_f32_16x16x32_bf16 v[44:47], v[128:131], v[168:171], v[44:47]
	v_mfma_f32_16x16x32_bf16 v[40:43], v[136:139], v[168:171], v[40:43]
	v_mfma_f32_16x16x32_bf16 v[28:31], v[128:131], v[176:179], v[28:31]
	v_mfma_f32_16x16x32_bf16 v[24:27], v[136:139], v[176:179], v[24:27]
	v_mfma_f32_16x16x32_bf16 v[12:15], v[128:131], v[194:197], v[12:15]
	v_mfma_f32_16x16x32_bf16 v[8:11], v[136:139], v[194:197], v[8:11]
	v_mfma_f32_16x16x32_bf16 v[60:63], v[132:135], v[148:151], v[60:63]
	v_mfma_f32_16x16x32_bf16 v[56:59], v[140:143], v[148:151], v[56:59]
	v_mfma_f32_16x16x32_bf16 v[44:47], v[132:135], v[172:175], v[44:47]
	v_mfma_f32_16x16x32_bf16 v[40:43], v[140:143], v[172:175], v[40:43]
	v_mfma_f32_16x16x32_bf16 v[28:31], v[132:135], v[180:183], v[28:31]
	v_mfma_f32_16x16x32_bf16 v[24:27], v[140:143], v[180:183], v[24:27]
	v_mfma_f32_16x16x32_bf16 v[12:15], v[132:135], v[198:201], v[12:15]
	v_mfma_f32_16x16x32_bf16 v[8:11], v[140:143], v[198:201], v[8:11]
	s_setprio 0
	s_barrier
; #define PG8_STAGE(bufoff, gbase, voff) do { _Pragma("unroll") for (int _i = 0; _i < 2; ++_i) \
;         __builtin_amdgcn_global_load_lds((const unsigned*)((const char*)(gbase) + (voff)[_i]), (LAS unsigned*)(lds + (bufoff) + ldsw + _i * 8192), 16, 0, 0); } while (0)
; #define PG8_LDA(dst, b, h) do { _Pragma("unroll") for (int m = 0; m < 4; ++m) _Pragma("unroll") for (int k = 0; k < 2; ++k) dst[m][k] = *(const LAS bf16x8*)(lds + PG8_SA(b, h) + aoff + m * 2048 + k * 1024); } while (0)
; #define PG8_LDB(dst, b, h) do { _Pragma("unroll") for (int n = 0; n < 2; ++n) _Pragma("unroll") for (int k = 0; k < 2; ++k) dst[n][k] = *(const LAS bf16x8*)(lds + PG8_SB(b, h) + boff + n * 2048 + k * 1024); } while (0)
; #define PG8_MMA(ai, bj, At, Bt) do { __builtin_amdgcn_s_setprio(1); _Pragma("unroll") for (int m = 0; m < 4; ++m) _Pragma("unroll") for (int n = 0; n < 2; ++n) _Pragma("unroll") for (int k = 0; k < 2; ++k) \
;         acc[ai][bj][m][n] = __builtin_amdgcn_mfma_f32_16x16x32_bf16(Bt[n][k], At[m][k], acc[ai][bj][m][n], 0, 0, 0); __builtin_amdgcn_s_setprio(0); } while (0)
; #define PG8_WAIT_V(n) asm volatile("s_waitcnt vmcnt(" #n ")" ::: "memory")
; #define PG8_WAIT_L(n) asm volatile("s_waitcnt lgkmcnt(" #n ")" ::: "memory")
; #define PG8_BAR __builtin_amdgcn_s_barrier()
; #define PG8_SCHED __builtin_amdgcn_sched_barrier(0)
; template <class Epi>
; __device__ __forceinline__ void gemm_phase(LAS unsigned char* lds, const Gemm g, const Order& S, const Epi& E, const int tid) {
;     ...
;             PG8_STAGE(PG8_SB(0, 1), b2 + hstepB, voffB);
;             PG8_WAIT_V(6); PG8_BAR; PG8_MMA(1, 1, At, B1); PG8_BAR;
;             PG8_LDB(B0, 1, 0); PG8_SCHED; PG8_LDA(At, 1, 0); PG8_STAGE(PG8_SA(0, 1), a2 + hstepA, voffA);
;             PG8_WAIT_L(8); PG8_BAR; PG8_WAIT_L(0); PG8_MMA(0, 0, At, B0); PG8_BAR; PG8_SCHED;
;             PG8_LDB(B1, 1, 1); PG8_STAGE(PG8_SB(1, 0), b3, voffB);
;             PG8_BAR; PG8_WAIT_L(0); PG8_MMA(0, 1, At, B1); PG8_BAR;
;             PG8_LDA(At, 1, 1); PG8_STAGE(PG8_SA(1, 0), a3, voffA);
;             PG8_BAR; PG8_WAIT_L(0); PG8_MMA(1, 0, At, B0); PG8_BAR; PG8_SCHED;
;             PG8_STAGE(PG8_SB(1, 1), b3 + hstepB, voffB);
	s_add_u32 s52, s28, 0x200000
	s_addc_u32 s53, s29, 0
	s_add_i32 s55, s46, s33
	v_lshl_add_u64 v[128:129], s[52:53], 0, v[154:155]
	s_mov_b32 m0, s55
	s_nop 0
	global_load_lds_dwordx4 v[128:129], off
	v_lshl_add_u64 v[128:129], s[52:53], 0, v[158:159]
	s_add_i32 m0, s55, 0x2000
	s_nop 0
	global_load_lds_dwordx4 v[128:129], off
	s_waitcnt vmcnt(6)
	s_barrier
	s_setprio 1
	v_mfma_f32_16x16x32_bf16 v[52:55], v[202:205], v[144:147], v[52:55]
	v_mfma_f32_16x16x32_bf16 v[48:51], v[210:213], v[144:147], v[48:51]
	v_mfma_f32_16x16x32_bf16 v[36:39], v[202:205], v[168:171], v[36:39]
	v_mfma_f32_16x16x32_bf16 v[32:35], v[210:213], v[168:171], v[32:35]
	v_mfma_f32_16x16x32_bf16 v[20:23], v[202:205], v[176:179], v[20:23]
	v_mfma_f32_16x16x32_bf16 v[16:19], v[210:213], v[176:179], v[16:19]
	v_mfma_f32_16x16x32_bf16 v[4:7], v[202:205], v[194:197], v[4:7]
	v_mfma_f32_16x16x32_bf16 v[0:3], v[210:213], v[194:197], v[0:3]
	v_mfma_f32_16x16x32_bf16 v[52:55], v[206:209], v[148:151], v[52:55]
	v_mfma_f32_16x16x32_bf16 v[48:51], v[214:217], v[148:151], v[48:51]
	v_mfma_f32_16x16x32_bf16 v[36:39], v[206:209], v[172:175], v[36:39]
	v_mfma_f32_16x16x32_bf16 v[32:35], v[214:217], v[172:175], v[32:35]
	v_mfma_f32_16x16x32_bf16 v[20:23], v[206:209], v[180:183], v[20:23]
	v_mfma_f32_16x16x32_bf16 v[16:19], v[214:217], v[180:183], v[16:19]
	v_mfma_f32_16x16x32_bf16 v[4:7], v[206:209], v[198:201], v[4:7]
	v_mfma_f32_16x16x32_bf16 v[0:3], v[214:217], v[198:201], v[0:3]
	s_setprio 0
	s_add_i32 s52, 0, 0x18000
	v_add_u32_e32 v140, s52, v187
	s_barrier
	ds_read_b128 v[128:131], v140
	ds_read_b128 v[132:135], v140 offset:1024
	ds_read_b128 v[136:139], v140 offset:2048
	ds_read_b128 v[140:143], v140 offset:3072
	s_add_u32 s30, s30, 0x200000
	s_addc_u32 s31, s31, 0
	s_mov_b32 m0, s39
	v_lshl_add_u64 v[202:203], s[30:31], 0, v[152:153]
	ds_read_b128 v[144:147], v190 offset:32768
	ds_read_b128 v[148:151], v190 offset:33792
	ds_read_b128 v[168:171], v190 offset:34816
	ds_read_b128 v[172:175], v190 offset:35840
	ds_read_b128 v[176:179], v190 offset:36864
	ds_read_b128 v[180:183], v190 offset:37888
	ds_read_b128 v[194:197], v190 offset:38912
	ds_read_b128 v[198:201], v190 offset:39936
	global_load_lds_dwordx4 v[202:203], off
	v_lshl_add_u64 v[202:203], s[30:31], 0, v[156:157]
	s_mov_b32 m0, s40
	s_nop 0
	global_load_lds_dwordx4 v[202:203], off
	s_waitcnt lgkmcnt(8)
	s_barrier
	s_waitcnt lgkmcnt(0)
	s_setprio 1
	s_waitcnt lgkmcnt(0)
	v_mfma_f32_16x16x32_bf16 v[124:127], v[128:131], v[144:147], v[124:127]
	v_mfma_f32_16x16x32_bf16 v[120:123], v[136:139], v[144:147], v[120:123]
	v_mfma_f32_16x16x32_bf16 v[108:111], v[128:131], v[168:171], v[108:111]
	v_mfma_f32_16x16x32_bf16 v[104:107], v[136:139], v[168:171], v[104:107]
	v_mfma_f32_16x16x32_bf16 v[92:95], v[128:131], v[176:179], v[92:95]
	v_mfma_f32_16x16x32_bf16 v[88:91], v[136:139], v[176:179], v[88:91]
	v_mfma_f32_16x16x32_bf16 v[76:79], v[128:131], v[194:197], v[76:79]
	v_mfma_f32_16x16x32_bf16 v[72:75], v[136:139], v[194:197], v[72:75]
	v_mfma_f32_16x16x32_bf16 v[124:127], v[132:135], v[148:151], v[124:127]
	v_mfma_f32_16x16x32_bf16 v[120:123], v[140:143], v[148:151], v[120:123]
	v_mfma_f32_16x16x32_bf16 v[108:111], v[132:135], v[172:175], v[108:111]
	v_mfma_f32_16x16x32_bf16 v[104:107], v[140:143], v[172:175], v[104:107]
	v_mfma_f32_16x16x32_bf16 v[92:95], v[132:135], v[180:183], v[92:95]
	v_mfma_f32_16x16x32_bf16 v[88:91], v[140:143], v[180:183], v[88:91]
	v_mfma_f32_16x16x32_bf16 v[76:79], v[132:135], v[198:201], v[76:79]
	v_mfma_f32_16x16x32_bf16 v[72:75], v[140:143], v[198:201], v[72:75]
	s_setprio 0
	s_barrier
	s_add_i32 s30, 0, 0x1c000
	s_add_i32 s31, s52, s33
	v_add_u32_e32 v193, s30, v187
	v_lshl_add_u64 v[184:185], v[184:185], 0, s[12:13]
	s_mov_b32 m0, s31
	ds_read_b128 v[202:205], v193
	ds_read_b128 v[206:209], v193 offset:1024
	ds_read_b128 v[210:213], v193 offset:2048
	ds_read_b128 v[214:217], v193 offset:3072
	global_load_lds_dwordx4 v[184:185], off
	v_lshl_add_u64 v[184:185], v[218:219], 0, s[12:13]
	s_add_i32 m0, s31, 0x2000
	s_nop 0
	global_load_lds_dwordx4 v[184:185], off
	s_barrier
	s_waitcnt lgkmcnt(0)
	s_setprio 1
	s_waitcnt lgkmcnt(0)
	v_mfma_f32_16x16x32_bf16 v[116:119], v[202:205], v[144:147], v[116:119]
	v_mfma_f32_16x16x32_bf16 v[112:115], v[210:213], v[144:147], v[112:115]
	v_mfma_f32_16x16x32_bf16 v[100:103], v[202:205], v[168:171], v[100:103]
	v_mfma_f32_16x16x32_bf16 v[96:99], v[210:213], v[168:171], v[96:99]
	v_mfma_f32_16x16x32_bf16 v[84:87], v[202:205], v[176:179], v[84:87]
	v_mfma_f32_16x16x32_bf16 v[80:83], v[210:213], v[176:179], v[80:83]
	v_mfma_f32_16x16x32_bf16 v[68:71], v[202:205], v[194:197], v[68:71]
	v_mfma_f32_16x16x32_bf16 v[64:67], v[210:213], v[194:197], v[64:67]
	v_mfma_f32_16x16x32_bf16 v[116:119], v[206:209], v[148:151], v[116:119]
	v_mfma_f32_16x16x32_bf16 v[112:115], v[214:217], v[148:151], v[112:115]
	v_mfma_f32_16x16x32_bf16 v[100:103], v[206:209], v[172:175], v[100:103]
	v_mfma_f32_16x16x32_bf16 v[96:99], v[214:217], v[172:175], v[96:99]
	v_mfma_f32_16x16x32_bf16 v[84:87], v[206:209], v[180:183], v[84:87]
	v_mfma_f32_16x16x32_bf16 v[80:83], v[214:217], v[180:183], v[80:83]
	v_mfma_f32_16x16x32_bf16 v[68:71], v[206:209], v[198:201], v[68:71]
	v_mfma_f32_16x16x32_bf16 v[64:67], v[214:217], v[198:201], v[64:67]
	s_setprio 0
	s_mov_b32 m0, s43
	v_lshl_add_u64 v[184:185], v[220:221], 0, s[12:13]
	s_barrier
	ds_read_b128 v[144:147], v190 offset:49152
	ds_read_b128 v[148:151], v190 offset:50176
	ds_read_b128 v[168:171], v190 offset:51200
	ds_read_b128 v[172:175], v190 offset:52224
	ds_read_b128 v[176:179], v190 offset:53248
	ds_read_b128 v[180:183], v190 offset:54272
	ds_read_b128 v[194:197], v190 offset:55296
	ds_read_b128 v[198:201], v190 offset:56320
	global_load_lds_dwordx4 v[184:185], off
	v_lshl_add_u64 v[184:185], v[222:223], 0, s[12:13]
	s_mov_b32 m0, s44
	s_nop 0
	global_load_lds_dwordx4 v[184:185], off
	s_barrier
; #define PG8_STAGE(bufoff, gbase, voff) do { _Pragma("unroll") for (int _i = 0; _i < 2; ++_i) \
;         __builtin_amdgcn_global_load_lds((const unsigned*)((const char*)(gbase) + (voff)[_i]), (LAS unsigned*)(lds + (bufoff) + ldsw + _i * 8192), 16, 0, 0); } while (0)
; #define PG8_MMA(ai, bj, At, Bt) do { __builtin_amdgcn_s_setprio(1); _Pragma("unroll") for (int m = 0; m < 4; ++m) _Pragma("unroll") for (int n = 0; n < 2; ++n) _Pragma("unroll") for (int k = 0; k < 2; ++k) \
;         acc[ai][bj][m][n] = __builtin_amdgcn_mfma_f32_16x16x32_bf16(Bt[n][k], At[m][k], acc[ai][bj][m][n], 0, 0, 0); __builtin_amdgcn_s_setprio(0); } while (0)
; #define PG8_WAIT_V(n) asm volatile("s_waitcnt vmcnt(" #n ")" ::: "memory")
; #define PG8_WAIT_L(n) asm volatile("s_waitcnt lgkmcnt(" #n ")" ::: "memory")
; #define PG8_BAR __builtin_amdgcn_s_barrier()
; #define PG8_SCHED __builtin_amdgcn_sched_barrier(0)
; template <class Epi>
; __device__ __forceinline__ void gemm_phase(LAS unsigned char* lds, const Gemm g, const Order& S, const Epi& E, const int tid) {
;     ...
;             PG8_BAR; PG8_WAIT_L(0); PG8_MMA(1, 0, At, B0); PG8_BAR; PG8_SCHED;
;             PG8_STAGE(PG8_SB(1, 1), b3 + hstepB, voffB);
;             PG8_WAIT_V(6); PG8_BAR; PG8_MMA(1, 1, At, B1); PG8_BAR;
;         }
	s_waitcnt lgkmcnt(0)
	s_setprio 1
	s_waitcnt lgkmcnt(0)
	v_mfma_f32_16x16x32_bf16 v[60:63], v[128:131], v[144:147], v[60:63]
	v_mfma_f32_16x16x32_bf16 v[56:59], v[136:139], v[144:147], v[56:59]
	v_mfma_f32_16x16x32_bf16 v[44:47], v[128:131], v[168:171], v[44:47]
	v_mfma_f32_16x16x32_bf16 v[40:43], v[136:139], v[168:171], v[40:43]
	v_mfma_f32_16x16x32_bf16 v[28:31], v[128:131], v[176:179], v[28:31]
	v_mfma_f32_16x16x32_bf16 v[24:27], v[136:139], v[176:179], v[24:27]
	v_mfma_f32_16x16x32_bf16 v[12:15], v[128:131], v[194:197], v[12:15]
	v_mfma_f32_16x16x32_bf16 v[8:11], v[136:139], v[194:197], v[8:11]
	v_mfma_f32_16x16x32_bf16 v[60:63], v[132:135], v[148:151], v[60:63]
	v_mfma_f32_16x16x32_bf16 v[56:59], v[140:143], v[148:151], v[56:59]
	v_mfma_f32_16x16x32_bf16 v[44:47], v[132:135], v[172:175], v[44:47]
	v_mfma_f32_16x16x32_bf16 v[40:43], v[140:143], v[172:175], v[40:43]
	v_mfma_f32_16x16x32_bf16 v[28:31], v[132:135], v[180:183], v[28:31]
	v_mfma_f32_16x16x32_bf16 v[24:27], v[140:143], v[180:183], v[24:27]
	v_mfma_f32_16x16x32_bf16 v[12:15], v[132:135], v[198:201], v[12:15]
	v_mfma_f32_16x16x32_bf16 v[8:11], v[140:143], v[198:201], v[8:11]
	s_setprio 0
	s_barrier
	s_add_u32 s28, s28, 0x200080
	s_addc_u32 s29, s29, 0
	s_add_i32 s30, s30, s33
	v_lshl_add_u64 v[128:129], s[28:29], 0, v[154:155]
	s_mov_b32 m0, s30
	s_nop 0
	global_load_lds_dwordx4 v[128:129], off
	v_lshl_add_u64 v[128:129], s[28:29], 0, v[158:159]
	s_add_i32 m0, s30, 0x2000
	s_nop 0
	global_load_lds_dwordx4 v[128:129], off
	s_waitcnt vmcnt(6)
	s_barrier
	s_setprio 1
	v_mfma_f32_16x16x32_bf16 v[52:55], v[202:205], v[144:147], v[52:55]
	v_mfma_f32_16x16x32_bf16 v[48:51], v[210:213], v[144:147], v[48:51]
	v_mfma_f32_16x16x32_bf16 v[36:39], v[202:205], v[168:171], v[36:39]
	v_mfma_f32_16x16x32_bf16 v[32:35], v[210:213], v[168:171], v[32:35]
	v_mfma_f32_16x16x32_bf16 v[20:23], v[202:205], v[176:179], v[20:23]
	v_mfma_f32_16x16x32_bf16 v[16:19], v[210:213], v[176:179], v[16:19]
	v_mfma_f32_16x16x32_bf16 v[4:7], v[202:205], v[194:197], v[4:7]
	v_mfma_f32_16x16x32_bf16 v[0:3], v[210:213], v[194:197], v[0:3]
	v_mfma_f32_16x16x32_bf16 v[52:55], v[206:209], v[148:151], v[52:55]
	v_mfma_f32_16x16x32_bf16 v[48:51], v[214:217], v[148:151], v[48:51]
	v_mfma_f32_16x16x32_bf16 v[36:39], v[206:209], v[172:175], v[36:39]
	v_mfma_f32_16x16x32_bf16 v[32:35], v[214:217], v[172:175], v[32:35]
	v_mfma_f32_16x16x32_bf16 v[20:23], v[206:209], v[180:183], v[20:23]
	v_mfma_f32_16x16x32_bf16 v[16:19], v[214:217], v[180:183], v[16:19]
	v_mfma_f32_16x16x32_bf16 v[4:7], v[206:209], v[198:201], v[4:7]
	v_mfma_f32_16x16x32_bf16 v[0:3], v[214:217], v[198:201], v[0:3]
	s_setprio 0
	s_add_i32 s51, s51, 2
	s_add_u32 s26, s26, 0x100
	s_addc_u32 s27, s27, 0
	s_add_u32 s49, s49, 0x100
	s_addc_u32 s50, s50, 0
	s_cmpk_gt_u32 s51, 0x7d
	s_barrier
	s_cbranch_scc0 .LBB0_688
; __device__ __forceinline__ float bflo(unsigned w) { return __uint_as_float(w << 16); }
; __device__ __forceinline__ float bfhi(unsigned w) { return __uint_as_float(w & 0xffff0000u); }
;     __device__ __forceinline__ void operator()(const f32x4 (&acc)[2][2][4][2], const Unit& u, int wr, int wc, int fr, int fq) const {
;     ...
;                 u32x4 bs[4][2];
; #pragma unroll
;                 for (int m = 0; m < 4; ++m) { const size_t off = (size_t)(row0 + ai * HALF + m * 16) * DM + col0;
; #pragma unroll
;                     for (int bj = 0; bj < 2; ++bj) bs[m][bj] = *(const u32x4*)(baseb + off + bj * HALF); }
; #pragma unroll
;                 for (int m = 0; m < 4; ++m) { const size_t off = (size_t)(row0 + ai * HALF + m * 16) * DM + col0;
;                     float ss = 0.f;
; #pragma unroll
;                     for (int bj = 0; bj < 2; ++bj) { const u32x4 q = bs[m][bj]; const f32x4 a0 = acc[ai][bj][m][0], a1 = acc[ai][bj][m][1];
;                         const float h0 = bflo(q.x) + a0[0], h1 = bfhi(q.x) + a0[1], h2 = bflo(q.y) + a0[2], h3 = bfhi(q.y) + a0[3], h4 = bflo(q.z) + a1[0], h5 = bfhi(q.z) + a1[1], h6 = bflo(q.w) + a1[2], h7 = bfhi(q.w) + a1[3];
;                         ss += (h0 * h0 + h1 * h1) + (h2 * h2 + h3 * h3) + (h4 * h4 + h5 * h5) + (h6 * h6 + h7 * h7);
;                         u32x4 w; w.x = pk2(h0, h1); w.y = pk2(h2, h3); w.z = pk2(h4, h5); w.w = pk2(h6, h7);
;                         *(u32x4*)(out + off + bj * HALF) = w; }
;                     if (ssqp) { ss += __shfl_xor(ss, 16); ss += __shfl_xor(ss, 32); if (fq == 0) ssqp[(size_t)(row0 + ai * HALF + m * 16) * 32 + u.pn * 4 + wc] = ss; } }
	v_lshl_or_b32 v168, s6, 8, v188
	v_lshl_add_u32 v172, s8, 8, v186
	v_ashrrev_i32_e32 v169, 31, v168
	v_lshlrev_b64 v[202:203], 1, v[168:169]
	v_ashrrev_i32_e32 v173, 31, v172
	v_or_b32_e32 v182, 16, v172
	v_or_b32_e32 v178, 32, v172
	v_lshl_add_u64 v[170:171], s[22:23], 0, v[202:203]
	v_lshlrev_b64 v[204:205], 12, v[172:173]
	v_or_b32_e32 v174, 48, v172
	v_ashrrev_i32_e32 v183, 31, v182
	v_ashrrev_i32_e32 v179, 31, v178
	v_lshl_add_u64 v[128:129], v[170:171], 0, v[204:205]
	v_ashrrev_i32_e32 v175, 31, v174
	v_lshlrev_b64 v[184:185], 12, v[182:183]
	v_lshlrev_b64 v[180:181], 12, v[178:179]
	global_load_dwordx4 v[194:197], v[128:129], off
	global_load_dwordx4 v[198:201], v[128:129], off offset:256
	v_lshlrev_b64 v[176:177], 12, v[174:175]
	v_lshl_add_u64 v[128:129], v[170:171], 0, v[184:185]
	v_lshl_add_u64 v[130:131], v[170:171], 0, v[180:181]
	v_lshl_add_u64 v[206:207], v[170:171], 0, v[176:177]
	global_load_dwordx4 v[148:151], v[128:129], off
	global_load_dwordx4 v[144:147], v[128:129], off offset:256
	global_load_dwordx4 v[140:143], v[130:131], off
	global_load_dwordx4 v[136:139], v[130:131], off offset:256
	global_load_dwordx4 v[132:135], v[206:207], off
	s_nop 0
	global_load_dwordx4 v[128:131], v[206:207], off offset:256
	v_cndmask_b32_e64 v193, 0, 1, s[10:11]
	v_lshl_add_u64 v[204:205], s[22:23], 0, v[204:205]
	s_lshl_b32 s26, s6, 2
	v_cmp_ne_u32_e64 s[6:7], 1, v193
	v_lshl_add_u64 v[204:205], v[204:205], 0, v[202:203]
	s_ashr_i32 s27, s26, 31
	s_andn2_b64 vcc, exec, s[10:11]
	s_waitcnt vmcnt(0)
	v_lshlrev_b32_e32 v193, 16, v194
	v_and_b32_e32 v194, 0xffff0000, v194
	v_lshlrev_b32_e32 v202, 16, v195
	v_and_b32_e32 v195, 0xffff0000, v195
	v_lshlrev_b32_e32 v203, 16, v196
	v_and_b32_e32 v196, 0xffff0000, v196
	v_lshlrev_b32_e32 v206, 16, v197
	v_and_b32_e32 v197, 0xffff0000, v197
	v_lshlrev_b32_e32 v207, 16, v198
	v_and_b32_e32 v198, 0xffff0000, v198
	v_lshlrev_b32_e32 v208, 16, v199
	v_and_b32_e32 v199, 0xffff0000, v199
	v_lshlrev_b32_e32 v209, 16, v200
	v_and_b32_e32 v200, 0xffff0000, v200
	v_lshlrev_b32_e32 v210, 16, v201
	v_and_b32_e32 v201, 0xffff0000, v201
	v_add_f32_e32 v193, v124, v193
	v_add_f32_e32 v194, v125, v194
	v_add_f32_e32 v124, v126, v202
	v_add_f32_e32 v125, v127, v195
	v_add_f32_e32 v126, v120, v203
	v_add_f32_e32 v127, v121, v196
	v_add_f32_e32 v122, v122, v206
	v_add_f32_e32 v123, v123, v197
	v_add_f32_e32 v120, v116, v207
	v_add_f32_e32 v121, v117, v198
	v_add_f32_e32 v116, v118, v208
	v_add_f32_e32 v117, v119, v199
	v_add_f32_e32 v112, v112, v209
	v_add_f32_e32 v113, v113, v200
	v_add_f32_e32 v114, v114, v210
	v_add_f32_e32 v115, v115, v201
	v_cvt_pk_bf16_f32 v196, v193, v194
	v_cvt_pk_bf16_f32 v197, v124, v125
	v_cvt_pk_bf16_f32 v198, v126, v127
	v_cvt_pk_bf16_f32 v199, v122, v123
	v_cvt_pk_bf16_f32 v200, v120, v121
	v_cvt_pk_bf16_f32 v201, v116, v117
	v_cvt_pk_bf16_f32 v202, v112, v113
	v_cvt_pk_bf16_f32 v203, v114, v115
	global_store_dwordx4 v[204:205], v[196:199], off nt
	global_store_dwordx4 v[204:205], v[200:203], off offset:256 nt
	s_cbranch_vccnz .LBB0_693
	v_mul_f32_e32 v115, v115, v115
	v_mul_f32_e32 v113, v113, v113
	v_mul_f32_e32 v118, v123, v123
	v_fmac_f32_e32 v115, v114, v114
	v_fmac_f32_e32 v113, v112, v112
	v_mul_f32_e32 v112, v121, v121
	v_mul_f32_e32 v114, v117, v117
	v_fmac_f32_e32 v118, v122, v122
	v_mul_f32_e32 v122, v194, v194
	v_mul_f32_e32 v123, v125, v125
	v_fmac_f32_e32 v112, v120, v120
	v_fmac_f32_e32 v114, v116, v116
	v_mul_f32_e32 v119, v127, v127
	v_fmac_f32_e32 v122, v193, v193
	v_fmac_f32_e32 v123, v124, v124
	v_add_f32_e32 v112, v112, v114
	v_and_b32_e32 v114, 64, v192
	v_fmac_f32_e32 v119, v126, v126
	v_add_f32_e32 v122, v122, v123
	v_add_f32_e32 v112, v113, v112
	v_xor_b32_e32 v113, 16, v192
	v_add_u32_e32 v114, 64, v114
	v_add_f32_e32 v119, v119, v122
	v_cmp_lt_i32_e32 vcc, v113, v114
	v_add_f32_e32 v118, v118, v119
	v_add_f32_e32 v112, v115, v112
	v_cndmask_b32_e32 v113, v192, v113, vcc
	v_add_f32_e32 v112, v118, v112
	v_lshlrev_b32_e32 v113, 2, v113
	ds_bpermute_b32 v113, v113, v112
	s_waitcnt lgkmcnt(0)
	v_add_f32_e32 v112, v112, v113
	v_xor_b32_e32 v113, 32, v192
	v_cmp_lt_i32_e32 vcc, v113, v114
	s_nop 1
	v_cndmask_b32_e32 v113, v192, v113, vcc
	v_lshlrev_b32_e32 v113, 2, v113
	ds_bpermute_b32 v113, v113, v112
	s_and_saveexec_b64 s[28:29], s[0:1]
	s_cbranch_execz .LBB0_692
	v_lshlrev_b64 v[114:115], 7, v[172:173]
	v_lshl_add_u64 v[114:115], s[24:25], 0, v[114:115]
	v_lshl_add_u64 v[114:115], s[26:27], 2, v[114:115]
	s_lshl_b32 s8, s41, 2
	v_lshl_add_u64 v[114:115], v[114:115], 0, s[8:9]
	s_waitcnt lgkmcnt(0)
	v_add_f32_e32 v112, v112, v113
	global_store_dword v[114:115], v112, off

; __device__ __forceinline__ float bflo(unsigned w) { return __uint_as_float(w << 16); }
; __device__ __forceinline__ float bfhi(unsigned w) { return __uint_as_float(w & 0xffff0000u); }
;     __device__ __forceinline__ void operator()(const f32x4 (&acc)[2][2][4][2], const Unit& u, int wr, int wc, int fr, int fq) const {
;     ...
;                 for (int m = 0; m < 4; ++m) { const size_t off = (size_t)(row0 + ai * HALF + m * 16) * DM + col0;
;                     float ss = 0.f;
; #pragma unroll
;                     for (int bj = 0; bj < 2; ++bj) { const u32x4 q = bs[m][bj]; const f32x4 a0 = acc[ai][bj][m][0], a1 = acc[ai][bj][m][1];
;                         const float h0 = bflo(q.x) + a0[0], h1 = bfhi(q.x) + a0[1], h2 = bflo(q.y) + a0[2], h3 = bfhi(q.y) + a0[3], h4 = bflo(q.z) + a1[0], h5 = bfhi(q.z) + a1[1], h6 = bflo(q.w) + a1[2], h7 = bfhi(q.w) + a1[3];
;                         ss += (h0 * h0 + h1 * h1) + (h2 * h2 + h3 * h3) + (h4 * h4 + h5 * h5) + (h6 * h6 + h7 * h7);
;                         u32x4 w; w.x = pk2(h0, h1); w.y = pk2(h2, h3); w.z = pk2(h4, h5); w.w = pk2(h6, h7);
;                         *(u32x4*)(out + off + bj * HALF) = w; }
;                     if (ssqp) { ss += __shfl_xor(ss, 16); ss += __shfl_xor(ss, 32); if (fq == 0) ssqp[(size_t)(row0 + ai * HALF + m * 16) * 32 + u.pn * 4 + wc] = ss; } }
.LBB0_693:
	v_lshlrev_b32_e32 v112, 16, v148
	v_add_f32_e32 v108, v108, v112
	v_and_b32_e32 v112, 0xffff0000, v148
	v_add_f32_e32 v112, v109, v112
	v_lshlrev_b32_e32 v109, 16, v149
	v_add_f32_e32 v109, v110, v109
	v_and_b32_e32 v110, 0xffff0000, v149
	v_add_f32_e32 v110, v111, v110
	v_lshlrev_b32_e32 v111, 16, v150
	v_add_f32_e32 v104, v104, v111
	v_and_b32_e32 v111, 0xffff0000, v150
	v_add_f32_e32 v105, v105, v111
	v_lshlrev_b32_e32 v111, 16, v151
	v_add_f32_e32 v111, v106, v111
	v_and_b32_e32 v106, 0xffff0000, v151
	v_add_f32_e32 v107, v107, v106
	v_lshlrev_b32_e32 v106, 16, v144
	v_add_f32_e32 v100, v100, v106
	v_and_b32_e32 v106, 0xffff0000, v144
	v_add_f32_e32 v106, v101, v106
	v_lshlrev_b32_e32 v101, 16, v145
	v_add_f32_e32 v101, v102, v101
	v_and_b32_e32 v102, 0xffff0000, v145
	v_add_f32_e32 v102, v103, v102
	v_lshlrev_b32_e32 v103, 16, v146
	v_add_f32_e32 v96, v96, v103
	v_and_b32_e32 v103, 0xffff0000, v146
	v_add_f32_e32 v97, v97, v103
	v_lshlrev_b32_e32 v103, 16, v147
	v_lshl_add_u64 v[118:119], s[22:23], 0, v[184:185]
	v_add_f32_e32 v98, v98, v103
	v_and_b32_e32 v103, 0xffff0000, v147
	v_cvt_pk_bf16_f32 v114, v108, v112
	v_cvt_pk_bf16_f32 v115, v109, v110
	v_cvt_pk_bf16_f32 v116, v104, v105
	v_cvt_pk_bf16_f32 v117, v111, v107
	v_lshl_add_u64 v[118:119], v[168:169], 1, v[118:119]
	v_add_f32_e32 v99, v99, v103
	global_store_dwordx4 v[118:119], v[114:117], off nt
	s_and_b64 vcc, exec, s[6:7]
	s_nop 0
	v_cvt_pk_bf16_f32 v114, v100, v106
	v_cvt_pk_bf16_f32 v115, v101, v102
	v_cvt_pk_bf16_f32 v116, v96, v97
	v_cvt_pk_bf16_f32 v117, v98, v99
	global_store_dwordx4 v[118:119], v[114:117], off offset:256 nt
	s_cbranch_vccnz .LBB0_697
	v_mul_f32_e32 v99, v99, v99
	v_mul_f32_e32 v97, v97, v97
	v_mul_f32_e32 v105, v105, v105
	v_fmac_f32_e32 v99, v98, v98
	v_fmac_f32_e32 v97, v96, v96
	v_mul_f32_e32 v96, v106, v106
	v_mul_f32_e32 v98, v102, v102
	v_mul_f32_e32 v103, v107, v107
	v_fmac_f32_e32 v105, v104, v104
	v_mul_f32_e32 v104, v112, v112
	v_mul_f32_e32 v107, v110, v110
	v_fmac_f32_e32 v96, v100, v100
	v_fmac_f32_e32 v98, v101, v101
	v_fmac_f32_e32 v104, v108, v108
	v_fmac_f32_e32 v107, v109, v109
	v_add_f32_e32 v96, v96, v98
	v_and_b32_e32 v98, 64, v192
	v_add_f32_e32 v104, v104, v107
	v_add_f32_e32 v96, v97, v96
	v_xor_b32_e32 v97, 16, v192
	v_add_u32_e32 v98, 64, v98
	v_fmac_f32_e32 v103, v111, v111
	v_add_f32_e32 v104, v105, v104
	v_cmp_lt_i32_e32 vcc, v97, v98
	v_add_f32_e32 v103, v103, v104
	v_add_f32_e32 v96, v99, v96
	v_cndmask_b32_e32 v97, v192, v97, vcc
	v_add_f32_e32 v96, v103, v96
	v_lshlrev_b32_e32 v97, 2, v97
	ds_bpermute_b32 v97, v97, v96
	s_waitcnt lgkmcnt(0)
	v_add_f32_e32 v96, v96, v97
	v_xor_b32_e32 v97, 32, v192
	v_cmp_lt_i32_e32 vcc, v97, v98
	s_nop 1
	v_cndmask_b32_e32 v97, v192, v97, vcc
	v_lshlrev_b32_e32 v97, 2, v97
	ds_bpermute_b32 v97, v97, v96
	s_and_saveexec_b64 s[28:29], s[0:1]
	s_cbranch_execz .LBB0_696
	v_lshlrev_b64 v[98:99], 7, v[182:183]
	v_lshl_add_u64 v[98:99], s[24:25], 0, v[98:99]
	v_lshl_add_u64 v[98:99], s[26:27], 2, v[98:99]
	s_lshl_b32 s8, s41, 2
	v_lshl_add_u64 v[98:99], v[98:99], 0, s[8:9]
	s_waitcnt lgkmcnt(0)
	v_add_f32_e32 v96, v96, v97
	global_store_dword v[98:99], v96, off

; __device__ __forceinline__ float bflo(unsigned w) { return __uint_as_float(w << 16); }
; __device__ __forceinline__ float bfhi(unsigned w) { return __uint_as_float(w & 0xffff0000u); }
;     __device__ __forceinline__ void operator()(const f32x4 (&acc)[2][2][4][2], const Unit& u, int wr, int wc, int fr, int fq) const {
;     ...
;                 for (int m = 0; m < 4; ++m) { const size_t off = (size_t)(row0 + ai * HALF + m * 16) * DM + col0;
;                     float ss = 0.f;
; #pragma unroll
;                     for (int bj = 0; bj < 2; ++bj) { const u32x4 q = bs[m][bj]; const f32x4 a0 = acc[ai][bj][m][0], a1 = acc[ai][bj][m][1];
;                         const float h0 = bflo(q.x) + a0[0], h1 = bfhi(q.x) + a0[1], h2 = bflo(q.y) + a0[2], h3 = bfhi(q.y) + a0[3], h4 = bflo(q.z) + a1[0], h5 = bfhi(q.z) + a1[1], h6 = bflo(q.w) + a1[2], h7 = bfhi(q.w) + a1[3];
;                         ss += (h0 * h0 + h1 * h1) + (h2 * h2 + h3 * h3) + (h4 * h4 + h5 * h5) + (h6 * h6 + h7 * h7);
;                         u32x4 w; w.x = pk2(h0, h1); w.y = pk2(h2, h3); w.z = pk2(h4, h5); w.w = pk2(h6, h7);
;                         *(u32x4*)(out + off + bj * HALF) = w; }
;                     if (ssqp) { ss += __shfl_xor(ss, 16); ss += __shfl_xor(ss, 32); if (fq == 0) ssqp[(size_t)(row0 + ai * HALF + m * 16) * 32 + u.pn * 4 + wc] = ss; } }
.LBB0_697:
	v_lshlrev_b32_e32 v96, 16, v140
	v_add_f32_e32 v92, v92, v96
	v_and_b32_e32 v96, 0xffff0000, v140
	v_add_f32_e32 v96, v93, v96
	v_lshlrev_b32_e32 v93, 16, v141
	v_add_f32_e32 v93, v94, v93
	v_and_b32_e32 v94, 0xffff0000, v141
	v_add_f32_e32 v94, v95, v94
	v_lshlrev_b32_e32 v95, 16, v142
	v_add_f32_e32 v88, v88, v95
	v_and_b32_e32 v95, 0xffff0000, v142
	v_add_f32_e32 v89, v89, v95
	v_lshlrev_b32_e32 v95, 16, v143
	v_add_f32_e32 v95, v90, v95
	v_and_b32_e32 v90, 0xffff0000, v143
	v_add_f32_e32 v91, v91, v90
	v_lshlrev_b32_e32 v90, 16, v136
	v_add_f32_e32 v84, v84, v90
	v_and_b32_e32 v90, 0xffff0000, v136
	v_add_f32_e32 v90, v85, v90
	v_lshlrev_b32_e32 v85, 16, v137
	v_add_f32_e32 v85, v86, v85
	v_and_b32_e32 v86, 0xffff0000, v137
	v_add_f32_e32 v86, v87, v86
	v_lshlrev_b32_e32 v87, 16, v138
	v_add_f32_e32 v80, v80, v87
	v_and_b32_e32 v87, 0xffff0000, v138
	v_add_f32_e32 v81, v81, v87
	v_lshlrev_b32_e32 v87, 16, v139
	v_lshl_add_u64 v[102:103], s[22:23], 0, v[180:181]
	v_add_f32_e32 v82, v82, v87
	v_and_b32_e32 v87, 0xffff0000, v139
	v_cvt_pk_bf16_f32 v98, v92, v96
	v_cvt_pk_bf16_f32 v99, v93, v94
	v_cvt_pk_bf16_f32 v100, v88, v89
	v_cvt_pk_bf16_f32 v101, v95, v91
	v_lshl_add_u64 v[102:103], v[168:169], 1, v[102:103]
	v_add_f32_e32 v83, v83, v87
	global_store_dwordx4 v[102:103], v[98:101], off nt
	s_and_b64 vcc, exec, s[6:7]
	s_nop 0
	v_cvt_pk_bf16_f32 v98, v84, v90
	v_cvt_pk_bf16_f32 v99, v85, v86
	v_cvt_pk_bf16_f32 v100, v80, v81
	v_cvt_pk_bf16_f32 v101, v82, v83
	global_store_dwordx4 v[102:103], v[98:101], off offset:256 nt
	s_cbranch_vccnz .LBB0_701
	v_mul_f32_e32 v83, v83, v83
	v_mul_f32_e32 v81, v81, v81
	v_mul_f32_e32 v89, v89, v89
	v_fmac_f32_e32 v83, v82, v82
	v_fmac_f32_e32 v81, v80, v80
	v_mul_f32_e32 v80, v90, v90
	v_mul_f32_e32 v82, v86, v86
	v_mul_f32_e32 v87, v91, v91
	v_fmac_f32_e32 v89, v88, v88
	v_mul_f32_e32 v88, v96, v96
	v_mul_f32_e32 v91, v94, v94
	v_fmac_f32_e32 v80, v84, v84
	v_fmac_f32_e32 v82, v85, v85
	v_fmac_f32_e32 v88, v92, v92
	v_fmac_f32_e32 v91, v93, v93
	v_add_f32_e32 v80, v80, v82
	v_and_b32_e32 v82, 64, v192
	v_add_f32_e32 v88, v88, v91
	v_add_f32_e32 v80, v81, v80
	v_xor_b32_e32 v81, 16, v192
	v_add_u32_e32 v82, 64, v82
	v_fmac_f32_e32 v87, v95, v95
	v_add_f32_e32 v88, v89, v88
	v_cmp_lt_i32_e32 vcc, v81, v82
	v_add_f32_e32 v87, v87, v88
	v_add_f32_e32 v80, v83, v80
	v_cndmask_b32_e32 v81, v192, v81, vcc
	v_add_f32_e32 v80, v87, v80
	v_lshlrev_b32_e32 v81, 2, v81
	ds_bpermute_b32 v81, v81, v80
	s_waitcnt lgkmcnt(0)
	v_add_f32_e32 v80, v80, v81
	v_xor_b32_e32 v81, 32, v192
	v_cmp_lt_i32_e32 vcc, v81, v82
	s_nop 1
	v_cndmask_b32_e32 v81, v192, v81, vcc
	v_lshlrev_b32_e32 v81, 2, v81
	ds_bpermute_b32 v81, v81, v80
	s_and_saveexec_b64 s[28:29], s[0:1]
	s_cbranch_execz .LBB0_700
	v_lshlrev_b64 v[82:83], 7, v[178:179]
	v_lshl_add_u64 v[82:83], s[24:25], 0, v[82:83]
	v_lshl_add_u64 v[82:83], s[26:27], 2, v[82:83]
	s_lshl_b32 s8, s41, 2
	v_lshl_add_u64 v[82:83], v[82:83], 0, s[8:9]
	s_waitcnt lgkmcnt(0)
	v_add_f32_e32 v80, v80, v81
	global_store_dword v[82:83], v80, off

; __device__ __forceinline__ float bflo(unsigned w) { return __uint_as_float(w << 16); }
; __device__ __forceinline__ float bfhi(unsigned w) { return __uint_as_float(w & 0xffff0000u); }
;     __device__ __forceinline__ void operator()(const f32x4 (&acc)[2][2][4][2], const Unit& u, int wr, int wc, int fr, int fq) const {
;     ...
;                 for (int m = 0; m < 4; ++m) { const size_t off = (size_t)(row0 + ai * HALF + m * 16) * DM + col0;
;                     float ss = 0.f;
; #pragma unroll
;                     for (int bj = 0; bj < 2; ++bj) { const u32x4 q = bs[m][bj]; const f32x4 a0 = acc[ai][bj][m][0], a1 = acc[ai][bj][m][1];
;                         const float h0 = bflo(q.x) + a0[0], h1 = bfhi(q.x) + a0[1], h2 = bflo(q.y) + a0[2], h3 = bfhi(q.y) + a0[3], h4 = bflo(q.z) + a1[0], h5 = bfhi(q.z) + a1[1], h6 = bflo(q.w) + a1[2], h7 = bfhi(q.w) + a1[3];
;                         ss += (h0 * h0 + h1 * h1) + (h2 * h2 + h3 * h3) + (h4 * h4 + h5 * h5) + (h6 * h6 + h7 * h7);
;                         u32x4 w; w.x = pk2(h0, h1); w.y = pk2(h2, h3); w.z = pk2(h4, h5); w.w = pk2(h6, h7);
;                         *(u32x4*)(out + off + bj * HALF) = w; }
;                     if (ssqp) { ss += __shfl_xor(ss, 16); ss += __shfl_xor(ss, 32); if (fq == 0) ssqp[(size_t)(row0 + ai * HALF + m * 16) * 32 + u.pn * 4 + wc] = ss; } }
.LBB0_701:
	v_lshlrev_b32_e32 v80, 16, v132
	v_add_f32_e32 v76, v76, v80
	v_and_b32_e32 v80, 0xffff0000, v132
	v_add_f32_e32 v80, v77, v80
	v_lshlrev_b32_e32 v77, 16, v133
	v_add_f32_e32 v77, v78, v77
	v_and_b32_e32 v78, 0xffff0000, v133
	v_add_f32_e32 v78, v79, v78
	v_lshlrev_b32_e32 v79, 16, v134
	v_add_f32_e32 v72, v72, v79
	v_and_b32_e32 v79, 0xffff0000, v134
	v_add_f32_e32 v73, v73, v79
	v_lshlrev_b32_e32 v79, 16, v135
	v_add_f32_e32 v79, v74, v79
	v_and_b32_e32 v74, 0xffff0000, v135
	v_add_f32_e32 v75, v75, v74
	v_lshlrev_b32_e32 v74, 16, v128
	v_add_f32_e32 v68, v68, v74
	v_and_b32_e32 v74, 0xffff0000, v128
	v_add_f32_e32 v74, v69, v74
	v_lshlrev_b32_e32 v69, 16, v129
	v_add_f32_e32 v69, v70, v69
	v_and_b32_e32 v70, 0xffff0000, v129
	v_add_f32_e32 v70, v71, v70
	v_lshlrev_b32_e32 v71, 16, v130
	v_add_f32_e32 v64, v64, v71
	v_and_b32_e32 v71, 0xffff0000, v130
	v_add_f32_e32 v65, v65, v71
	v_lshlrev_b32_e32 v71, 16, v131
	v_lshl_add_u64 v[86:87], s[22:23], 0, v[176:177]
	v_add_f32_e32 v66, v66, v71
	v_and_b32_e32 v71, 0xffff0000, v131
	v_cvt_pk_bf16_f32 v82, v76, v80
	v_cvt_pk_bf16_f32 v83, v77, v78
	v_cvt_pk_bf16_f32 v84, v72, v73
	v_cvt_pk_bf16_f32 v85, v79, v75
	v_lshl_add_u64 v[86:87], v[168:169], 1, v[86:87]
	v_add_f32_e32 v67, v67, v71
	global_store_dwordx4 v[86:87], v[82:85], off nt
	s_and_b64 vcc, exec, s[6:7]
	s_nop 0
	v_cvt_pk_bf16_f32 v82, v68, v74
	v_cvt_pk_bf16_f32 v83, v69, v70
	v_cvt_pk_bf16_f32 v84, v64, v65
	v_cvt_pk_bf16_f32 v85, v66, v67
	global_store_dwordx4 v[86:87], v[82:85], off offset:256 nt
	s_cbranch_vccnz .LBB0_705
	v_mul_f32_e32 v67, v67, v67
	v_mul_f32_e32 v65, v65, v65
	v_mul_f32_e32 v73, v73, v73
	v_fmac_f32_e32 v67, v66, v66
	v_fmac_f32_e32 v65, v64, v64
	v_mul_f32_e32 v64, v74, v74
	v_mul_f32_e32 v66, v70, v70
	v_mul_f32_e32 v71, v75, v75
	v_fmac_f32_e32 v73, v72, v72
	v_mul_f32_e32 v72, v80, v80
	v_mul_f32_e32 v75, v78, v78
	v_fmac_f32_e32 v64, v68, v68
	v_fmac_f32_e32 v66, v69, v69
	v_fmac_f32_e32 v72, v76, v76
	v_fmac_f32_e32 v75, v77, v77
	v_add_f32_e32 v64, v64, v66
	v_and_b32_e32 v66, 64, v192
	v_add_f32_e32 v72, v72, v75
	v_add_f32_e32 v64, v65, v64
	v_xor_b32_e32 v65, 16, v192
	v_add_u32_e32 v66, 64, v66
	v_fmac_f32_e32 v71, v79, v79
	v_add_f32_e32 v72, v73, v72
	v_cmp_lt_i32_e32 vcc, v65, v66
	v_add_f32_e32 v71, v71, v72
	v_add_f32_e32 v64, v67, v64
	v_cndmask_b32_e32 v65, v192, v65, vcc
	v_add_f32_e32 v64, v71, v64
	v_lshlrev_b32_e32 v65, 2, v65
	ds_bpermute_b32 v65, v65, v64
	s_waitcnt lgkmcnt(0)
	v_add_f32_e32 v64, v64, v65
	v_xor_b32_e32 v65, 32, v192
	v_cmp_lt_i32_e32 vcc, v65, v66
	s_nop 1
	v_cndmask_b32_e32 v65, v192, v65, vcc
	v_lshlrev_b32_e32 v65, 2, v65
	ds_bpermute_b32 v65, v65, v64
	s_and_saveexec_b64 s[28:29], s[0:1]
	s_cbranch_execz .LBB0_704
	v_lshlrev_b64 v[66:67], 7, v[174:175]
	v_lshl_add_u64 v[66:67], s[24:25], 0, v[66:67]
	v_lshl_add_u64 v[66:67], s[26:27], 2, v[66:67]
	s_lshl_b32 s8, s41, 2
	v_lshl_add_u64 v[66:67], v[66:67], 0, s[8:9]
	s_waitcnt lgkmcnt(0)
	v_add_f32_e32 v64, v64, v65
	global_store_dword v[66:67], v64, off

; __device__ __forceinline__ float bflo(unsigned w) { return __uint_as_float(w << 16); }
; __device__ __forceinline__ float bfhi(unsigned w) { return __uint_as_float(w & 0xffff0000u); }
;     __device__ __forceinline__ void operator()(const f32x4 (&acc)[2][2][4][2], const Unit& u, int wr, int wc, int fr, int fq) const {
;     ...
;                 u32x4 bs[4][2];
; #pragma unroll
;                 for (int m = 0; m < 4; ++m) { const size_t off = (size_t)(row0 + ai * HALF + m * 16) * DM + col0;
; #pragma unroll
;                     for (int bj = 0; bj < 2; ++bj) bs[m][bj] = *(const u32x4*)(baseb + off + bj * HALF); }
; #pragma unroll
;                 for (int m = 0; m < 4; ++m) { const size_t off = (size_t)(row0 + ai * HALF + m * 16) * DM + col0;
;                     float ss = 0.f;
; #pragma unroll
;                     for (int bj = 0; bj < 2; ++bj) { const u32x4 q = bs[m][bj]; const f32x4 a0 = acc[ai][bj][m][0], a1 = acc[ai][bj][m][1];
;                         const float h0 = bflo(q.x) + a0[0], h1 = bfhi(q.x) + a0[1], h2 = bflo(q.y) + a0[2], h3 = bfhi(q.y) + a0[3], h4 = bflo(q.z) + a1[0], h5 = bfhi(q.z) + a1[1], h6 = bflo(q.w) + a1[2], h7 = bfhi(q.w) + a1[3];
;                         ss += (h0 * h0 + h1 * h1) + (h2 * h2 + h3 * h3) + (h4 * h4 + h5 * h5) + (h6 * h6 + h7 * h7);
;                         u32x4 w; w.x = pk2(h0, h1); w.y = pk2(h2, h3); w.z = pk2(h4, h5); w.w = pk2(h6, h7);
;                         *(u32x4*)(out + off + bj * HALF) = w; }
;                     if (ssqp) { ss += __shfl_xor(ss, 16); ss += __shfl_xor(ss, 32); if (fq == 0) ssqp[(size_t)(row0 + ai * HALF + m * 16) * 32 + u.pn * 4 + wc] = ss; } }
.LBB0_705:
	v_add_u32_e32 v100, 0x80, v172
	v_ashrrev_i32_e32 v101, 31, v100
	v_add_u32_e32 v96, 0x90, v172
	v_add_u32_e32 v92, 0xa0, v172
	v_lshlrev_b64 v[110:111], 12, v[100:101]
	v_add_u32_e32 v88, 0xb0, v172
	s_waitcnt lgkmcnt(0)
	v_ashrrev_i32_e32 v97, 31, v96
	v_ashrrev_i32_e32 v93, 31, v92
	v_lshl_add_u64 v[64:65], v[170:171], 0, v[110:111]
	v_ashrrev_i32_e32 v89, 31, v88
	v_lshlrev_b64 v[98:99], 12, v[96:97]
	v_lshlrev_b64 v[94:95], 12, v[92:93]
	global_load_dwordx4 v[102:105], v[64:65], off
	global_load_dwordx4 v[106:109], v[64:65], off offset:256
	v_lshlrev_b64 v[90:91], 12, v[88:89]
	v_lshl_add_u64 v[64:65], v[170:171], 0, v[98:99]
	v_lshl_add_u64 v[66:67], v[170:171], 0, v[94:95]
	v_lshl_add_u64 v[112:113], v[170:171], 0, v[90:91]
	global_load_dwordx4 v[84:87], v[64:65], off
	global_load_dwordx4 v[80:83], v[64:65], off offset:256
	global_load_dwordx4 v[76:79], v[66:67], off
	global_load_dwordx4 v[72:75], v[66:67], off offset:256
	global_load_dwordx4 v[68:71], v[112:113], off
	s_nop 0
	global_load_dwordx4 v[64:67], v[112:113], off offset:256
	v_lshl_add_u64 v[110:111], s[22:23], 0, v[110:111]
	v_lshl_add_u64 v[112:113], v[168:169], 1, v[110:111]
	s_and_b64 vcc, exec, s[6:7]
	s_waitcnt vmcnt(7)
	v_lshlrev_b32_e32 v110, 16, v102
	v_and_b32_e32 v111, 0xffff0000, v102
	v_lshlrev_b32_e32 v114, 16, v103
	v_and_b32_e32 v115, 0xffff0000, v103
	v_lshlrev_b32_e32 v116, 16, v104
	v_and_b32_e32 v104, 0xffff0000, v104
	v_lshlrev_b32_e32 v117, 16, v105
	v_and_b32_e32 v105, 0xffff0000, v105
	s_waitcnt vmcnt(6)
	v_lshlrev_b32_e32 v118, 16, v106
	v_and_b32_e32 v106, 0xffff0000, v106
	v_lshlrev_b32_e32 v119, 16, v107
	v_and_b32_e32 v107, 0xffff0000, v107
	v_lshlrev_b32_e32 v120, 16, v108
	v_and_b32_e32 v108, 0xffff0000, v108
	v_lshlrev_b32_e32 v121, 16, v109
	v_and_b32_e32 v109, 0xffff0000, v109
	v_add_f32_e32 v102, v60, v110
	v_add_f32_e32 v103, v61, v111
	v_add_f32_e32 v60, v62, v114
	v_add_f32_e32 v61, v63, v115
	v_add_f32_e32 v62, v56, v116
	v_add_f32_e32 v63, v57, v104
	v_add_f32_e32 v58, v58, v117
	v_add_f32_e32 v59, v59, v105
	v_add_f32_e32 v56, v52, v118
	v_add_f32_e32 v57, v53, v106
	v_add_f32_e32 v52, v54, v119
	v_add_f32_e32 v53, v55, v107
	v_add_f32_e32 v48, v48, v120
	v_add_f32_e32 v49, v49, v108
	v_add_f32_e32 v50, v50, v121
	v_add_f32_e32 v51, v51, v109
	v_cvt_pk_bf16_f32 v104, v102, v103
	v_cvt_pk_bf16_f32 v105, v60, v61
	v_cvt_pk_bf16_f32 v106, v62, v63
	v_cvt_pk_bf16_f32 v107, v58, v59
	v_cvt_pk_bf16_f32 v108, v56, v57
	v_cvt_pk_bf16_f32 v109, v52, v53
	v_cvt_pk_bf16_f32 v110, v48, v49
	v_cvt_pk_bf16_f32 v111, v50, v51
	global_store_dwordx4 v[112:113], v[104:107], off nt
	global_store_dwordx4 v[112:113], v[108:111], off offset:256 nt
	s_cbranch_vccnz .LBB0_709
	v_mul_f32_e32 v51, v51, v51
	v_mul_f32_e32 v49, v49, v49
	v_mul_f32_e32 v54, v59, v59
	v_fmac_f32_e32 v51, v50, v50
	v_fmac_f32_e32 v49, v48, v48
	v_mul_f32_e32 v48, v57, v57
	v_mul_f32_e32 v50, v53, v53
	v_fmac_f32_e32 v54, v58, v58
	v_mul_f32_e32 v58, v103, v103
	v_mul_f32_e32 v59, v61, v61
	v_fmac_f32_e32 v48, v56, v56
	v_fmac_f32_e32 v50, v52, v52
	v_mul_f32_e32 v55, v63, v63
	v_fmac_f32_e32 v58, v102, v102
	v_fmac_f32_e32 v59, v60, v60
	v_add_f32_e32 v48, v48, v50
	v_and_b32_e32 v50, 64, v192
	v_fmac_f32_e32 v55, v62, v62
	v_add_f32_e32 v58, v58, v59
	v_add_f32_e32 v48, v49, v48
	v_xor_b32_e32 v49, 16, v192
	v_add_u32_e32 v50, 64, v50
	v_add_f32_e32 v55, v55, v58
	v_cmp_lt_i32_e32 vcc, v49, v50
	v_add_f32_e32 v54, v54, v55
	v_add_f32_e32 v48, v51, v48
	v_cndmask_b32_e32 v49, v192, v49, vcc
	v_add_f32_e32 v48, v54, v48
	v_lshlrev_b32_e32 v49, 2, v49
	ds_bpermute_b32 v49, v49, v48
	s_waitcnt lgkmcnt(0)
	v_add_f32_e32 v48, v48, v49
	v_xor_b32_e32 v49, 32, v192
	v_cmp_lt_i32_e32 vcc, v49, v50
	s_nop 1
	v_cndmask_b32_e32 v49, v192, v49, vcc
	v_lshlrev_b32_e32 v49, 2, v49
	ds_bpermute_b32 v49, v49, v48
	s_and_saveexec_b64 s[28:29], s[0:1]
	s_cbranch_execz .LBB0_708
	v_lshlrev_b64 v[50:51], 7, v[100:101]
	v_lshl_add_u64 v[50:51], s[24:25], 0, v[50:51]
	v_lshl_add_u64 v[50:51], s[26:27], 2, v[50:51]
	s_lshl_b32 s8, s41, 2
	v_lshl_add_u64 v[50:51], v[50:51], 0, s[8:9]
	s_waitcnt lgkmcnt(0)
	v_add_f32_e32 v48, v48, v49
	global_store_dword v[50:51], v48, off

; __device__ __forceinline__ float bflo(unsigned w) { return __uint_as_float(w << 16); }
; __device__ __forceinline__ float bfhi(unsigned w) { return __uint_as_float(w & 0xffff0000u); }
;     __device__ __forceinline__ void operator()(const f32x4 (&acc)[2][2][4][2], const Unit& u, int wr, int wc, int fr, int fq) const {
;     ...
;                 for (int m = 0; m < 4; ++m) { const size_t off = (size_t)(row0 + ai * HALF + m * 16) * DM + col0;
;                     float ss = 0.f;
; #pragma unroll
;                     for (int bj = 0; bj < 2; ++bj) { const u32x4 q = bs[m][bj]; const f32x4 a0 = acc[ai][bj][m][0], a1 = acc[ai][bj][m][1];
;                         const float h0 = bflo(q.x) + a0[0], h1 = bfhi(q.x) + a0[1], h2 = bflo(q.y) + a0[2], h3 = bfhi(q.y) + a0[3], h4 = bflo(q.z) + a1[0], h5 = bfhi(q.z) + a1[1], h6 = bflo(q.w) + a1[2], h7 = bfhi(q.w) + a1[3];
;                         ss += (h0 * h0 + h1 * h1) + (h2 * h2 + h3 * h3) + (h4 * h4 + h5 * h5) + (h6 * h6 + h7 * h7);
;                         u32x4 w; w.x = pk2(h0, h1); w.y = pk2(h2, h3); w.z = pk2(h4, h5); w.w = pk2(h6, h7);
;                         *(u32x4*)(out + off + bj * HALF) = w; }
;                     if (ssqp) { ss += __shfl_xor(ss, 16); ss += __shfl_xor(ss, 32); if (fq == 0) ssqp[(size_t)(row0 + ai * HALF + m * 16) * 32 + u.pn * 4 + wc] = ss; } }
.LBB0_709:
	s_waitcnt vmcnt(7)
	v_lshlrev_b32_e32 v48, 16, v84
	v_add_f32_e32 v44, v44, v48
	v_and_b32_e32 v48, 0xffff0000, v84
	v_add_f32_e32 v48, v45, v48
	v_lshlrev_b32_e32 v45, 16, v85
	v_add_f32_e32 v45, v46, v45
	v_and_b32_e32 v46, 0xffff0000, v85
	v_add_f32_e32 v46, v47, v46
	v_lshlrev_b32_e32 v47, 16, v86
	v_add_f32_e32 v40, v40, v47
	v_and_b32_e32 v47, 0xffff0000, v86
	v_add_f32_e32 v41, v41, v47
	v_lshlrev_b32_e32 v47, 16, v87
	v_add_f32_e32 v47, v42, v47
	v_and_b32_e32 v42, 0xffff0000, v87
	v_add_f32_e32 v43, v43, v42
	s_waitcnt vmcnt(6)
	v_lshlrev_b32_e32 v42, 16, v80
	v_add_f32_e32 v36, v36, v42
	v_and_b32_e32 v42, 0xffff0000, v80
	v_add_f32_e32 v42, v37, v42
	v_lshlrev_b32_e32 v37, 16, v81
	v_add_f32_e32 v37, v38, v37
	v_and_b32_e32 v38, 0xffff0000, v81
	v_add_f32_e32 v38, v39, v38
	v_lshlrev_b32_e32 v39, 16, v82
	v_add_f32_e32 v32, v32, v39
	v_and_b32_e32 v39, 0xffff0000, v82
	v_add_f32_e32 v33, v33, v39
	v_lshlrev_b32_e32 v39, 16, v83
	v_lshl_add_u64 v[54:55], s[22:23], 0, v[98:99]
	v_add_f32_e32 v34, v34, v39
	v_and_b32_e32 v39, 0xffff0000, v83
	v_cvt_pk_bf16_f32 v50, v44, v48
	v_cvt_pk_bf16_f32 v51, v45, v46
	v_cvt_pk_bf16_f32 v52, v40, v41
	v_cvt_pk_bf16_f32 v53, v47, v43
	v_lshl_add_u64 v[54:55], v[168:169], 1, v[54:55]
	v_add_f32_e32 v35, v35, v39
	global_store_dwordx4 v[54:55], v[50:53], off nt
	s_and_b64 vcc, exec, s[6:7]
	s_nop 0
	v_cvt_pk_bf16_f32 v50, v36, v42
	v_cvt_pk_bf16_f32 v51, v37, v38
	v_cvt_pk_bf16_f32 v52, v32, v33
	v_cvt_pk_bf16_f32 v53, v34, v35
	global_store_dwordx4 v[54:55], v[50:53], off offset:256 nt
	s_cbranch_vccnz .LBB0_713
	v_mul_f32_e32 v35, v35, v35
	v_mul_f32_e32 v33, v33, v33
	v_mul_f32_e32 v41, v41, v41
	v_fmac_f32_e32 v35, v34, v34
	v_fmac_f32_e32 v33, v32, v32
	v_mul_f32_e32 v32, v42, v42
	v_mul_f32_e32 v34, v38, v38
	v_mul_f32_e32 v39, v43, v43
	v_fmac_f32_e32 v41, v40, v40
	v_mul_f32_e32 v40, v48, v48
	v_mul_f32_e32 v43, v46, v46
	v_fmac_f32_e32 v32, v36, v36
	v_fmac_f32_e32 v34, v37, v37
	v_fmac_f32_e32 v40, v44, v44
	v_fmac_f32_e32 v43, v45, v45
	v_add_f32_e32 v32, v32, v34
	v_and_b32_e32 v34, 64, v192
	v_add_f32_e32 v40, v40, v43
	v_add_f32_e32 v32, v33, v32
	v_xor_b32_e32 v33, 16, v192
	v_add_u32_e32 v34, 64, v34
	v_fmac_f32_e32 v39, v47, v47
	v_add_f32_e32 v40, v41, v40
	v_cmp_lt_i32_e32 vcc, v33, v34
	v_add_f32_e32 v39, v39, v40
	v_add_f32_e32 v32, v35, v32
	v_cndmask_b32_e32 v33, v192, v33, vcc
	v_add_f32_e32 v32, v39, v32
	v_lshlrev_b32_e32 v33, 2, v33
	ds_bpermute_b32 v33, v33, v32
	s_waitcnt lgkmcnt(0)
	v_add_f32_e32 v32, v32, v33
	v_xor_b32_e32 v33, 32, v192
	v_cmp_lt_i32_e32 vcc, v33, v34
	s_nop 1
	v_cndmask_b32_e32 v33, v192, v33, vcc
	v_lshlrev_b32_e32 v33, 2, v33
	ds_bpermute_b32 v33, v33, v32
	s_and_saveexec_b64 s[28:29], s[0:1]
	s_cbranch_execz .LBB0_712
	v_lshlrev_b64 v[34:35], 7, v[96:97]
	v_lshl_add_u64 v[34:35], s[24:25], 0, v[34:35]
	v_lshl_add_u64 v[34:35], s[26:27], 2, v[34:35]
	s_lshl_b32 s8, s41, 2
	v_lshl_add_u64 v[34:35], v[34:35], 0, s[8:9]
	s_waitcnt lgkmcnt(0)
	v_add_f32_e32 v32, v32, v33
	global_store_dword v[34:35], v32, off

; __device__ __forceinline__ float bflo(unsigned w) { return __uint_as_float(w << 16); }
; __device__ __forceinline__ float bfhi(unsigned w) { return __uint_as_float(w & 0xffff0000u); }
;     __device__ __forceinline__ void operator()(const f32x4 (&acc)[2][2][4][2], const Unit& u, int wr, int wc, int fr, int fq) const {
;     ...
;                 for (int m = 0; m < 4; ++m) { const size_t off = (size_t)(row0 + ai * HALF + m * 16) * DM + col0;
;                     float ss = 0.f;
; #pragma unroll
;                     for (int bj = 0; bj < 2; ++bj) { const u32x4 q = bs[m][bj]; const f32x4 a0 = acc[ai][bj][m][0], a1 = acc[ai][bj][m][1];
;                         const float h0 = bflo(q.x) + a0[0], h1 = bfhi(q.x) + a0[1], h2 = bflo(q.y) + a0[2], h3 = bfhi(q.y) + a0[3], h4 = bflo(q.z) + a1[0], h5 = bfhi(q.z) + a1[1], h6 = bflo(q.w) + a1[2], h7 = bfhi(q.w) + a1[3];
;                         ss += (h0 * h0 + h1 * h1) + (h2 * h2 + h3 * h3) + (h4 * h4 + h5 * h5) + (h6 * h6 + h7 * h7);
;                         u32x4 w; w.x = pk2(h0, h1); w.y = pk2(h2, h3); w.z = pk2(h4, h5); w.w = pk2(h6, h7);
;                         *(u32x4*)(out + off + bj * HALF) = w; }
;                     if (ssqp) { ss += __shfl_xor(ss, 16); ss += __shfl_xor(ss, 32); if (fq == 0) ssqp[(size_t)(row0 + ai * HALF + m * 16) * 32 + u.pn * 4 + wc] = ss; } }
.LBB0_713:
	s_waitcnt vmcnt(7)
	v_lshlrev_b32_e32 v32, 16, v76
	v_add_f32_e32 v28, v28, v32
	v_and_b32_e32 v32, 0xffff0000, v76
	v_add_f32_e32 v32, v29, v32
	v_lshlrev_b32_e32 v29, 16, v77
	v_add_f32_e32 v29, v30, v29
	v_and_b32_e32 v30, 0xffff0000, v77
	v_add_f32_e32 v30, v31, v30
	v_lshlrev_b32_e32 v31, 16, v78
	v_add_f32_e32 v24, v24, v31
	v_and_b32_e32 v31, 0xffff0000, v78
	v_add_f32_e32 v25, v25, v31
	v_lshlrev_b32_e32 v31, 16, v79
	v_add_f32_e32 v31, v26, v31
	v_and_b32_e32 v26, 0xffff0000, v79
	v_add_f32_e32 v27, v27, v26
	s_waitcnt vmcnt(6)
	v_lshlrev_b32_e32 v26, 16, v72
	v_add_f32_e32 v20, v20, v26
	v_and_b32_e32 v26, 0xffff0000, v72
	v_add_f32_e32 v26, v21, v26
	v_lshlrev_b32_e32 v21, 16, v73
	v_add_f32_e32 v21, v22, v21
	v_and_b32_e32 v22, 0xffff0000, v73
	v_add_f32_e32 v22, v23, v22
	v_lshlrev_b32_e32 v23, 16, v74
	v_add_f32_e32 v16, v16, v23
	v_and_b32_e32 v23, 0xffff0000, v74
	v_add_f32_e32 v17, v17, v23
	v_lshlrev_b32_e32 v23, 16, v75
	v_lshl_add_u64 v[38:39], s[22:23], 0, v[94:95]
	v_add_f32_e32 v18, v18, v23
	v_and_b32_e32 v23, 0xffff0000, v75
	v_cvt_pk_bf16_f32 v34, v28, v32
	v_cvt_pk_bf16_f32 v35, v29, v30
	v_cvt_pk_bf16_f32 v36, v24, v25
	v_cvt_pk_bf16_f32 v37, v31, v27
	v_lshl_add_u64 v[38:39], v[168:169], 1, v[38:39]
	v_add_f32_e32 v19, v19, v23
	global_store_dwordx4 v[38:39], v[34:37], off nt
	s_and_b64 vcc, exec, s[6:7]
	s_nop 0
	v_cvt_pk_bf16_f32 v34, v20, v26
	v_cvt_pk_bf16_f32 v35, v21, v22
	v_cvt_pk_bf16_f32 v36, v16, v17
	v_cvt_pk_bf16_f32 v37, v18, v19
	global_store_dwordx4 v[38:39], v[34:37], off offset:256 nt
	s_cbranch_vccnz .LBB0_717
	v_mul_f32_e32 v19, v19, v19
	v_mul_f32_e32 v17, v17, v17
	v_mul_f32_e32 v25, v25, v25
	v_fmac_f32_e32 v19, v18, v18
	v_fmac_f32_e32 v17, v16, v16
	v_mul_f32_e32 v16, v26, v26
	v_mul_f32_e32 v18, v22, v22
	v_mul_f32_e32 v23, v27, v27
	v_fmac_f32_e32 v25, v24, v24
	v_mul_f32_e32 v24, v32, v32
	v_mul_f32_e32 v27, v30, v30
	v_fmac_f32_e32 v16, v20, v20
	v_fmac_f32_e32 v18, v21, v21
	v_fmac_f32_e32 v24, v28, v28
	v_fmac_f32_e32 v27, v29, v29
	v_add_f32_e32 v16, v16, v18
	v_and_b32_e32 v18, 64, v192
	v_add_f32_e32 v24, v24, v27
	v_add_f32_e32 v16, v17, v16
	v_xor_b32_e32 v17, 16, v192
	v_add_u32_e32 v18, 64, v18
	v_fmac_f32_e32 v23, v31, v31
	v_add_f32_e32 v24, v25, v24
	v_cmp_lt_i32_e32 vcc, v17, v18
	v_add_f32_e32 v23, v23, v24
	v_add_f32_e32 v16, v19, v16
	v_cndmask_b32_e32 v17, v192, v17, vcc
	v_add_f32_e32 v16, v23, v16
	v_lshlrev_b32_e32 v17, 2, v17
	ds_bpermute_b32 v17, v17, v16
	s_waitcnt lgkmcnt(0)
	v_add_f32_e32 v16, v16, v17
	v_xor_b32_e32 v17, 32, v192
	v_cmp_lt_i32_e32 vcc, v17, v18
	s_nop 1
	v_cndmask_b32_e32 v17, v192, v17, vcc
	v_lshlrev_b32_e32 v17, 2, v17
	ds_bpermute_b32 v17, v17, v16
	s_and_saveexec_b64 s[28:29], s[0:1]
	s_cbranch_execz .LBB0_716
	v_lshlrev_b64 v[18:19], 7, v[92:93]
	v_lshl_add_u64 v[18:19], s[24:25], 0, v[18:19]
	v_lshl_add_u64 v[18:19], s[26:27], 2, v[18:19]
	s_lshl_b32 s8, s41, 2
	v_lshl_add_u64 v[18:19], v[18:19], 0, s[8:9]
	s_waitcnt lgkmcnt(0)
	v_add_f32_e32 v16, v16, v17
	global_store_dword v[18:19], v16, off

; __device__ __forceinline__ float bflo(unsigned w) { return __uint_as_float(w << 16); }
; __device__ __forceinline__ float bfhi(unsigned w) { return __uint_as_float(w & 0xffff0000u); }
;     __device__ __forceinline__ void operator()(const f32x4 (&acc)[2][2][4][2], const Unit& u, int wr, int wc, int fr, int fq) const {
;     ...
;                 for (int m = 0; m < 4; ++m) { const size_t off = (size_t)(row0 + ai * HALF + m * 16) * DM + col0;
;                     float ss = 0.f;
; #pragma unroll
;                     for (int bj = 0; bj < 2; ++bj) { const u32x4 q = bs[m][bj]; const f32x4 a0 = acc[ai][bj][m][0], a1 = acc[ai][bj][m][1];
;                         const float h0 = bflo(q.x) + a0[0], h1 = bfhi(q.x) + a0[1], h2 = bflo(q.y) + a0[2], h3 = bfhi(q.y) + a0[3], h4 = bflo(q.z) + a1[0], h5 = bfhi(q.z) + a1[1], h6 = bflo(q.w) + a1[2], h7 = bfhi(q.w) + a1[3];
;                         ss += (h0 * h0 + h1 * h1) + (h2 * h2 + h3 * h3) + (h4 * h4 + h5 * h5) + (h6 * h6 + h7 * h7);
;                         u32x4 w; w.x = pk2(h0, h1); w.y = pk2(h2, h3); w.z = pk2(h4, h5); w.w = pk2(h6, h7);
;                         *(u32x4*)(out + off + bj * HALF) = w; }
;                     if (ssqp) { ss += __shfl_xor(ss, 16); ss += __shfl_xor(ss, 32); if (fq == 0) ssqp[(size_t)(row0 + ai * HALF + m * 16) * 32 + u.pn * 4 + wc] = ss; } }
.LBB0_717:
	s_waitcnt vmcnt(7)
	v_lshlrev_b32_e32 v16, 16, v68
	v_add_f32_e32 v12, v12, v16
	v_and_b32_e32 v16, 0xffff0000, v68
	v_add_f32_e32 v16, v13, v16
	v_lshlrev_b32_e32 v13, 16, v69
	v_add_f32_e32 v13, v14, v13
	v_and_b32_e32 v14, 0xffff0000, v69
	v_add_f32_e32 v14, v15, v14
	v_lshlrev_b32_e32 v15, 16, v70
	v_add_f32_e32 v8, v8, v15
	v_and_b32_e32 v15, 0xffff0000, v70
	v_add_f32_e32 v9, v9, v15
	v_lshlrev_b32_e32 v15, 16, v71
	v_add_f32_e32 v15, v10, v15
	v_and_b32_e32 v10, 0xffff0000, v71
	v_add_f32_e32 v11, v11, v10
	s_waitcnt vmcnt(6)
	v_lshlrev_b32_e32 v10, 16, v64
	v_add_f32_e32 v4, v4, v10
	v_and_b32_e32 v10, 0xffff0000, v64
	v_add_f32_e32 v10, v5, v10
	v_lshlrev_b32_e32 v5, 16, v65
	v_add_f32_e32 v5, v6, v5
	v_and_b32_e32 v6, 0xffff0000, v65
	v_add_f32_e32 v6, v7, v6
	v_lshlrev_b32_e32 v7, 16, v66
	v_add_f32_e32 v0, v0, v7
	v_and_b32_e32 v7, 0xffff0000, v66
	v_add_f32_e32 v1, v1, v7
	v_lshlrev_b32_e32 v7, 16, v67
	v_lshl_add_u64 v[22:23], s[22:23], 0, v[90:91]
	v_add_f32_e32 v2, v2, v7
	v_and_b32_e32 v7, 0xffff0000, v67
	v_cvt_pk_bf16_f32 v18, v12, v16
	v_cvt_pk_bf16_f32 v19, v13, v14
	v_cvt_pk_bf16_f32 v20, v8, v9
	v_cvt_pk_bf16_f32 v21, v15, v11
	v_lshl_add_u64 v[22:23], v[168:169], 1, v[22:23]
	v_add_f32_e32 v3, v3, v7
	global_store_dwordx4 v[22:23], v[18:21], off nt
	s_and_b64 vcc, exec, s[6:7]
	s_nop 0
	v_cvt_pk_bf16_f32 v18, v4, v10
	v_cvt_pk_bf16_f32 v19, v5, v6
	v_cvt_pk_bf16_f32 v20, v0, v1
	v_cvt_pk_bf16_f32 v21, v2, v3
	global_store_dwordx4 v[22:23], v[18:21], off offset:256 nt
	s_cbranch_vccnz .LBB0_680
	v_mul_f32_e32 v3, v3, v3
	v_mul_f32_e32 v1, v1, v1
	v_mul_f32_e32 v9, v9, v9
	v_fmac_f32_e32 v3, v2, v2
	v_fmac_f32_e32 v1, v0, v0
	v_mul_f32_e32 v0, v10, v10
	v_mul_f32_e32 v2, v6, v6
	v_mul_f32_e32 v7, v11, v11
	v_fmac_f32_e32 v9, v8, v8
	v_mul_f32_e32 v8, v16, v16
	v_mul_f32_e32 v11, v14, v14
	v_fmac_f32_e32 v0, v4, v4
	v_fmac_f32_e32 v2, v5, v5
	v_fmac_f32_e32 v8, v12, v12
	v_fmac_f32_e32 v11, v13, v13
	v_add_f32_e32 v0, v0, v2
	v_and_b32_e32 v2, 64, v192
	v_add_f32_e32 v8, v8, v11
	v_add_f32_e32 v0, v1, v0
	v_xor_b32_e32 v1, 16, v192
	v_add_u32_e32 v2, 64, v2
	v_fmac_f32_e32 v7, v15, v15
	v_add_f32_e32 v8, v9, v8
	v_cmp_lt_i32_e32 vcc, v1, v2
	v_add_f32_e32 v7, v7, v8
	v_add_f32_e32 v0, v3, v0
	v_cndmask_b32_e32 v1, v192, v1, vcc
	v_add_f32_e32 v0, v7, v0
	v_lshlrev_b32_e32 v1, 2, v1
	ds_bpermute_b32 v1, v1, v0
	s_waitcnt lgkmcnt(0)
	v_add_f32_e32 v0, v0, v1
	v_xor_b32_e32 v1, 32, v192
	v_cmp_lt_i32_e32 vcc, v1, v2
	s_nop 1
	v_cndmask_b32_e32 v1, v192, v1, vcc
	v_lshlrev_b32_e32 v1, 2, v1
	ds_bpermute_b32 v1, v1, v0
	s_and_saveexec_b64 s[6:7], s[0:1]
	s_cbranch_execz .LBB0_679
	v_lshlrev_b64 v[2:3], 7, v[88:89]
	v_lshl_add_u64 v[2:3], s[24:25], 0, v[2:3]
	v_lshl_add_u64 v[2:3], s[26:27], 2, v[2:3]
	s_lshl_b32 s8, s41, 2
	v_lshl_add_u64 v[2:3], v[2:3], 0, s[8:9]
	s_waitcnt lgkmcnt(0)
	v_add_f32_e32 v0, v0, v1
	global_store_dword v[2:3], v0, off
	s_branch .LBB0_679

;     __device__ __forceinline__ void operator()(f32x4 (&acc)[2][2][4][2], const Unit& u, int wr, int wc, int fr, int fq) const {
;     ...
;                 bf16_t* rowp = O + (size_t)row * INC + col0;
; #pragma unroll
;                 for (int bj = 0; bj < 2; ++bj)
; #pragma unroll
;                     for (int n = 0; n < 2; ++n) { const f32x4 v = acc[ai][bj][m][n] * (scale * rt[u.i * 256 + wr * 64 + fr + ai * HALF + m * 16]); u32x2 w; w.x = pk2(v[0], v[1]); w.y = pk2(v[2], v[3]); *(u32x2*)(rowp + bj * HALF + n * 16) = w; }
;             }
.LBB0_743:
	ds_read_b32 v20, v154 offset:704
	v_mov_b64_e32 v[18:19], s[72:73]
	v_mad_i64_i32 v[16:17], s[4:5], v16, s43, v[18:19]
	v_lshl_add_u64 v[16:17], v[142:143], 1, v[16:17]
	s_waitcnt lgkmcnt(0)
	v_mul_f32_e32 v18, v145, v20
	v_pk_mul_f32 v[14:15], v[14:15], v[18:19] op_sel_hi:[1,0]
	v_pk_mul_f32 v[12:13], v[12:13], v[18:19] op_sel_hi:[1,0]
	v_pk_mul_f32 v[10:11], v[10:11], v[18:19] op_sel_hi:[1,0]
	v_pk_mul_f32 v[8:9], v[8:9], v[18:19] op_sel_hi:[1,0]
	v_pk_mul_f32 v[6:7], v[6:7], v[18:19] op_sel_hi:[1,0]
	v_pk_mul_f32 v[4:5], v[4:5], v[18:19] op_sel_hi:[1,0]
	v_pk_mul_f32 v[2:3], v[2:3], v[18:19] op_sel_hi:[1,0]
	v_pk_mul_f32 v[0:1], v[0:1], v[18:19] op_sel_hi:[1,0]
	v_cvt_pk_bf16_f32 v12, v12, v13
	v_cvt_pk_bf16_f32 v13, v14, v15
	v_cvt_pk_bf16_f32 v8, v8, v9
	v_cvt_pk_bf16_f32 v9, v10, v11
	v_cvt_pk_bf16_f32 v4, v4, v5
	v_cvt_pk_bf16_f32 v5, v6, v7
	v_cvt_pk_bf16_f32 v0, v0, v1
	v_cvt_pk_bf16_f32 v1, v2, v3
	s_and_b64 vcc, exec, s[0:1]
	s_mov_b32 s46, s45
	s_mov_b32 s47, s12
	s_mov_b32 s4, s10
	s_mov_b64 s[20:21], s[16:17]
	s_mov_b64 s[18:19], s[14:15]
	s_nop 1
	v_permlane16_swap_b32_e32 v12, v8
	v_permlane16_swap_b32_e32 v13, v9
	v_permlane16_swap_b32_e32 v4, v0
	v_permlane16_swap_b32_e32 v5, v1
	v_mov_b32_e32 v14, v8
	v_mov_b32_e32 v15, v9
	v_mov_b32_e32 v6, v0
	v_mov_b32_e32 v7, v1
	v_lshl_add_u64 v[246:247], v[16:17], 0, v[244:245]
	global_store_dwordx4 v[246:247], v[12:15], off nt
	global_store_dwordx4 v[246:247], v[4:7], off offset:256 nt
	s_nop 1
	s_cbranch_vccnz .LBB0_764

;     __device__ __forceinline__ void operator()(f32x4 (&acc)[2][2][4][2], const Unit& u, int wr, int wc, int fr, int fq) const {
;         const int row0 = u.pm * BM + wr * 64 + fr, col0 = u.pn * BM + wc * 32 + 4 * fq;
;         const int sec = u.pn >> 3;
;         const float scale = (sec == 0) ? 0.08838834764831845f : 1.0f;
; #pragma unroll
;         for (int ai = 0; ai < 2; ++ai)
; #pragma unroll
;             for (int m = 0; m < 4; ++m) {
;                 const int row = row0 + ai * HALF + m * 16;
;                 if (sec < 2 && wc == 0) {
;                     const f32x4 t0 = *(const f32x4*)(tab + (size_t)row * 32 + 8 * fq), t1 = *(const f32x4*)(tab + (size_t)row * 32 + 8 * fq + 4);
;                     const float cs[4] = {t0[0], t0[2], t1[0], t1[2]}, sn[4] = {t0[1], t0[3], t1[1], t1[3]};
; #pragma unroll
;                     for (int bj = 0; bj < 2; ++bj)
; #pragma unroll
;                         for (int j = 0; j < 4; ++j) { const float a = acc[ai][bj][m][0][j], b = acc[ai][bj][m][1][j];
;                             acc[ai][bj][m][0][j] = a * cs[j] - b * sn[j]; acc[ai][bj][m][1][j] = b * cs[j] + a * sn[j]; }
;                 }
;                 bf16_t* rowp = O + (size_t)row * INC + col0;
; #pragma unroll
;                 for (int bj = 0; bj < 2; ++bj)
; #pragma unroll
;                     for (int n = 0; n < 2; ++n) { const f32x4 v = acc[ai][bj][m][n] * (scale * rt[u.i * 256 + wr * 64 + fr + ai * HALF + m * 16]); u32x2 w; w.x = pk2(v[0], v[1]); w.y = pk2(v[2], v[3]); *(u32x2*)(rowp + bj * HALF + n * 16) = w; }
;             }
.LBB0_750:
	s_cmp_lt_u32 s47, 8
	s_cselect_b64 vcc, -1, 0
	s_lshl_b32 s11, s46, 10
	v_add_u32_e32 v154, s11, v149
	ds_read_b32 v155, v154
	v_cndmask_b32_e32 v145, 1.0, v153, vcc
	v_lshl_or_b32 v142, s47, 8, v148
	v_mov_b64_e32 v[156:157], s[72:73]
	v_ashrrev_i32_e32 v143, 31, v142
	s_waitcnt lgkmcnt(0)
	v_mul_f32_e32 v158, v145, v155
	v_mad_i64_i32 v[156:157], s[18:19], v144, s43, v[156:157]
	v_pk_mul_f32 v[114:115], v[114:115], v[158:159] op_sel_hi:[1,0]
	v_pk_mul_f32 v[112:113], v[112:113], v[158:159] op_sel_hi:[1,0]
	v_lshl_add_u64 v[156:157], v[142:143], 1, v[156:157]
	v_cvt_pk_bf16_f32 v112, v112, v113
	v_cvt_pk_bf16_f32 v113, v114, v115
	v_pk_mul_f32 v[126:127], v[126:127], v[158:159] op_sel_hi:[1,0]
	v_pk_mul_f32 v[124:125], v[124:125], v[158:159] op_sel_hi:[1,0]
	v_pk_mul_f32 v[122:123], v[122:123], v[158:159] op_sel_hi:[1,0]
	v_pk_mul_f32 v[120:121], v[120:121], v[158:159] op_sel_hi:[1,0]
	v_pk_mul_f32 v[118:119], v[118:119], v[158:159] op_sel_hi:[1,0]
	v_pk_mul_f32 v[116:117], v[116:117], v[158:159] op_sel_hi:[1,0]
	v_cvt_pk_bf16_f32 v124, v124, v125
	v_cvt_pk_bf16_f32 v125, v126, v127
	v_cvt_pk_bf16_f32 v120, v120, v121
	v_cvt_pk_bf16_f32 v121, v122, v123
	v_cvt_pk_bf16_f32 v116, v116, v117
	v_cvt_pk_bf16_f32 v117, v118, v119
	s_and_b64 vcc, exec, s[4:5]
	s_nop 1
	v_permlane16_swap_b32_e32 v124, v120
	v_permlane16_swap_b32_e32 v125, v121
	v_permlane16_swap_b32_e32 v116, v112
	v_permlane16_swap_b32_e32 v117, v113
	v_mov_b32_e32 v126, v120
	v_mov_b32_e32 v127, v121
	v_mov_b32_e32 v118, v112
	v_mov_b32_e32 v119, v113
	v_lshl_add_u64 v[246:247], v[156:157], 0, v[244:245]
	global_store_dwordx4 v[246:247], v[124:127], off nt
	global_store_dwordx4 v[246:247], v[116:119], off offset:256 nt
	v_or_b32_e32 v112, 16, v144
	v_ashrrev_i32_e32 v113, 31, v112
	s_cbranch_vccnz .LBB0_752
	s_waitcnt vmcnt(14)
	v_mov_b32_e32 v114, v186
	v_mov_b32_e32 v115, v187
	v_mov_b32_e32 v116, v188
	v_mov_b32_e32 v117, v189
	v_mov_b32_e32 v118, v190
	v_mov_b32_e32 v119, v191
	v_mov_b32_e32 v120, v192
	v_mov_b32_e32 v121, v193
	v_mov_b32_e32 v122, v114
	v_mov_b32_e32 v123, v116
	v_mov_b32_e32 v116, v115
	v_mul_f32_e32 v114, v110, v118
	v_mul_f32_e32 v124, v106, v119
	v_mul_f32_e32 v126, v106, v118
	v_mul_f32_e32 v156, v110, v119
	v_mov_b32_e32 v106, v111
	v_mov_b32_e32 v110, v107
	v_mul_f32_e32 v158, v102, v118
	v_mul_f32_e32 v160, v98, v119
	v_mul_f32_e32 v118, v98, v118
	v_mul_f32_e32 v162, v102, v119
	v_mov_b32_e32 v98, v103
	v_mov_b32_e32 v102, v99
	v_pk_mul_f32 v[164:165], v[104:105], v[116:117]
	v_pk_mul_f32 v[104:105], v[104:105], v[122:123]
	v_pk_mul_f32 v[106:107], v[106:107], v[120:121]
	v_pk_mul_f32 v[110:111], v[110:111], v[120:121]
	v_pk_mul_f32 v[166:167], v[96:97], v[116:117]
	v_pk_mul_f32 v[98:99], v[98:99], v[120:121]
	v_pk_mul_f32 v[102:103], v[102:103], v[120:121]
	v_pk_mul_f32 v[96:97], v[96:97], v[122:123]
	v_mov_b32_e32 v115, v106
	v_mov_b32_e32 v125, v107
	v_pk_fma_f32 v[120:121], v[108:109], v[122:123], v[164:165] neg_lo:[0,0,1] neg_hi:[0,0,1]
	v_mov_b32_e32 v157, v111
	v_mov_b32_e32 v127, v110
	v_pk_fma_f32 v[104:105], v[108:109], v[116:117], v[104:105]
	v_mov_b32_e32 v159, v98
	v_mov_b32_e32 v161, v99
	v_pk_fma_f32 v[108:109], v[100:101], v[122:123], v[166:167] neg_lo:[0,0,1] neg_hi:[0,0,1]
	v_mov_b32_e32 v163, v103
	v_mov_b32_e32 v119, v102
	v_pk_fma_f32 v[96:97], v[100:101], v[116:117], v[96:97]
	v_pk_add_f32 v[110:111], v[114:115], v[124:125] neg_lo:[0,1] neg_hi:[0,1]
	v_pk_add_f32 v[106:107], v[156:157], v[126:127]
	v_pk_add_f32 v[102:103], v[158:159], v[160:161] neg_lo:[0,1] neg_hi:[0,1]
	v_pk_add_f32 v[98:99], v[162:163], v[118:119]
	v_mov_b32_e32 v100, v108
	v_mov_b32_e32 v101, v109
	v_mov_b32_e32 v108, v120
	v_mov_b32_e32 v109, v121
.LBB0_752:
	ds_read_b32 v116, v154 offset:64
	v_mov_b64_e32 v[114:115], s[72:73]
	v_mad_i64_i32 v[112:113], s[18:19], v112, s43, v[114:115]
	v_lshl_add_u64 v[112:113], v[142:143], 1, v[112:113]
	s_waitcnt lgkmcnt(0)
	v_mul_f32_e32 v114, v145, v116
	v_pk_mul_f32 v[98:99], v[98:99], v[114:115] op_sel_hi:[1,0]
	v_pk_mul_f32 v[96:97], v[96:97], v[114:115] op_sel_hi:[1,0]
	v_pk_mul_f32 v[110:111], v[110:111], v[114:115] op_sel_hi:[1,0]
	v_cvt_pk_bf16_f32 v96, v96, v97
	v_cvt_pk_bf16_f32 v97, v98, v99
	v_pk_mul_f32 v[108:109], v[108:109], v[114:115] op_sel_hi:[1,0]
	v_pk_mul_f32 v[106:107], v[106:107], v[114:115] op_sel_hi:[1,0]
	v_pk_mul_f32 v[104:105], v[104:105], v[114:115] op_sel_hi:[1,0]
	v_pk_mul_f32 v[102:103], v[102:103], v[114:115] op_sel_hi:[1,0]
	v_pk_mul_f32 v[100:101], v[100:101], v[114:115] op_sel_hi:[1,0]
	v_cvt_pk_bf16_f32 v108, v108, v109
	v_cvt_pk_bf16_f32 v109, v110, v111
	v_cvt_pk_bf16_f32 v104, v104, v105
	v_cvt_pk_bf16_f32 v105, v106, v107
	v_cvt_pk_bf16_f32 v100, v100, v101
	v_cvt_pk_bf16_f32 v101, v102, v103
	s_and_b64 vcc, exec, s[4:5]
	s_nop 1
	v_permlane16_swap_b32_e32 v108, v104
	v_permlane16_swap_b32_e32 v109, v105
	v_permlane16_swap_b32_e32 v100, v96
	v_permlane16_swap_b32_e32 v101, v97
	v_mov_b32_e32 v110, v104
	v_mov_b32_e32 v111, v105
	v_mov_b32_e32 v102, v96
	v_mov_b32_e32 v103, v97
	v_lshl_add_u64 v[246:247], v[112:113], 0, v[244:245]
	global_store_dwordx4 v[246:247], v[108:111], off nt
	global_store_dwordx4 v[246:247], v[100:103], off offset:256 nt
	v_or_b32_e32 v96, 32, v144
	v_ashrrev_i32_e32 v97, 31, v96
	s_cbranch_vccnz .LBB0_754
;     __device__ __forceinline__ void operator()(f32x4 (&acc)[2][2][4][2], const Unit& u, int wr, int wc, int fr, int fq) const {
;         const int row0 = u.pm * BM + wr * 64 + fr, col0 = u.pn * BM + wc * 32 + 4 * fq;
;         const int sec = u.pn >> 3;
;         const float scale = (sec == 0) ? 0.08838834764831845f : 1.0f;
; #pragma unroll
;         for (int ai = 0; ai < 2; ++ai)
; #pragma unroll
;             for (int m = 0; m < 4; ++m) {
;                 const int row = row0 + ai * HALF + m * 16;
;                 if (sec < 2 && wc == 0) {
;                     const f32x4 t0 = *(const f32x4*)(tab + (size_t)row * 32 + 8 * fq), t1 = *(const f32x4*)(tab + (size_t)row * 32 + 8 * fq + 4);
;                     const float cs[4] = {t0[0], t0[2], t1[0], t1[2]}, sn[4] = {t0[1], t0[3], t1[1], t1[3]};
; #pragma unroll
;                     for (int bj = 0; bj < 2; ++bj)
; #pragma unroll
;                         for (int j = 0; j < 4; ++j) { const float a = acc[ai][bj][m][0][j], b = acc[ai][bj][m][1][j];
;                             acc[ai][bj][m][0][j] = a * cs[j] - b * sn[j]; acc[ai][bj][m][1][j] = b * cs[j] + a * sn[j]; }
;                 }
;                 bf16_t* rowp = O + (size_t)row * INC + col0;
; #pragma unroll
;                 for (int bj = 0; bj < 2; ++bj)
; #pragma unroll
;                     for (int n = 0; n < 2; ++n) { const f32x4 v = acc[ai][bj][m][n] * (scale * rt[u.i * 256 + wr * 64 + fr + ai * HALF + m * 16]); u32x2 w; w.x = pk2(v[0], v[1]); w.y = pk2(v[2], v[3]); *(u32x2*)(rowp + bj * HALF + n * 16) = w; }
;             }
	s_waitcnt vmcnt(14)
	v_mov_b32_e32 v98, v194
	v_mov_b32_e32 v99, v195
	v_mov_b32_e32 v100, v196
	v_mov_b32_e32 v101, v197
	v_mov_b32_e32 v102, v198
	v_mov_b32_e32 v103, v199
	v_mov_b32_e32 v104, v200
	v_mov_b32_e32 v105, v201
	v_mov_b32_e32 v106, v98
	v_mov_b32_e32 v107, v100
	v_mov_b32_e32 v100, v99
	v_mul_f32_e32 v98, v94, v102
	v_mul_f32_e32 v108, v90, v103
	v_mul_f32_e32 v110, v90, v102
	v_mul_f32_e32 v112, v94, v103
	v_mov_b32_e32 v90, v95
	v_mov_b32_e32 v94, v91
	v_mul_f32_e32 v114, v86, v102
	v_mul_f32_e32 v116, v82, v103
	v_mul_f32_e32 v102, v82, v102
	v_mul_f32_e32 v118, v86, v103
	v_mov_b32_e32 v82, v87
	v_mov_b32_e32 v86, v83
	v_pk_mul_f32 v[120:121], v[88:89], v[100:101]
	v_pk_mul_f32 v[88:89], v[88:89], v[106:107]
	v_pk_mul_f32 v[90:91], v[90:91], v[104:105]
	v_pk_mul_f32 v[94:95], v[94:95], v[104:105]
	v_pk_mul_f32 v[122:123], v[80:81], v[100:101]
	v_pk_mul_f32 v[82:83], v[82:83], v[104:105]
	v_pk_mul_f32 v[86:87], v[86:87], v[104:105]
	v_pk_mul_f32 v[80:81], v[80:81], v[106:107]
	v_mov_b32_e32 v99, v90
	v_mov_b32_e32 v109, v91
	v_pk_fma_f32 v[104:105], v[92:93], v[106:107], v[120:121] neg_lo:[0,0,1] neg_hi:[0,0,1]
	v_mov_b32_e32 v113, v95
	v_mov_b32_e32 v111, v94
	v_pk_fma_f32 v[88:89], v[92:93], v[100:101], v[88:89]
	v_mov_b32_e32 v115, v82
	v_mov_b32_e32 v117, v83
	v_pk_fma_f32 v[92:93], v[84:85], v[106:107], v[122:123] neg_lo:[0,0,1] neg_hi:[0,0,1]
	v_mov_b32_e32 v119, v87
	v_mov_b32_e32 v103, v86
	v_pk_fma_f32 v[80:81], v[84:85], v[100:101], v[80:81]
	v_pk_add_f32 v[94:95], v[98:99], v[108:109] neg_lo:[0,1] neg_hi:[0,1]
	v_pk_add_f32 v[90:91], v[112:113], v[110:111]
	v_pk_add_f32 v[86:87], v[114:115], v[116:117] neg_lo:[0,1] neg_hi:[0,1]
	v_pk_add_f32 v[82:83], v[118:119], v[102:103]
	v_mov_b32_e32 v84, v92
	v_mov_b32_e32 v85, v93
	v_mov_b32_e32 v92, v104
	v_mov_b32_e32 v93, v105
.LBB0_754:
	ds_read_b32 v100, v154 offset:128
	v_mov_b64_e32 v[98:99], s[72:73]
	v_mad_i64_i32 v[96:97], s[18:19], v96, s43, v[98:99]
	v_lshl_add_u64 v[96:97], v[142:143], 1, v[96:97]
	s_waitcnt lgkmcnt(0)
	v_mul_f32_e32 v98, v145, v100
	v_pk_mul_f32 v[82:83], v[82:83], v[98:99] op_sel_hi:[1,0]
	v_pk_mul_f32 v[80:81], v[80:81], v[98:99] op_sel_hi:[1,0]
	v_pk_mul_f32 v[94:95], v[94:95], v[98:99] op_sel_hi:[1,0]
	v_cvt_pk_bf16_f32 v80, v80, v81
	v_cvt_pk_bf16_f32 v81, v82, v83
	v_pk_mul_f32 v[92:93], v[92:93], v[98:99] op_sel_hi:[1,0]
	v_pk_mul_f32 v[90:91], v[90:91], v[98:99] op_sel_hi:[1,0]
	v_pk_mul_f32 v[88:89], v[88:89], v[98:99] op_sel_hi:[1,0]
	v_pk_mul_f32 v[86:87], v[86:87], v[98:99] op_sel_hi:[1,0]
	v_pk_mul_f32 v[84:85], v[84:85], v[98:99] op_sel_hi:[1,0]
	v_cvt_pk_bf16_f32 v92, v92, v93
	v_cvt_pk_bf16_f32 v93, v94, v95
	v_cvt_pk_bf16_f32 v88, v88, v89
	v_cvt_pk_bf16_f32 v89, v90, v91
	v_cvt_pk_bf16_f32 v84, v84, v85
	v_cvt_pk_bf16_f32 v85, v86, v87
	s_and_b64 vcc, exec, s[4:5]
	s_nop 1
	v_permlane16_swap_b32_e32 v92, v88
	v_permlane16_swap_b32_e32 v93, v89
	v_permlane16_swap_b32_e32 v84, v80
	v_permlane16_swap_b32_e32 v85, v81
	v_mov_b32_e32 v94, v88
	v_mov_b32_e32 v95, v89
	v_mov_b32_e32 v86, v80
	v_mov_b32_e32 v87, v81
	v_lshl_add_u64 v[246:247], v[96:97], 0, v[244:245]
	global_store_dwordx4 v[246:247], v[92:95], off nt
	global_store_dwordx4 v[246:247], v[84:87], off offset:256 nt
	v_or_b32_e32 v80, 48, v144
	v_ashrrev_i32_e32 v81, 31, v80
	s_cbranch_vccnz .LBB0_756
	s_waitcnt vmcnt(14)
	v_mov_b32_e32 v82, v202
	v_mov_b32_e32 v83, v203
	v_mov_b32_e32 v84, v204
	v_mov_b32_e32 v85, v205
	v_mov_b32_e32 v86, v206
	v_mov_b32_e32 v87, v207
	v_mov_b32_e32 v88, v208
	v_mov_b32_e32 v89, v209
	v_mov_b32_e32 v90, v82
	v_mov_b32_e32 v91, v84
	v_mov_b32_e32 v84, v83
	v_mul_f32_e32 v82, v78, v86
	v_mul_f32_e32 v92, v74, v87
	v_mul_f32_e32 v94, v74, v86
	v_mul_f32_e32 v96, v78, v87
	v_mov_b32_e32 v74, v79
	v_mov_b32_e32 v78, v75
	v_mul_f32_e32 v98, v70, v86
	v_mul_f32_e32 v100, v66, v87
	v_mul_f32_e32 v86, v66, v86
	v_mul_f32_e32 v102, v70, v87
	v_mov_b32_e32 v66, v71
	v_mov_b32_e32 v70, v67
	v_pk_mul_f32 v[104:105], v[72:73], v[84:85]
	v_pk_mul_f32 v[72:73], v[72:73], v[90:91]
	v_pk_mul_f32 v[74:75], v[74:75], v[88:89]
	v_pk_mul_f32 v[78:79], v[78:79], v[88:89]
	v_pk_mul_f32 v[106:107], v[64:65], v[84:85]
	v_pk_mul_f32 v[66:67], v[66:67], v[88:89]
	v_pk_mul_f32 v[70:71], v[70:71], v[88:89]
	v_pk_mul_f32 v[64:65], v[64:65], v[90:91]
	v_mov_b32_e32 v83, v74
	v_mov_b32_e32 v93, v75
	v_pk_fma_f32 v[88:89], v[76:77], v[90:91], v[104:105] neg_lo:[0,0,1] neg_hi:[0,0,1]
	v_mov_b32_e32 v97, v79
	v_mov_b32_e32 v95, v78
	v_pk_fma_f32 v[72:73], v[76:77], v[84:85], v[72:73]
	v_mov_b32_e32 v99, v66
	v_mov_b32_e32 v101, v67
	v_pk_fma_f32 v[76:77], v[68:69], v[90:91], v[106:107] neg_lo:[0,0,1] neg_hi:[0,0,1]
	v_mov_b32_e32 v103, v71
	v_mov_b32_e32 v87, v70
	v_pk_fma_f32 v[64:65], v[68:69], v[84:85], v[64:65]
	v_pk_add_f32 v[78:79], v[82:83], v[92:93] neg_lo:[0,1] neg_hi:[0,1]
	v_pk_add_f32 v[74:75], v[96:97], v[94:95]
	v_pk_add_f32 v[70:71], v[98:99], v[100:101] neg_lo:[0,1] neg_hi:[0,1]
	v_pk_add_f32 v[66:67], v[102:103], v[86:87]
	v_mov_b32_e32 v68, v76
	v_mov_b32_e32 v69, v77
	v_mov_b32_e32 v76, v88
	v_mov_b32_e32 v77, v89
;     __device__ __forceinline__ void operator()(f32x4 (&acc)[2][2][4][2], const Unit& u, int wr, int wc, int fr, int fq) const {
;         const int row0 = u.pm * BM + wr * 64 + fr, col0 = u.pn * BM + wc * 32 + 4 * fq;
;         const int sec = u.pn >> 3;
;         const float scale = (sec == 0) ? 0.08838834764831845f : 1.0f;
; #pragma unroll
;         for (int ai = 0; ai < 2; ++ai)
; #pragma unroll
;             for (int m = 0; m < 4; ++m) {
;                 const int row = row0 + ai * HALF + m * 16;
;                 if (sec < 2 && wc == 0) {
;                     const f32x4 t0 = *(const f32x4*)(tab + (size_t)row * 32 + 8 * fq), t1 = *(const f32x4*)(tab + (size_t)row * 32 + 8 * fq + 4);
;                     const float cs[4] = {t0[0], t0[2], t1[0], t1[2]}, sn[4] = {t0[1], t0[3], t1[1], t1[3]};
; #pragma unroll
;                     for (int bj = 0; bj < 2; ++bj)
; #pragma unroll
;                         for (int j = 0; j < 4; ++j) { const float a = acc[ai][bj][m][0][j], b = acc[ai][bj][m][1][j];
;                             acc[ai][bj][m][0][j] = a * cs[j] - b * sn[j]; acc[ai][bj][m][1][j] = b * cs[j] + a * sn[j]; }
;                 }
;                 bf16_t* rowp = O + (size_t)row * INC + col0;
; #pragma unroll
;                 for (int bj = 0; bj < 2; ++bj)
; #pragma unroll
;                     for (int n = 0; n < 2; ++n) { const f32x4 v = acc[ai][bj][m][n] * (scale * rt[u.i * 256 + wr * 64 + fr + ai * HALF + m * 16]); u32x2 w; w.x = pk2(v[0], v[1]); w.y = pk2(v[2], v[3]); *(u32x2*)(rowp + bj * HALF + n * 16) = w; }
;             }
.LBB0_756:
	ds_read_b32 v84, v154 offset:192
	v_mov_b64_e32 v[82:83], s[72:73]
	v_mad_i64_i32 v[80:81], s[18:19], v80, s43, v[82:83]
	v_lshl_add_u64 v[80:81], v[142:143], 1, v[80:81]
	s_waitcnt lgkmcnt(0)
	v_mul_f32_e32 v82, v145, v84
	v_pk_mul_f32 v[66:67], v[66:67], v[82:83] op_sel_hi:[1,0]
	v_pk_mul_f32 v[64:65], v[64:65], v[82:83] op_sel_hi:[1,0]
	v_pk_mul_f32 v[78:79], v[78:79], v[82:83] op_sel_hi:[1,0]
	v_cvt_pk_bf16_f32 v64, v64, v65
	v_cvt_pk_bf16_f32 v65, v66, v67
	v_pk_mul_f32 v[76:77], v[76:77], v[82:83] op_sel_hi:[1,0]
	v_pk_mul_f32 v[74:75], v[74:75], v[82:83] op_sel_hi:[1,0]
	v_pk_mul_f32 v[72:73], v[72:73], v[82:83] op_sel_hi:[1,0]
	v_pk_mul_f32 v[70:71], v[70:71], v[82:83] op_sel_hi:[1,0]
	v_pk_mul_f32 v[68:69], v[68:69], v[82:83] op_sel_hi:[1,0]
	v_cvt_pk_bf16_f32 v76, v76, v77
	v_cvt_pk_bf16_f32 v77, v78, v79
	v_cvt_pk_bf16_f32 v72, v72, v73
	v_cvt_pk_bf16_f32 v73, v74, v75
	v_cvt_pk_bf16_f32 v68, v68, v69
	v_cvt_pk_bf16_f32 v69, v70, v71
	s_and_b64 vcc, exec, s[4:5]
	s_nop 1
	v_permlane16_swap_b32_e32 v76, v72
	v_permlane16_swap_b32_e32 v77, v73
	v_permlane16_swap_b32_e32 v68, v64
	v_permlane16_swap_b32_e32 v69, v65
	v_mov_b32_e32 v78, v72
	v_mov_b32_e32 v79, v73
	v_mov_b32_e32 v70, v64
	v_mov_b32_e32 v71, v65
	v_lshl_add_u64 v[246:247], v[80:81], 0, v[244:245]
	global_store_dwordx4 v[246:247], v[76:79], off nt
	global_store_dwordx4 v[246:247], v[68:71], off offset:256 nt
	v_add_u32_e32 v64, 0x80, v144
	v_ashrrev_i32_e32 v65, 31, v64
	s_cbranch_vccnz .LBB0_758
	s_waitcnt vmcnt(14)
	v_mov_b32_e32 v66, v210
	v_mov_b32_e32 v67, v211
	v_mov_b32_e32 v68, v212
	v_mov_b32_e32 v69, v213
	v_mov_b32_e32 v70, v214
	v_mov_b32_e32 v71, v215
	v_mov_b32_e32 v72, v216
	v_mov_b32_e32 v73, v217
	v_mov_b32_e32 v74, v66
	v_mov_b32_e32 v75, v68
	v_mov_b32_e32 v68, v67
	v_mul_f32_e32 v66, v62, v70
	v_mul_f32_e32 v76, v58, v71
	v_mul_f32_e32 v78, v58, v70
	v_mul_f32_e32 v80, v62, v71
	v_mov_b32_e32 v58, v63
	v_mov_b32_e32 v62, v59
	v_mul_f32_e32 v82, v54, v70
	v_mul_f32_e32 v84, v50, v71
	v_mul_f32_e32 v70, v50, v70
	v_mul_f32_e32 v86, v54, v71
	v_mov_b32_e32 v50, v55
	v_mov_b32_e32 v54, v51
	v_pk_mul_f32 v[88:89], v[56:57], v[68:69]
	v_pk_mul_f32 v[56:57], v[56:57], v[74:75]
	v_pk_mul_f32 v[58:59], v[58:59], v[72:73]
	v_pk_mul_f32 v[62:63], v[62:63], v[72:73]
	v_pk_mul_f32 v[90:91], v[48:49], v[68:69]
	v_pk_mul_f32 v[50:51], v[50:51], v[72:73]
	v_pk_mul_f32 v[54:55], v[54:55], v[72:73]
	v_pk_mul_f32 v[48:49], v[48:49], v[74:75]
	v_mov_b32_e32 v67, v58
	v_mov_b32_e32 v77, v59
	v_pk_fma_f32 v[72:73], v[60:61], v[74:75], v[88:89] neg_lo:[0,0,1] neg_hi:[0,0,1]
	v_mov_b32_e32 v81, v63
	v_mov_b32_e32 v79, v62
	v_pk_fma_f32 v[56:57], v[60:61], v[68:69], v[56:57]
	v_mov_b32_e32 v83, v50
	v_mov_b32_e32 v85, v51
	v_pk_fma_f32 v[60:61], v[52:53], v[74:75], v[90:91] neg_lo:[0,0,1] neg_hi:[0,0,1]
	v_mov_b32_e32 v87, v55
	v_mov_b32_e32 v71, v54
	v_pk_fma_f32 v[48:49], v[52:53], v[68:69], v[48:49]
	v_pk_add_f32 v[62:63], v[66:67], v[76:77] neg_lo:[0,1] neg_hi:[0,1]
	v_pk_add_f32 v[58:59], v[80:81], v[78:79]
	v_pk_add_f32 v[54:55], v[82:83], v[84:85] neg_lo:[0,1] neg_hi:[0,1]
	v_pk_add_f32 v[50:51], v[86:87], v[70:71]
	v_mov_b32_e32 v52, v60
	v_mov_b32_e32 v53, v61
	v_mov_b32_e32 v60, v72
	v_mov_b32_e32 v61, v73
.LBB0_758:
	ds_read_b32 v68, v154 offset:512
	v_mov_b64_e32 v[66:67], s[72:73]
	v_mad_i64_i32 v[64:65], s[18:19], v64, s43, v[66:67]
	v_lshl_add_u64 v[64:65], v[142:143], 1, v[64:65]
	s_waitcnt lgkmcnt(0)
	v_mul_f32_e32 v66, v145, v68
	v_pk_mul_f32 v[50:51], v[50:51], v[66:67] op_sel_hi:[1,0]
	v_pk_mul_f32 v[48:49], v[48:49], v[66:67] op_sel_hi:[1,0]
	v_pk_mul_f32 v[62:63], v[62:63], v[66:67] op_sel_hi:[1,0]
	v_cvt_pk_bf16_f32 v48, v48, v49
	v_cvt_pk_bf16_f32 v49, v50, v51
	v_pk_mul_f32 v[60:61], v[60:61], v[66:67] op_sel_hi:[1,0]
	v_pk_mul_f32 v[58:59], v[58:59], v[66:67] op_sel_hi:[1,0]
	v_pk_mul_f32 v[56:57], v[56:57], v[66:67] op_sel_hi:[1,0]
	v_pk_mul_f32 v[54:55], v[54:55], v[66:67] op_sel_hi:[1,0]
	v_pk_mul_f32 v[52:53], v[52:53], v[66:67] op_sel_hi:[1,0]
	v_cvt_pk_bf16_f32 v60, v60, v61
	v_cvt_pk_bf16_f32 v61, v62, v63
	v_cvt_pk_bf16_f32 v56, v56, v57
	v_cvt_pk_bf16_f32 v57, v58, v59
	v_cvt_pk_bf16_f32 v52, v52, v53
	v_cvt_pk_bf16_f32 v53, v54, v55
	s_and_b64 vcc, exec, s[4:5]
	s_nop 1
	v_permlane16_swap_b32_e32 v60, v56
	v_permlane16_swap_b32_e32 v61, v57
	v_permlane16_swap_b32_e32 v52, v48
	v_permlane16_swap_b32_e32 v53, v49
	v_mov_b32_e32 v62, v56
	v_mov_b32_e32 v63, v57
	v_mov_b32_e32 v54, v48
	v_mov_b32_e32 v55, v49
	v_lshl_add_u64 v[246:247], v[64:65], 0, v[244:245]
	global_store_dwordx4 v[246:247], v[60:63], off nt
	global_store_dwordx4 v[246:247], v[52:55], off offset:256 nt
	v_add_u32_e32 v48, 0x90, v144
	v_ashrrev_i32_e32 v49, 31, v48
	s_cbranch_vccnz .LBB0_760
	s_waitcnt vmcnt(14)
	v_mov_b32_e32 v50, v218
	v_mov_b32_e32 v51, v219
	v_mov_b32_e32 v52, v220
	v_mov_b32_e32 v53, v221
	v_mov_b32_e32 v54, v222
	v_mov_b32_e32 v55, v223
	v_mov_b32_e32 v56, v224
	v_mov_b32_e32 v57, v225
	v_mov_b32_e32 v58, v50
	v_mov_b32_e32 v59, v52
	v_mov_b32_e32 v52, v51
	v_mul_f32_e32 v50, v46, v54
	v_mul_f32_e32 v60, v42, v55
	v_mul_f32_e32 v62, v42, v54
	v_mul_f32_e32 v64, v46, v55
	v_mov_b32_e32 v42, v47
	v_mov_b32_e32 v46, v43
	v_mul_f32_e32 v66, v38, v54
	v_mul_f32_e32 v68, v34, v55
	v_mul_f32_e32 v54, v34, v54
	v_mul_f32_e32 v70, v38, v55
	v_mov_b32_e32 v34, v39
	v_mov_b32_e32 v38, v35
	v_pk_mul_f32 v[72:73], v[40:41], v[52:53]
	v_pk_mul_f32 v[40:41], v[40:41], v[58:59]
	v_pk_mul_f32 v[42:43], v[42:43], v[56:57]
	v_pk_mul_f32 v[46:47], v[46:47], v[56:57]
	v_pk_mul_f32 v[74:75], v[32:33], v[52:53]
	v_pk_mul_f32 v[34:35], v[34:35], v[56:57]
	v_pk_mul_f32 v[38:39], v[38:39], v[56:57]
	v_pk_mul_f32 v[32:33], v[32:33], v[58:59]
	v_mov_b32_e32 v51, v42
	v_mov_b32_e32 v61, v43
	v_pk_fma_f32 v[56:57], v[44:45], v[58:59], v[72:73] neg_lo:[0,0,1] neg_hi:[0,0,1]
	v_mov_b32_e32 v65, v47
	v_mov_b32_e32 v63, v46
	v_pk_fma_f32 v[40:41], v[44:45], v[52:53], v[40:41]
	v_mov_b32_e32 v67, v34
	v_mov_b32_e32 v69, v35
	v_pk_fma_f32 v[44:45], v[36:37], v[58:59], v[74:75] neg_lo:[0,0,1] neg_hi:[0,0,1]
	v_mov_b32_e32 v71, v39
	v_mov_b32_e32 v55, v38
	v_pk_fma_f32 v[32:33], v[36:37], v[52:53], v[32:33]
	v_pk_add_f32 v[46:47], v[50:51], v[60:61] neg_lo:[0,1] neg_hi:[0,1]
	v_pk_add_f32 v[42:43], v[64:65], v[62:63]
	v_pk_add_f32 v[38:39], v[66:67], v[68:69] neg_lo:[0,1] neg_hi:[0,1]
	v_pk_add_f32 v[34:35], v[70:71], v[54:55]
	v_mov_b32_e32 v36, v44
	v_mov_b32_e32 v37, v45
	v_mov_b32_e32 v44, v56
	v_mov_b32_e32 v45, v57
;     __device__ __forceinline__ void operator()(f32x4 (&acc)[2][2][4][2], const Unit& u, int wr, int wc, int fr, int fq) const {
;         const int row0 = u.pm * BM + wr * 64 + fr, col0 = u.pn * BM + wc * 32 + 4 * fq;
;         const int sec = u.pn >> 3;
;         const float scale = (sec == 0) ? 0.08838834764831845f : 1.0f;
; #pragma unroll
;         for (int ai = 0; ai < 2; ++ai)
; #pragma unroll
;             for (int m = 0; m < 4; ++m) {
;                 const int row = row0 + ai * HALF + m * 16;
;                 if (sec < 2 && wc == 0) {
;                     const f32x4 t0 = *(const f32x4*)(tab + (size_t)row * 32 + 8 * fq), t1 = *(const f32x4*)(tab + (size_t)row * 32 + 8 * fq + 4);
;                     const float cs[4] = {t0[0], t0[2], t1[0], t1[2]}, sn[4] = {t0[1], t0[3], t1[1], t1[3]};
; #pragma unroll
;                     for (int bj = 0; bj < 2; ++bj)
; #pragma unroll
;                         for (int j = 0; j < 4; ++j) { const float a = acc[ai][bj][m][0][j], b = acc[ai][bj][m][1][j];
;                             acc[ai][bj][m][0][j] = a * cs[j] - b * sn[j]; acc[ai][bj][m][1][j] = b * cs[j] + a * sn[j]; }
;                 }
;                 bf16_t* rowp = O + (size_t)row * INC + col0;
; #pragma unroll
;                 for (int bj = 0; bj < 2; ++bj)
; #pragma unroll
;                     for (int n = 0; n < 2; ++n) { const f32x4 v = acc[ai][bj][m][n] * (scale * rt[u.i * 256 + wr * 64 + fr + ai * HALF + m * 16]); u32x2 w; w.x = pk2(v[0], v[1]); w.y = pk2(v[2], v[3]); *(u32x2*)(rowp + bj * HALF + n * 16) = w; }
;             }
.LBB0_760:
	ds_read_b32 v52, v154 offset:576
	v_mov_b64_e32 v[50:51], s[72:73]
	v_mad_i64_i32 v[48:49], s[18:19], v48, s43, v[50:51]
	v_lshl_add_u64 v[48:49], v[142:143], 1, v[48:49]
	s_waitcnt lgkmcnt(0)
	v_mul_f32_e32 v50, v145, v52
	v_pk_mul_f32 v[34:35], v[34:35], v[50:51] op_sel_hi:[1,0]
	v_pk_mul_f32 v[32:33], v[32:33], v[50:51] op_sel_hi:[1,0]
	v_pk_mul_f32 v[46:47], v[46:47], v[50:51] op_sel_hi:[1,0]
	v_cvt_pk_bf16_f32 v32, v32, v33
	v_cvt_pk_bf16_f32 v33, v34, v35
	v_pk_mul_f32 v[44:45], v[44:45], v[50:51] op_sel_hi:[1,0]
	v_pk_mul_f32 v[42:43], v[42:43], v[50:51] op_sel_hi:[1,0]
	v_pk_mul_f32 v[40:41], v[40:41], v[50:51] op_sel_hi:[1,0]
	v_pk_mul_f32 v[38:39], v[38:39], v[50:51] op_sel_hi:[1,0]
	v_pk_mul_f32 v[36:37], v[36:37], v[50:51] op_sel_hi:[1,0]
	v_cvt_pk_bf16_f32 v44, v44, v45
	v_cvt_pk_bf16_f32 v45, v46, v47
	v_cvt_pk_bf16_f32 v40, v40, v41
	v_cvt_pk_bf16_f32 v41, v42, v43
	v_cvt_pk_bf16_f32 v36, v36, v37
	v_cvt_pk_bf16_f32 v37, v38, v39
	s_and_b64 vcc, exec, s[4:5]
	s_nop 1
	v_permlane16_swap_b32_e32 v44, v40
	v_permlane16_swap_b32_e32 v45, v41
	v_permlane16_swap_b32_e32 v36, v32
	v_permlane16_swap_b32_e32 v37, v33
	v_mov_b32_e32 v46, v40
	v_mov_b32_e32 v47, v41
	v_mov_b32_e32 v38, v32
	v_mov_b32_e32 v39, v33
	v_lshl_add_u64 v[246:247], v[48:49], 0, v[244:245]
	global_store_dwordx4 v[246:247], v[44:47], off nt
	global_store_dwordx4 v[246:247], v[36:39], off offset:256 nt
	v_add_u32_e32 v32, 0xa0, v144
	v_ashrrev_i32_e32 v33, 31, v32
	s_cbranch_vccnz .LBB0_762
	s_waitcnt vmcnt(14)
	v_mov_b32_e32 v34, v226
	v_mov_b32_e32 v35, v227
	v_mov_b32_e32 v36, v228
	v_mov_b32_e32 v37, v229
	v_mov_b32_e32 v38, v230
	v_mov_b32_e32 v39, v231
	v_mov_b32_e32 v40, v232
	v_mov_b32_e32 v41, v233
	v_mov_b32_e32 v42, v34
	v_mov_b32_e32 v43, v36
	v_mov_b32_e32 v36, v35
	v_mul_f32_e32 v34, v30, v38
	v_mul_f32_e32 v44, v26, v39
	v_mul_f32_e32 v46, v26, v38
	v_mul_f32_e32 v48, v30, v39
	v_mov_b32_e32 v26, v31
	v_mov_b32_e32 v30, v27
	v_mul_f32_e32 v50, v22, v38
	v_mul_f32_e32 v52, v18, v39
	v_mul_f32_e32 v38, v18, v38
	v_mul_f32_e32 v54, v22, v39
	v_mov_b32_e32 v18, v23
	v_mov_b32_e32 v22, v19
	v_pk_mul_f32 v[56:57], v[24:25], v[36:37]
	v_pk_mul_f32 v[24:25], v[24:25], v[42:43]
	v_pk_mul_f32 v[26:27], v[26:27], v[40:41]
	v_pk_mul_f32 v[30:31], v[30:31], v[40:41]
	v_pk_mul_f32 v[58:59], v[16:17], v[36:37]
	v_pk_mul_f32 v[18:19], v[18:19], v[40:41]
	v_pk_mul_f32 v[22:23], v[22:23], v[40:41]
	v_pk_mul_f32 v[16:17], v[16:17], v[42:43]
	v_mov_b32_e32 v35, v26
	v_mov_b32_e32 v45, v27
	v_pk_fma_f32 v[40:41], v[28:29], v[42:43], v[56:57] neg_lo:[0,0,1] neg_hi:[0,0,1]
	v_mov_b32_e32 v49, v31
	v_mov_b32_e32 v47, v30
	v_pk_fma_f32 v[24:25], v[28:29], v[36:37], v[24:25]
	v_mov_b32_e32 v51, v18
	v_mov_b32_e32 v53, v19
	v_pk_fma_f32 v[28:29], v[20:21], v[42:43], v[58:59] neg_lo:[0,0,1] neg_hi:[0,0,1]
	v_mov_b32_e32 v55, v23
	v_mov_b32_e32 v39, v22
	v_pk_fma_f32 v[16:17], v[20:21], v[36:37], v[16:17]
	v_pk_add_f32 v[30:31], v[34:35], v[44:45] neg_lo:[0,1] neg_hi:[0,1]
	v_pk_add_f32 v[26:27], v[48:49], v[46:47]
	v_pk_add_f32 v[22:23], v[50:51], v[52:53] neg_lo:[0,1] neg_hi:[0,1]
	v_pk_add_f32 v[18:19], v[54:55], v[38:39]
	v_mov_b32_e32 v20, v28
	v_mov_b32_e32 v21, v29
	v_mov_b32_e32 v28, v40
	v_mov_b32_e32 v29, v41
.LBB0_762:
	ds_read_b32 v36, v154 offset:640
	v_mov_b64_e32 v[34:35], s[72:73]
	v_mad_i64_i32 v[32:33], s[18:19], v32, s43, v[34:35]
	v_lshl_add_u64 v[32:33], v[142:143], 1, v[32:33]
	s_waitcnt lgkmcnt(0)
	v_mul_f32_e32 v34, v145, v36
	v_pk_mul_f32 v[18:19], v[18:19], v[34:35] op_sel_hi:[1,0]
	v_pk_mul_f32 v[16:17], v[16:17], v[34:35] op_sel_hi:[1,0]
	v_pk_mul_f32 v[30:31], v[30:31], v[34:35] op_sel_hi:[1,0]
	v_cvt_pk_bf16_f32 v16, v16, v17
	v_cvt_pk_bf16_f32 v17, v18, v19
	v_pk_mul_f32 v[28:29], v[28:29], v[34:35] op_sel_hi:[1,0]
	v_pk_mul_f32 v[26:27], v[26:27], v[34:35] op_sel_hi:[1,0]
	v_pk_mul_f32 v[24:25], v[24:25], v[34:35] op_sel_hi:[1,0]
	v_pk_mul_f32 v[22:23], v[22:23], v[34:35] op_sel_hi:[1,0]
	v_pk_mul_f32 v[20:21], v[20:21], v[34:35] op_sel_hi:[1,0]
	v_cvt_pk_bf16_f32 v28, v28, v29
	v_cvt_pk_bf16_f32 v29, v30, v31
	v_cvt_pk_bf16_f32 v24, v24, v25
	v_cvt_pk_bf16_f32 v25, v26, v27
	v_cvt_pk_bf16_f32 v20, v20, v21
	v_cvt_pk_bf16_f32 v21, v22, v23
	s_and_b64 vcc, exec, s[4:5]
	s_nop 1
	v_permlane16_swap_b32_e32 v28, v24
	v_permlane16_swap_b32_e32 v29, v25
	v_permlane16_swap_b32_e32 v20, v16
	v_permlane16_swap_b32_e32 v21, v17
	v_mov_b32_e32 v30, v24
	v_mov_b32_e32 v31, v25
	v_mov_b32_e32 v22, v16
	v_mov_b32_e32 v23, v17
	v_lshl_add_u64 v[246:247], v[32:33], 0, v[244:245]
	global_store_dwordx4 v[246:247], v[28:31], off nt
	global_store_dwordx4 v[246:247], v[20:23], off offset:256 nt
	v_add_u32_e32 v16, 0xb0, v144
	v_ashrrev_i32_e32 v17, 31, v16
	s_cbranch_vccnz .LBB0_743
	s_waitcnt vmcnt(14)
	v_mov_b32_e32 v18, v234
	v_mov_b32_e32 v19, v235
	v_mov_b32_e32 v20, v236
	v_mov_b32_e32 v21, v237
	v_mov_b32_e32 v22, v238
	v_mov_b32_e32 v23, v239
	v_mov_b32_e32 v24, v240
	v_mov_b32_e32 v25, v241
	v_mov_b32_e32 v26, v18
	v_mov_b32_e32 v27, v20
	v_mov_b32_e32 v20, v19
	v_mul_f32_e32 v18, v14, v22
	v_mul_f32_e32 v28, v10, v23
	v_mul_f32_e32 v30, v10, v22
	v_mul_f32_e32 v32, v14, v23
	v_mov_b32_e32 v10, v15
	v_mov_b32_e32 v14, v11
	v_mul_f32_e32 v34, v6, v22
	v_mul_f32_e32 v36, v2, v23
	v_mul_f32_e32 v22, v2, v22
	v_mul_f32_e32 v38, v6, v23
	v_mov_b32_e32 v2, v7
	v_mov_b32_e32 v6, v3
	v_pk_mul_f32 v[40:41], v[8:9], v[20:21]
	v_pk_mul_f32 v[8:9], v[8:9], v[26:27]
	v_pk_mul_f32 v[10:11], v[10:11], v[24:25]
	v_pk_mul_f32 v[14:15], v[14:15], v[24:25]
	v_pk_mul_f32 v[42:43], v[0:1], v[20:21]
	v_pk_mul_f32 v[2:3], v[2:3], v[24:25]
	v_pk_mul_f32 v[6:7], v[6:7], v[24:25]
	v_pk_mul_f32 v[0:1], v[0:1], v[26:27]
	v_mov_b32_e32 v19, v10
	v_mov_b32_e32 v29, v11
	v_pk_fma_f32 v[24:25], v[12:13], v[26:27], v[40:41] neg_lo:[0,0,1] neg_hi:[0,0,1]
	v_mov_b32_e32 v33, v15
	v_mov_b32_e32 v31, v14
	v_pk_fma_f32 v[8:9], v[12:13], v[20:21], v[8:9]
	v_mov_b32_e32 v35, v2
	v_mov_b32_e32 v37, v3
	v_pk_fma_f32 v[12:13], v[4:5], v[26:27], v[42:43] neg_lo:[0,0,1] neg_hi:[0,0,1]
	v_mov_b32_e32 v39, v7
	v_mov_b32_e32 v23, v6
	v_pk_fma_f32 v[0:1], v[4:5], v[20:21], v[0:1]
	v_pk_add_f32 v[14:15], v[18:19], v[28:29] neg_lo:[0,1] neg_hi:[0,1]
	v_pk_add_f32 v[10:11], v[32:33], v[30:31]
	v_pk_add_f32 v[6:7], v[34:35], v[36:37] neg_lo:[0,1] neg_hi:[0,1]
	v_pk_add_f32 v[2:3], v[38:39], v[22:23]
	v_mov_b32_e32 v4, v12
	v_mov_b32_e32 v5, v13
	v_mov_b32_e32 v12, v24
	v_mov_b32_e32 v13, v25
	s_branch .LBB0_743

; #define PG8_STAGE(bufoff, gbase, voff) do { _Pragma("unroll") for (int _i = 0; _i < 2; ++_i) \
;         __builtin_amdgcn_global_load_lds((const unsigned*)((const char*)(gbase) + (voff)[_i]), (LAS unsigned*)(lds + (bufoff) + ldsw + _i * 8192), 16, 0, 0); } while (0)
; #define PG8_LDA(dst, b, h) do { _Pragma("unroll") for (int m = 0; m < 4; ++m) _Pragma("unroll") for (int k = 0; k < 2; ++k) dst[m][k] = *(const LAS bf16x8*)(lds + PG8_SA(b, h) + aoff + m * 2048 + k * 1024); } while (0)
; #define PG8_LDB(dst, b, h) do { _Pragma("unroll") for (int n = 0; n < 2; ++n) _Pragma("unroll") for (int k = 0; k < 2; ++k) dst[n][k] = *(const LAS bf16x8*)(lds + PG8_SB(b, h) + boff + n * 2048 + k * 1024); } while (0)
; #define PG8_MMA(ai, bj, At, Bt) do { __builtin_amdgcn_s_setprio(1); _Pragma("unroll") for (int m = 0; m < 4; ++m) _Pragma("unroll") for (int n = 0; n < 2; ++n) _Pragma("unroll") for (int k = 0; k < 2; ++k) \
;         acc[ai][bj][m][n] = __builtin_amdgcn_mfma_f32_16x16x32_bf16(Bt[n][k], At[m][k], acc[ai][bj][m][n], 0, 0, 0); __builtin_amdgcn_s_setprio(0); } while (0)
; #define PG8_WAIT_L(n) asm volatile("s_waitcnt lgkmcnt(" #n ")" ::: "memory")
; #define PG8_BAR __builtin_amdgcn_s_barrier()
; #define PG8_SCHED __builtin_amdgcn_sched_barrier(0)
; template <class Epi>
; __device__ __forceinline__ void gemm_phase(LAS unsigned char* lds, const Gemm g, const Order& S, const Epi& E, const int tid) {
;     ...
;             const char* a1 = cA + (size_t)(t + 1) * kstep;
;             const char* a2 = last ? nA : cA + (size_t)(t + 2) * kstep; const char* b2 = last ? nB : cB + (size_t)(t + 2) * kstep;
;             const char* a3 = a2 + kstep; const char* b3 = b2 + kstep;
;             PG8_LDB(B0, 0, 0); PG8_SCHED; PG8_LDA(At, 0, 0); PG8_STAGE(PG8_SA(1, 1), a1 + hstepA, voffA);
;             PG8_WAIT_L(8); PG8_BAR; PG8_WAIT_L(0); PG8_MMA(0, 0, At, B0); PG8_BAR; PG8_SCHED;
;             PG8_LDB(B1, 0, 1); PG8_STAGE(PG8_SB(0, 0), b2, voffB);
;             PG8_BAR; PG8_WAIT_L(0); PG8_MMA(0, 1, At, B1); PG8_BAR;
;             PG8_LDA(At, 0, 1); PG8_STAGE(PG8_SA(0, 0), a2, voffA);
;             PG8_BAR; PG8_WAIT_L(0); PG8_MMA(1, 0, At, B0); PG8_BAR; PG8_SCHED;
.LBB0_846:
	ds_read_b128 v[128:131], v189
	ds_read_b128 v[132:135], v189 offset:1024
	ds_read_b128 v[136:139], v189 offset:2048
	ds_read_b128 v[140:143], v189 offset:3072
	s_add_u32 s28, s26, 0xfff80080
	s_addc_u32 s29, s27, -1
	s_cmp_eq_u32 s50, 28
	s_cselect_b32 s31, s7, s29
	s_cselect_b32 s30, s15, s28
	s_cselect_b32 s29, s17, s49
	s_cselect_b32 s28, s47, s48
	v_lshl_add_u64 v[184:185], s[26:27], 0, v[160:161]
	s_add_i32 m0, s34, 0xc000
	ds_read_b128 v[144:147], v190
	ds_read_b128 v[148:151], v190 offset:1024
	ds_read_b128 v[168:171], v190 offset:2048
	ds_read_b128 v[172:175], v190 offset:3072
	ds_read_b128 v[176:179], v190 offset:4096
	ds_read_b128 v[180:183], v190 offset:5120
	ds_read_b128 v[194:197], v190 offset:6144
	ds_read_b128 v[198:201], v190 offset:7168
	global_load_lds_dwordx4 v[184:185], off
	v_lshl_add_u64 v[184:185], s[26:27], 0, v[162:163]
	s_add_i32 m0, s34, 0xe000
	s_nop 0
	global_load_lds_dwordx4 v[184:185], off
	s_waitcnt lgkmcnt(8)
	s_barrier
	s_waitcnt lgkmcnt(0)
	s_setprio 1
	s_waitcnt lgkmcnt(0)
	v_mfma_f32_16x16x32_bf16 v[124:127], v[128:131], v[144:147], v[124:127]
	v_mfma_f32_16x16x32_bf16 v[120:123], v[136:139], v[144:147], v[120:123]
	v_mfma_f32_16x16x32_bf16 v[108:111], v[128:131], v[168:171], v[108:111]
	v_mfma_f32_16x16x32_bf16 v[104:107], v[136:139], v[168:171], v[104:107]
	v_mfma_f32_16x16x32_bf16 v[92:95], v[128:131], v[176:179], v[92:95]
	v_mfma_f32_16x16x32_bf16 v[88:91], v[136:139], v[176:179], v[88:91]
	v_mfma_f32_16x16x32_bf16 v[76:79], v[128:131], v[194:197], v[76:79]
	v_mfma_f32_16x16x32_bf16 v[72:75], v[136:139], v[194:197], v[72:75]
	v_mfma_f32_16x16x32_bf16 v[124:127], v[132:135], v[148:151], v[124:127]
	v_mfma_f32_16x16x32_bf16 v[120:123], v[140:143], v[148:151], v[120:123]
	v_mfma_f32_16x16x32_bf16 v[108:111], v[132:135], v[172:175], v[108:111]
	v_mfma_f32_16x16x32_bf16 v[104:107], v[140:143], v[172:175], v[104:107]
	v_mfma_f32_16x16x32_bf16 v[92:95], v[132:135], v[180:183], v[92:95]
	v_mfma_f32_16x16x32_bf16 v[88:91], v[140:143], v[180:183], v[88:91]
	v_mfma_f32_16x16x32_bf16 v[76:79], v[132:135], v[198:201], v[76:79]
	v_mfma_f32_16x16x32_bf16 v[72:75], v[140:143], v[198:201], v[72:75]
	s_setprio 0
	s_barrier
	s_add_i32 s51, s44, s33
	v_lshl_add_u64 v[184:185], s[28:29], 0, v[154:155]
	s_mov_b32 m0, s51
	ds_read_b128 v[202:205], v191
	ds_read_b128 v[206:209], v191 offset:1024
	ds_read_b128 v[210:213], v191 offset:2048
	ds_read_b128 v[214:217], v191 offset:3072
	global_load_lds_dwordx4 v[184:185], off
	v_lshl_add_u64 v[218:219], s[28:29], 0, v[158:159]
	s_add_i32 m0, s51, 0x2000
	s_nop 0
	global_load_lds_dwordx4 v[218:219], off
	s_barrier
	s_waitcnt lgkmcnt(0)
	s_setprio 1
	s_waitcnt lgkmcnt(0)
	v_mfma_f32_16x16x32_bf16 v[116:119], v[202:205], v[144:147], v[116:119]
	v_mfma_f32_16x16x32_bf16 v[112:115], v[210:213], v[144:147], v[112:115]
	v_mfma_f32_16x16x32_bf16 v[100:103], v[202:205], v[168:171], v[100:103]
	v_mfma_f32_16x16x32_bf16 v[96:99], v[210:213], v[168:171], v[96:99]
	v_mfma_f32_16x16x32_bf16 v[84:87], v[202:205], v[176:179], v[84:87]
	v_mfma_f32_16x16x32_bf16 v[80:83], v[210:213], v[176:179], v[80:83]
	v_mfma_f32_16x16x32_bf16 v[68:71], v[202:205], v[194:197], v[68:71]
	v_mfma_f32_16x16x32_bf16 v[64:67], v[210:213], v[194:197], v[64:67]
	v_mfma_f32_16x16x32_bf16 v[116:119], v[206:209], v[148:151], v[116:119]
	v_mfma_f32_16x16x32_bf16 v[112:115], v[214:217], v[148:151], v[112:115]
	v_mfma_f32_16x16x32_bf16 v[100:103], v[206:209], v[172:175], v[100:103]
	v_mfma_f32_16x16x32_bf16 v[96:99], v[214:217], v[172:175], v[96:99]
	v_mfma_f32_16x16x32_bf16 v[84:87], v[206:209], v[180:183], v[84:87]
	v_mfma_f32_16x16x32_bf16 v[80:83], v[214:217], v[180:183], v[80:83]
	v_mfma_f32_16x16x32_bf16 v[68:71], v[206:209], v[198:201], v[68:71]
	v_mfma_f32_16x16x32_bf16 v[64:67], v[214:217], v[198:201], v[64:67]
	s_setprio 0
	s_mov_b32 m0, s34
	v_lshl_add_u64 v[220:221], s[30:31], 0, v[152:153]
	s_barrier
	ds_read_b128 v[144:147], v190 offset:16384
	ds_read_b128 v[148:151], v190 offset:17408
	ds_read_b128 v[168:171], v190 offset:18432
	ds_read_b128 v[172:175], v190 offset:19456
	ds_read_b128 v[176:179], v190 offset:20480
	ds_read_b128 v[180:183], v190 offset:21504
	ds_read_b128 v[194:197], v190 offset:22528
	ds_read_b128 v[198:201], v190 offset:23552
	global_load_lds_dwordx4 v[220:221], off
	v_lshl_add_u64 v[222:223], s[30:31], 0, v[156:157]
	s_mov_b32 m0, s35
	s_nop 0
	global_load_lds_dwordx4 v[222:223], off
	s_barrier
	s_waitcnt lgkmcnt(0)
	s_setprio 1
	s_waitcnt lgkmcnt(0)
	v_mfma_f32_16x16x32_bf16 v[60:63], v[128:131], v[144:147], v[60:63]
	v_mfma_f32_16x16x32_bf16 v[56:59], v[136:139], v[144:147], v[56:59]
	v_mfma_f32_16x16x32_bf16 v[44:47], v[128:131], v[168:171], v[44:47]
	v_mfma_f32_16x16x32_bf16 v[40:43], v[136:139], v[168:171], v[40:43]
	v_mfma_f32_16x16x32_bf16 v[28:31], v[128:131], v[176:179], v[28:31]
	v_mfma_f32_16x16x32_bf16 v[24:27], v[136:139], v[176:179], v[24:27]
	v_mfma_f32_16x16x32_bf16 v[12:15], v[128:131], v[194:197], v[12:15]
	v_mfma_f32_16x16x32_bf16 v[8:11], v[136:139], v[194:197], v[8:11]
	v_mfma_f32_16x16x32_bf16 v[60:63], v[132:135], v[148:151], v[60:63]
	v_mfma_f32_16x16x32_bf16 v[56:59], v[140:143], v[148:151], v[56:59]
	v_mfma_f32_16x16x32_bf16 v[44:47], v[132:135], v[172:175], v[44:47]
	v_mfma_f32_16x16x32_bf16 v[40:43], v[140:143], v[172:175], v[40:43]
	v_mfma_f32_16x16x32_bf16 v[28:31], v[132:135], v[180:183], v[28:31]
	v_mfma_f32_16x16x32_bf16 v[24:27], v[140:143], v[180:183], v[24:27]
	v_mfma_f32_16x16x32_bf16 v[12:15], v[132:135], v[198:201], v[12:15]
	v_mfma_f32_16x16x32_bf16 v[8:11], v[140:143], v[198:201], v[8:11]
	s_setprio 0
	s_barrier
; #define PG8_STAGE(bufoff, gbase, voff) do { _Pragma("unroll") for (int _i = 0; _i < 2; ++_i) \
;         __builtin_amdgcn_global_load_lds((const unsigned*)((const char*)(gbase) + (voff)[_i]), (LAS unsigned*)(lds + (bufoff) + ldsw + _i * 8192), 16, 0, 0); } while (0)
; #define PG8_LDA(dst, b, h) do { _Pragma("unroll") for (int m = 0; m < 4; ++m) _Pragma("unroll") for (int k = 0; k < 2; ++k) dst[m][k] = *(const LAS bf16x8*)(lds + PG8_SA(b, h) + aoff + m * 2048 + k * 1024); } while (0)
; #define PG8_LDB(dst, b, h) do { _Pragma("unroll") for (int n = 0; n < 2; ++n) _Pragma("unroll") for (int k = 0; k < 2; ++k) dst[n][k] = *(const LAS bf16x8*)(lds + PG8_SB(b, h) + boff + n * 2048 + k * 1024); } while (0)
; #define PG8_MMA(ai, bj, At, Bt) do { __builtin_amdgcn_s_setprio(1); _Pragma("unroll") for (int m = 0; m < 4; ++m) _Pragma("unroll") for (int n = 0; n < 2; ++n) _Pragma("unroll") for (int k = 0; k < 2; ++k) \
;         acc[ai][bj][m][n] = __builtin_amdgcn_mfma_f32_16x16x32_bf16(Bt[n][k], At[m][k], acc[ai][bj][m][n], 0, 0, 0); __builtin_amdgcn_s_setprio(0); } while (0)
; #define PG8_WAIT_V(n) asm volatile("s_waitcnt vmcnt(" #n ")" ::: "memory")
; #define PG8_WAIT_L(n) asm volatile("s_waitcnt lgkmcnt(" #n ")" ::: "memory")
; #define PG8_BAR __builtin_amdgcn_s_barrier()
; #define PG8_SCHED __builtin_amdgcn_sched_barrier(0)
; template <class Epi>
; __device__ __forceinline__ void gemm_phase(LAS unsigned char* lds, const Gemm g, const Order& S, const Epi& E, const int tid) {
;     ...
;             PG8_STAGE(PG8_SB(0, 1), b2 + hstepB, voffB);
;             PG8_WAIT_V(6); PG8_BAR; PG8_MMA(1, 1, At, B1); PG8_BAR;
;             PG8_LDB(B0, 1, 0); PG8_SCHED; PG8_LDA(At, 1, 0); PG8_STAGE(PG8_SA(0, 1), a2 + hstepA, voffA);
;             PG8_WAIT_L(8); PG8_BAR; PG8_WAIT_L(0); PG8_MMA(0, 0, At, B0); PG8_BAR; PG8_SCHED;
;             PG8_LDB(B1, 1, 1); PG8_STAGE(PG8_SB(1, 0), b3, voffB);
;             PG8_BAR; PG8_WAIT_L(0); PG8_MMA(0, 1, At, B1); PG8_BAR;
;             PG8_LDA(At, 1, 1); PG8_STAGE(PG8_SA(1, 0), a3, voffA);
;             PG8_BAR; PG8_WAIT_L(0); PG8_MMA(1, 0, At, B0); PG8_BAR; PG8_SCHED;
;             PG8_STAGE(PG8_SB(1, 1), b3 + hstepB, voffB);
	s_add_u32 s52, s28, 0x80000
	s_addc_u32 s53, s29, 0
	s_add_i32 s51, s45, s33
	v_lshl_add_u64 v[128:129], s[52:53], 0, v[154:155]
	s_mov_b32 m0, s51
	s_nop 0
	global_load_lds_dwordx4 v[128:129], off
	v_lshl_add_u64 v[128:129], s[52:53], 0, v[158:159]
	s_add_i32 m0, s51, 0x2000
	s_nop 0
	global_load_lds_dwordx4 v[128:129], off
	s_waitcnt vmcnt(6)
	s_barrier
	s_setprio 1
	v_mfma_f32_16x16x32_bf16 v[52:55], v[202:205], v[144:147], v[52:55]
	v_mfma_f32_16x16x32_bf16 v[48:51], v[210:213], v[144:147], v[48:51]
	v_mfma_f32_16x16x32_bf16 v[36:39], v[202:205], v[168:171], v[36:39]
	v_mfma_f32_16x16x32_bf16 v[32:35], v[210:213], v[168:171], v[32:35]
	v_mfma_f32_16x16x32_bf16 v[20:23], v[202:205], v[176:179], v[20:23]
	v_mfma_f32_16x16x32_bf16 v[16:19], v[210:213], v[176:179], v[16:19]
	v_mfma_f32_16x16x32_bf16 v[4:7], v[202:205], v[194:197], v[4:7]
	v_mfma_f32_16x16x32_bf16 v[0:3], v[210:213], v[194:197], v[0:3]
	v_mfma_f32_16x16x32_bf16 v[52:55], v[206:209], v[148:151], v[52:55]
	v_mfma_f32_16x16x32_bf16 v[48:51], v[214:217], v[148:151], v[48:51]
	v_mfma_f32_16x16x32_bf16 v[36:39], v[206:209], v[172:175], v[36:39]
	v_mfma_f32_16x16x32_bf16 v[32:35], v[214:217], v[172:175], v[32:35]
	v_mfma_f32_16x16x32_bf16 v[20:23], v[206:209], v[180:183], v[20:23]
	v_mfma_f32_16x16x32_bf16 v[16:19], v[214:217], v[180:183], v[16:19]
	v_mfma_f32_16x16x32_bf16 v[4:7], v[206:209], v[198:201], v[4:7]
	v_mfma_f32_16x16x32_bf16 v[0:3], v[214:217], v[198:201], v[0:3]
	s_setprio 0
	s_add_i32 s51, 0, 0x18000
	v_add_u32_e32 v140, s51, v187
	s_barrier
	ds_read_b128 v[128:131], v140
	ds_read_b128 v[132:135], v140 offset:1024
	ds_read_b128 v[136:139], v140 offset:2048
	ds_read_b128 v[140:143], v140 offset:3072
	s_add_u32 s30, s30, 0x80000
	s_addc_u32 s31, s31, 0
	s_mov_b32 m0, s38
	v_lshl_add_u64 v[202:203], s[30:31], 0, v[152:153]
	ds_read_b128 v[144:147], v190 offset:32768
	ds_read_b128 v[148:151], v190 offset:33792
	ds_read_b128 v[168:171], v190 offset:34816
	ds_read_b128 v[172:175], v190 offset:35840
	ds_read_b128 v[176:179], v190 offset:36864
	ds_read_b128 v[180:183], v190 offset:37888
	ds_read_b128 v[194:197], v190 offset:38912
	ds_read_b128 v[198:201], v190 offset:39936
	global_load_lds_dwordx4 v[202:203], off
	v_lshl_add_u64 v[202:203], s[30:31], 0, v[156:157]
	s_mov_b32 m0, s39
	s_nop 0
	global_load_lds_dwordx4 v[202:203], off
	s_waitcnt lgkmcnt(8)
	s_barrier
	s_waitcnt lgkmcnt(0)
	s_setprio 1
	s_waitcnt lgkmcnt(0)
	v_mfma_f32_16x16x32_bf16 v[124:127], v[128:131], v[144:147], v[124:127]
	v_mfma_f32_16x16x32_bf16 v[120:123], v[136:139], v[144:147], v[120:123]
	v_mfma_f32_16x16x32_bf16 v[108:111], v[128:131], v[168:171], v[108:111]
	v_mfma_f32_16x16x32_bf16 v[104:107], v[136:139], v[168:171], v[104:107]
	v_mfma_f32_16x16x32_bf16 v[92:95], v[128:131], v[176:179], v[92:95]
	v_mfma_f32_16x16x32_bf16 v[88:91], v[136:139], v[176:179], v[88:91]
	v_mfma_f32_16x16x32_bf16 v[76:79], v[128:131], v[194:197], v[76:79]
	v_mfma_f32_16x16x32_bf16 v[72:75], v[136:139], v[194:197], v[72:75]
	v_mfma_f32_16x16x32_bf16 v[124:127], v[132:135], v[148:151], v[124:127]
	v_mfma_f32_16x16x32_bf16 v[120:123], v[140:143], v[148:151], v[120:123]
	v_mfma_f32_16x16x32_bf16 v[108:111], v[132:135], v[172:175], v[108:111]
	v_mfma_f32_16x16x32_bf16 v[104:107], v[140:143], v[172:175], v[104:107]
	v_mfma_f32_16x16x32_bf16 v[92:95], v[132:135], v[180:183], v[92:95]
	v_mfma_f32_16x16x32_bf16 v[88:91], v[140:143], v[180:183], v[88:91]
	v_mfma_f32_16x16x32_bf16 v[76:79], v[132:135], v[198:201], v[76:79]
	v_mfma_f32_16x16x32_bf16 v[72:75], v[140:143], v[198:201], v[72:75]
	s_setprio 0
	s_barrier
	s_add_i32 s30, 0, 0x1c000
	s_add_i32 s31, s51, s33
	v_add_u32_e32 v193, s30, v187
	v_lshl_add_u64 v[184:185], v[184:185], 0, s[12:13]
	s_mov_b32 m0, s31
	ds_read_b128 v[202:205], v193
	ds_read_b128 v[206:209], v193 offset:1024
	ds_read_b128 v[210:213], v193 offset:2048
	ds_read_b128 v[214:217], v193 offset:3072
	global_load_lds_dwordx4 v[184:185], off
	v_lshl_add_u64 v[184:185], v[218:219], 0, s[12:13]
	s_add_i32 m0, s31, 0x2000
	s_nop 0
	global_load_lds_dwordx4 v[184:185], off
	s_barrier
	s_waitcnt lgkmcnt(0)
	s_setprio 1
	s_waitcnt lgkmcnt(0)
	v_mfma_f32_16x16x32_bf16 v[116:119], v[202:205], v[144:147], v[116:119]
	v_mfma_f32_16x16x32_bf16 v[112:115], v[210:213], v[144:147], v[112:115]
	v_mfma_f32_16x16x32_bf16 v[100:103], v[202:205], v[168:171], v[100:103]
	v_mfma_f32_16x16x32_bf16 v[96:99], v[210:213], v[168:171], v[96:99]
	v_mfma_f32_16x16x32_bf16 v[84:87], v[202:205], v[176:179], v[84:87]
	v_mfma_f32_16x16x32_bf16 v[80:83], v[210:213], v[176:179], v[80:83]
	v_mfma_f32_16x16x32_bf16 v[68:71], v[202:205], v[194:197], v[68:71]
	v_mfma_f32_16x16x32_bf16 v[64:67], v[210:213], v[194:197], v[64:67]
	v_mfma_f32_16x16x32_bf16 v[116:119], v[206:209], v[148:151], v[116:119]
	v_mfma_f32_16x16x32_bf16 v[112:115], v[214:217], v[148:151], v[112:115]
	v_mfma_f32_16x16x32_bf16 v[100:103], v[206:209], v[172:175], v[100:103]
	v_mfma_f32_16x16x32_bf16 v[96:99], v[214:217], v[172:175], v[96:99]
	v_mfma_f32_16x16x32_bf16 v[84:87], v[206:209], v[180:183], v[84:87]
	v_mfma_f32_16x16x32_bf16 v[80:83], v[214:217], v[180:183], v[80:83]
	v_mfma_f32_16x16x32_bf16 v[68:71], v[206:209], v[198:201], v[68:71]
	v_mfma_f32_16x16x32_bf16 v[64:67], v[214:217], v[198:201], v[64:67]
	s_setprio 0
	s_mov_b32 m0, s42
	v_lshl_add_u64 v[184:185], v[220:221], 0, s[12:13]
	s_barrier
	ds_read_b128 v[144:147], v190 offset:49152
	ds_read_b128 v[148:151], v190 offset:50176
	ds_read_b128 v[168:171], v190 offset:51200
	ds_read_b128 v[172:175], v190 offset:52224
	ds_read_b128 v[176:179], v190 offset:53248
	ds_read_b128 v[180:183], v190 offset:54272
	ds_read_b128 v[194:197], v190 offset:55296
	ds_read_b128 v[198:201], v190 offset:56320
	global_load_lds_dwordx4 v[184:185], off
	v_lshl_add_u64 v[184:185], v[222:223], 0, s[12:13]
	s_mov_b32 m0, s43
	s_nop 0
	global_load_lds_dwordx4 v[184:185], off
	s_barrier
; #define PG8_STAGE(bufoff, gbase, voff) do { _Pragma("unroll") for (int _i = 0; _i < 2; ++_i) \
;         __builtin_amdgcn_global_load_lds((const unsigned*)((const char*)(gbase) + (voff)[_i]), (LAS unsigned*)(lds + (bufoff) + ldsw + _i * 8192), 16, 0, 0); } while (0)
; #define PG8_MMA(ai, bj, At, Bt) do { __builtin_amdgcn_s_setprio(1); _Pragma("unroll") for (int m = 0; m < 4; ++m) _Pragma("unroll") for (int n = 0; n < 2; ++n) _Pragma("unroll") for (int k = 0; k < 2; ++k) \
;         acc[ai][bj][m][n] = __builtin_amdgcn_mfma_f32_16x16x32_bf16(Bt[n][k], At[m][k], acc[ai][bj][m][n], 0, 0, 0); __builtin_amdgcn_s_setprio(0); } while (0)
; #define PG8_WAIT_V(n) asm volatile("s_waitcnt vmcnt(" #n ")" ::: "memory")
; #define PG8_WAIT_L(n) asm volatile("s_waitcnt lgkmcnt(" #n ")" ::: "memory")
; #define PG8_BAR __builtin_amdgcn_s_barrier()
; #define PG8_SCHED __builtin_amdgcn_sched_barrier(0)
; template <class Epi>
; __device__ __forceinline__ void gemm_phase(LAS unsigned char* lds, const Gemm g, const Order& S, const Epi& E, const int tid) {
;     ...
;             PG8_BAR; PG8_WAIT_L(0); PG8_MMA(1, 0, At, B0); PG8_BAR; PG8_SCHED;
;             PG8_STAGE(PG8_SB(1, 1), b3 + hstepB, voffB);
;             PG8_WAIT_V(6); PG8_BAR; PG8_MMA(1, 1, At, B1); PG8_BAR;
;         }
	s_waitcnt lgkmcnt(0)
	s_setprio 1
	s_waitcnt lgkmcnt(0)
	v_mfma_f32_16x16x32_bf16 v[60:63], v[128:131], v[144:147], v[60:63]
	v_mfma_f32_16x16x32_bf16 v[56:59], v[136:139], v[144:147], v[56:59]
	v_mfma_f32_16x16x32_bf16 v[44:47], v[128:131], v[168:171], v[44:47]
	v_mfma_f32_16x16x32_bf16 v[40:43], v[136:139], v[168:171], v[40:43]
	v_mfma_f32_16x16x32_bf16 v[28:31], v[128:131], v[176:179], v[28:31]
	v_mfma_f32_16x16x32_bf16 v[24:27], v[136:139], v[176:179], v[24:27]
	v_mfma_f32_16x16x32_bf16 v[12:15], v[128:131], v[194:197], v[12:15]
	v_mfma_f32_16x16x32_bf16 v[8:11], v[136:139], v[194:197], v[8:11]
	v_mfma_f32_16x16x32_bf16 v[60:63], v[132:135], v[148:151], v[60:63]
	v_mfma_f32_16x16x32_bf16 v[56:59], v[140:143], v[148:151], v[56:59]
	v_mfma_f32_16x16x32_bf16 v[44:47], v[132:135], v[172:175], v[44:47]
	v_mfma_f32_16x16x32_bf16 v[40:43], v[140:143], v[172:175], v[40:43]
	v_mfma_f32_16x16x32_bf16 v[28:31], v[132:135], v[180:183], v[28:31]
	v_mfma_f32_16x16x32_bf16 v[24:27], v[140:143], v[180:183], v[24:27]
	v_mfma_f32_16x16x32_bf16 v[12:15], v[132:135], v[198:201], v[12:15]
	v_mfma_f32_16x16x32_bf16 v[8:11], v[140:143], v[198:201], v[8:11]
	s_setprio 0
	s_barrier
	s_add_u32 s28, s28, 0x80080
	s_addc_u32 s29, s29, 0
	s_add_i32 s30, s30, s33
	v_lshl_add_u64 v[128:129], s[28:29], 0, v[154:155]
	s_mov_b32 m0, s30
	s_nop 0
	global_load_lds_dwordx4 v[128:129], off
	v_lshl_add_u64 v[128:129], s[28:29], 0, v[158:159]
	s_add_i32 m0, s30, 0x2000
	s_nop 0
	global_load_lds_dwordx4 v[128:129], off
	s_waitcnt vmcnt(6)
	s_barrier
	s_setprio 1
	v_mfma_f32_16x16x32_bf16 v[52:55], v[202:205], v[144:147], v[52:55]
	v_mfma_f32_16x16x32_bf16 v[48:51], v[210:213], v[144:147], v[48:51]
	v_mfma_f32_16x16x32_bf16 v[36:39], v[202:205], v[168:171], v[36:39]
	v_mfma_f32_16x16x32_bf16 v[32:35], v[210:213], v[168:171], v[32:35]
	v_mfma_f32_16x16x32_bf16 v[20:23], v[202:205], v[176:179], v[20:23]
	v_mfma_f32_16x16x32_bf16 v[16:19], v[210:213], v[176:179], v[16:19]
	v_mfma_f32_16x16x32_bf16 v[4:7], v[202:205], v[194:197], v[4:7]
	v_mfma_f32_16x16x32_bf16 v[0:3], v[210:213], v[194:197], v[0:3]
	v_mfma_f32_16x16x32_bf16 v[52:55], v[206:209], v[148:151], v[52:55]
	v_mfma_f32_16x16x32_bf16 v[48:51], v[214:217], v[148:151], v[48:51]
	v_mfma_f32_16x16x32_bf16 v[36:39], v[206:209], v[172:175], v[36:39]
	v_mfma_f32_16x16x32_bf16 v[32:35], v[214:217], v[172:175], v[32:35]
	v_mfma_f32_16x16x32_bf16 v[20:23], v[206:209], v[180:183], v[20:23]
	v_mfma_f32_16x16x32_bf16 v[16:19], v[214:217], v[180:183], v[16:19]
	v_mfma_f32_16x16x32_bf16 v[4:7], v[206:209], v[198:201], v[4:7]
	v_mfma_f32_16x16x32_bf16 v[0:3], v[214:217], v[198:201], v[0:3]
	s_setprio 0
	s_add_i32 s50, s50, 2
	s_add_u32 s26, s26, 0x100
	s_addc_u32 s27, s27, 0
	s_add_u32 s48, s48, 0x100
	s_addc_u32 s49, s49, 0
	s_cmp_gt_u32 s50, 29
	s_barrier
	s_cbranch_scc0 .LBB0_846
; __device__ __forceinline__ float bflo(unsigned w) { return __uint_as_float(w << 16); }
; __device__ __forceinline__ float bfhi(unsigned w) { return __uint_as_float(w & 0xffff0000u); }
;     __device__ __forceinline__ void operator()(const f32x4 (&acc)[2][2][4][2], const Unit& u, int wr, int wc, int fr, int fq) const {
;     ...
;                 u32x4 bs[4][2];
; #pragma unroll
;                 for (int m = 0; m < 4; ++m) { const size_t off = (size_t)(row0 + ai * HALF + m * 16) * DM + col0;
; #pragma unroll
;                     for (int bj = 0; bj < 2; ++bj) bs[m][bj] = *(const u32x4*)(baseb + off + bj * HALF); }
; #pragma unroll
;                 for (int m = 0; m < 4; ++m) { const size_t off = (size_t)(row0 + ai * HALF + m * 16) * DM + col0;
;                     float ss = 0.f;
; #pragma unroll
;                     for (int bj = 0; bj < 2; ++bj) { const u32x4 q = bs[m][bj]; const f32x4 a0 = acc[ai][bj][m][0], a1 = acc[ai][bj][m][1];
;                         const float h0 = bflo(q.x) + a0[0], h1 = bfhi(q.x) + a0[1], h2 = bflo(q.y) + a0[2], h3 = bfhi(q.y) + a0[3], h4 = bflo(q.z) + a1[0], h5 = bfhi(q.z) + a1[1], h6 = bflo(q.w) + a1[2], h7 = bfhi(q.w) + a1[3];
;                         ss += (h0 * h0 + h1 * h1) + (h2 * h2 + h3 * h3) + (h4 * h4 + h5 * h5) + (h6 * h6 + h7 * h7);
;                         u32x4 w; w.x = pk2(h0, h1); w.y = pk2(h2, h3); w.z = pk2(h4, h5); w.w = pk2(h6, h7);
;                         *(u32x4*)(out + off + bj * HALF) = w; }
;                     if (ssqp) { ss += __shfl_xor(ss, 16); ss += __shfl_xor(ss, 32); if (fq == 0) ssqp[(size_t)(row0 + ai * HALF + m * 16) * 32 + u.pn * 4 + wc] = ss; } }
	v_lshl_or_b32 v168, s6, 8, v188
	v_lshl_add_u32 v172, s8, 8, v186
	v_ashrrev_i32_e32 v169, 31, v168
	v_lshlrev_b64 v[202:203], 1, v[168:169]
	v_ashrrev_i32_e32 v173, 31, v172
	v_or_b32_e32 v182, 16, v172
	v_or_b32_e32 v178, 32, v172
	v_lshl_add_u64 v[170:171], s[22:23], 0, v[202:203]
	v_lshlrev_b64 v[204:205], 12, v[172:173]
	v_or_b32_e32 v174, 48, v172
	v_ashrrev_i32_e32 v183, 31, v182
	v_ashrrev_i32_e32 v179, 31, v178
	v_lshl_add_u64 v[128:129], v[170:171], 0, v[204:205]
	v_ashrrev_i32_e32 v175, 31, v174
	v_lshlrev_b64 v[184:185], 12, v[182:183]
	v_lshlrev_b64 v[180:181], 12, v[178:179]
	global_load_dwordx4 v[194:197], v[128:129], off
	global_load_dwordx4 v[198:201], v[128:129], off offset:256
	v_lshlrev_b64 v[176:177], 12, v[174:175]
	v_lshl_add_u64 v[128:129], v[170:171], 0, v[184:185]
	v_lshl_add_u64 v[130:131], v[170:171], 0, v[180:181]
	v_lshl_add_u64 v[206:207], v[170:171], 0, v[176:177]
	global_load_dwordx4 v[148:151], v[128:129], off
	global_load_dwordx4 v[144:147], v[128:129], off offset:256
	global_load_dwordx4 v[140:143], v[130:131], off
	global_load_dwordx4 v[136:139], v[130:131], off offset:256
	global_load_dwordx4 v[132:135], v[206:207], off
	s_nop 0
	global_load_dwordx4 v[128:131], v[206:207], off offset:256
	v_cndmask_b32_e64 v193, 0, 1, s[10:11]
	v_lshl_add_u64 v[204:205], s[22:23], 0, v[204:205]
	s_lshl_b32 s26, s6, 2
	v_cmp_ne_u32_e64 s[6:7], 1, v193
	v_lshl_add_u64 v[204:205], v[204:205], 0, v[202:203]
	s_ashr_i32 s27, s26, 31
	s_andn2_b64 vcc, exec, s[10:11]
	s_waitcnt vmcnt(0)
	v_lshlrev_b32_e32 v193, 16, v194
	v_and_b32_e32 v194, 0xffff0000, v194
	v_lshlrev_b32_e32 v202, 16, v195
	v_and_b32_e32 v195, 0xffff0000, v195
	v_lshlrev_b32_e32 v203, 16, v196
	v_and_b32_e32 v196, 0xffff0000, v196
	v_lshlrev_b32_e32 v206, 16, v197
	v_and_b32_e32 v197, 0xffff0000, v197
	v_lshlrev_b32_e32 v207, 16, v198
	v_and_b32_e32 v198, 0xffff0000, v198
	v_lshlrev_b32_e32 v208, 16, v199
	v_and_b32_e32 v199, 0xffff0000, v199
	v_lshlrev_b32_e32 v209, 16, v200
	v_and_b32_e32 v200, 0xffff0000, v200
	v_lshlrev_b32_e32 v210, 16, v201
	v_and_b32_e32 v201, 0xffff0000, v201
	v_add_f32_e32 v193, v124, v193
	v_add_f32_e32 v194, v125, v194
	v_add_f32_e32 v124, v126, v202
	v_add_f32_e32 v125, v127, v195
	v_add_f32_e32 v126, v120, v203
	v_add_f32_e32 v127, v121, v196
	v_add_f32_e32 v122, v122, v206
	v_add_f32_e32 v123, v123, v197
	v_add_f32_e32 v120, v116, v207
	v_add_f32_e32 v121, v117, v198
	v_add_f32_e32 v116, v118, v208
	v_add_f32_e32 v117, v119, v199
	v_add_f32_e32 v112, v112, v209
	v_add_f32_e32 v113, v113, v200
	v_add_f32_e32 v114, v114, v210
	v_add_f32_e32 v115, v115, v201
	v_cvt_pk_bf16_f32 v196, v193, v194
	v_cvt_pk_bf16_f32 v197, v124, v125
	v_cvt_pk_bf16_f32 v198, v126, v127
	v_cvt_pk_bf16_f32 v199, v122, v123
	v_cvt_pk_bf16_f32 v200, v120, v121
	v_cvt_pk_bf16_f32 v201, v116, v117
	v_cvt_pk_bf16_f32 v202, v112, v113
	v_cvt_pk_bf16_f32 v203, v114, v115
	global_store_dwordx4 v[204:205], v[196:199], off nt
	global_store_dwordx4 v[204:205], v[200:203], off offset:256 nt
	s_cbranch_vccnz .LBB0_851
	v_mul_f32_e32 v115, v115, v115
	v_mul_f32_e32 v113, v113, v113
	v_mul_f32_e32 v118, v123, v123
	v_fmac_f32_e32 v115, v114, v114
	v_fmac_f32_e32 v113, v112, v112
	v_mul_f32_e32 v112, v121, v121
	v_mul_f32_e32 v114, v117, v117
	v_fmac_f32_e32 v118, v122, v122
	v_mul_f32_e32 v122, v194, v194
	v_mul_f32_e32 v123, v125, v125
	v_fmac_f32_e32 v112, v120, v120
	v_fmac_f32_e32 v114, v116, v116
	v_mul_f32_e32 v119, v127, v127
	v_fmac_f32_e32 v122, v193, v193
	v_fmac_f32_e32 v123, v124, v124
	v_add_f32_e32 v112, v112, v114
	v_and_b32_e32 v114, 64, v192
	v_fmac_f32_e32 v119, v126, v126
	v_add_f32_e32 v122, v122, v123
	v_add_f32_e32 v112, v113, v112
	v_xor_b32_e32 v113, 16, v192
	v_add_u32_e32 v114, 64, v114
	v_add_f32_e32 v119, v119, v122
	v_cmp_lt_i32_e32 vcc, v113, v114
	v_add_f32_e32 v118, v118, v119
	v_add_f32_e32 v112, v115, v112
	v_cndmask_b32_e32 v113, v192, v113, vcc
	v_add_f32_e32 v112, v118, v112
	v_lshlrev_b32_e32 v113, 2, v113
	ds_bpermute_b32 v113, v113, v112
	s_waitcnt lgkmcnt(0)
	v_add_f32_e32 v112, v112, v113
	v_xor_b32_e32 v113, 32, v192
	v_cmp_lt_i32_e32 vcc, v113, v114
	s_nop 1
	v_cndmask_b32_e32 v113, v192, v113, vcc
	v_lshlrev_b32_e32 v113, 2, v113
	ds_bpermute_b32 v113, v113, v112
	s_and_saveexec_b64 s[28:29], s[0:1]
	s_cbranch_execz .LBB0_850
	v_lshlrev_b64 v[114:115], 7, v[172:173]
	v_lshl_add_u64 v[114:115], s[24:25], 0, v[114:115]
	v_lshl_add_u64 v[114:115], s[26:27], 2, v[114:115]
	s_lshl_b32 s8, s40, 2
	v_lshl_add_u64 v[114:115], v[114:115], 0, s[8:9]
	s_waitcnt lgkmcnt(0)
	v_add_f32_e32 v112, v112, v113
	global_store_dword v[114:115], v112, off

; __device__ __forceinline__ float bflo(unsigned w) { return __uint_as_float(w << 16); }
; __device__ __forceinline__ float bfhi(unsigned w) { return __uint_as_float(w & 0xffff0000u); }
;     __device__ __forceinline__ void operator()(const f32x4 (&acc)[2][2][4][2], const Unit& u, int wr, int wc, int fr, int fq) const {
;     ...
;                 for (int m = 0; m < 4; ++m) { const size_t off = (size_t)(row0 + ai * HALF + m * 16) * DM + col0;
;                     float ss = 0.f;
; #pragma unroll
;                     for (int bj = 0; bj < 2; ++bj) { const u32x4 q = bs[m][bj]; const f32x4 a0 = acc[ai][bj][m][0], a1 = acc[ai][bj][m][1];
;                         const float h0 = bflo(q.x) + a0[0], h1 = bfhi(q.x) + a0[1], h2 = bflo(q.y) + a0[2], h3 = bfhi(q.y) + a0[3], h4 = bflo(q.z) + a1[0], h5 = bfhi(q.z) + a1[1], h6 = bflo(q.w) + a1[2], h7 = bfhi(q.w) + a1[3];
;                         ss += (h0 * h0 + h1 * h1) + (h2 * h2 + h3 * h3) + (h4 * h4 + h5 * h5) + (h6 * h6 + h7 * h7);
;                         u32x4 w; w.x = pk2(h0, h1); w.y = pk2(h2, h3); w.z = pk2(h4, h5); w.w = pk2(h6, h7);
;                         *(u32x4*)(out + off + bj * HALF) = w; }
;                     if (ssqp) { ss += __shfl_xor(ss, 16); ss += __shfl_xor(ss, 32); if (fq == 0) ssqp[(size_t)(row0 + ai * HALF + m * 16) * 32 + u.pn * 4 + wc] = ss; } }
.LBB0_851:
	v_lshlrev_b32_e32 v112, 16, v148
	v_add_f32_e32 v108, v108, v112
	v_and_b32_e32 v112, 0xffff0000, v148
	v_add_f32_e32 v112, v109, v112
	v_lshlrev_b32_e32 v109, 16, v149
	v_add_f32_e32 v109, v110, v109
	v_and_b32_e32 v110, 0xffff0000, v149
	v_add_f32_e32 v110, v111, v110
	v_lshlrev_b32_e32 v111, 16, v150
	v_add_f32_e32 v104, v104, v111
	v_and_b32_e32 v111, 0xffff0000, v150
	v_add_f32_e32 v105, v105, v111
	v_lshlrev_b32_e32 v111, 16, v151
	v_add_f32_e32 v111, v106, v111
	v_and_b32_e32 v106, 0xffff0000, v151
	v_add_f32_e32 v107, v107, v106
	v_lshlrev_b32_e32 v106, 16, v144
	v_add_f32_e32 v100, v100, v106
	v_and_b32_e32 v106, 0xffff0000, v144
	v_add_f32_e32 v106, v101, v106
	v_lshlrev_b32_e32 v101, 16, v145
	v_add_f32_e32 v101, v102, v101
	v_and_b32_e32 v102, 0xffff0000, v145
	v_add_f32_e32 v102, v103, v102
	v_lshlrev_b32_e32 v103, 16, v146
	v_add_f32_e32 v96, v96, v103
	v_and_b32_e32 v103, 0xffff0000, v146
	v_add_f32_e32 v97, v97, v103
	v_lshlrev_b32_e32 v103, 16, v147
	v_lshl_add_u64 v[118:119], s[22:23], 0, v[184:185]
	v_add_f32_e32 v98, v98, v103
	v_and_b32_e32 v103, 0xffff0000, v147
	v_cvt_pk_bf16_f32 v114, v108, v112
	v_cvt_pk_bf16_f32 v115, v109, v110
	v_cvt_pk_bf16_f32 v116, v104, v105
	v_cvt_pk_bf16_f32 v117, v111, v107
	v_lshl_add_u64 v[118:119], v[168:169], 1, v[118:119]
	v_add_f32_e32 v99, v99, v103
	global_store_dwordx4 v[118:119], v[114:117], off nt
	s_and_b64 vcc, exec, s[6:7]
	s_nop 0
	v_cvt_pk_bf16_f32 v114, v100, v106
	v_cvt_pk_bf16_f32 v115, v101, v102
	v_cvt_pk_bf16_f32 v116, v96, v97
	v_cvt_pk_bf16_f32 v117, v98, v99
	global_store_dwordx4 v[118:119], v[114:117], off offset:256 nt
	s_cbranch_vccnz .LBB0_855
	v_mul_f32_e32 v99, v99, v99
	v_mul_f32_e32 v97, v97, v97
	v_mul_f32_e32 v105, v105, v105
	v_fmac_f32_e32 v99, v98, v98
	v_fmac_f32_e32 v97, v96, v96
	v_mul_f32_e32 v96, v106, v106
	v_mul_f32_e32 v98, v102, v102
	v_mul_f32_e32 v103, v107, v107
	v_fmac_f32_e32 v105, v104, v104
	v_mul_f32_e32 v104, v112, v112
	v_mul_f32_e32 v107, v110, v110
	v_fmac_f32_e32 v96, v100, v100
	v_fmac_f32_e32 v98, v101, v101
	v_fmac_f32_e32 v104, v108, v108
	v_fmac_f32_e32 v107, v109, v109
	v_add_f32_e32 v96, v96, v98
	v_and_b32_e32 v98, 64, v192
	v_add_f32_e32 v104, v104, v107
	v_add_f32_e32 v96, v97, v96
	v_xor_b32_e32 v97, 16, v192
	v_add_u32_e32 v98, 64, v98
	v_fmac_f32_e32 v103, v111, v111
	v_add_f32_e32 v104, v105, v104
	v_cmp_lt_i32_e32 vcc, v97, v98
	v_add_f32_e32 v103, v103, v104
	v_add_f32_e32 v96, v99, v96
	v_cndmask_b32_e32 v97, v192, v97, vcc
	v_add_f32_e32 v96, v103, v96
	v_lshlrev_b32_e32 v97, 2, v97
	ds_bpermute_b32 v97, v97, v96
	s_waitcnt lgkmcnt(0)
	v_add_f32_e32 v96, v96, v97
	v_xor_b32_e32 v97, 32, v192
	v_cmp_lt_i32_e32 vcc, v97, v98
	s_nop 1
	v_cndmask_b32_e32 v97, v192, v97, vcc
	v_lshlrev_b32_e32 v97, 2, v97
	ds_bpermute_b32 v97, v97, v96
	s_and_saveexec_b64 s[28:29], s[0:1]
	s_cbranch_execz .LBB0_854
	v_lshlrev_b64 v[98:99], 7, v[182:183]
	v_lshl_add_u64 v[98:99], s[24:25], 0, v[98:99]
	v_lshl_add_u64 v[98:99], s[26:27], 2, v[98:99]
	s_lshl_b32 s8, s40, 2
	v_lshl_add_u64 v[98:99], v[98:99], 0, s[8:9]
	s_waitcnt lgkmcnt(0)
	v_add_f32_e32 v96, v96, v97
	global_store_dword v[98:99], v96, off

; __device__ __forceinline__ float bflo(unsigned w) { return __uint_as_float(w << 16); }
; __device__ __forceinline__ float bfhi(unsigned w) { return __uint_as_float(w & 0xffff0000u); }
;     __device__ __forceinline__ void operator()(const f32x4 (&acc)[2][2][4][2], const Unit& u, int wr, int wc, int fr, int fq) const {
;     ...
;                 for (int m = 0; m < 4; ++m) { const size_t off = (size_t)(row0 + ai * HALF + m * 16) * DM + col0;
;                     float ss = 0.f;
; #pragma unroll
;                     for (int bj = 0; bj < 2; ++bj) { const u32x4 q = bs[m][bj]; const f32x4 a0 = acc[ai][bj][m][0], a1 = acc[ai][bj][m][1];
;                         const float h0 = bflo(q.x) + a0[0], h1 = bfhi(q.x) + a0[1], h2 = bflo(q.y) + a0[2], h3 = bfhi(q.y) + a0[3], h4 = bflo(q.z) + a1[0], h5 = bfhi(q.z) + a1[1], h6 = bflo(q.w) + a1[2], h7 = bfhi(q.w) + a1[3];
;                         ss += (h0 * h0 + h1 * h1) + (h2 * h2 + h3 * h3) + (h4 * h4 + h5 * h5) + (h6 * h6 + h7 * h7);
;                         u32x4 w; w.x = pk2(h0, h1); w.y = pk2(h2, h3); w.z = pk2(h4, h5); w.w = pk2(h6, h7);
;                         *(u32x4*)(out + off + bj * HALF) = w; }
;                     if (ssqp) { ss += __shfl_xor(ss, 16); ss += __shfl_xor(ss, 32); if (fq == 0) ssqp[(size_t)(row0 + ai * HALF + m * 16) * 32 + u.pn * 4 + wc] = ss; } }
.LBB0_855:
	v_lshlrev_b32_e32 v96, 16, v140
	v_add_f32_e32 v92, v92, v96
	v_and_b32_e32 v96, 0xffff0000, v140
	v_add_f32_e32 v96, v93, v96
	v_lshlrev_b32_e32 v93, 16, v141
	v_add_f32_e32 v93, v94, v93
	v_and_b32_e32 v94, 0xffff0000, v141
	v_add_f32_e32 v94, v95, v94
	v_lshlrev_b32_e32 v95, 16, v142
	v_add_f32_e32 v88, v88, v95
	v_and_b32_e32 v95, 0xffff0000, v142
	v_add_f32_e32 v89, v89, v95
	v_lshlrev_b32_e32 v95, 16, v143
	v_add_f32_e32 v95, v90, v95
	v_and_b32_e32 v90, 0xffff0000, v143
	v_add_f32_e32 v91, v91, v90
	v_lshlrev_b32_e32 v90, 16, v136
	v_add_f32_e32 v84, v84, v90
	v_and_b32_e32 v90, 0xffff0000, v136
	v_add_f32_e32 v90, v85, v90
	v_lshlrev_b32_e32 v85, 16, v137
	v_add_f32_e32 v85, v86, v85
	v_and_b32_e32 v86, 0xffff0000, v137
	v_add_f32_e32 v86, v87, v86
	v_lshlrev_b32_e32 v87, 16, v138
	v_add_f32_e32 v80, v80, v87
	v_and_b32_e32 v87, 0xffff0000, v138
	v_add_f32_e32 v81, v81, v87
	v_lshlrev_b32_e32 v87, 16, v139
	v_lshl_add_u64 v[102:103], s[22:23], 0, v[180:181]
	v_add_f32_e32 v82, v82, v87
	v_and_b32_e32 v87, 0xffff0000, v139
	v_cvt_pk_bf16_f32 v98, v92, v96
	v_cvt_pk_bf16_f32 v99, v93, v94
	v_cvt_pk_bf16_f32 v100, v88, v89
	v_cvt_pk_bf16_f32 v101, v95, v91
	v_lshl_add_u64 v[102:103], v[168:169], 1, v[102:103]
	v_add_f32_e32 v83, v83, v87
	global_store_dwordx4 v[102:103], v[98:101], off nt
	s_and_b64 vcc, exec, s[6:7]
	s_nop 0
	v_cvt_pk_bf16_f32 v98, v84, v90
	v_cvt_pk_bf16_f32 v99, v85, v86
	v_cvt_pk_bf16_f32 v100, v80, v81
	v_cvt_pk_bf16_f32 v101, v82, v83
	global_store_dwordx4 v[102:103], v[98:101], off offset:256 nt
	s_cbranch_vccnz .LBB0_859
	v_mul_f32_e32 v83, v83, v83
	v_mul_f32_e32 v81, v81, v81
	v_mul_f32_e32 v89, v89, v89
	v_fmac_f32_e32 v83, v82, v82
	v_fmac_f32_e32 v81, v80, v80
	v_mul_f32_e32 v80, v90, v90
	v_mul_f32_e32 v82, v86, v86
	v_mul_f32_e32 v87, v91, v91
	v_fmac_f32_e32 v89, v88, v88
	v_mul_f32_e32 v88, v96, v96
	v_mul_f32_e32 v91, v94, v94
	v_fmac_f32_e32 v80, v84, v84
	v_fmac_f32_e32 v82, v85, v85
	v_fmac_f32_e32 v88, v92, v92
	v_fmac_f32_e32 v91, v93, v93
	v_add_f32_e32 v80, v80, v82
	v_and_b32_e32 v82, 64, v192
	v_add_f32_e32 v88, v88, v91
	v_add_f32_e32 v80, v81, v80
	v_xor_b32_e32 v81, 16, v192
	v_add_u32_e32 v82, 64, v82
	v_fmac_f32_e32 v87, v95, v95
	v_add_f32_e32 v88, v89, v88
	v_cmp_lt_i32_e32 vcc, v81, v82
	v_add_f32_e32 v87, v87, v88
	v_add_f32_e32 v80, v83, v80
	v_cndmask_b32_e32 v81, v192, v81, vcc
	v_add_f32_e32 v80, v87, v80
	v_lshlrev_b32_e32 v81, 2, v81
	ds_bpermute_b32 v81, v81, v80
	s_waitcnt lgkmcnt(0)
	v_add_f32_e32 v80, v80, v81
	v_xor_b32_e32 v81, 32, v192
	v_cmp_lt_i32_e32 vcc, v81, v82
	s_nop 1
	v_cndmask_b32_e32 v81, v192, v81, vcc
	v_lshlrev_b32_e32 v81, 2, v81
	ds_bpermute_b32 v81, v81, v80
	s_and_saveexec_b64 s[28:29], s[0:1]
	s_cbranch_execz .LBB0_858
	v_lshlrev_b64 v[82:83], 7, v[178:179]
	v_lshl_add_u64 v[82:83], s[24:25], 0, v[82:83]
	v_lshl_add_u64 v[82:83], s[26:27], 2, v[82:83]
	s_lshl_b32 s8, s40, 2
	v_lshl_add_u64 v[82:83], v[82:83], 0, s[8:9]
	s_waitcnt lgkmcnt(0)
	v_add_f32_e32 v80, v80, v81
	global_store_dword v[82:83], v80, off

; __device__ __forceinline__ float bflo(unsigned w) { return __uint_as_float(w << 16); }
; __device__ __forceinline__ float bfhi(unsigned w) { return __uint_as_float(w & 0xffff0000u); }
;     __device__ __forceinline__ void operator()(const f32x4 (&acc)[2][2][4][2], const Unit& u, int wr, int wc, int fr, int fq) const {
;     ...
;                 for (int m = 0; m < 4; ++m) { const size_t off = (size_t)(row0 + ai * HALF + m * 16) * DM + col0;
;                     float ss = 0.f;
; #pragma unroll
;                     for (int bj = 0; bj < 2; ++bj) { const u32x4 q = bs[m][bj]; const f32x4 a0 = acc[ai][bj][m][0], a1 = acc[ai][bj][m][1];
;                         const float h0 = bflo(q.x) + a0[0], h1 = bfhi(q.x) + a0[1], h2 = bflo(q.y) + a0[2], h3 = bfhi(q.y) + a0[3], h4 = bflo(q.z) + a1[0], h5 = bfhi(q.z) + a1[1], h6 = bflo(q.w) + a1[2], h7 = bfhi(q.w) + a1[3];
;                         ss += (h0 * h0 + h1 * h1) + (h2 * h2 + h3 * h3) + (h4 * h4 + h5 * h5) + (h6 * h6 + h7 * h7);
;                         u32x4 w; w.x = pk2(h0, h1); w.y = pk2(h2, h3); w.z = pk2(h4, h5); w.w = pk2(h6, h7);
;                         *(u32x4*)(out + off + bj * HALF) = w; }
;                     if (ssqp) { ss += __shfl_xor(ss, 16); ss += __shfl_xor(ss, 32); if (fq == 0) ssqp[(size_t)(row0 + ai * HALF + m * 16) * 32 + u.pn * 4 + wc] = ss; } }
.LBB0_859:
	v_lshlrev_b32_e32 v80, 16, v132
	v_add_f32_e32 v76, v76, v80
	v_and_b32_e32 v80, 0xffff0000, v132
	v_add_f32_e32 v80, v77, v80
	v_lshlrev_b32_e32 v77, 16, v133
	v_add_f32_e32 v77, v78, v77
	v_and_b32_e32 v78, 0xffff0000, v133
	v_add_f32_e32 v78, v79, v78
	v_lshlrev_b32_e32 v79, 16, v134
	v_add_f32_e32 v72, v72, v79
	v_and_b32_e32 v79, 0xffff0000, v134
	v_add_f32_e32 v73, v73, v79
	v_lshlrev_b32_e32 v79, 16, v135
	v_add_f32_e32 v79, v74, v79
	v_and_b32_e32 v74, 0xffff0000, v135
	v_add_f32_e32 v75, v75, v74
	v_lshlrev_b32_e32 v74, 16, v128
	v_add_f32_e32 v68, v68, v74
	v_and_b32_e32 v74, 0xffff0000, v128
	v_add_f32_e32 v74, v69, v74
	v_lshlrev_b32_e32 v69, 16, v129
	v_add_f32_e32 v69, v70, v69
	v_and_b32_e32 v70, 0xffff0000, v129
	v_add_f32_e32 v70, v71, v70
	v_lshlrev_b32_e32 v71, 16, v130
	v_add_f32_e32 v64, v64, v71
	v_and_b32_e32 v71, 0xffff0000, v130
	v_add_f32_e32 v65, v65, v71
	v_lshlrev_b32_e32 v71, 16, v131
	v_lshl_add_u64 v[86:87], s[22:23], 0, v[176:177]
	v_add_f32_e32 v66, v66, v71
	v_and_b32_e32 v71, 0xffff0000, v131
	v_cvt_pk_bf16_f32 v82, v76, v80
	v_cvt_pk_bf16_f32 v83, v77, v78
	v_cvt_pk_bf16_f32 v84, v72, v73
	v_cvt_pk_bf16_f32 v85, v79, v75
	v_lshl_add_u64 v[86:87], v[168:169], 1, v[86:87]
	v_add_f32_e32 v67, v67, v71
	global_store_dwordx4 v[86:87], v[82:85], off nt
	s_and_b64 vcc, exec, s[6:7]
	s_nop 0
	v_cvt_pk_bf16_f32 v82, v68, v74
	v_cvt_pk_bf16_f32 v83, v69, v70
	v_cvt_pk_bf16_f32 v84, v64, v65
	v_cvt_pk_bf16_f32 v85, v66, v67
	global_store_dwordx4 v[86:87], v[82:85], off offset:256 nt
	s_cbranch_vccnz .LBB0_863
	v_mul_f32_e32 v67, v67, v67
	v_mul_f32_e32 v65, v65, v65
	v_mul_f32_e32 v73, v73, v73
	v_fmac_f32_e32 v67, v66, v66
	v_fmac_f32_e32 v65, v64, v64
	v_mul_f32_e32 v64, v74, v74
	v_mul_f32_e32 v66, v70, v70
	v_mul_f32_e32 v71, v75, v75
	v_fmac_f32_e32 v73, v72, v72
	v_mul_f32_e32 v72, v80, v80
	v_mul_f32_e32 v75, v78, v78
	v_fmac_f32_e32 v64, v68, v68
	v_fmac_f32_e32 v66, v69, v69
	v_fmac_f32_e32 v72, v76, v76
	v_fmac_f32_e32 v75, v77, v77
	v_add_f32_e32 v64, v64, v66
	v_and_b32_e32 v66, 64, v192
	v_add_f32_e32 v72, v72, v75
	v_add_f32_e32 v64, v65, v64
	v_xor_b32_e32 v65, 16, v192
	v_add_u32_e32 v66, 64, v66
	v_fmac_f32_e32 v71, v79, v79
	v_add_f32_e32 v72, v73, v72
	v_cmp_lt_i32_e32 vcc, v65, v66
	v_add_f32_e32 v71, v71, v72
	v_add_f32_e32 v64, v67, v64
	v_cndmask_b32_e32 v65, v192, v65, vcc
	v_add_f32_e32 v64, v71, v64
	v_lshlrev_b32_e32 v65, 2, v65
	ds_bpermute_b32 v65, v65, v64
	s_waitcnt lgkmcnt(0)
	v_add_f32_e32 v64, v64, v65
	v_xor_b32_e32 v65, 32, v192
	v_cmp_lt_i32_e32 vcc, v65, v66
	s_nop 1
	v_cndmask_b32_e32 v65, v192, v65, vcc
	v_lshlrev_b32_e32 v65, 2, v65
	ds_bpermute_b32 v65, v65, v64
	s_and_saveexec_b64 s[28:29], s[0:1]
	s_cbranch_execz .LBB0_862
	v_lshlrev_b64 v[66:67], 7, v[174:175]
	v_lshl_add_u64 v[66:67], s[24:25], 0, v[66:67]
	v_lshl_add_u64 v[66:67], s[26:27], 2, v[66:67]
	s_lshl_b32 s8, s40, 2
	v_lshl_add_u64 v[66:67], v[66:67], 0, s[8:9]
	s_waitcnt lgkmcnt(0)
	v_add_f32_e32 v64, v64, v65
	global_store_dword v[66:67], v64, off

; __device__ __forceinline__ float bflo(unsigned w) { return __uint_as_float(w << 16); }
; __device__ __forceinline__ float bfhi(unsigned w) { return __uint_as_float(w & 0xffff0000u); }
;     __device__ __forceinline__ void operator()(const f32x4 (&acc)[2][2][4][2], const Unit& u, int wr, int wc, int fr, int fq) const {
;     ...
;                 u32x4 bs[4][2];
; #pragma unroll
;                 for (int m = 0; m < 4; ++m) { const size_t off = (size_t)(row0 + ai * HALF + m * 16) * DM + col0;
; #pragma unroll
;                     for (int bj = 0; bj < 2; ++bj) bs[m][bj] = *(const u32x4*)(baseb + off + bj * HALF); }
; #pragma unroll
;                 for (int m = 0; m < 4; ++m) { const size_t off = (size_t)(row0 + ai * HALF + m * 16) * DM + col0;
;                     float ss = 0.f;
; #pragma unroll
;                     for (int bj = 0; bj < 2; ++bj) { const u32x4 q = bs[m][bj]; const f32x4 a0 = acc[ai][bj][m][0], a1 = acc[ai][bj][m][1];
;                         const float h0 = bflo(q.x) + a0[0], h1 = bfhi(q.x) + a0[1], h2 = bflo(q.y) + a0[2], h3 = bfhi(q.y) + a0[3], h4 = bflo(q.z) + a1[0], h5 = bfhi(q.z) + a1[1], h6 = bflo(q.w) + a1[2], h7 = bfhi(q.w) + a1[3];
;                         ss += (h0 * h0 + h1 * h1) + (h2 * h2 + h3 * h3) + (h4 * h4 + h5 * h5) + (h6 * h6 + h7 * h7);
;                         u32x4 w; w.x = pk2(h0, h1); w.y = pk2(h2, h3); w.z = pk2(h4, h5); w.w = pk2(h6, h7);
;                         *(u32x4*)(out + off + bj * HALF) = w; }
;                     if (ssqp) { ss += __shfl_xor(ss, 16); ss += __shfl_xor(ss, 32); if (fq == 0) ssqp[(size_t)(row0 + ai * HALF + m * 16) * 32 + u.pn * 4 + wc] = ss; } }
.LBB0_863:
	v_add_u32_e32 v100, 0x80, v172
	v_ashrrev_i32_e32 v101, 31, v100
	v_add_u32_e32 v96, 0x90, v172
	v_add_u32_e32 v92, 0xa0, v172
	v_lshlrev_b64 v[110:111], 12, v[100:101]
	v_add_u32_e32 v88, 0xb0, v172
	s_waitcnt lgkmcnt(0)
	v_ashrrev_i32_e32 v97, 31, v96
	v_ashrrev_i32_e32 v93, 31, v92
	v_lshl_add_u64 v[64:65], v[170:171], 0, v[110:111]
	v_ashrrev_i32_e32 v89, 31, v88
	v_lshlrev_b64 v[98:99], 12, v[96:97]
	v_lshlrev_b64 v[94:95], 12, v[92:93]
	global_load_dwordx4 v[102:105], v[64:65], off
	global_load_dwordx4 v[106:109], v[64:65], off offset:256
	v_lshlrev_b64 v[90:91], 12, v[88:89]
	v_lshl_add_u64 v[64:65], v[170:171], 0, v[98:99]
	v_lshl_add_u64 v[66:67], v[170:171], 0, v[94:95]
	v_lshl_add_u64 v[112:113], v[170:171], 0, v[90:91]
	global_load_dwordx4 v[84:87], v[64:65], off
	global_load_dwordx4 v[80:83], v[64:65], off offset:256
	global_load_dwordx4 v[76:79], v[66:67], off
	global_load_dwordx4 v[72:75], v[66:67], off offset:256
	global_load_dwordx4 v[68:71], v[112:113], off
	s_nop 0
	global_load_dwordx4 v[64:67], v[112:113], off offset:256
	v_lshl_add_u64 v[110:111], s[22:23], 0, v[110:111]
	v_lshl_add_u64 v[112:113], v[168:169], 1, v[110:111]
	s_and_b64 vcc, exec, s[6:7]
	s_waitcnt vmcnt(7)
	v_lshlrev_b32_e32 v110, 16, v102
	v_and_b32_e32 v111, 0xffff0000, v102
	v_lshlrev_b32_e32 v114, 16, v103
	v_and_b32_e32 v115, 0xffff0000, v103
	v_lshlrev_b32_e32 v116, 16, v104
	v_and_b32_e32 v104, 0xffff0000, v104
	v_lshlrev_b32_e32 v117, 16, v105
	v_and_b32_e32 v105, 0xffff0000, v105
	s_waitcnt vmcnt(6)
	v_lshlrev_b32_e32 v118, 16, v106
	v_and_b32_e32 v106, 0xffff0000, v106
	v_lshlrev_b32_e32 v119, 16, v107
	v_and_b32_e32 v107, 0xffff0000, v107
	v_lshlrev_b32_e32 v120, 16, v108
	v_and_b32_e32 v108, 0xffff0000, v108
	v_lshlrev_b32_e32 v121, 16, v109
	v_and_b32_e32 v109, 0xffff0000, v109
	v_add_f32_e32 v102, v60, v110
	v_add_f32_e32 v103, v61, v111
	v_add_f32_e32 v60, v62, v114
	v_add_f32_e32 v61, v63, v115
	v_add_f32_e32 v62, v56, v116
	v_add_f32_e32 v63, v57, v104
	v_add_f32_e32 v58, v58, v117
	v_add_f32_e32 v59, v59, v105
	v_add_f32_e32 v56, v52, v118
	v_add_f32_e32 v57, v53, v106
	v_add_f32_e32 v52, v54, v119
	v_add_f32_e32 v53, v55, v107
	v_add_f32_e32 v48, v48, v120
	v_add_f32_e32 v49, v49, v108
	v_add_f32_e32 v50, v50, v121
	v_add_f32_e32 v51, v51, v109
	v_cvt_pk_bf16_f32 v104, v102, v103
	v_cvt_pk_bf16_f32 v105, v60, v61
	v_cvt_pk_bf16_f32 v106, v62, v63
	v_cvt_pk_bf16_f32 v107, v58, v59
	v_cvt_pk_bf16_f32 v108, v56, v57
	v_cvt_pk_bf16_f32 v109, v52, v53
	v_cvt_pk_bf16_f32 v110, v48, v49
	v_cvt_pk_bf16_f32 v111, v50, v51
	global_store_dwordx4 v[112:113], v[104:107], off nt
	global_store_dwordx4 v[112:113], v[108:111], off offset:256 nt
	s_cbranch_vccnz .LBB0_867
	v_mul_f32_e32 v51, v51, v51
	v_mul_f32_e32 v49, v49, v49
	v_mul_f32_e32 v54, v59, v59
	v_fmac_f32_e32 v51, v50, v50
	v_fmac_f32_e32 v49, v48, v48
	v_mul_f32_e32 v48, v57, v57
	v_mul_f32_e32 v50, v53, v53
	v_fmac_f32_e32 v54, v58, v58
	v_mul_f32_e32 v58, v103, v103
	v_mul_f32_e32 v59, v61, v61
	v_fmac_f32_e32 v48, v56, v56
	v_fmac_f32_e32 v50, v52, v52
	v_mul_f32_e32 v55, v63, v63
	v_fmac_f32_e32 v58, v102, v102
	v_fmac_f32_e32 v59, v60, v60
	v_add_f32_e32 v48, v48, v50
	v_and_b32_e32 v50, 64, v192
	v_fmac_f32_e32 v55, v62, v62
	v_add_f32_e32 v58, v58, v59
	v_add_f32_e32 v48, v49, v48
	v_xor_b32_e32 v49, 16, v192
	v_add_u32_e32 v50, 64, v50
	v_add_f32_e32 v55, v55, v58
	v_cmp_lt_i32_e32 vcc, v49, v50
	v_add_f32_e32 v54, v54, v55
	v_add_f32_e32 v48, v51, v48
	v_cndmask_b32_e32 v49, v192, v49, vcc
	v_add_f32_e32 v48, v54, v48
	v_lshlrev_b32_e32 v49, 2, v49
	ds_bpermute_b32 v49, v49, v48
	s_waitcnt lgkmcnt(0)
	v_add_f32_e32 v48, v48, v49
	v_xor_b32_e32 v49, 32, v192
	v_cmp_lt_i32_e32 vcc, v49, v50
	s_nop 1
	v_cndmask_b32_e32 v49, v192, v49, vcc
	v_lshlrev_b32_e32 v49, 2, v49
	ds_bpermute_b32 v49, v49, v48
	s_and_saveexec_b64 s[28:29], s[0:1]
	s_cbranch_execz .LBB0_866
	v_lshlrev_b64 v[50:51], 7, v[100:101]
	v_lshl_add_u64 v[50:51], s[24:25], 0, v[50:51]
	v_lshl_add_u64 v[50:51], s[26:27], 2, v[50:51]
	s_lshl_b32 s8, s40, 2
	v_lshl_add_u64 v[50:51], v[50:51], 0, s[8:9]
	s_waitcnt lgkmcnt(0)
	v_add_f32_e32 v48, v48, v49
	global_store_dword v[50:51], v48, off

; __device__ __forceinline__ float bflo(unsigned w) { return __uint_as_float(w << 16); }
; __device__ __forceinline__ float bfhi(unsigned w) { return __uint_as_float(w & 0xffff0000u); }
;     __device__ __forceinline__ void operator()(const f32x4 (&acc)[2][2][4][2], const Unit& u, int wr, int wc, int fr, int fq) const {
;     ...
;                 for (int m = 0; m < 4; ++m) { const size_t off = (size_t)(row0 + ai * HALF + m * 16) * DM + col0;
;                     float ss = 0.f;
; #pragma unroll
;                     for (int bj = 0; bj < 2; ++bj) { const u32x4 q = bs[m][bj]; const f32x4 a0 = acc[ai][bj][m][0], a1 = acc[ai][bj][m][1];
;                         const float h0 = bflo(q.x) + a0[0], h1 = bfhi(q.x) + a0[1], h2 = bflo(q.y) + a0[2], h3 = bfhi(q.y) + a0[3], h4 = bflo(q.z) + a1[0], h5 = bfhi(q.z) + a1[1], h6 = bflo(q.w) + a1[2], h7 = bfhi(q.w) + a1[3];
;                         ss += (h0 * h0 + h1 * h1) + (h2 * h2 + h3 * h3) + (h4 * h4 + h5 * h5) + (h6 * h6 + h7 * h7);
;                         u32x4 w; w.x = pk2(h0, h1); w.y = pk2(h2, h3); w.z = pk2(h4, h5); w.w = pk2(h6, h7);
;                         *(u32x4*)(out + off + bj * HALF) = w; }
;                     if (ssqp) { ss += __shfl_xor(ss, 16); ss += __shfl_xor(ss, 32); if (fq == 0) ssqp[(size_t)(row0 + ai * HALF + m * 16) * 32 + u.pn * 4 + wc] = ss; } }
.LBB0_867:
	s_waitcnt vmcnt(7)
	v_lshlrev_b32_e32 v48, 16, v84
	v_add_f32_e32 v44, v44, v48
	v_and_b32_e32 v48, 0xffff0000, v84
	v_add_f32_e32 v48, v45, v48
	v_lshlrev_b32_e32 v45, 16, v85
	v_add_f32_e32 v45, v46, v45
	v_and_b32_e32 v46, 0xffff0000, v85
	v_add_f32_e32 v46, v47, v46
	v_lshlrev_b32_e32 v47, 16, v86
	v_add_f32_e32 v40, v40, v47
	v_and_b32_e32 v47, 0xffff0000, v86
	v_add_f32_e32 v41, v41, v47
	v_lshlrev_b32_e32 v47, 16, v87
	v_add_f32_e32 v47, v42, v47
	v_and_b32_e32 v42, 0xffff0000, v87
	v_add_f32_e32 v43, v43, v42
	s_waitcnt vmcnt(6)
	v_lshlrev_b32_e32 v42, 16, v80
	v_add_f32_e32 v36, v36, v42
	v_and_b32_e32 v42, 0xffff0000, v80
	v_add_f32_e32 v42, v37, v42
	v_lshlrev_b32_e32 v37, 16, v81
	v_add_f32_e32 v37, v38, v37
	v_and_b32_e32 v38, 0xffff0000, v81
	v_add_f32_e32 v38, v39, v38
	v_lshlrev_b32_e32 v39, 16, v82
	v_add_f32_e32 v32, v32, v39
	v_and_b32_e32 v39, 0xffff0000, v82
	v_add_f32_e32 v33, v33, v39
	v_lshlrev_b32_e32 v39, 16, v83
	v_lshl_add_u64 v[54:55], s[22:23], 0, v[98:99]
	v_add_f32_e32 v34, v34, v39
	v_and_b32_e32 v39, 0xffff0000, v83
	v_cvt_pk_bf16_f32 v50, v44, v48
	v_cvt_pk_bf16_f32 v51, v45, v46
	v_cvt_pk_bf16_f32 v52, v40, v41
	v_cvt_pk_bf16_f32 v53, v47, v43
	v_lshl_add_u64 v[54:55], v[168:169], 1, v[54:55]
	v_add_f32_e32 v35, v35, v39
	global_store_dwordx4 v[54:55], v[50:53], off nt
	s_and_b64 vcc, exec, s[6:7]
	s_nop 0
	v_cvt_pk_bf16_f32 v50, v36, v42
	v_cvt_pk_bf16_f32 v51, v37, v38
	v_cvt_pk_bf16_f32 v52, v32, v33
	v_cvt_pk_bf16_f32 v53, v34, v35
	global_store_dwordx4 v[54:55], v[50:53], off offset:256 nt
	s_cbranch_vccnz .LBB0_871
	v_mul_f32_e32 v35, v35, v35
	v_mul_f32_e32 v33, v33, v33
	v_mul_f32_e32 v41, v41, v41
	v_fmac_f32_e32 v35, v34, v34
	v_fmac_f32_e32 v33, v32, v32
	v_mul_f32_e32 v32, v42, v42
	v_mul_f32_e32 v34, v38, v38
	v_mul_f32_e32 v39, v43, v43
	v_fmac_f32_e32 v41, v40, v40
	v_mul_f32_e32 v40, v48, v48
	v_mul_f32_e32 v43, v46, v46
	v_fmac_f32_e32 v32, v36, v36
	v_fmac_f32_e32 v34, v37, v37
	v_fmac_f32_e32 v40, v44, v44
	v_fmac_f32_e32 v43, v45, v45
	v_add_f32_e32 v32, v32, v34
	v_and_b32_e32 v34, 64, v192
	v_add_f32_e32 v40, v40, v43
	v_add_f32_e32 v32, v33, v32
	v_xor_b32_e32 v33, 16, v192
	v_add_u32_e32 v34, 64, v34
	v_fmac_f32_e32 v39, v47, v47
	v_add_f32_e32 v40, v41, v40
	v_cmp_lt_i32_e32 vcc, v33, v34
	v_add_f32_e32 v39, v39, v40
	v_add_f32_e32 v32, v35, v32
	v_cndmask_b32_e32 v33, v192, v33, vcc
	v_add_f32_e32 v32, v39, v32
	v_lshlrev_b32_e32 v33, 2, v33
	ds_bpermute_b32 v33, v33, v32
	s_waitcnt lgkmcnt(0)
	v_add_f32_e32 v32, v32, v33
	v_xor_b32_e32 v33, 32, v192
	v_cmp_lt_i32_e32 vcc, v33, v34
	s_nop 1
	v_cndmask_b32_e32 v33, v192, v33, vcc
	v_lshlrev_b32_e32 v33, 2, v33
	ds_bpermute_b32 v33, v33, v32
	s_and_saveexec_b64 s[28:29], s[0:1]
	s_cbranch_execz .LBB0_870
	v_lshlrev_b64 v[34:35], 7, v[96:97]
	v_lshl_add_u64 v[34:35], s[24:25], 0, v[34:35]
	v_lshl_add_u64 v[34:35], s[26:27], 2, v[34:35]
	s_lshl_b32 s8, s40, 2
	v_lshl_add_u64 v[34:35], v[34:35], 0, s[8:9]
	s_waitcnt lgkmcnt(0)
	v_add_f32_e32 v32, v32, v33
	global_store_dword v[34:35], v32, off

; __device__ __forceinline__ float bflo(unsigned w) { return __uint_as_float(w << 16); }
; __device__ __forceinline__ float bfhi(unsigned w) { return __uint_as_float(w & 0xffff0000u); }
;     __device__ __forceinline__ void operator()(const f32x4 (&acc)[2][2][4][2], const Unit& u, int wr, int wc, int fr, int fq) const {
;     ...
;                 for (int m = 0; m < 4; ++m) { const size_t off = (size_t)(row0 + ai * HALF + m * 16) * DM + col0;
;                     float ss = 0.f;
; #pragma unroll
;                     for (int bj = 0; bj < 2; ++bj) { const u32x4 q = bs[m][bj]; const f32x4 a0 = acc[ai][bj][m][0], a1 = acc[ai][bj][m][1];
;                         const float h0 = bflo(q.x) + a0[0], h1 = bfhi(q.x) + a0[1], h2 = bflo(q.y) + a0[2], h3 = bfhi(q.y) + a0[3], h4 = bflo(q.z) + a1[0], h5 = bfhi(q.z) + a1[1], h6 = bflo(q.w) + a1[2], h7 = bfhi(q.w) + a1[3];
;                         ss += (h0 * h0 + h1 * h1) + (h2 * h2 + h3 * h3) + (h4 * h4 + h5 * h5) + (h6 * h6 + h7 * h7);
;                         u32x4 w; w.x = pk2(h0, h1); w.y = pk2(h2, h3); w.z = pk2(h4, h5); w.w = pk2(h6, h7);
;                         *(u32x4*)(out + off + bj * HALF) = w; }
;                     if (ssqp) { ss += __shfl_xor(ss, 16); ss += __shfl_xor(ss, 32); if (fq == 0) ssqp[(size_t)(row0 + ai * HALF + m * 16) * 32 + u.pn * 4 + wc] = ss; } }
.LBB0_871:
	s_waitcnt vmcnt(7)
	v_lshlrev_b32_e32 v32, 16, v76
	v_add_f32_e32 v28, v28, v32
	v_and_b32_e32 v32, 0xffff0000, v76
	v_add_f32_e32 v32, v29, v32
	v_lshlrev_b32_e32 v29, 16, v77
	v_add_f32_e32 v29, v30, v29
	v_and_b32_e32 v30, 0xffff0000, v77
	v_add_f32_e32 v30, v31, v30
	v_lshlrev_b32_e32 v31, 16, v78
	v_add_f32_e32 v24, v24, v31
	v_and_b32_e32 v31, 0xffff0000, v78
	v_add_f32_e32 v25, v25, v31
	v_lshlrev_b32_e32 v31, 16, v79
	v_add_f32_e32 v31, v26, v31
	v_and_b32_e32 v26, 0xffff0000, v79
	v_add_f32_e32 v27, v27, v26
	s_waitcnt vmcnt(6)
	v_lshlrev_b32_e32 v26, 16, v72
	v_add_f32_e32 v20, v20, v26
	v_and_b32_e32 v26, 0xffff0000, v72
	v_add_f32_e32 v26, v21, v26
	v_lshlrev_b32_e32 v21, 16, v73
	v_add_f32_e32 v21, v22, v21
	v_and_b32_e32 v22, 0xffff0000, v73
	v_add_f32_e32 v22, v23, v22
	v_lshlrev_b32_e32 v23, 16, v74
	v_add_f32_e32 v16, v16, v23
	v_and_b32_e32 v23, 0xffff0000, v74
	v_add_f32_e32 v17, v17, v23
	v_lshlrev_b32_e32 v23, 16, v75
	v_lshl_add_u64 v[38:39], s[22:23], 0, v[94:95]
	v_add_f32_e32 v18, v18, v23
	v_and_b32_e32 v23, 0xffff0000, v75
	v_cvt_pk_bf16_f32 v34, v28, v32
	v_cvt_pk_bf16_f32 v35, v29, v30
	v_cvt_pk_bf16_f32 v36, v24, v25
	v_cvt_pk_bf16_f32 v37, v31, v27
	v_lshl_add_u64 v[38:39], v[168:169], 1, v[38:39]
	v_add_f32_e32 v19, v19, v23
	global_store_dwordx4 v[38:39], v[34:37], off nt
	s_and_b64 vcc, exec, s[6:7]
	s_nop 0
	v_cvt_pk_bf16_f32 v34, v20, v26
	v_cvt_pk_bf16_f32 v35, v21, v22
	v_cvt_pk_bf16_f32 v36, v16, v17
	v_cvt_pk_bf16_f32 v37, v18, v19
	global_store_dwordx4 v[38:39], v[34:37], off offset:256 nt
	s_cbranch_vccnz .LBB0_875
	v_mul_f32_e32 v19, v19, v19
	v_mul_f32_e32 v17, v17, v17
	v_mul_f32_e32 v25, v25, v25
	v_fmac_f32_e32 v19, v18, v18
	v_fmac_f32_e32 v17, v16, v16
	v_mul_f32_e32 v16, v26, v26
	v_mul_f32_e32 v18, v22, v22
	v_mul_f32_e32 v23, v27, v27
	v_fmac_f32_e32 v25, v24, v24
	v_mul_f32_e32 v24, v32, v32
	v_mul_f32_e32 v27, v30, v30
	v_fmac_f32_e32 v16, v20, v20
	v_fmac_f32_e32 v18, v21, v21
	v_fmac_f32_e32 v24, v28, v28
	v_fmac_f32_e32 v27, v29, v29
	v_add_f32_e32 v16, v16, v18
	v_and_b32_e32 v18, 64, v192
	v_add_f32_e32 v24, v24, v27
	v_add_f32_e32 v16, v17, v16
	v_xor_b32_e32 v17, 16, v192
	v_add_u32_e32 v18, 64, v18
	v_fmac_f32_e32 v23, v31, v31
	v_add_f32_e32 v24, v25, v24
	v_cmp_lt_i32_e32 vcc, v17, v18
	v_add_f32_e32 v23, v23, v24
	v_add_f32_e32 v16, v19, v16
	v_cndmask_b32_e32 v17, v192, v17, vcc
	v_add_f32_e32 v16, v23, v16
	v_lshlrev_b32_e32 v17, 2, v17
	ds_bpermute_b32 v17, v17, v16
	s_waitcnt lgkmcnt(0)
	v_add_f32_e32 v16, v16, v17
	v_xor_b32_e32 v17, 32, v192
	v_cmp_lt_i32_e32 vcc, v17, v18
	s_nop 1
	v_cndmask_b32_e32 v17, v192, v17, vcc
	v_lshlrev_b32_e32 v17, 2, v17
	ds_bpermute_b32 v17, v17, v16
	s_and_saveexec_b64 s[28:29], s[0:1]
	s_cbranch_execz .LBB0_874
	v_lshlrev_b64 v[18:19], 7, v[92:93]
	v_lshl_add_u64 v[18:19], s[24:25], 0, v[18:19]
	v_lshl_add_u64 v[18:19], s[26:27], 2, v[18:19]
	s_lshl_b32 s8, s40, 2
	v_lshl_add_u64 v[18:19], v[18:19], 0, s[8:9]
	s_waitcnt lgkmcnt(0)
	v_add_f32_e32 v16, v16, v17
	global_store_dword v[18:19], v16, off

; __device__ __forceinline__ float bflo(unsigned w) { return __uint_as_float(w << 16); }
; __device__ __forceinline__ float bfhi(unsigned w) { return __uint_as_float(w & 0xffff0000u); }
;     __device__ __forceinline__ void operator()(const f32x4 (&acc)[2][2][4][2], const Unit& u, int wr, int wc, int fr, int fq) const {
;     ...
;                 for (int m = 0; m < 4; ++m) { const size_t off = (size_t)(row0 + ai * HALF + m * 16) * DM + col0;
;                     float ss = 0.f;
; #pragma unroll
;                     for (int bj = 0; bj < 2; ++bj) { const u32x4 q = bs[m][bj]; const f32x4 a0 = acc[ai][bj][m][0], a1 = acc[ai][bj][m][1];
;                         const float h0 = bflo(q.x) + a0[0], h1 = bfhi(q.x) + a0[1], h2 = bflo(q.y) + a0[2], h3 = bfhi(q.y) + a0[3], h4 = bflo(q.z) + a1[0], h5 = bfhi(q.z) + a1[1], h6 = bflo(q.w) + a1[2], h7 = bfhi(q.w) + a1[3];
;                         ss += (h0 * h0 + h1 * h1) + (h2 * h2 + h3 * h3) + (h4 * h4 + h5 * h5) + (h6 * h6 + h7 * h7);
;                         u32x4 w; w.x = pk2(h0, h1); w.y = pk2(h2, h3); w.z = pk2(h4, h5); w.w = pk2(h6, h7);
;                         *(u32x4*)(out + off + bj * HALF) = w; }
;                     if (ssqp) { ss += __shfl_xor(ss, 16); ss += __shfl_xor(ss, 32); if (fq == 0) ssqp[(size_t)(row0 + ai * HALF + m * 16) * 32 + u.pn * 4 + wc] = ss; } }
.LBB0_875:
	s_waitcnt vmcnt(7)
	v_lshlrev_b32_e32 v16, 16, v68
	v_add_f32_e32 v12, v12, v16
	v_and_b32_e32 v16, 0xffff0000, v68
	v_add_f32_e32 v16, v13, v16
	v_lshlrev_b32_e32 v13, 16, v69
	v_add_f32_e32 v13, v14, v13
	v_and_b32_e32 v14, 0xffff0000, v69
	v_add_f32_e32 v14, v15, v14
	v_lshlrev_b32_e32 v15, 16, v70
	v_add_f32_e32 v8, v8, v15
	v_and_b32_e32 v15, 0xffff0000, v70
	v_add_f32_e32 v9, v9, v15
	v_lshlrev_b32_e32 v15, 16, v71
	v_add_f32_e32 v15, v10, v15
	v_and_b32_e32 v10, 0xffff0000, v71
	v_add_f32_e32 v11, v11, v10
	s_waitcnt vmcnt(6)
	v_lshlrev_b32_e32 v10, 16, v64
	v_add_f32_e32 v4, v4, v10
	v_and_b32_e32 v10, 0xffff0000, v64
	v_add_f32_e32 v10, v5, v10
	v_lshlrev_b32_e32 v5, 16, v65
	v_add_f32_e32 v5, v6, v5
	v_and_b32_e32 v6, 0xffff0000, v65
	v_add_f32_e32 v6, v7, v6
	v_lshlrev_b32_e32 v7, 16, v66
	v_add_f32_e32 v0, v0, v7
	v_and_b32_e32 v7, 0xffff0000, v66
	v_add_f32_e32 v1, v1, v7
	v_lshlrev_b32_e32 v7, 16, v67
	v_lshl_add_u64 v[22:23], s[22:23], 0, v[90:91]
	v_add_f32_e32 v2, v2, v7
	v_and_b32_e32 v7, 0xffff0000, v67
	v_cvt_pk_bf16_f32 v18, v12, v16
	v_cvt_pk_bf16_f32 v19, v13, v14
	v_cvt_pk_bf16_f32 v20, v8, v9
	v_cvt_pk_bf16_f32 v21, v15, v11
	v_lshl_add_u64 v[22:23], v[168:169], 1, v[22:23]
	v_add_f32_e32 v3, v3, v7
	global_store_dwordx4 v[22:23], v[18:21], off nt
	s_and_b64 vcc, exec, s[6:7]
	s_nop 0
	v_cvt_pk_bf16_f32 v18, v4, v10
	v_cvt_pk_bf16_f32 v19, v5, v6
	v_cvt_pk_bf16_f32 v20, v0, v1
	v_cvt_pk_bf16_f32 v21, v2, v3
	global_store_dwordx4 v[22:23], v[18:21], off offset:256 nt
	s_cbranch_vccnz .LBB0_838
	v_mul_f32_e32 v3, v3, v3
	v_mul_f32_e32 v1, v1, v1
	v_mul_f32_e32 v9, v9, v9
	v_fmac_f32_e32 v3, v2, v2
	v_fmac_f32_e32 v1, v0, v0
	v_mul_f32_e32 v0, v10, v10
	v_mul_f32_e32 v2, v6, v6
	v_mul_f32_e32 v7, v11, v11
	v_fmac_f32_e32 v9, v8, v8
	v_mul_f32_e32 v8, v16, v16
	v_mul_f32_e32 v11, v14, v14
	v_fmac_f32_e32 v0, v4, v4
	v_fmac_f32_e32 v2, v5, v5
	v_fmac_f32_e32 v8, v12, v12
	v_fmac_f32_e32 v11, v13, v13
	v_add_f32_e32 v0, v0, v2
	v_and_b32_e32 v2, 64, v192
	v_add_f32_e32 v8, v8, v11
	v_add_f32_e32 v0, v1, v0
	v_xor_b32_e32 v1, 16, v192
	v_add_u32_e32 v2, 64, v2
	v_fmac_f32_e32 v7, v15, v15
	v_add_f32_e32 v8, v9, v8
	v_cmp_lt_i32_e32 vcc, v1, v2
	v_add_f32_e32 v7, v7, v8
	v_add_f32_e32 v0, v3, v0
	v_cndmask_b32_e32 v1, v192, v1, vcc
	v_add_f32_e32 v0, v7, v0
	v_lshlrev_b32_e32 v1, 2, v1
	ds_bpermute_b32 v1, v1, v0
	s_waitcnt lgkmcnt(0)
	v_add_f32_e32 v0, v0, v1
	v_xor_b32_e32 v1, 32, v192
	v_cmp_lt_i32_e32 vcc, v1, v2
	s_nop 1
	v_cndmask_b32_e32 v1, v192, v1, vcc
	v_lshlrev_b32_e32 v1, 2, v1
	ds_bpermute_b32 v1, v1, v0
	s_and_saveexec_b64 s[6:7], s[0:1]
	s_cbranch_execz .LBB0_837
	v_lshlrev_b64 v[2:3], 7, v[88:89]
	v_lshl_add_u64 v[2:3], s[24:25], 0, v[2:3]
	v_lshl_add_u64 v[2:3], s[26:27], 2, v[2:3]
	s_lshl_b32 s8, s40, 2
	v_lshl_add_u64 v[2:3], v[2:3], 0, s[8:9]
	s_waitcnt lgkmcnt(0)
	v_add_f32_e32 v0, v0, v1
	global_store_dword v[2:3], v0, off
	s_branch .LBB0_837

; #define PG8_STAGE(bufoff, gbase, voff) do { _Pragma("unroll") for (int _i = 0; _i < 2; ++_i) \
;         __builtin_amdgcn_global_load_lds((const unsigned*)((const char*)(gbase) + (voff)[_i]), (LAS unsigned*)(lds + (bufoff) + ldsw + _i * 8192), 16, 0, 0); } while (0)
; #define PG8_LDA(dst, b, h) do { _Pragma("unroll") for (int m = 0; m < 4; ++m) _Pragma("unroll") for (int k = 0; k < 2; ++k) dst[m][k] = *(const LAS bf16x8*)(lds + PG8_SA(b, h) + aoff + m * 2048 + k * 1024); } while (0)
; #define PG8_LDB(dst, b, h) do { _Pragma("unroll") for (int n = 0; n < 2; ++n) _Pragma("unroll") for (int k = 0; k < 2; ++k) dst[n][k] = *(const LAS bf16x8*)(lds + PG8_SB(b, h) + boff + n * 2048 + k * 1024); } while (0)
; #define PG8_MMA(ai, bj, At, Bt) do { __builtin_amdgcn_s_setprio(1); _Pragma("unroll") for (int m = 0; m < 4; ++m) _Pragma("unroll") for (int n = 0; n < 2; ++n) _Pragma("unroll") for (int k = 0; k < 2; ++k) \
;         acc[ai][bj][m][n] = __builtin_amdgcn_mfma_f32_16x16x32_bf16(Bt[n][k], At[m][k], acc[ai][bj][m][n], 0, 0, 0); __builtin_amdgcn_s_setprio(0); } while (0)
; #define PG8_WAIT_L(n) asm volatile("s_waitcnt lgkmcnt(" #n ")" ::: "memory")
; #define PG8_BAR __builtin_amdgcn_s_barrier()
; #define PG8_SCHED __builtin_amdgcn_sched_barrier(0)
; template <class Epi>
; __device__ __forceinline__ void gemm_phase(LAS unsigned char* lds, const Gemm g, const Order& S, const Epi& E, const int tid) {
;     ...
;             const char* a1 = cA + (size_t)(t + 1) * kstep;
;             const char* a2 = last ? nA : cA + (size_t)(t + 2) * kstep; const char* b2 = last ? nB : cB + (size_t)(t + 2) * kstep;
;             const char* a3 = a2 + kstep; const char* b3 = b2 + kstep;
;             PG8_LDB(B0, 0, 0); PG8_SCHED; PG8_LDA(At, 0, 0); PG8_STAGE(PG8_SA(1, 1), a1 + hstepA, voffA);
;             PG8_WAIT_L(8); PG8_BAR; PG8_WAIT_L(0); PG8_MMA(0, 0, At, B0); PG8_BAR; PG8_SCHED;
;             PG8_LDB(B1, 0, 1); PG8_STAGE(PG8_SB(0, 0), b2, voffB);
;             PG8_BAR; PG8_WAIT_L(0); PG8_MMA(0, 1, At, B1); PG8_BAR;
;             PG8_LDA(At, 0, 1); PG8_STAGE(PG8_SA(0, 0), a2, voffA);
;             PG8_BAR; PG8_WAIT_L(0); PG8_MMA(1, 0, At, B0); PG8_BAR; PG8_SCHED;
.LBB0_912:
	ds_read_b128 v[154:157], v150
	ds_read_b128 v[158:161], v150 offset:1024
	ds_read_b128 v[162:165], v150 offset:2048
	ds_read_b128 v[166:169], v150 offset:3072
	s_add_u32 s28, s26, 0xfff80080
	s_addc_u32 s29, s27, -1
	s_cmp_eq_u32 s55, 28
	s_cselect_b32 s31, s15, s29
	s_cselect_b32 s30, s50, s28
	s_cselect_b32 s29, s17, s53
	s_cselect_b32 s28, s51, s52
	v_lshl_add_u64 v[144:145], s[26:27], 0, v[136:137]
	s_add_i32 m0, s25, 0xc000
	ds_read_b128 v[170:173], v151
	ds_read_b128 v[174:177], v151 offset:1024
	ds_read_b128 v[178:181], v151 offset:2048
	ds_read_b128 v[182:185], v151 offset:3072
	ds_read_b128 v[186:189], v151 offset:4096
	ds_read_b128 v[190:193], v151 offset:5120
	ds_read_b128 v[194:197], v151 offset:6144
	ds_read_b128 v[198:201], v151 offset:7168
	global_load_lds_dwordx4 v[144:145], off
	v_lshl_add_u64 v[144:145], s[26:27], 0, v[138:139]
	s_add_i32 m0, s25, 0xe000
	s_nop 0
	global_load_lds_dwordx4 v[144:145], off
	s_waitcnt lgkmcnt(8)
	s_barrier
	s_waitcnt lgkmcnt(0)
	s_setprio 1
	s_waitcnt lgkmcnt(0)
	v_mfma_f32_16x16x32_bf16 v[124:127], v[154:157], v[170:173], v[124:127]
	v_mfma_f32_16x16x32_bf16 v[120:123], v[162:165], v[170:173], v[120:123]
	v_mfma_f32_16x16x32_bf16 v[108:111], v[154:157], v[178:181], v[108:111]
	v_mfma_f32_16x16x32_bf16 v[104:107], v[162:165], v[178:181], v[104:107]
	v_mfma_f32_16x16x32_bf16 v[92:95], v[154:157], v[186:189], v[92:95]
	v_mfma_f32_16x16x32_bf16 v[88:91], v[162:165], v[186:189], v[88:91]
	v_mfma_f32_16x16x32_bf16 v[76:79], v[154:157], v[194:197], v[76:79]
	v_mfma_f32_16x16x32_bf16 v[72:75], v[162:165], v[194:197], v[72:75]
	v_mfma_f32_16x16x32_bf16 v[124:127], v[158:161], v[174:177], v[124:127]
	v_mfma_f32_16x16x32_bf16 v[120:123], v[166:169], v[174:177], v[120:123]
	v_mfma_f32_16x16x32_bf16 v[108:111], v[158:161], v[182:185], v[108:111]
	v_mfma_f32_16x16x32_bf16 v[104:107], v[166:169], v[182:185], v[104:107]
	v_mfma_f32_16x16x32_bf16 v[92:95], v[158:161], v[190:193], v[92:95]
	v_mfma_f32_16x16x32_bf16 v[88:91], v[166:169], v[190:193], v[88:91]
	v_mfma_f32_16x16x32_bf16 v[76:79], v[158:161], v[198:201], v[76:79]
	v_mfma_f32_16x16x32_bf16 v[72:75], v[166:169], v[198:201], v[72:75]
	s_setprio 0
	s_barrier
	s_add_i32 s56, s40, s34
	v_lshl_add_u64 v[144:145], s[28:29], 0, v[132:133]
	s_mov_b32 m0, s56
	ds_read_b128 v[202:205], v152
	ds_read_b128 v[206:209], v152 offset:1024
	ds_read_b128 v[210:213], v152 offset:2048
	ds_read_b128 v[214:217], v152 offset:3072
	global_load_lds_dwordx4 v[144:145], off
	v_lshl_add_u64 v[218:219], s[28:29], 0, v[128:129]
	s_add_i32 m0, s56, 0x2000
	s_nop 0
	global_load_lds_dwordx4 v[218:219], off
	s_barrier
	s_waitcnt lgkmcnt(0)
	s_setprio 1
	s_waitcnt lgkmcnt(0)
	v_mfma_f32_16x16x32_bf16 v[116:119], v[202:205], v[170:173], v[116:119]
	v_mfma_f32_16x16x32_bf16 v[112:115], v[210:213], v[170:173], v[112:115]
	v_mfma_f32_16x16x32_bf16 v[100:103], v[202:205], v[178:181], v[100:103]
	v_mfma_f32_16x16x32_bf16 v[96:99], v[210:213], v[178:181], v[96:99]
	v_mfma_f32_16x16x32_bf16 v[84:87], v[202:205], v[186:189], v[84:87]
	v_mfma_f32_16x16x32_bf16 v[80:83], v[210:213], v[186:189], v[80:83]
	v_mfma_f32_16x16x32_bf16 v[68:71], v[202:205], v[194:197], v[68:71]
	v_mfma_f32_16x16x32_bf16 v[64:67], v[210:213], v[194:197], v[64:67]
	v_mfma_f32_16x16x32_bf16 v[116:119], v[206:209], v[174:177], v[116:119]
	v_mfma_f32_16x16x32_bf16 v[112:115], v[214:217], v[174:177], v[112:115]
	v_mfma_f32_16x16x32_bf16 v[100:103], v[206:209], v[182:185], v[100:103]
	v_mfma_f32_16x16x32_bf16 v[96:99], v[214:217], v[182:185], v[96:99]
	v_mfma_f32_16x16x32_bf16 v[84:87], v[206:209], v[190:193], v[84:87]
	v_mfma_f32_16x16x32_bf16 v[80:83], v[214:217], v[190:193], v[80:83]
	v_mfma_f32_16x16x32_bf16 v[68:71], v[206:209], v[198:201], v[68:71]
	v_mfma_f32_16x16x32_bf16 v[64:67], v[214:217], v[198:201], v[64:67]
	s_setprio 0
	s_mov_b32 m0, s25
	v_lshl_add_u64 v[220:221], s[30:31], 0, v[134:135]
	s_barrier
	ds_read_b128 v[170:173], v151 offset:16384
	ds_read_b128 v[174:177], v151 offset:17408
	ds_read_b128 v[178:181], v151 offset:18432
	ds_read_b128 v[182:185], v151 offset:19456
	ds_read_b128 v[186:189], v151 offset:20480
	ds_read_b128 v[190:193], v151 offset:21504
	ds_read_b128 v[194:197], v151 offset:22528
	ds_read_b128 v[198:201], v151 offset:23552
	global_load_lds_dwordx4 v[220:221], off
	v_lshl_add_u64 v[222:223], s[30:31], 0, v[130:131]
	s_mov_b32 m0, s35
	s_nop 0
	global_load_lds_dwordx4 v[222:223], off
	s_barrier
	s_waitcnt lgkmcnt(0)
	s_setprio 1
	s_waitcnt lgkmcnt(0)
	v_mfma_f32_16x16x32_bf16 v[60:63], v[154:157], v[170:173], v[60:63]
	v_mfma_f32_16x16x32_bf16 v[56:59], v[162:165], v[170:173], v[56:59]
	v_mfma_f32_16x16x32_bf16 v[44:47], v[154:157], v[178:181], v[44:47]
	v_mfma_f32_16x16x32_bf16 v[40:43], v[162:165], v[178:181], v[40:43]
	v_mfma_f32_16x16x32_bf16 v[28:31], v[154:157], v[186:189], v[28:31]
	v_mfma_f32_16x16x32_bf16 v[24:27], v[162:165], v[186:189], v[24:27]
	v_mfma_f32_16x16x32_bf16 v[12:15], v[154:157], v[194:197], v[12:15]
	v_mfma_f32_16x16x32_bf16 v[8:11], v[162:165], v[194:197], v[8:11]
	v_mfma_f32_16x16x32_bf16 v[60:63], v[158:161], v[174:177], v[60:63]
	v_mfma_f32_16x16x32_bf16 v[56:59], v[166:169], v[174:177], v[56:59]
	v_mfma_f32_16x16x32_bf16 v[44:47], v[158:161], v[182:185], v[44:47]
	v_mfma_f32_16x16x32_bf16 v[40:43], v[166:169], v[182:185], v[40:43]
	v_mfma_f32_16x16x32_bf16 v[28:31], v[158:161], v[190:193], v[28:31]
	v_mfma_f32_16x16x32_bf16 v[24:27], v[166:169], v[190:193], v[24:27]
	v_mfma_f32_16x16x32_bf16 v[12:15], v[158:161], v[198:201], v[12:15]
	v_mfma_f32_16x16x32_bf16 v[8:11], v[166:169], v[198:201], v[8:11]
	s_setprio 0
	s_barrier
; #define PG8_STAGE(bufoff, gbase, voff) do { _Pragma("unroll") for (int _i = 0; _i < 2; ++_i) \
;         __builtin_amdgcn_global_load_lds((const unsigned*)((const char*)(gbase) + (voff)[_i]), (LAS unsigned*)(lds + (bufoff) + ldsw + _i * 8192), 16, 0, 0); } while (0)
; #define PG8_LDA(dst, b, h) do { _Pragma("unroll") for (int m = 0; m < 4; ++m) _Pragma("unroll") for (int k = 0; k < 2; ++k) dst[m][k] = *(const LAS bf16x8*)(lds + PG8_SA(b, h) + aoff + m * 2048 + k * 1024); } while (0)
; #define PG8_LDB(dst, b, h) do { _Pragma("unroll") for (int n = 0; n < 2; ++n) _Pragma("unroll") for (int k = 0; k < 2; ++k) dst[n][k] = *(const LAS bf16x8*)(lds + PG8_SB(b, h) + boff + n * 2048 + k * 1024); } while (0)
; #define PG8_MMA(ai, bj, At, Bt) do { __builtin_amdgcn_s_setprio(1); _Pragma("unroll") for (int m = 0; m < 4; ++m) _Pragma("unroll") for (int n = 0; n < 2; ++n) _Pragma("unroll") for (int k = 0; k < 2; ++k) \
;         acc[ai][bj][m][n] = __builtin_amdgcn_mfma_f32_16x16x32_bf16(Bt[n][k], At[m][k], acc[ai][bj][m][n], 0, 0, 0); __builtin_amdgcn_s_setprio(0); } while (0)
; #define PG8_WAIT_V(n) asm volatile("s_waitcnt vmcnt(" #n ")" ::: "memory")
; #define PG8_WAIT_L(n) asm volatile("s_waitcnt lgkmcnt(" #n ")" ::: "memory")
; #define PG8_BAR __builtin_amdgcn_s_barrier()
; #define PG8_SCHED __builtin_amdgcn_sched_barrier(0)
; template <class Epi>
; __device__ __forceinline__ void gemm_phase(LAS unsigned char* lds, const Gemm g, const Order& S, const Epi& E, const int tid) {
;     ...
;             PG8_STAGE(PG8_SB(0, 1), b2 + hstepB, voffB);
;             PG8_WAIT_V(6); PG8_BAR; PG8_MMA(1, 1, At, B1); PG8_BAR;
;             PG8_LDB(B0, 1, 0); PG8_SCHED; PG8_LDA(At, 1, 0); PG8_STAGE(PG8_SA(0, 1), a2 + hstepA, voffA);
;             PG8_WAIT_L(8); PG8_BAR; PG8_WAIT_L(0); PG8_MMA(0, 0, At, B0); PG8_BAR; PG8_SCHED;
;             PG8_LDB(B1, 1, 1); PG8_STAGE(PG8_SB(1, 0), b3, voffB);
;             PG8_BAR; PG8_WAIT_L(0); PG8_MMA(0, 1, At, B1); PG8_BAR;
;             PG8_LDA(At, 1, 1); PG8_STAGE(PG8_SA(1, 0), a3, voffA);
;             PG8_BAR; PG8_WAIT_L(0); PG8_MMA(1, 0, At, B0); PG8_BAR; PG8_SCHED;
;             PG8_STAGE(PG8_SB(1, 1), b3 + hstepB, voffB);
	s_add_u32 s56, s28, 0x80000
	s_addc_u32 s57, s29, 0
	s_add_i32 s58, s41, s34
	v_lshl_add_u64 v[154:155], s[56:57], 0, v[132:133]
	s_mov_b32 m0, s58
	s_nop 0
	global_load_lds_dwordx4 v[154:155], off
	v_lshl_add_u64 v[154:155], s[56:57], 0, v[128:129]
	s_add_i32 m0, s58, 0x2000
	s_nop 0
	global_load_lds_dwordx4 v[154:155], off
	s_waitcnt vmcnt(6)
	s_barrier
	s_setprio 1
	v_mfma_f32_16x16x32_bf16 v[52:55], v[202:205], v[170:173], v[52:55]
	v_mfma_f32_16x16x32_bf16 v[48:51], v[210:213], v[170:173], v[48:51]
	v_mfma_f32_16x16x32_bf16 v[36:39], v[202:205], v[178:181], v[36:39]
	v_mfma_f32_16x16x32_bf16 v[32:35], v[210:213], v[178:181], v[32:35]
	v_mfma_f32_16x16x32_bf16 v[20:23], v[202:205], v[186:189], v[20:23]
	v_mfma_f32_16x16x32_bf16 v[16:19], v[210:213], v[186:189], v[16:19]
	v_mfma_f32_16x16x32_bf16 v[4:7], v[202:205], v[194:197], v[4:7]
	v_mfma_f32_16x16x32_bf16 v[0:3], v[210:213], v[194:197], v[0:3]
	v_mfma_f32_16x16x32_bf16 v[52:55], v[206:209], v[174:177], v[52:55]
	v_mfma_f32_16x16x32_bf16 v[48:51], v[214:217], v[174:177], v[48:51]
	v_mfma_f32_16x16x32_bf16 v[36:39], v[206:209], v[182:185], v[36:39]
	v_mfma_f32_16x16x32_bf16 v[32:35], v[214:217], v[182:185], v[32:35]
	v_mfma_f32_16x16x32_bf16 v[20:23], v[206:209], v[190:193], v[20:23]
	v_mfma_f32_16x16x32_bf16 v[16:19], v[214:217], v[190:193], v[16:19]
	v_mfma_f32_16x16x32_bf16 v[4:7], v[206:209], v[198:201], v[4:7]
	v_mfma_f32_16x16x32_bf16 v[0:3], v[214:217], v[198:201], v[0:3]
	s_setprio 0
	s_add_i32 s56, 0, 0x18000
	v_add_u32_e32 v153, s56, v147
	s_barrier
	ds_read_b128 v[154:157], v153
	ds_read_b128 v[158:161], v153 offset:1024
	ds_read_b128 v[162:165], v153 offset:2048
	ds_read_b128 v[166:169], v153 offset:3072
	s_add_u32 s30, s30, 0x80000
	s_addc_u32 s31, s31, 0
	s_mov_b32 m0, s36
	v_lshl_add_u64 v[202:203], s[30:31], 0, v[134:135]
	ds_read_b128 v[170:173], v151 offset:32768
	ds_read_b128 v[174:177], v151 offset:33792
	ds_read_b128 v[178:181], v151 offset:34816
	ds_read_b128 v[182:185], v151 offset:35840
	ds_read_b128 v[186:189], v151 offset:36864
	ds_read_b128 v[190:193], v151 offset:37888
	ds_read_b128 v[194:197], v151 offset:38912
	ds_read_b128 v[198:201], v151 offset:39936
	global_load_lds_dwordx4 v[202:203], off
	v_lshl_add_u64 v[202:203], s[30:31], 0, v[130:131]
	s_mov_b32 m0, s37
	s_nop 0
	global_load_lds_dwordx4 v[202:203], off
	s_waitcnt lgkmcnt(8)
	s_barrier
	s_waitcnt lgkmcnt(0)
	s_setprio 1
	s_waitcnt lgkmcnt(0)
	v_mfma_f32_16x16x32_bf16 v[124:127], v[154:157], v[170:173], v[124:127]
	v_mfma_f32_16x16x32_bf16 v[120:123], v[162:165], v[170:173], v[120:123]
	v_mfma_f32_16x16x32_bf16 v[108:111], v[154:157], v[178:181], v[108:111]
	v_mfma_f32_16x16x32_bf16 v[104:107], v[162:165], v[178:181], v[104:107]
	v_mfma_f32_16x16x32_bf16 v[92:95], v[154:157], v[186:189], v[92:95]
	v_mfma_f32_16x16x32_bf16 v[88:91], v[162:165], v[186:189], v[88:91]
	v_mfma_f32_16x16x32_bf16 v[76:79], v[154:157], v[194:197], v[76:79]
	v_mfma_f32_16x16x32_bf16 v[72:75], v[162:165], v[194:197], v[72:75]
	v_mfma_f32_16x16x32_bf16 v[124:127], v[158:161], v[174:177], v[124:127]
	v_mfma_f32_16x16x32_bf16 v[120:123], v[166:169], v[174:177], v[120:123]
	v_mfma_f32_16x16x32_bf16 v[108:111], v[158:161], v[182:185], v[108:111]
	v_mfma_f32_16x16x32_bf16 v[104:107], v[166:169], v[182:185], v[104:107]
	v_mfma_f32_16x16x32_bf16 v[92:95], v[158:161], v[190:193], v[92:95]
	v_mfma_f32_16x16x32_bf16 v[88:91], v[166:169], v[190:193], v[88:91]
	v_mfma_f32_16x16x32_bf16 v[76:79], v[158:161], v[198:201], v[76:79]
	v_mfma_f32_16x16x32_bf16 v[72:75], v[166:169], v[198:201], v[72:75]
	s_setprio 0
	s_barrier
	s_add_i32 s30, 0, 0x1c000
	s_add_i32 s31, s56, s34
	v_add_u32_e32 v153, s30, v147
	v_lshl_add_u64 v[144:145], v[144:145], 0, s[4:5]
	s_mov_b32 m0, s31
	ds_read_b128 v[202:205], v153
	ds_read_b128 v[206:209], v153 offset:1024
	ds_read_b128 v[210:213], v153 offset:2048
	ds_read_b128 v[214:217], v153 offset:3072
	global_load_lds_dwordx4 v[144:145], off
	v_lshl_add_u64 v[144:145], v[218:219], 0, s[4:5]
	s_add_i32 m0, s31, 0x2000
	s_nop 0
	global_load_lds_dwordx4 v[144:145], off
	s_barrier
	s_waitcnt lgkmcnt(0)
	s_setprio 1
	s_waitcnt lgkmcnt(0)
	v_mfma_f32_16x16x32_bf16 v[116:119], v[202:205], v[170:173], v[116:119]
	v_mfma_f32_16x16x32_bf16 v[112:115], v[210:213], v[170:173], v[112:115]
	v_mfma_f32_16x16x32_bf16 v[100:103], v[202:205], v[178:181], v[100:103]
	v_mfma_f32_16x16x32_bf16 v[96:99], v[210:213], v[178:181], v[96:99]
	v_mfma_f32_16x16x32_bf16 v[84:87], v[202:205], v[186:189], v[84:87]
	v_mfma_f32_16x16x32_bf16 v[80:83], v[210:213], v[186:189], v[80:83]
	v_mfma_f32_16x16x32_bf16 v[68:71], v[202:205], v[194:197], v[68:71]
	v_mfma_f32_16x16x32_bf16 v[64:67], v[210:213], v[194:197], v[64:67]
	v_mfma_f32_16x16x32_bf16 v[116:119], v[206:209], v[174:177], v[116:119]
	v_mfma_f32_16x16x32_bf16 v[112:115], v[214:217], v[174:177], v[112:115]
	v_mfma_f32_16x16x32_bf16 v[100:103], v[206:209], v[182:185], v[100:103]
	v_mfma_f32_16x16x32_bf16 v[96:99], v[214:217], v[182:185], v[96:99]
	v_mfma_f32_16x16x32_bf16 v[84:87], v[206:209], v[190:193], v[84:87]
	v_mfma_f32_16x16x32_bf16 v[80:83], v[214:217], v[190:193], v[80:83]
	v_mfma_f32_16x16x32_bf16 v[68:71], v[206:209], v[198:201], v[68:71]
	v_mfma_f32_16x16x32_bf16 v[64:67], v[214:217], v[198:201], v[64:67]
	s_setprio 0
	s_mov_b32 m0, s38
	v_lshl_add_u64 v[144:145], v[220:221], 0, s[4:5]
	s_barrier
	ds_read_b128 v[170:173], v151 offset:49152
	ds_read_b128 v[174:177], v151 offset:50176
	ds_read_b128 v[178:181], v151 offset:51200
	ds_read_b128 v[182:185], v151 offset:52224
	ds_read_b128 v[186:189], v151 offset:53248
	ds_read_b128 v[190:193], v151 offset:54272
	ds_read_b128 v[194:197], v151 offset:55296
	ds_read_b128 v[198:201], v151 offset:56320
	global_load_lds_dwordx4 v[144:145], off
	v_lshl_add_u64 v[144:145], v[222:223], 0, s[4:5]
	s_mov_b32 m0, s39
	s_nop 0
	global_load_lds_dwordx4 v[144:145], off
	s_barrier
; #define PG8_STAGE(bufoff, gbase, voff) do { _Pragma("unroll") for (int _i = 0; _i < 2; ++_i) \
;         __builtin_amdgcn_global_load_lds((const unsigned*)((const char*)(gbase) + (voff)[_i]), (LAS unsigned*)(lds + (bufoff) + ldsw + _i * 8192), 16, 0, 0); } while (0)
; #define PG8_MMA(ai, bj, At, Bt) do { __builtin_amdgcn_s_setprio(1); _Pragma("unroll") for (int m = 0; m < 4; ++m) _Pragma("unroll") for (int n = 0; n < 2; ++n) _Pragma("unroll") for (int k = 0; k < 2; ++k) \
;         acc[ai][bj][m][n] = __builtin_amdgcn_mfma_f32_16x16x32_bf16(Bt[n][k], At[m][k], acc[ai][bj][m][n], 0, 0, 0); __builtin_amdgcn_s_setprio(0); } while (0)
; #define PG8_WAIT_V(n) asm volatile("s_waitcnt vmcnt(" #n ")" ::: "memory")
; #define PG8_WAIT_L(n) asm volatile("s_waitcnt lgkmcnt(" #n ")" ::: "memory")
; #define PG8_BAR __builtin_amdgcn_s_barrier()
; #define PG8_SCHED __builtin_amdgcn_sched_barrier(0)
; template <class Epi>
; __device__ __forceinline__ void gemm_phase(LAS unsigned char* lds, const Gemm g, const Order& S, const Epi& E, const int tid) {
;     ...
;             PG8_BAR; PG8_WAIT_L(0); PG8_MMA(1, 0, At, B0); PG8_BAR; PG8_SCHED;
;             PG8_STAGE(PG8_SB(1, 1), b3 + hstepB, voffB);
;             PG8_WAIT_V(6); PG8_BAR; PG8_MMA(1, 1, At, B1); PG8_BAR;
;         }
;     __device__ __forceinline__ void operator()(const f32x4 (&acc)[2][2][4][2], const Unit& u, int wr, int wc, int fr, int fq) const {
;         const int row0 = u.pm * BM + wr * 64 + fr, col0 = u.pn * BM + wc * 32 + 8 * fq;
; #pragma unroll
;         for (int ai = 0; ai < 2; ++ai)
; #pragma unroll
;             for (int m = 0; m < 4; ++m) { bf16_t* rowp = O + (size_t)(row0 + ai * HALF + m * 16) * ldc + col0;
;                 float rs = 1.0f; if (RS) rs = rt[u.i * 256 + wr * 64 + fr + ai * HALF + m * 16];
; #pragma unroll
;                 for (int bj = 0; bj < 2; ++bj) { f32x4 v0 = acc[ai][bj][m][0], v1 = acc[ai][bj][m][1];
;                     if (RS) { v0 *= rs; v1 *= rs; }
;                     if (ACT == 1) {
; #pragma unroll
;                         for (int j = 0; j < 4; ++j) { const float a = fmaxf(v0[j], 0.f), b = fmaxf(v1[j], 0.f); v0[j] = a * a; v1[j] = b * b; } }
;                     u32x4 w; w.x = pk2(v0[0], v0[1]); w.y = pk2(v0[2], v0[3]); w.z = pk2(v1[0], v1[1]); w.w = pk2(v1[2], v1[3]);
;                     *(u32x4*)(rowp + bj * HALF) = w; } }
	s_waitcnt lgkmcnt(0)
	s_setprio 1
	s_waitcnt lgkmcnt(0)
	v_mfma_f32_16x16x32_bf16 v[60:63], v[154:157], v[170:173], v[60:63]
	v_mfma_f32_16x16x32_bf16 v[56:59], v[162:165], v[170:173], v[56:59]
	v_mfma_f32_16x16x32_bf16 v[44:47], v[154:157], v[178:181], v[44:47]
	v_mfma_f32_16x16x32_bf16 v[40:43], v[162:165], v[178:181], v[40:43]
	v_mfma_f32_16x16x32_bf16 v[28:31], v[154:157], v[186:189], v[28:31]
	v_mfma_f32_16x16x32_bf16 v[24:27], v[162:165], v[186:189], v[24:27]
	v_mfma_f32_16x16x32_bf16 v[12:15], v[154:157], v[194:197], v[12:15]
	v_mfma_f32_16x16x32_bf16 v[8:11], v[162:165], v[194:197], v[8:11]
	v_mfma_f32_16x16x32_bf16 v[60:63], v[158:161], v[174:177], v[60:63]
	v_mfma_f32_16x16x32_bf16 v[56:59], v[166:169], v[174:177], v[56:59]
	v_mfma_f32_16x16x32_bf16 v[44:47], v[158:161], v[182:185], v[44:47]
	v_mfma_f32_16x16x32_bf16 v[40:43], v[166:169], v[182:185], v[40:43]
	v_mfma_f32_16x16x32_bf16 v[28:31], v[158:161], v[190:193], v[28:31]
	v_mfma_f32_16x16x32_bf16 v[24:27], v[166:169], v[190:193], v[24:27]
	v_mfma_f32_16x16x32_bf16 v[12:15], v[158:161], v[198:201], v[12:15]
	v_mfma_f32_16x16x32_bf16 v[8:11], v[166:169], v[198:201], v[8:11]
	s_setprio 0
	s_barrier
	s_add_u32 s28, s28, 0x80080
	s_addc_u32 s29, s29, 0
	s_add_i32 s30, s30, s34
	v_lshl_add_u64 v[144:145], s[28:29], 0, v[132:133]
	s_mov_b32 m0, s30
	s_nop 0
	global_load_lds_dwordx4 v[144:145], off
	v_lshl_add_u64 v[144:145], s[28:29], 0, v[128:129]
	s_add_i32 m0, s30, 0x2000
	s_nop 0
	global_load_lds_dwordx4 v[144:145], off
	s_waitcnt vmcnt(6)
	s_barrier
	s_setprio 1
	v_mfma_f32_16x16x32_bf16 v[52:55], v[202:205], v[170:173], v[52:55]
	v_mfma_f32_16x16x32_bf16 v[48:51], v[210:213], v[170:173], v[48:51]
	v_mfma_f32_16x16x32_bf16 v[36:39], v[202:205], v[178:181], v[36:39]
	v_mfma_f32_16x16x32_bf16 v[32:35], v[210:213], v[178:181], v[32:35]
	v_mfma_f32_16x16x32_bf16 v[20:23], v[202:205], v[186:189], v[20:23]
	v_mfma_f32_16x16x32_bf16 v[16:19], v[210:213], v[186:189], v[16:19]
	v_mfma_f32_16x16x32_bf16 v[4:7], v[202:205], v[194:197], v[4:7]
	v_mfma_f32_16x16x32_bf16 v[0:3], v[210:213], v[194:197], v[0:3]
	v_mfma_f32_16x16x32_bf16 v[52:55], v[206:209], v[174:177], v[52:55]
	v_mfma_f32_16x16x32_bf16 v[48:51], v[214:217], v[174:177], v[48:51]
	v_mfma_f32_16x16x32_bf16 v[36:39], v[206:209], v[182:185], v[36:39]
	v_mfma_f32_16x16x32_bf16 v[32:35], v[214:217], v[182:185], v[32:35]
	v_mfma_f32_16x16x32_bf16 v[20:23], v[206:209], v[190:193], v[20:23]
	v_mfma_f32_16x16x32_bf16 v[16:19], v[214:217], v[190:193], v[16:19]
	v_mfma_f32_16x16x32_bf16 v[4:7], v[206:209], v[198:201], v[4:7]
	v_mfma_f32_16x16x32_bf16 v[0:3], v[214:217], v[198:201], v[0:3]
	s_setprio 0
	s_add_i32 s55, s55, 2
	s_add_u32 s26, s26, 0x100
	s_addc_u32 s27, s27, 0
	s_add_u32 s52, s52, 0x100
	s_addc_u32 s53, s53, 0
	s_cmp_gt_u32 s55, 29
	s_barrier
	s_cbranch_scc0 .LBB0_912
	v_lshl_add_u32 v153, s48, 10, v148
	ds_read2_b32 v[156:157], v153 offset1:16
	v_lshl_add_u32 v154, s24, 8, v146
	v_lshl_or_b32 v144, s49, 8, v149
	v_ashrrev_i32_e32 v155, 31, v154
	v_ashrrev_i32_e32 v145, 31, v144
	s_waitcnt lgkmcnt(0)
	v_pk_mul_f32 v[122:123], v[122:123], v[156:157] op_sel_hi:[1,0]
	v_pk_mul_f32 v[120:121], v[120:121], v[156:157] op_sel_hi:[1,0]
	v_pk_mul_f32 v[126:127], v[126:127], v[156:157] op_sel_hi:[1,0]
	v_pk_mul_f32 v[124:125], v[124:125], v[156:157] op_sel_hi:[1,0]
	v_max_f32_e32 v120, 0, v120
	v_max_f32_e32 v121, 0, v121
	v_max_f32_e32 v122, 0, v122
	v_lshlrev_b64 v[158:159], 14, v[154:155]
	v_max_f32_e32 v124, 0, v124
	v_mul_f32_e32 v155, v120, v120
	v_max_f32_e32 v120, 0, v125
	v_mul_f32_e32 v125, v121, v121
	v_max_f32_e32 v121, 0, v126
	v_mul_f32_e32 v126, v122, v122
	v_max_f32_e32 v122, 0, v127
	v_max_f32_e32 v123, 0, v123
	v_lshl_add_u64 v[158:159], s[72:73], 0, v[158:159]
	v_lshlrev_b64 v[160:161], 1, v[144:145]
	v_mul_f32_e32 v124, v124, v124
	v_mul_f32_e32 v120, v120, v120
	v_mul_f32_e32 v121, v121, v121
	v_mul_f32_e32 v122, v122, v122
	v_mul_f32_e32 v123, v123, v123
	v_pk_mul_f32 v[114:115], v[114:115], v[156:157] op_sel_hi:[1,0]
	v_pk_mul_f32 v[112:113], v[112:113], v[156:157] op_sel_hi:[1,0]
	v_lshl_add_u64 v[144:145], v[158:159], 0, v[160:161]
	v_cvt_pk_bf16_f32 v120, v124, v120
	v_cvt_pk_bf16_f32 v121, v121, v122
	v_cvt_pk_bf16_f32 v122, v155, v125
	v_cvt_pk_bf16_f32 v123, v126, v123
	v_pk_mul_f32 v[118:119], v[118:119], v[156:157] op_sel_hi:[1,0]
	v_pk_mul_f32 v[116:117], v[116:117], v[156:157] op_sel_hi:[1,0]
	v_max_f32_e32 v112, 0, v112
	v_max_f32_e32 v113, 0, v113
	v_max_f32_e32 v114, 0, v114
	global_store_dwordx4 v[144:145], v[120:123], off nt
	v_max_f32_e32 v116, 0, v116
	v_max_f32_e32 v115, 0, v115
	v_mul_f32_e32 v120, v112, v112
	v_max_f32_e32 v112, 0, v117
	v_mul_f32_e32 v117, v113, v113
	v_max_f32_e32 v113, 0, v118
	v_mul_f32_e32 v118, v114, v114
	v_max_f32_e32 v114, 0, v119
	v_mul_f32_e32 v116, v116, v116
	v_mul_f32_e32 v112, v112, v112
	v_mul_f32_e32 v113, v113, v113
	v_mul_f32_e32 v114, v114, v114
	v_mul_f32_e32 v115, v115, v115
	v_cvt_pk_bf16_f32 v112, v116, v112
	v_cvt_pk_bf16_f32 v113, v113, v114
	v_cvt_pk_bf16_f32 v114, v120, v117
	v_cvt_pk_bf16_f32 v115, v118, v115
	global_store_dwordx4 v[144:145], v[112:115], off offset:256 nt
	s_mov_b32 s48, s47
	s_mov_b32 s49, s16
	v_mov_b32_e32 v114, v157
	v_or_b32_e32 v112, 16, v154
	v_pk_mul_f32 v[106:107], v[106:107], v[114:115] op_sel_hi:[1,0]
	v_pk_mul_f32 v[104:105], v[104:105], v[114:115] op_sel_hi:[1,0]
	v_ashrrev_i32_e32 v113, 31, v112
	v_pk_mul_f32 v[110:111], v[110:111], v[114:115] op_sel_hi:[1,0]
	v_pk_mul_f32 v[108:109], v[108:109], v[114:115] op_sel_hi:[1,0]
	v_max_f32_e32 v104, 0, v104
	v_max_f32_e32 v105, 0, v105
	v_max_f32_e32 v106, 0, v106
;     __device__ __forceinline__ void operator()(const f32x4 (&acc)[2][2][4][2], const Unit& u, int wr, int wc, int fr, int fq) const {
;         const int row0 = u.pm * BM + wr * 64 + fr, col0 = u.pn * BM + wc * 32 + 8 * fq;
; #pragma unroll
;         for (int ai = 0; ai < 2; ++ai)
; #pragma unroll
;             for (int m = 0; m < 4; ++m) { bf16_t* rowp = O + (size_t)(row0 + ai * HALF + m * 16) * ldc + col0;
;                 float rs = 1.0f; if (RS) rs = rt[u.i * 256 + wr * 64 + fr + ai * HALF + m * 16];
; #pragma unroll
;                 for (int bj = 0; bj < 2; ++bj) { f32x4 v0 = acc[ai][bj][m][0], v1 = acc[ai][bj][m][1];
;                     if (RS) { v0 *= rs; v1 *= rs; }
;                     if (ACT == 1) {
; #pragma unroll
;                         for (int j = 0; j < 4; ++j) { const float a = fmaxf(v0[j], 0.f), b = fmaxf(v1[j], 0.f); v0[j] = a * a; v1[j] = b * b; } }
;                     u32x4 w; w.x = pk2(v0[0], v0[1]); w.y = pk2(v0[2], v0[3]); w.z = pk2(v1[0], v1[1]); w.w = pk2(v1[2], v1[3]);
;                     *(u32x4*)(rowp + bj * HALF) = w; } }
	v_lshlrev_b64 v[112:113], 14, v[112:113]
	v_max_f32_e32 v108, 0, v108
	v_mul_f32_e32 v115, v104, v104
	v_max_f32_e32 v104, 0, v109
	v_mul_f32_e32 v109, v105, v105
	v_max_f32_e32 v105, 0, v110
	v_mul_f32_e32 v110, v106, v106
	v_max_f32_e32 v106, 0, v111
	v_max_f32_e32 v107, 0, v107
	v_lshl_add_u64 v[112:113], s[72:73], 0, v[112:113]
	v_mul_f32_e32 v108, v108, v108
	v_mul_f32_e32 v104, v104, v104
	v_mul_f32_e32 v105, v105, v105
	v_mul_f32_e32 v106, v106, v106
	v_mul_f32_e32 v107, v107, v107
	v_pk_mul_f32 v[98:99], v[98:99], v[114:115] op_sel_hi:[1,0]
	v_pk_mul_f32 v[96:97], v[96:97], v[114:115] op_sel_hi:[1,0]
	v_lshl_add_u64 v[112:113], v[112:113], 0, v[160:161]
	v_cvt_pk_bf16_f32 v104, v108, v104
	v_cvt_pk_bf16_f32 v105, v105, v106
	v_cvt_pk_bf16_f32 v106, v115, v109
	v_cvt_pk_bf16_f32 v107, v110, v107
	v_pk_mul_f32 v[102:103], v[102:103], v[114:115] op_sel_hi:[1,0]
	v_pk_mul_f32 v[100:101], v[100:101], v[114:115] op_sel_hi:[1,0]
	v_max_f32_e32 v96, 0, v96
	v_max_f32_e32 v97, 0, v97
	v_max_f32_e32 v98, 0, v98
	global_store_dwordx4 v[112:113], v[104:107], off nt
	v_max_f32_e32 v100, 0, v100
	v_max_f32_e32 v99, 0, v99
	v_mul_f32_e32 v104, v96, v96
	v_max_f32_e32 v96, 0, v101
	v_mul_f32_e32 v101, v97, v97
	v_max_f32_e32 v97, 0, v102
	v_mul_f32_e32 v102, v98, v98
	v_max_f32_e32 v98, 0, v103
	v_mul_f32_e32 v100, v100, v100
	v_mul_f32_e32 v96, v96, v96
	v_mul_f32_e32 v97, v97, v97
	v_mul_f32_e32 v98, v98, v98
	v_mul_f32_e32 v99, v99, v99
	v_cvt_pk_bf16_f32 v96, v100, v96
	v_cvt_pk_bf16_f32 v97, v97, v98
	v_cvt_pk_bf16_f32 v98, v104, v101
	v_cvt_pk_bf16_f32 v99, v102, v99
	global_store_dwordx4 v[112:113], v[96:99], off offset:256 nt
	ds_read2_b32 v[98:99], v153 offset0:32 offset1:48
	s_mov_b32 s24, s14
	v_or_b32_e32 v96, 32, v154
	v_ashrrev_i32_e32 v97, 31, v96
	v_lshlrev_b64 v[96:97], 14, v[96:97]
	s_waitcnt lgkmcnt(0)
	v_pk_mul_f32 v[90:91], v[90:91], v[98:99] op_sel_hi:[1,0]
	v_pk_mul_f32 v[88:89], v[88:89], v[98:99] op_sel_hi:[1,0]
	v_pk_mul_f32 v[94:95], v[94:95], v[98:99] op_sel_hi:[1,0]
	v_pk_mul_f32 v[92:93], v[92:93], v[98:99] op_sel_hi:[1,0]
	v_max_f32_e32 v88, 0, v88
	v_max_f32_e32 v89, 0, v89
	v_max_f32_e32 v90, 0, v90
	v_max_f32_e32 v92, 0, v92
	v_mul_f32_e32 v100, v88, v88
	v_max_f32_e32 v88, 0, v93
	v_mul_f32_e32 v93, v89, v89
	v_max_f32_e32 v89, 0, v94
	v_mul_f32_e32 v94, v90, v90
	v_max_f32_e32 v90, 0, v95
	v_max_f32_e32 v91, 0, v91
	v_lshl_add_u64 v[96:97], s[72:73], 0, v[96:97]
	v_mul_f32_e32 v92, v92, v92
	v_mul_f32_e32 v88, v88, v88
	v_mul_f32_e32 v89, v89, v89
	v_mul_f32_e32 v90, v90, v90
	v_mul_f32_e32 v91, v91, v91
	v_pk_mul_f32 v[82:83], v[82:83], v[98:99] op_sel_hi:[1,0]
	v_pk_mul_f32 v[80:81], v[80:81], v[98:99] op_sel_hi:[1,0]
	v_lshl_add_u64 v[96:97], v[96:97], 0, v[160:161]
	v_cvt_pk_bf16_f32 v88, v92, v88
	v_cvt_pk_bf16_f32 v89, v89, v90
	v_cvt_pk_bf16_f32 v90, v100, v93
	v_cvt_pk_bf16_f32 v91, v94, v91
	v_pk_mul_f32 v[86:87], v[86:87], v[98:99] op_sel_hi:[1,0]
	v_pk_mul_f32 v[84:85], v[84:85], v[98:99] op_sel_hi:[1,0]
	v_max_f32_e32 v80, 0, v80
	v_max_f32_e32 v81, 0, v81
	v_max_f32_e32 v82, 0, v82
	global_store_dwordx4 v[96:97], v[88:91], off nt
	v_max_f32_e32 v84, 0, v84
	v_max_f32_e32 v83, 0, v83
	v_mul_f32_e32 v88, v80, v80
	v_max_f32_e32 v80, 0, v85
	v_mul_f32_e32 v85, v81, v81
	v_max_f32_e32 v81, 0, v86
	v_mul_f32_e32 v86, v82, v82
	v_max_f32_e32 v82, 0, v87
	v_mul_f32_e32 v84, v84, v84
	v_mul_f32_e32 v80, v80, v80
	v_mul_f32_e32 v81, v81, v81
	v_mul_f32_e32 v82, v82, v82
	v_mul_f32_e32 v83, v83, v83
	v_cvt_pk_bf16_f32 v80, v84, v80
	v_cvt_pk_bf16_f32 v81, v81, v82
	v_cvt_pk_bf16_f32 v82, v88, v85
	v_cvt_pk_bf16_f32 v83, v86, v83
	global_store_dwordx4 v[96:97], v[80:83], off offset:256 nt
	s_mov_b64 s[28:29], s[20:21]
	s_mov_b64 s[26:27], s[18:19]
	v_mov_b32_e32 v82, v99
	v_or_b32_e32 v80, 48, v154
	v_pk_mul_f32 v[74:75], v[74:75], v[82:83] op_sel_hi:[1,0]
	v_pk_mul_f32 v[72:73], v[72:73], v[82:83] op_sel_hi:[1,0]
	v_ashrrev_i32_e32 v81, 31, v80
	v_pk_mul_f32 v[78:79], v[78:79], v[82:83] op_sel_hi:[1,0]
	v_pk_mul_f32 v[76:77], v[76:77], v[82:83] op_sel_hi:[1,0]
	v_max_f32_e32 v72, 0, v72
	v_max_f32_e32 v73, 0, v73
	v_max_f32_e32 v74, 0, v74
	v_lshlrev_b64 v[80:81], 14, v[80:81]
	v_max_f32_e32 v76, 0, v76
	v_mul_f32_e32 v83, v72, v72
	v_max_f32_e32 v72, 0, v77
	v_mul_f32_e32 v77, v73, v73
	v_max_f32_e32 v73, 0, v78
	v_mul_f32_e32 v78, v74, v74
	v_max_f32_e32 v74, 0, v79
	v_max_f32_e32 v75, 0, v75
	v_lshl_add_u64 v[80:81], s[72:73], 0, v[80:81]
	v_mul_f32_e32 v76, v76, v76
	v_mul_f32_e32 v72, v72, v72
	v_mul_f32_e32 v73, v73, v73
	v_mul_f32_e32 v74, v74, v74
	v_mul_f32_e32 v75, v75, v75
	v_pk_mul_f32 v[64:65], v[64:65], v[82:83] op_sel_hi:[1,0]
	v_lshl_add_u64 v[80:81], v[80:81], 0, v[160:161]
	v_cvt_pk_bf16_f32 v72, v76, v72
	v_cvt_pk_bf16_f32 v73, v73, v74
	v_cvt_pk_bf16_f32 v74, v83, v77
	v_cvt_pk_bf16_f32 v75, v78, v75
	v_pk_mul_f32 v[68:69], v[68:69], v[82:83] op_sel_hi:[1,0]
	v_max_f32_e32 v64, 0, v64
	global_store_dwordx4 v[80:81], v[72:75], off nt
	v_max_f32_e32 v68, 0, v68
	v_mul_f32_e32 v68, v68, v68
	v_mul_f32_e32 v72, v64, v64
	v_max_f32_e32 v64, 0, v69
	v_mul_f32_e32 v64, v64, v64
	v_cvt_pk_bf16_f32 v64, v68, v64
	ds_read2_b32 v[68:69], v153 offset0:128 offset1:144
	v_pk_mul_f32 v[66:67], v[66:67], v[82:83] op_sel_hi:[1,0]
	v_pk_mul_f32 v[70:71], v[70:71], v[82:83] op_sel_hi:[1,0]
	v_max_f32_e32 v65, 0, v65
	v_max_f32_e32 v66, 0, v66
	v_mul_f32_e32 v73, v65, v65
	v_max_f32_e32 v65, 0, v70
	v_mul_f32_e32 v70, v66, v66
	v_max_f32_e32 v66, 0, v71
	v_max_f32_e32 v67, 0, v67
	v_mul_f32_e32 v65, v65, v65
	v_mul_f32_e32 v66, v66, v66
	v_mul_f32_e32 v67, v67, v67
	s_waitcnt lgkmcnt(0)
;     __device__ __forceinline__ void operator()(const f32x4 (&acc)[2][2][4][2], const Unit& u, int wr, int wc, int fr, int fq) const {
;     ...
;             for (int m = 0; m < 4; ++m) { bf16_t* rowp = O + (size_t)(row0 + ai * HALF + m * 16) * ldc + col0;
;                 float rs = 1.0f; if (RS) rs = rt[u.i * 256 + wr * 64 + fr + ai * HALF + m * 16];
; #pragma unroll
;                 for (int bj = 0; bj < 2; ++bj) { f32x4 v0 = acc[ai][bj][m][0], v1 = acc[ai][bj][m][1];
;                     if (RS) { v0 *= rs; v1 *= rs; }
;                     if (ACT == 1) {
; #pragma unroll
;                         for (int j = 0; j < 4; ++j) { const float a = fmaxf(v0[j], 0.f), b = fmaxf(v1[j], 0.f); v0[j] = a * a; v1[j] = b * b; } }
;                     u32x4 w; w.x = pk2(v0[0], v0[1]); w.y = pk2(v0[2], v0[3]); w.z = pk2(v1[0], v1[1]); w.w = pk2(v1[2], v1[3]);
;                     *(u32x4*)(rowp + bj * HALF) = w; } }
	v_pk_mul_f32 v[56:57], v[56:57], v[68:69] op_sel_hi:[1,0]
	v_cvt_pk_bf16_f32 v65, v65, v66
	v_cvt_pk_bf16_f32 v66, v72, v73
	v_cvt_pk_bf16_f32 v67, v70, v67
	v_pk_mul_f32 v[60:61], v[60:61], v[68:69] op_sel_hi:[1,0]
	v_pk_mul_f32 v[58:59], v[58:59], v[68:69] op_sel_hi:[1,0]
	v_max_f32_e32 v56, 0, v56
	global_store_dwordx4 v[80:81], v[64:67], off offset:256 nt
	v_pk_mul_f32 v[62:63], v[62:63], v[68:69] op_sel_hi:[1,0]
	v_max_f32_e32 v60, 0, v60
	v_mul_f32_e32 v66, v56, v56
	v_max_f32_e32 v56, 0, v61
	v_max_f32_e32 v57, 0, v57
	v_max_f32_e32 v58, 0, v58
	v_mul_f32_e32 v60, v60, v60
	v_mul_f32_e32 v56, v56, v56
	v_mul_f32_e32 v61, v57, v57
	v_max_f32_e32 v57, 0, v62
	v_mul_f32_e32 v62, v58, v58
	v_max_f32_e32 v58, 0, v63
	v_max_f32_e32 v59, 0, v59
	v_mul_f32_e32 v57, v57, v57
	v_mul_f32_e32 v58, v58, v58
	v_mul_f32_e32 v59, v59, v59
	v_cvt_pk_bf16_f32 v56, v60, v56
	v_add_co_u32_e32 v60, vcc, s42, v144
	v_pk_mul_f32 v[50:51], v[50:51], v[68:69] op_sel_hi:[1,0]
	v_pk_mul_f32 v[48:49], v[48:49], v[68:69] op_sel_hi:[1,0]
	v_cvt_pk_bf16_f32 v57, v57, v58
	v_cvt_pk_bf16_f32 v58, v66, v61
	v_cvt_pk_bf16_f32 v59, v62, v59
	v_addc_co_u32_e32 v61, vcc, 0, v145, vcc
	v_pk_mul_f32 v[54:55], v[54:55], v[68:69] op_sel_hi:[1,0]
	v_pk_mul_f32 v[52:53], v[52:53], v[68:69] op_sel_hi:[1,0]
	v_max_f32_e32 v48, 0, v48
	v_max_f32_e32 v49, 0, v49
	v_max_f32_e32 v50, 0, v50
	global_store_dwordx4 v[60:61], v[56:59], off nt
	v_max_f32_e32 v52, 0, v52
	v_max_f32_e32 v51, 0, v51
	v_mul_f32_e32 v56, v48, v48
	v_max_f32_e32 v48, 0, v53
	v_mul_f32_e32 v53, v49, v49
	v_max_f32_e32 v49, 0, v54
	v_mul_f32_e32 v54, v50, v50
	v_max_f32_e32 v50, 0, v55
	v_mul_f32_e32 v52, v52, v52
	v_mul_f32_e32 v48, v48, v48
	v_mul_f32_e32 v49, v49, v49
	v_mul_f32_e32 v50, v50, v50
	v_mul_f32_e32 v51, v51, v51
	v_lshl_add_u64 v[64:65], v[144:145], 0, s[6:7]
	v_cvt_pk_bf16_f32 v48, v52, v48
	v_cvt_pk_bf16_f32 v49, v49, v50
	v_cvt_pk_bf16_f32 v50, v56, v53
	v_cvt_pk_bf16_f32 v51, v54, v51
	global_store_dwordx4 v[64:65], v[48:51], off offset:256 nt
	s_nop 1
	v_mov_b32_e32 v50, v69
	v_pk_mul_f32 v[40:41], v[40:41], v[50:51] op_sel_hi:[1,0]
	v_pk_mul_f32 v[44:45], v[44:45], v[50:51] op_sel_hi:[1,0]
	v_pk_mul_f32 v[42:43], v[42:43], v[50:51] op_sel_hi:[1,0]
	v_max_f32_e32 v40, 0, v40
	v_pk_mul_f32 v[46:47], v[46:47], v[50:51] op_sel_hi:[1,0]
	v_max_f32_e32 v44, 0, v44
	v_mul_f32_e32 v51, v40, v40
	v_max_f32_e32 v40, 0, v45
	v_max_f32_e32 v41, 0, v41
	v_max_f32_e32 v42, 0, v42
	v_mul_f32_e32 v44, v44, v44
	v_mul_f32_e32 v40, v40, v40
	v_mul_f32_e32 v45, v41, v41
	v_max_f32_e32 v41, 0, v46
	v_mul_f32_e32 v46, v42, v42
	v_max_f32_e32 v42, 0, v47
	v_max_f32_e32 v43, 0, v43
	v_mul_f32_e32 v41, v41, v41
	v_mul_f32_e32 v42, v42, v42
	v_mul_f32_e32 v43, v43, v43
	v_cvt_pk_bf16_f32 v40, v44, v40
	v_add_co_u32_e32 v44, vcc, s43, v144
	v_pk_mul_f32 v[32:33], v[32:33], v[50:51] op_sel_hi:[1,0]
	v_cvt_pk_bf16_f32 v41, v41, v42
	v_cvt_pk_bf16_f32 v42, v51, v45
	v_cvt_pk_bf16_f32 v43, v46, v43
	v_addc_co_u32_e32 v45, vcc, 0, v145, vcc
	v_pk_mul_f32 v[36:37], v[36:37], v[50:51] op_sel_hi:[1,0]
	v_max_f32_e32 v32, 0, v32
	global_store_dwordx4 v[44:45], v[40:43], off nt
	v_max_f32_e32 v36, 0, v36
	v_mul_f32_e32 v36, v36, v36
	v_mul_f32_e32 v40, v32, v32
	v_max_f32_e32 v32, 0, v37
	v_mul_f32_e32 v32, v32, v32
	v_cvt_pk_bf16_f32 v32, v36, v32
	ds_read2_b32 v[36:37], v153 offset0:160 offset1:176
	v_pk_mul_f32 v[34:35], v[34:35], v[50:51] op_sel_hi:[1,0]
	v_pk_mul_f32 v[38:39], v[38:39], v[50:51] op_sel_hi:[1,0]
	v_max_f32_e32 v33, 0, v33
	v_max_f32_e32 v34, 0, v34
	v_mul_f32_e32 v41, v33, v33
	v_max_f32_e32 v33, 0, v38
	v_mul_f32_e32 v38, v34, v34
	v_max_f32_e32 v34, 0, v39
	v_max_f32_e32 v35, 0, v35
	v_mul_f32_e32 v33, v33, v33
	v_mul_f32_e32 v34, v34, v34
	v_mul_f32_e32 v35, v35, v35
	s_waitcnt lgkmcnt(0)
; #define PG8_WAIT_V(n) asm volatile("s_waitcnt vmcnt(" #n ")" ::: "memory")
; #define PG8_BAR __builtin_amdgcn_s_barrier()
; template <class Epi>
; __device__ __forceinline__ void gemm_phase(LAS unsigned char* lds, const Gemm g, const Order& S, const Epi& E, const int tid) {
;     ...
;         E(acc, cur, wr, wc, fr, fq);
;         if (!has_next) break;
; #pragma unroll
;         for (int a = 0; a < 2; ++a)
; #pragma unroll
;             for (int b = 0; b < 2; ++b)
; #pragma unroll
;                 for (int m = 0; m < 4; ++m)
; #pragma unroll
;                     for (int n = 0; n < 2; ++n) acc[a][b][m][n] = (f32x4){0.f, 0.f, 0.f, 0.f};
;         cur = nxt; cA = nA; cB = nB; ++ui;
;     }
;     PG8_WAIT_V(0);
;     if (wr == 0) PG8_BAR;
;     PG8_BAR;
;     __device__ __forceinline__ void operator()(const f32x4 (&acc)[2][2][4][2], const Unit& u, int wr, int wc, int fr, int fq) const {
;     ...
;             for (int m = 0; m < 4; ++m) { bf16_t* rowp = O + (size_t)(row0 + ai * HALF + m * 16) * ldc + col0;
;                 float rs = 1.0f; if (RS) rs = rt[u.i * 256 + wr * 64 + fr + ai * HALF + m * 16];
; #pragma unroll
;                 for (int bj = 0; bj < 2; ++bj) { f32x4 v0 = acc[ai][bj][m][0], v1 = acc[ai][bj][m][1];
;                     if (RS) { v0 *= rs; v1 *= rs; }
;                     if (ACT == 1) {
; #pragma unroll
;                         for (int j = 0; j < 4; ++j) { const float a = fmaxf(v0[j], 0.f), b = fmaxf(v1[j], 0.f); v0[j] = a * a; v1[j] = b * b; } }
;                     u32x4 w; w.x = pk2(v0[0], v0[1]); w.y = pk2(v0[2], v0[3]); w.z = pk2(v1[0], v1[1]); w.w = pk2(v1[2], v1[3]);
;                     *(u32x4*)(rowp + bj * HALF) = w; } }
	v_pk_mul_f32 v[24:25], v[24:25], v[36:37] op_sel_hi:[1,0]
	v_lshl_add_u64 v[48:49], v[144:145], 0, s[8:9]
	v_cvt_pk_bf16_f32 v33, v33, v34
	v_cvt_pk_bf16_f32 v34, v40, v41
	v_cvt_pk_bf16_f32 v35, v38, v35
	v_pk_mul_f32 v[28:29], v[28:29], v[36:37] op_sel_hi:[1,0]
	v_pk_mul_f32 v[26:27], v[26:27], v[36:37] op_sel_hi:[1,0]
	v_max_f32_e32 v24, 0, v24
	global_store_dwordx4 v[48:49], v[32:35], off offset:256 nt
	v_pk_mul_f32 v[30:31], v[30:31], v[36:37] op_sel_hi:[1,0]
	v_max_f32_e32 v28, 0, v28
	v_mul_f32_e32 v34, v24, v24
	v_max_f32_e32 v24, 0, v29
	v_max_f32_e32 v25, 0, v25
	v_max_f32_e32 v26, 0, v26
	v_mul_f32_e32 v28, v28, v28
	v_mul_f32_e32 v24, v24, v24
	v_mul_f32_e32 v29, v25, v25
	v_max_f32_e32 v25, 0, v30
	v_mul_f32_e32 v30, v26, v26
	v_max_f32_e32 v26, 0, v31
	v_max_f32_e32 v27, 0, v27
	v_mul_f32_e32 v25, v25, v25
	v_mul_f32_e32 v26, v26, v26
	v_mul_f32_e32 v27, v27, v27
	v_cvt_pk_bf16_f32 v24, v28, v24
	v_add_co_u32_e32 v28, vcc, s44, v144
	v_pk_mul_f32 v[18:19], v[18:19], v[36:37] op_sel_hi:[1,0]
	v_pk_mul_f32 v[16:17], v[16:17], v[36:37] op_sel_hi:[1,0]
	v_cvt_pk_bf16_f32 v25, v25, v26
	v_cvt_pk_bf16_f32 v26, v34, v29
	v_cvt_pk_bf16_f32 v27, v30, v27
	v_addc_co_u32_e32 v29, vcc, 0, v145, vcc
	v_pk_mul_f32 v[22:23], v[22:23], v[36:37] op_sel_hi:[1,0]
	v_pk_mul_f32 v[20:21], v[20:21], v[36:37] op_sel_hi:[1,0]
	v_max_f32_e32 v16, 0, v16
	v_max_f32_e32 v17, 0, v17
	v_max_f32_e32 v18, 0, v18
	global_store_dwordx4 v[28:29], v[24:27], off nt
	v_max_f32_e32 v20, 0, v20
	v_max_f32_e32 v19, 0, v19
	v_mul_f32_e32 v24, v16, v16
	v_max_f32_e32 v16, 0, v21
	v_mul_f32_e32 v21, v17, v17
	v_max_f32_e32 v17, 0, v22
	v_mul_f32_e32 v22, v18, v18
	v_max_f32_e32 v18, 0, v23
	v_mul_f32_e32 v20, v20, v20
	v_mul_f32_e32 v16, v16, v16
	v_mul_f32_e32 v17, v17, v17
	v_mul_f32_e32 v18, v18, v18
	v_mul_f32_e32 v19, v19, v19
	v_lshl_add_u64 v[32:33], v[144:145], 0, s[10:11]
	v_cvt_pk_bf16_f32 v16, v20, v16
	v_cvt_pk_bf16_f32 v17, v17, v18
	v_cvt_pk_bf16_f32 v18, v24, v21
	v_cvt_pk_bf16_f32 v19, v22, v19
	global_store_dwordx4 v[32:33], v[16:19], off offset:256 nt
	s_nop 1
	v_mov_b32_e32 v18, v37
	v_pk_mul_f32 v[8:9], v[8:9], v[18:19] op_sel_hi:[1,0]
	v_pk_mul_f32 v[12:13], v[12:13], v[18:19] op_sel_hi:[1,0]
	v_pk_mul_f32 v[10:11], v[10:11], v[18:19] op_sel_hi:[1,0]
	v_max_f32_e32 v8, 0, v8
	v_pk_mul_f32 v[14:15], v[14:15], v[18:19] op_sel_hi:[1,0]
	v_max_f32_e32 v12, 0, v12
	v_mul_f32_e32 v19, v8, v8
	v_max_f32_e32 v8, 0, v13
	v_max_f32_e32 v9, 0, v9
	v_max_f32_e32 v10, 0, v10
	v_mul_f32_e32 v12, v12, v12
	v_mul_f32_e32 v8, v8, v8
	v_mul_f32_e32 v13, v9, v9
	v_max_f32_e32 v9, 0, v14
	v_mul_f32_e32 v14, v10, v10
	v_max_f32_e32 v10, 0, v15
	v_max_f32_e32 v11, 0, v11
	v_mul_f32_e32 v9, v9, v9
	v_mul_f32_e32 v10, v10, v10
	v_mul_f32_e32 v11, v11, v11
	v_cvt_pk_bf16_f32 v8, v12, v8
	v_add_co_u32_e32 v12, vcc, s45, v144
	v_pk_mul_f32 v[2:3], v[2:3], v[18:19] op_sel_hi:[1,0]
	v_pk_mul_f32 v[0:1], v[0:1], v[18:19] op_sel_hi:[1,0]
	v_cvt_pk_bf16_f32 v9, v9, v10
	v_cvt_pk_bf16_f32 v10, v19, v13
	v_cvt_pk_bf16_f32 v11, v14, v11
	v_addc_co_u32_e32 v13, vcc, 0, v145, vcc
	v_pk_mul_f32 v[6:7], v[6:7], v[18:19] op_sel_hi:[1,0]
	v_pk_mul_f32 v[4:5], v[4:5], v[18:19] op_sel_hi:[1,0]
	v_max_f32_e32 v0, 0, v0
	v_max_f32_e32 v1, 0, v1
	v_max_f32_e32 v2, 0, v2
	global_store_dwordx4 v[12:13], v[8:11], off nt
	v_max_f32_e32 v4, 0, v4
	v_max_f32_e32 v3, 0, v3
	v_mul_f32_e32 v8, v0, v0
	v_max_f32_e32 v0, 0, v5
	v_mul_f32_e32 v5, v1, v1
	v_max_f32_e32 v1, 0, v6
	v_mul_f32_e32 v6, v2, v2
	v_max_f32_e32 v2, 0, v7
	v_mul_f32_e32 v4, v4, v4
	v_mul_f32_e32 v0, v0, v0
	v_mul_f32_e32 v1, v1, v1
	v_mul_f32_e32 v2, v2, v2
	v_mul_f32_e32 v3, v3, v3
	v_lshl_add_u64 v[16:17], v[144:145], 0, s[12:13]
	v_cvt_pk_bf16_f32 v0, v4, v0
	v_cvt_pk_bf16_f32 v1, v1, v2
	v_cvt_pk_bf16_f32 v2, v8, v5
	v_cvt_pk_bf16_f32 v3, v6, v3
	s_and_b64 vcc, exec, s[0:1]
	global_store_dwordx4 v[16:17], v[0:3], off offset:256 nt
	s_cbranch_vccz .LBB0_905
	s_waitcnt vmcnt(0)
	s_cmpk_gt_u32 s33, 0xff
	s_cbranch_scc1 .LBB0_916
	s_barrier

; #define PG8_STAGE(bufoff, gbase, voff) do { _Pragma("unroll") for (int _i = 0; _i < 2; ++_i) \
;         __builtin_amdgcn_global_load_lds((const unsigned*)((const char*)(gbase) + (voff)[_i]), (LAS unsigned*)(lds + (bufoff) + ldsw + _i * 8192), 16, 0, 0); } while (0)
; #define PG8_LDA(dst, b, h) do { _Pragma("unroll") for (int m = 0; m < 4; ++m) _Pragma("unroll") for (int k = 0; k < 2; ++k) dst[m][k] = *(const LAS bf16x8*)(lds + PG8_SA(b, h) + aoff + m * 2048 + k * 1024); } while (0)
; #define PG8_LDB(dst, b, h) do { _Pragma("unroll") for (int n = 0; n < 2; ++n) _Pragma("unroll") for (int k = 0; k < 2; ++k) dst[n][k] = *(const LAS bf16x8*)(lds + PG8_SB(b, h) + boff + n * 2048 + k * 1024); } while (0)
; #define PG8_MMA(ai, bj, At, Bt) do { __builtin_amdgcn_s_setprio(1); _Pragma("unroll") for (int m = 0; m < 4; ++m) _Pragma("unroll") for (int n = 0; n < 2; ++n) _Pragma("unroll") for (int k = 0; k < 2; ++k) \
;         acc[ai][bj][m][n] = __builtin_amdgcn_mfma_f32_16x16x32_bf16(Bt[n][k], At[m][k], acc[ai][bj][m][n], 0, 0, 0); __builtin_amdgcn_s_setprio(0); } while (0)
; #define PG8_WAIT_V(n) asm volatile("s_waitcnt vmcnt(" #n ")" ::: "memory")
; #define PG8_WAIT_L(n) asm volatile("s_waitcnt lgkmcnt(" #n ")" ::: "memory")
; #define PG8_BAR __builtin_amdgcn_s_barrier()
; #define PG8_SCHED __builtin_amdgcn_sched_barrier(0)
; template <class Epi>
; __device__ __forceinline__ void gemm_phase(LAS unsigned char* lds, const Gemm g, const Order& S, const Epi& E, const int tid) {
;     ...
;             PG8_LDB(B0, 0, 0); PG8_SCHED; PG8_LDA(At, 0, 0); PG8_STAGE(PG8_SA(1, 1), a1 + hstepA, voffA);
;             PG8_WAIT_L(8); PG8_BAR; PG8_WAIT_L(0); PG8_MMA(0, 0, At, B0); PG8_BAR; PG8_SCHED;
;             PG8_LDB(B1, 0, 1); PG8_STAGE(PG8_SB(0, 0), b2, voffB);
;             PG8_BAR; PG8_WAIT_L(0); PG8_MMA(0, 1, At, B1); PG8_BAR;
;             PG8_LDA(At, 0, 1); PG8_STAGE(PG8_SA(0, 0), a2, voffA);
;             PG8_BAR; PG8_WAIT_L(0); PG8_MMA(1, 0, At, B0); PG8_BAR; PG8_SCHED;
;             PG8_STAGE(PG8_SB(0, 1), b2 + hstepB, voffB);
;             PG8_WAIT_V(6); PG8_BAR; PG8_MMA(1, 1, At, B1); PG8_BAR;
.LBB0_938:
	ds_read_b128 v[144:147], v153
	ds_read_b128 v[156:159], v153 offset:1024
	ds_read_b128 v[160:163], v153 offset:2048
	ds_read_b128 v[164:167], v153 offset:3072
	s_add_u32 s28, s26, 0xffe00080
	s_addc_u32 s29, s27, -1
	s_cmpk_eq_i32 s48, 0x7c
	s_cselect_b32 s31, s15, s29
	s_cselect_b32 s30, s44, s28
	s_cselect_b32 s29, s17, s47
	s_cselect_b32 s28, s45, s46
	v_lshl_add_u64 v[148:149], s[26:27], 0, v[136:137]
	s_add_i32 m0, s25, 0xc000
	ds_read_b128 v[168:171], v154
	ds_read_b128 v[172:175], v154 offset:1024
	ds_read_b128 v[176:179], v154 offset:2048
	ds_read_b128 v[180:183], v154 offset:3072
	ds_read_b128 v[184:187], v154 offset:4096
	ds_read_b128 v[188:191], v154 offset:5120
	ds_read_b128 v[192:195], v154 offset:6144
	ds_read_b128 v[196:199], v154 offset:7168
	global_load_lds_dwordx4 v[148:149], off
	v_lshl_add_u64 v[148:149], s[26:27], 0, v[138:139]
	s_add_i32 m0, s25, 0xe000
	s_nop 0
	global_load_lds_dwordx4 v[148:149], off
	s_waitcnt lgkmcnt(8)
	s_barrier
	s_waitcnt lgkmcnt(0)
	s_setprio 1
	s_waitcnt lgkmcnt(0)
	v_mfma_f32_16x16x32_bf16 v[124:127], v[144:147], v[168:171], v[124:127]
	v_mfma_f32_16x16x32_bf16 v[120:123], v[160:163], v[168:171], v[120:123]
	v_mfma_f32_16x16x32_bf16 v[116:119], v[144:147], v[176:179], v[116:119]
	v_mfma_f32_16x16x32_bf16 v[112:115], v[160:163], v[176:179], v[112:115]
	v_mfma_f32_16x16x32_bf16 v[96:99], v[144:147], v[184:187], v[96:99]
	v_mfma_f32_16x16x32_bf16 v[88:91], v[160:163], v[184:187], v[88:91]
	v_mfma_f32_16x16x32_bf16 v[80:83], v[144:147], v[192:195], v[80:83]
	v_mfma_f32_16x16x32_bf16 v[72:75], v[160:163], v[192:195], v[72:75]
	v_mfma_f32_16x16x32_bf16 v[124:127], v[156:159], v[172:175], v[124:127]
	v_mfma_f32_16x16x32_bf16 v[120:123], v[164:167], v[172:175], v[120:123]
	v_mfma_f32_16x16x32_bf16 v[116:119], v[156:159], v[180:183], v[116:119]
	v_mfma_f32_16x16x32_bf16 v[112:115], v[164:167], v[180:183], v[112:115]
	v_mfma_f32_16x16x32_bf16 v[96:99], v[156:159], v[188:191], v[96:99]
	v_mfma_f32_16x16x32_bf16 v[88:91], v[164:167], v[188:191], v[88:91]
	v_mfma_f32_16x16x32_bf16 v[80:83], v[156:159], v[196:199], v[80:83]
	v_mfma_f32_16x16x32_bf16 v[72:75], v[164:167], v[196:199], v[72:75]
	s_setprio 0
	s_barrier
	s_add_i32 s49, s41, s33
	v_lshl_add_u64 v[148:149], s[28:29], 0, v[132:133]
	s_mov_b32 m0, s49
	ds_read_b128 v[200:203], v155
	ds_read_b128 v[204:207], v155 offset:1024
	ds_read_b128 v[208:211], v155 offset:2048
	ds_read_b128 v[212:215], v155 offset:3072
	global_load_lds_dwordx4 v[148:149], off
	v_lshl_add_u64 v[216:217], s[28:29], 0, v[128:129]
	s_add_i32 m0, s49, 0x2000
	s_nop 0
	global_load_lds_dwordx4 v[216:217], off
	s_barrier
	s_waitcnt lgkmcnt(0)
	s_setprio 1
	s_waitcnt lgkmcnt(0)
	v_mfma_f32_16x16x32_bf16 v[108:111], v[200:203], v[168:171], v[108:111]
	v_mfma_f32_16x16x32_bf16 v[104:107], v[208:211], v[168:171], v[104:107]
	v_mfma_f32_16x16x32_bf16 v[100:103], v[200:203], v[176:179], v[100:103]
	v_mfma_f32_16x16x32_bf16 v[92:95], v[208:211], v[176:179], v[92:95]
	v_mfma_f32_16x16x32_bf16 v[84:87], v[200:203], v[184:187], v[84:87]
	v_mfma_f32_16x16x32_bf16 v[76:79], v[208:211], v[184:187], v[76:79]
	v_mfma_f32_16x16x32_bf16 v[68:71], v[200:203], v[192:195], v[68:71]
	v_mfma_f32_16x16x32_bf16 v[64:67], v[208:211], v[192:195], v[64:67]
	v_mfma_f32_16x16x32_bf16 v[108:111], v[204:207], v[172:175], v[108:111]
	v_mfma_f32_16x16x32_bf16 v[104:107], v[212:215], v[172:175], v[104:107]
	v_mfma_f32_16x16x32_bf16 v[100:103], v[204:207], v[180:183], v[100:103]
	v_mfma_f32_16x16x32_bf16 v[92:95], v[212:215], v[180:183], v[92:95]
	v_mfma_f32_16x16x32_bf16 v[84:87], v[204:207], v[188:191], v[84:87]
	v_mfma_f32_16x16x32_bf16 v[76:79], v[212:215], v[188:191], v[76:79]
	v_mfma_f32_16x16x32_bf16 v[68:71], v[204:207], v[196:199], v[68:71]
	v_mfma_f32_16x16x32_bf16 v[64:67], v[212:215], v[196:199], v[64:67]
	s_setprio 0
	s_mov_b32 m0, s25
	v_lshl_add_u64 v[218:219], s[30:31], 0, v[134:135]
	s_barrier
	ds_read_b128 v[168:171], v154 offset:16384
	ds_read_b128 v[172:175], v154 offset:17408
	ds_read_b128 v[176:179], v154 offset:18432
	ds_read_b128 v[180:183], v154 offset:19456
	ds_read_b128 v[184:187], v154 offset:20480
	ds_read_b128 v[188:191], v154 offset:21504
	ds_read_b128 v[192:195], v154 offset:22528
	ds_read_b128 v[196:199], v154 offset:23552
	global_load_lds_dwordx4 v[218:219], off
	v_lshl_add_u64 v[220:221], s[30:31], 0, v[130:131]
	s_mov_b32 m0, s35
	s_nop 0
	global_load_lds_dwordx4 v[220:221], off
	s_barrier
	s_waitcnt lgkmcnt(0)
	s_setprio 1
	s_waitcnt lgkmcnt(0)
	v_mfma_f32_16x16x32_bf16 v[60:63], v[144:147], v[168:171], v[60:63]
	v_mfma_f32_16x16x32_bf16 v[56:59], v[160:163], v[168:171], v[56:59]
	v_mfma_f32_16x16x32_bf16 v[48:51], v[144:147], v[176:179], v[48:51]
	v_mfma_f32_16x16x32_bf16 v[40:43], v[160:163], v[176:179], v[40:43]
	v_mfma_f32_16x16x32_bf16 v[32:35], v[144:147], v[184:187], v[32:35]
	v_mfma_f32_16x16x32_bf16 v[24:27], v[160:163], v[184:187], v[24:27]
	v_mfma_f32_16x16x32_bf16 v[16:19], v[144:147], v[192:195], v[16:19]
	v_mfma_f32_16x16x32_bf16 v[8:11], v[160:163], v[192:195], v[8:11]
	v_mfma_f32_16x16x32_bf16 v[60:63], v[156:159], v[172:175], v[60:63]
	v_mfma_f32_16x16x32_bf16 v[56:59], v[164:167], v[172:175], v[56:59]
	v_mfma_f32_16x16x32_bf16 v[48:51], v[156:159], v[180:183], v[48:51]
	v_mfma_f32_16x16x32_bf16 v[40:43], v[164:167], v[180:183], v[40:43]
	v_mfma_f32_16x16x32_bf16 v[32:35], v[156:159], v[188:191], v[32:35]
	v_mfma_f32_16x16x32_bf16 v[24:27], v[164:167], v[188:191], v[24:27]
	v_mfma_f32_16x16x32_bf16 v[16:19], v[156:159], v[196:199], v[16:19]
	v_mfma_f32_16x16x32_bf16 v[8:11], v[164:167], v[196:199], v[8:11]
	s_setprio 0
	s_barrier
; #define PG8_STAGE(bufoff, gbase, voff) do { _Pragma("unroll") for (int _i = 0; _i < 2; ++_i) \
;         __builtin_amdgcn_global_load_lds((const unsigned*)((const char*)(gbase) + (voff)[_i]), (LAS unsigned*)(lds + (bufoff) + ldsw + _i * 8192), 16, 0, 0); } while (0)
; #define PG8_LDA(dst, b, h) do { _Pragma("unroll") for (int m = 0; m < 4; ++m) _Pragma("unroll") for (int k = 0; k < 2; ++k) dst[m][k] = *(const LAS bf16x8*)(lds + PG8_SA(b, h) + aoff + m * 2048 + k * 1024); } while (0)
; #define PG8_LDB(dst, b, h) do { _Pragma("unroll") for (int n = 0; n < 2; ++n) _Pragma("unroll") for (int k = 0; k < 2; ++k) dst[n][k] = *(const LAS bf16x8*)(lds + PG8_SB(b, h) + boff + n * 2048 + k * 1024); } while (0)
; #define PG8_MMA(ai, bj, At, Bt) do { __builtin_amdgcn_s_setprio(1); _Pragma("unroll") for (int m = 0; m < 4; ++m) _Pragma("unroll") for (int n = 0; n < 2; ++n) _Pragma("unroll") for (int k = 0; k < 2; ++k) \
;         acc[ai][bj][m][n] = __builtin_amdgcn_mfma_f32_16x16x32_bf16(Bt[n][k], At[m][k], acc[ai][bj][m][n], 0, 0, 0); __builtin_amdgcn_s_setprio(0); } while (0)
; #define PG8_WAIT_V(n) asm volatile("s_waitcnt vmcnt(" #n ")" ::: "memory")
; #define PG8_WAIT_L(n) asm volatile("s_waitcnt lgkmcnt(" #n ")" ::: "memory")
; #define PG8_BAR __builtin_amdgcn_s_barrier()
; #define PG8_SCHED __builtin_amdgcn_sched_barrier(0)
; template <class Epi>
; __device__ __forceinline__ void gemm_phase(LAS unsigned char* lds, const Gemm g, const Order& S, const Epi& E, const int tid) {
;     ...
;             PG8_WAIT_V(6); PG8_BAR; PG8_MMA(1, 1, At, B1); PG8_BAR;
;             PG8_LDB(B0, 1, 0); PG8_SCHED; PG8_LDA(At, 1, 0); PG8_STAGE(PG8_SA(0, 1), a2 + hstepA, voffA);
;             PG8_WAIT_L(8); PG8_BAR; PG8_WAIT_L(0); PG8_MMA(0, 0, At, B0); PG8_BAR; PG8_SCHED;
;             PG8_LDB(B1, 1, 1); PG8_STAGE(PG8_SB(1, 0), b3, voffB);
;             PG8_BAR; PG8_WAIT_L(0); PG8_MMA(0, 1, At, B1); PG8_BAR;
;             PG8_LDA(At, 1, 1); PG8_STAGE(PG8_SA(1, 0), a3, voffA);
	s_add_u32 s50, s28, 0x200000
	s_addc_u32 s51, s29, 0
	s_add_i32 s49, s42, s33
	v_lshl_add_u64 v[144:145], s[50:51], 0, v[132:133]
	s_mov_b32 m0, s49
	s_nop 0
	global_load_lds_dwordx4 v[144:145], off
	v_lshl_add_u64 v[144:145], s[50:51], 0, v[128:129]
	s_add_i32 m0, s49, 0x2000
	s_nop 0
	global_load_lds_dwordx4 v[144:145], off
	s_waitcnt vmcnt(6)
	s_barrier
	s_setprio 1
	v_mfma_f32_16x16x32_bf16 v[52:55], v[200:203], v[168:171], v[52:55]
	v_mfma_f32_16x16x32_bf16 v[44:47], v[208:211], v[168:171], v[44:47]
	v_mfma_f32_16x16x32_bf16 v[36:39], v[200:203], v[176:179], v[36:39]
	v_mfma_f32_16x16x32_bf16 v[28:31], v[208:211], v[176:179], v[28:31]
	v_mfma_f32_16x16x32_bf16 v[20:23], v[200:203], v[184:187], v[20:23]
	v_mfma_f32_16x16x32_bf16 v[12:15], v[208:211], v[184:187], v[12:15]
	v_mfma_f32_16x16x32_bf16 v[4:7], v[200:203], v[192:195], v[4:7]
	v_mfma_f32_16x16x32_bf16 v[0:3], v[208:211], v[192:195], v[0:3]
	v_mfma_f32_16x16x32_bf16 v[52:55], v[204:207], v[172:175], v[52:55]
	v_mfma_f32_16x16x32_bf16 v[44:47], v[212:215], v[172:175], v[44:47]
	v_mfma_f32_16x16x32_bf16 v[36:39], v[204:207], v[180:183], v[36:39]
	v_mfma_f32_16x16x32_bf16 v[28:31], v[212:215], v[180:183], v[28:31]
	v_mfma_f32_16x16x32_bf16 v[20:23], v[204:207], v[188:191], v[20:23]
	v_mfma_f32_16x16x32_bf16 v[12:15], v[212:215], v[188:191], v[12:15]
	v_mfma_f32_16x16x32_bf16 v[4:7], v[204:207], v[196:199], v[4:7]
	v_mfma_f32_16x16x32_bf16 v[0:3], v[212:215], v[196:199], v[0:3]
	s_setprio 0
	s_add_i32 s49, 0, 0x18000
	v_add_u32_e32 v164, s49, v151
	s_barrier
	ds_read_b128 v[144:147], v164
	ds_read_b128 v[156:159], v164 offset:1024
	ds_read_b128 v[160:163], v164 offset:2048
	ds_read_b128 v[164:167], v164 offset:3072
	s_add_u32 s30, s30, 0x200000
	s_addc_u32 s31, s31, 0
	s_mov_b32 m0, s36
	v_lshl_add_u64 v[200:201], s[30:31], 0, v[134:135]
	ds_read_b128 v[168:171], v154 offset:32768
	ds_read_b128 v[172:175], v154 offset:33792
	ds_read_b128 v[176:179], v154 offset:34816
	ds_read_b128 v[180:183], v154 offset:35840
	ds_read_b128 v[184:187], v154 offset:36864
	ds_read_b128 v[188:191], v154 offset:37888
	ds_read_b128 v[192:195], v154 offset:38912
	ds_read_b128 v[196:199], v154 offset:39936
	global_load_lds_dwordx4 v[200:201], off
	v_lshl_add_u64 v[200:201], s[30:31], 0, v[130:131]
	s_mov_b32 m0, s37
	s_nop 0
	global_load_lds_dwordx4 v[200:201], off
	s_waitcnt lgkmcnt(8)
	s_barrier
	s_waitcnt lgkmcnt(0)
	s_setprio 1
	s_waitcnt lgkmcnt(0)
	v_mfma_f32_16x16x32_bf16 v[124:127], v[144:147], v[168:171], v[124:127]
	v_mfma_f32_16x16x32_bf16 v[120:123], v[160:163], v[168:171], v[120:123]
	v_mfma_f32_16x16x32_bf16 v[116:119], v[144:147], v[176:179], v[116:119]
	v_mfma_f32_16x16x32_bf16 v[112:115], v[160:163], v[176:179], v[112:115]
	v_mfma_f32_16x16x32_bf16 v[96:99], v[144:147], v[184:187], v[96:99]
	v_mfma_f32_16x16x32_bf16 v[88:91], v[160:163], v[184:187], v[88:91]
	v_mfma_f32_16x16x32_bf16 v[80:83], v[144:147], v[192:195], v[80:83]
	v_mfma_f32_16x16x32_bf16 v[72:75], v[160:163], v[192:195], v[72:75]
	v_mfma_f32_16x16x32_bf16 v[124:127], v[156:159], v[172:175], v[124:127]
	v_mfma_f32_16x16x32_bf16 v[120:123], v[164:167], v[172:175], v[120:123]
	v_mfma_f32_16x16x32_bf16 v[116:119], v[156:159], v[180:183], v[116:119]
	v_mfma_f32_16x16x32_bf16 v[112:115], v[164:167], v[180:183], v[112:115]
	v_mfma_f32_16x16x32_bf16 v[96:99], v[156:159], v[188:191], v[96:99]
	v_mfma_f32_16x16x32_bf16 v[88:91], v[164:167], v[188:191], v[88:91]
	v_mfma_f32_16x16x32_bf16 v[80:83], v[156:159], v[196:199], v[80:83]
	v_mfma_f32_16x16x32_bf16 v[72:75], v[164:167], v[196:199], v[72:75]
	s_setprio 0
	s_barrier
	s_add_i32 s30, 0, 0x1c000
	s_add_i32 s31, s49, s33
	v_add_u32_e32 v212, s30, v151
	v_lshl_add_u64 v[148:149], v[148:149], 0, s[4:5]
	s_mov_b32 m0, s31
	ds_read_b128 v[200:203], v212
	ds_read_b128 v[204:207], v212 offset:1024
	ds_read_b128 v[208:211], v212 offset:2048
	ds_read_b128 v[212:215], v212 offset:3072
	global_load_lds_dwordx4 v[148:149], off
	v_lshl_add_u64 v[148:149], v[216:217], 0, s[4:5]
	s_add_i32 m0, s31, 0x2000
	s_nop 0
	global_load_lds_dwordx4 v[148:149], off
	s_barrier
	s_waitcnt lgkmcnt(0)
	s_setprio 1
	s_waitcnt lgkmcnt(0)
	v_mfma_f32_16x16x32_bf16 v[108:111], v[200:203], v[168:171], v[108:111]
	v_mfma_f32_16x16x32_bf16 v[104:107], v[208:211], v[168:171], v[104:107]
	v_mfma_f32_16x16x32_bf16 v[100:103], v[200:203], v[176:179], v[100:103]
	v_mfma_f32_16x16x32_bf16 v[92:95], v[208:211], v[176:179], v[92:95]
	v_mfma_f32_16x16x32_bf16 v[84:87], v[200:203], v[184:187], v[84:87]
	v_mfma_f32_16x16x32_bf16 v[76:79], v[208:211], v[184:187], v[76:79]
	v_mfma_f32_16x16x32_bf16 v[68:71], v[200:203], v[192:195], v[68:71]
	v_mfma_f32_16x16x32_bf16 v[64:67], v[208:211], v[192:195], v[64:67]
	v_mfma_f32_16x16x32_bf16 v[108:111], v[204:207], v[172:175], v[108:111]
	v_mfma_f32_16x16x32_bf16 v[104:107], v[212:215], v[172:175], v[104:107]
	v_mfma_f32_16x16x32_bf16 v[100:103], v[204:207], v[180:183], v[100:103]
	v_mfma_f32_16x16x32_bf16 v[92:95], v[212:215], v[180:183], v[92:95]
	v_mfma_f32_16x16x32_bf16 v[84:87], v[204:207], v[188:191], v[84:87]
	v_mfma_f32_16x16x32_bf16 v[76:79], v[212:215], v[188:191], v[76:79]
	v_mfma_f32_16x16x32_bf16 v[68:71], v[204:207], v[196:199], v[68:71]
	v_mfma_f32_16x16x32_bf16 v[64:67], v[212:215], v[196:199], v[64:67]
	s_setprio 0
	s_mov_b32 m0, s39
	v_lshl_add_u64 v[148:149], v[218:219], 0, s[4:5]
	s_barrier
	ds_read_b128 v[168:171], v154 offset:49152
	ds_read_b128 v[172:175], v154 offset:50176
	ds_read_b128 v[176:179], v154 offset:51200
	ds_read_b128 v[180:183], v154 offset:52224
	ds_read_b128 v[184:187], v154 offset:53248
	ds_read_b128 v[188:191], v154 offset:54272
	ds_read_b128 v[192:195], v154 offset:55296
	ds_read_b128 v[196:199], v154 offset:56320
	global_load_lds_dwordx4 v[148:149], off
	v_lshl_add_u64 v[148:149], v[220:221], 0, s[4:5]
	s_mov_b32 m0, s40
	s_nop 0
	global_load_lds_dwordx4 v[148:149], off
	s_barrier
; #define PG8_STAGE(bufoff, gbase, voff) do { _Pragma("unroll") for (int _i = 0; _i < 2; ++_i) \
;         __builtin_amdgcn_global_load_lds((const unsigned*)((const char*)(gbase) + (voff)[_i]), (LAS unsigned*)(lds + (bufoff) + ldsw + _i * 8192), 16, 0, 0); } while (0)
; #define PG8_LDA(dst, b, h) do { _Pragma("unroll") for (int m = 0; m < 4; ++m) _Pragma("unroll") for (int k = 0; k < 2; ++k) dst[m][k] = *(const LAS bf16x8*)(lds + PG8_SA(b, h) + aoff + m * 2048 + k * 1024); } while (0)
; #define PG8_MMA(ai, bj, At, Bt) do { __builtin_amdgcn_s_setprio(1); _Pragma("unroll") for (int m = 0; m < 4; ++m) _Pragma("unroll") for (int n = 0; n < 2; ++n) _Pragma("unroll") for (int k = 0; k < 2; ++k) \
;         acc[ai][bj][m][n] = __builtin_amdgcn_mfma_f32_16x16x32_bf16(Bt[n][k], At[m][k], acc[ai][bj][m][n], 0, 0, 0); __builtin_amdgcn_s_setprio(0); } while (0)
; #define PG8_WAIT_V(n) asm volatile("s_waitcnt vmcnt(" #n ")" ::: "memory")
; #define PG8_WAIT_L(n) asm volatile("s_waitcnt lgkmcnt(" #n ")" ::: "memory")
; #define PG8_BAR __builtin_amdgcn_s_barrier()
; #define PG8_SCHED __builtin_amdgcn_sched_barrier(0)
; template <class Epi>
; __device__ __forceinline__ void gemm_phase(LAS unsigned char* lds, const Gemm g, const Order& S, const Epi& E, const int tid) {
;     ...
;             PG8_BAR; PG8_WAIT_L(0); PG8_MMA(0, 1, At, B1); PG8_BAR;
;             PG8_LDA(At, 1, 1); PG8_STAGE(PG8_SA(1, 0), a3, voffA);
;             PG8_BAR; PG8_WAIT_L(0); PG8_MMA(1, 0, At, B0); PG8_BAR; PG8_SCHED;
;             PG8_STAGE(PG8_SB(1, 1), b3 + hstepB, voffB);
;             PG8_WAIT_V(6); PG8_BAR; PG8_MMA(1, 1, At, B1); PG8_BAR;
;     __device__ __forceinline__ void operator()(const f32x4 (&acc)[2][2][4][2], const Unit& u, int wr, int wc, int fr, int fq) const {
;     ...
;                 u32x4 bs[4][2];
; #pragma unroll
;                 for (int m = 0; m < 4; ++m) { const size_t off = (size_t)(row0 + ai * HALF + m * 16) * DM + col0;
; #pragma unroll
;                     for (int bj = 0; bj < 2; ++bj) bs[m][bj] = *(const u32x4*)(baseb + off + bj * HALF); }
	s_waitcnt lgkmcnt(0)
	s_setprio 1
	s_waitcnt lgkmcnt(0)
	v_mfma_f32_16x16x32_bf16 v[60:63], v[144:147], v[168:171], v[60:63]
	v_mfma_f32_16x16x32_bf16 v[56:59], v[160:163], v[168:171], v[56:59]
	v_mfma_f32_16x16x32_bf16 v[48:51], v[144:147], v[176:179], v[48:51]
	v_mfma_f32_16x16x32_bf16 v[40:43], v[160:163], v[176:179], v[40:43]
	v_mfma_f32_16x16x32_bf16 v[32:35], v[144:147], v[184:187], v[32:35]
	v_mfma_f32_16x16x32_bf16 v[24:27], v[160:163], v[184:187], v[24:27]
	v_mfma_f32_16x16x32_bf16 v[16:19], v[144:147], v[192:195], v[16:19]
	v_mfma_f32_16x16x32_bf16 v[8:11], v[160:163], v[192:195], v[8:11]
	v_mfma_f32_16x16x32_bf16 v[60:63], v[156:159], v[172:175], v[60:63]
	v_mfma_f32_16x16x32_bf16 v[56:59], v[164:167], v[172:175], v[56:59]
	v_mfma_f32_16x16x32_bf16 v[48:51], v[156:159], v[180:183], v[48:51]
	v_mfma_f32_16x16x32_bf16 v[40:43], v[164:167], v[180:183], v[40:43]
	v_mfma_f32_16x16x32_bf16 v[32:35], v[156:159], v[188:191], v[32:35]
	v_mfma_f32_16x16x32_bf16 v[24:27], v[164:167], v[188:191], v[24:27]
	v_mfma_f32_16x16x32_bf16 v[16:19], v[156:159], v[196:199], v[16:19]
	v_mfma_f32_16x16x32_bf16 v[8:11], v[164:167], v[196:199], v[8:11]
	s_setprio 0
	s_barrier
	s_add_u32 s28, s28, 0x200080
	s_addc_u32 s29, s29, 0
	s_add_i32 s30, s30, s33
	v_lshl_add_u64 v[144:145], s[28:29], 0, v[132:133]
	s_mov_b32 m0, s30
	s_nop 0
	global_load_lds_dwordx4 v[144:145], off
	v_lshl_add_u64 v[144:145], s[28:29], 0, v[128:129]
	s_add_i32 m0, s30, 0x2000
	s_nop 0
	global_load_lds_dwordx4 v[144:145], off
	s_waitcnt vmcnt(6)
	s_barrier
	s_setprio 1
	v_mfma_f32_16x16x32_bf16 v[52:55], v[200:203], v[168:171], v[52:55]
	v_mfma_f32_16x16x32_bf16 v[44:47], v[208:211], v[168:171], v[44:47]
	v_mfma_f32_16x16x32_bf16 v[36:39], v[200:203], v[176:179], v[36:39]
	v_mfma_f32_16x16x32_bf16 v[28:31], v[208:211], v[176:179], v[28:31]
	v_mfma_f32_16x16x32_bf16 v[20:23], v[200:203], v[184:187], v[20:23]
	v_mfma_f32_16x16x32_bf16 v[12:15], v[208:211], v[184:187], v[12:15]
	v_mfma_f32_16x16x32_bf16 v[4:7], v[200:203], v[192:195], v[4:7]
	v_mfma_f32_16x16x32_bf16 v[0:3], v[208:211], v[192:195], v[0:3]
	v_mfma_f32_16x16x32_bf16 v[52:55], v[204:207], v[172:175], v[52:55]
	v_mfma_f32_16x16x32_bf16 v[44:47], v[212:215], v[172:175], v[44:47]
	v_mfma_f32_16x16x32_bf16 v[36:39], v[204:207], v[180:183], v[36:39]
	v_mfma_f32_16x16x32_bf16 v[28:31], v[212:215], v[180:183], v[28:31]
	v_mfma_f32_16x16x32_bf16 v[20:23], v[204:207], v[188:191], v[20:23]
	v_mfma_f32_16x16x32_bf16 v[12:15], v[212:215], v[188:191], v[12:15]
	v_mfma_f32_16x16x32_bf16 v[4:7], v[204:207], v[196:199], v[4:7]
	v_mfma_f32_16x16x32_bf16 v[0:3], v[212:215], v[196:199], v[0:3]
	s_setprio 0
	s_add_i32 s48, s48, 2
	s_add_u32 s26, s26, 0x100
	s_addc_u32 s27, s27, 0
	s_add_u32 s46, s46, 0x100
	s_addc_u32 s47, s47, 0
	s_cmpk_gt_u32 s48, 0x7d
	s_barrier
	s_cbranch_scc0 .LBB0_938
	v_lshl_or_b32 v144, s43, 8, v152
	v_lshl_add_u32 v172, s24, 8, v150
	v_ashrrev_i32_e32 v145, 31, v144
	v_lshlrev_b64 v[144:145], 1, v[144:145]
	v_ashrrev_i32_e32 v173, 31, v172
	v_lshl_add_u64 v[146:147], s[22:23], 0, v[144:145]
	v_lshlrev_b64 v[148:149], 12, v[172:173]
	v_or_b32_e32 v164, 16, v172
	v_lshl_add_u64 v[160:161], v[146:147], 0, v[148:149]
	v_ashrrev_i32_e32 v165, 31, v164
	global_load_dwordx4 v[156:159], v[160:161], off
	s_nop 0
	global_load_dwordx4 v[160:163], v[160:161], off offset:256
	v_lshlrev_b64 v[188:189], 12, v[164:165]
	v_lshl_add_u64 v[168:169], v[146:147], 0, v[188:189]
	global_load_dwordx4 v[164:167], v[168:169], off
	s_nop 0
	global_load_dwordx4 v[168:171], v[168:169], off offset:256
	v_or_b32_e32 v174, 32, v172
	v_or_b32_e32 v172, 48, v172
	v_ashrrev_i32_e32 v175, 31, v174
	v_ashrrev_i32_e32 v173, 31, v172
	v_lshlrev_b64 v[190:191], 12, v[174:175]
	v_lshlrev_b64 v[192:193], 12, v[172:173]
	v_lshl_add_u64 v[172:173], s[22:23], 0, v[148:149]
	v_lshl_add_u64 v[176:177], v[146:147], 0, v[190:191]
	v_lshl_add_u64 v[184:185], v[146:147], 0, v[192:193]
	v_lshl_add_u64 v[194:195], v[172:173], 0, v[144:145]
	global_load_dwordx4 v[172:175], v[176:177], off
	s_nop 0
	global_load_dwordx4 v[176:179], v[176:177], off offset:256
	s_nop 0
	global_load_dwordx4 v[180:183], v[184:185], off
	s_nop 0
	global_load_dwordx4 v[184:187], v[184:185], off offset:256
	s_and_b64 vcc, exec, s[0:1]
	s_mov_b32 s43, s16
	s_mov_b32 s24, s14
	s_mov_b64 s[28:29], s[20:21]
	s_mov_b64 s[26:27], s[18:19]
	s_waitcnt vmcnt(0)
; __device__ __forceinline__ float bflo(unsigned w) { return __uint_as_float(w << 16); }
; __device__ __forceinline__ float bfhi(unsigned w) { return __uint_as_float(w & 0xffff0000u); }
;     __device__ __forceinline__ void operator()(const f32x4 (&acc)[2][2][4][2], const Unit& u, int wr, int wc, int fr, int fq) const {
;     ...
;                 for (int m = 0; m < 4; ++m) { const size_t off = (size_t)(row0 + ai * HALF + m * 16) * DM + col0;
;                     float ss = 0.f;
; #pragma unroll
;                     for (int bj = 0; bj < 2; ++bj) { const u32x4 q = bs[m][bj]; const f32x4 a0 = acc[ai][bj][m][0], a1 = acc[ai][bj][m][1];
;                         const float h0 = bflo(q.x) + a0[0], h1 = bfhi(q.x) + a0[1], h2 = bflo(q.y) + a0[2], h3 = bfhi(q.y) + a0[3], h4 = bflo(q.z) + a1[0], h5 = bfhi(q.z) + a1[1], h6 = bflo(q.w) + a1[2], h7 = bfhi(q.w) + a1[3];
;                         ss += (h0 * h0 + h1 * h1) + (h2 * h2 + h3 * h3) + (h4 * h4 + h5 * h5) + (h6 * h6 + h7 * h7);
;                         u32x4 w; w.x = pk2(h0, h1); w.y = pk2(h2, h3); w.z = pk2(h4, h5); w.w = pk2(h6, h7);
;                         *(u32x4*)(out + off + bj * HALF) = w; }
	v_lshlrev_b32_e32 v196, 16, v156
	v_and_b32_e32 v156, 0xffff0000, v156
	v_lshlrev_b32_e32 v197, 16, v157
	v_and_b32_e32 v157, 0xffff0000, v157
	v_lshlrev_b32_e32 v198, 16, v158
	v_and_b32_e32 v158, 0xffff0000, v158
	v_lshlrev_b32_e32 v199, 16, v159
	v_and_b32_e32 v159, 0xffff0000, v159
	v_lshlrev_b32_e32 v200, 16, v160
	v_and_b32_e32 v160, 0xffff0000, v160
	v_lshlrev_b32_e32 v201, 16, v161
	v_and_b32_e32 v161, 0xffff0000, v161
	v_lshlrev_b32_e32 v202, 16, v162
	v_and_b32_e32 v162, 0xffff0000, v162
	v_lshlrev_b32_e32 v203, 16, v163
	v_and_b32_e32 v163, 0xffff0000, v163
	v_add_f32_e32 v124, v124, v196
	v_add_f32_e32 v125, v125, v156
	v_add_f32_e32 v126, v126, v197
	v_add_f32_e32 v127, v127, v157
	v_add_f32_e32 v120, v120, v198
	v_add_f32_e32 v121, v121, v158
	v_add_f32_e32 v122, v122, v199
	v_add_f32_e32 v123, v123, v159
	v_add_f32_e32 v108, v108, v200
	v_add_f32_e32 v109, v109, v160
	v_add_f32_e32 v110, v110, v201
	v_add_f32_e32 v111, v111, v161
	v_add_f32_e32 v156, v104, v202
	v_add_f32_e32 v157, v105, v162
	v_add_f32_e32 v158, v106, v203
	v_add_f32_e32 v159, v107, v163
	v_cvt_pk_bf16_f32 v104, v124, v125
	v_cvt_pk_bf16_f32 v105, v126, v127
	v_cvt_pk_bf16_f32 v106, v120, v121
	v_cvt_pk_bf16_f32 v107, v122, v123
	v_cvt_pk_bf16_f32 v108, v108, v109
	v_cvt_pk_bf16_f32 v109, v110, v111
	v_cvt_pk_bf16_f32 v110, v156, v157
	v_cvt_pk_bf16_f32 v111, v158, v159
	global_store_dwordx4 v[194:195], v[104:107], off nt
	global_store_dwordx4 v[194:195], v[108:111], off offset:256 nt
	v_lshlrev_b32_e32 v204, 16, v164
	v_lshlrev_b32_e32 v106, 16, v168
	v_add_f32_e32 v100, v100, v106
	v_and_b32_e32 v106, 0xffff0000, v168
	v_add_f32_e32 v101, v101, v106
	v_lshlrev_b32_e32 v106, 16, v169
	v_add_f32_e32 v102, v102, v106
	v_and_b32_e32 v106, 0xffff0000, v169
	v_add_f32_e32 v103, v103, v106
	v_lshlrev_b32_e32 v106, 16, v170
	v_add_f32_e32 v106, v92, v106
	v_and_b32_e32 v92, 0xffff0000, v170
	v_add_f32_e32 v107, v93, v92
	v_lshlrev_b32_e32 v92, 16, v171
	v_add_f32_e32 v108, v94, v92
	v_and_b32_e32 v92, 0xffff0000, v171
	v_lshl_add_u64 v[104:105], s[22:23], 0, v[188:189]
	v_add_f32_e32 v95, v95, v92
	v_lshl_add_u64 v[104:105], v[104:105], 0, v[144:145]
	v_cvt_pk_bf16_f32 v92, v100, v101
	v_cvt_pk_bf16_f32 v93, v102, v103
	v_cvt_pk_bf16_f32 v94, v106, v107
	v_cvt_pk_bf16_f32 v95, v108, v95
	global_store_dwordx4 v[104:105], v[92:95], off offset:256 nt
	v_and_b32_e32 v164, 0xffff0000, v164
	v_lshlrev_b32_e32 v205, 16, v165
	v_lshlrev_b32_e32 v92, 16, v172
	v_add_f32_e32 v92, v96, v92
	v_lshlrev_b32_e32 v96, 16, v174
	v_and_b32_e32 v93, 0xffff0000, v172
	v_add_f32_e32 v96, v88, v96
	v_and_b32_e32 v88, 0xffff0000, v174
	v_add_f32_e32 v93, v97, v93
	v_lshlrev_b32_e32 v94, 16, v173
	v_add_f32_e32 v97, v89, v88
	v_lshlrev_b32_e32 v88, 16, v175
	v_add_f32_e32 v94, v98, v94
	v_and_b32_e32 v95, 0xffff0000, v173
	v_add_f32_e32 v98, v90, v88
	v_and_b32_e32 v88, 0xffff0000, v175
	v_add_f32_e32 v95, v99, v95
	v_add_f32_e32 v91, v91, v88
	v_cvt_pk_bf16_f32 v88, v92, v93
	v_lshl_add_u64 v[92:93], s[22:23], 0, v[190:191]
	v_cvt_pk_bf16_f32 v89, v94, v95
	v_cvt_pk_bf16_f32 v90, v96, v97
	v_cvt_pk_bf16_f32 v91, v98, v91
	v_lshl_add_u64 v[92:93], v[92:93], 0, v[144:145]
	global_store_dwordx4 v[92:93], v[88:91], off nt
	v_and_b32_e32 v165, 0xffff0000, v165
	v_lshlrev_b32_e32 v206, 16, v166
	v_lshlrev_b32_e32 v88, 16, v176
	v_add_f32_e32 v84, v84, v88
	v_and_b32_e32 v88, 0xffff0000, v176
	v_add_f32_e32 v85, v85, v88
	v_lshlrev_b32_e32 v88, 16, v177
	v_add_f32_e32 v86, v86, v88
	v_and_b32_e32 v88, 0xffff0000, v177
	v_add_f32_e32 v87, v87, v88
	v_lshlrev_b32_e32 v88, 16, v178
	v_add_f32_e32 v88, v76, v88
	v_and_b32_e32 v76, 0xffff0000, v178
	v_add_f32_e32 v89, v77, v76
	v_lshlrev_b32_e32 v76, 16, v179
	v_add_f32_e32 v90, v78, v76
	v_and_b32_e32 v76, 0xffff0000, v179
	v_add_f32_e32 v79, v79, v76
	v_cvt_pk_bf16_f32 v76, v84, v85
	v_cvt_pk_bf16_f32 v77, v86, v87
	v_cvt_pk_bf16_f32 v78, v88, v89
	v_cvt_pk_bf16_f32 v79, v90, v79
	global_store_dwordx4 v[92:93], v[76:79], off offset:256 nt
	v_and_b32_e32 v166, 0xffff0000, v166
	v_lshlrev_b32_e32 v207, 16, v167
	v_lshlrev_b32_e32 v76, 16, v180
	v_add_f32_e32 v76, v80, v76
	v_lshlrev_b32_e32 v80, 16, v182
	v_and_b32_e32 v77, 0xffff0000, v180
	v_add_f32_e32 v80, v72, v80
	v_and_b32_e32 v72, 0xffff0000, v182
	v_add_f32_e32 v77, v81, v77
	v_lshlrev_b32_e32 v78, 16, v181
	v_add_f32_e32 v81, v73, v72
	v_lshlrev_b32_e32 v72, 16, v183
	v_add_f32_e32 v78, v82, v78
	v_and_b32_e32 v79, 0xffff0000, v181
	v_add_f32_e32 v82, v74, v72
	v_and_b32_e32 v72, 0xffff0000, v183
	v_add_f32_e32 v79, v83, v79
	v_add_f32_e32 v75, v75, v72
	v_cvt_pk_bf16_f32 v72, v76, v77
	v_lshl_add_u64 v[76:77], s[22:23], 0, v[192:193]
	v_cvt_pk_bf16_f32 v73, v78, v79
	v_cvt_pk_bf16_f32 v74, v80, v81
	v_cvt_pk_bf16_f32 v75, v82, v75
	v_lshl_add_u64 v[76:77], v[76:77], 0, v[144:145]
	global_store_dwordx4 v[76:77], v[72:75], off nt
	v_and_b32_e32 v167, 0xffff0000, v167
	v_add_f32_e32 v116, v116, v204
	v_lshlrev_b32_e32 v72, 16, v184
	v_add_f32_e32 v68, v68, v72
	v_and_b32_e32 v72, 0xffff0000, v184
	v_add_f32_e32 v69, v69, v72
	v_lshlrev_b32_e32 v72, 16, v185
	v_add_f32_e32 v70, v70, v72
	v_and_b32_e32 v72, 0xffff0000, v185
	v_add_f32_e32 v71, v71, v72
	v_lshlrev_b32_e32 v72, 16, v186
	v_add_f32_e32 v72, v64, v72
	v_and_b32_e32 v64, 0xffff0000, v186
	v_add_f32_e32 v73, v65, v64
	v_lshlrev_b32_e32 v64, 16, v187
	v_add_f32_e32 v74, v66, v64
	v_and_b32_e32 v64, 0xffff0000, v187
	v_add_f32_e32 v117, v117, v164
	v_add_f32_e32 v118, v118, v205
	v_add_f32_e32 v119, v119, v165
	v_add_f32_e32 v160, v112, v206
	v_add_f32_e32 v161, v113, v166
	v_add_f32_e32 v162, v114, v207
	v_add_f32_e32 v115, v115, v167
	v_add_f32_e32 v67, v67, v64
	v_cvt_pk_bf16_f32 v112, v116, v117
	v_cvt_pk_bf16_f32 v113, v118, v119
	v_cvt_pk_bf16_f32 v114, v160, v161
	v_cvt_pk_bf16_f32 v115, v162, v115
	v_cvt_pk_bf16_f32 v64, v68, v69
	v_cvt_pk_bf16_f32 v65, v70, v71
	v_cvt_pk_bf16_f32 v66, v72, v73
	v_cvt_pk_bf16_f32 v67, v74, v67
	global_store_dwordx4 v[104:105], v[112:115], off nt
	global_store_dwordx4 v[76:77], v[64:67], off offset:256 nt
	v_lshl_add_u64 v[96:97], v[148:149], 0, s[6:7]
	v_lshl_add_u64 v[68:69], v[146:147], 0, v[96:97]
	global_load_dwordx4 v[64:67], v[68:69], off
	s_nop 0
	global_load_dwordx4 v[68:71], v[68:69], off offset:256
	v_lshl_add_u64 v[98:99], v[148:149], 0, s[8:9]
	v_lshl_add_u64 v[76:77], v[146:147], 0, v[98:99]
	global_load_dwordx4 v[72:75], v[76:77], off
	s_nop 0
	global_load_dwordx4 v[76:79], v[76:77], off offset:256
	v_lshl_add_u64 v[100:101], v[148:149], 0, s[10:11]
	v_lshl_add_u64 v[84:85], v[146:147], 0, v[100:101]
	global_load_dwordx4 v[80:83], v[84:85], off
	s_nop 0
	global_load_dwordx4 v[84:87], v[84:85], off offset:256
	v_lshl_add_u64 v[102:103], v[148:149], 0, s[12:13]
	v_lshl_add_u64 v[92:93], v[146:147], 0, v[102:103]
	global_load_dwordx4 v[88:91], v[92:93], off
	s_nop 0
	global_load_dwordx4 v[92:95], v[92:93], off offset:256
	s_waitcnt vmcnt(0)
; __device__ __forceinline__ float bflo(unsigned w) { return __uint_as_float(w << 16); }
; __device__ __forceinline__ float bfhi(unsigned w) { return __uint_as_float(w & 0xffff0000u); }
; #define PG8_WAIT_V(n) asm volatile("s_waitcnt vmcnt(" #n ")" ::: "memory")
; #define PG8_BAR __builtin_amdgcn_s_barrier()
; template <class Epi>
; __device__ __forceinline__ void gemm_phase(LAS unsigned char* lds, const Gemm g, const Order& S, const Epi& E, const int tid) {
;     ...
;     PG8_WAIT_V(0);
;     if (wr == 0) PG8_BAR;
;     PG8_BAR;
;     __device__ __forceinline__ void operator()(const f32x4 (&acc)[2][2][4][2], const Unit& u, int wr, int wc, int fr, int fq) const {
;     ...
;                 for (int m = 0; m < 4; ++m) { const size_t off = (size_t)(row0 + ai * HALF + m * 16) * DM + col0;
;                     float ss = 0.f;
; #pragma unroll
;                     for (int bj = 0; bj < 2; ++bj) { const u32x4 q = bs[m][bj]; const f32x4 a0 = acc[ai][bj][m][0], a1 = acc[ai][bj][m][1];
;                         const float h0 = bflo(q.x) + a0[0], h1 = bfhi(q.x) + a0[1], h2 = bflo(q.y) + a0[2], h3 = bfhi(q.y) + a0[3], h4 = bflo(q.z) + a1[0], h5 = bfhi(q.z) + a1[1], h6 = bflo(q.w) + a1[2], h7 = bfhi(q.w) + a1[3];
;                         ss += (h0 * h0 + h1 * h1) + (h2 * h2 + h3 * h3) + (h4 * h4 + h5 * h5) + (h6 * h6 + h7 * h7);
;                         u32x4 w; w.x = pk2(h0, h1); w.y = pk2(h2, h3); w.z = pk2(h4, h5); w.w = pk2(h6, h7);
;                         *(u32x4*)(out + off + bj * HALF) = w; }
	v_lshlrev_b32_e32 v104, 16, v64
	v_and_b32_e32 v64, 0xffff0000, v64
	v_add_f32_e32 v61, v61, v64
	v_lshlrev_b32_e32 v64, 16, v65
	v_add_f32_e32 v62, v62, v64
	v_and_b32_e32 v64, 0xffff0000, v65
	v_add_f32_e32 v63, v63, v64
	v_lshlrev_b32_e32 v64, 16, v66
	v_add_f32_e32 v64, v56, v64
	v_and_b32_e32 v56, 0xffff0000, v66
	v_add_f32_e32 v65, v57, v56
	v_lshlrev_b32_e32 v56, 16, v67
	v_add_f32_e32 v60, v60, v104
	v_add_f32_e32 v66, v58, v56
	v_and_b32_e32 v56, 0xffff0000, v67
	v_add_f32_e32 v59, v59, v56
	v_cvt_pk_bf16_f32 v56, v60, v61
	v_lshl_add_u64 v[60:61], s[22:23], 0, v[96:97]
	v_cvt_pk_bf16_f32 v57, v62, v63
	v_cvt_pk_bf16_f32 v58, v64, v65
	v_cvt_pk_bf16_f32 v59, v66, v59
	v_lshl_add_u64 v[60:61], v[60:61], 0, v[144:145]
	global_store_dwordx4 v[60:61], v[56:59], off nt
	s_nop 1
	v_lshlrev_b32_e32 v56, 16, v68
	v_add_f32_e32 v52, v52, v56
	v_and_b32_e32 v56, 0xffff0000, v68
	v_add_f32_e32 v53, v53, v56
	v_lshlrev_b32_e32 v56, 16, v69
	v_add_f32_e32 v54, v54, v56
	v_and_b32_e32 v56, 0xffff0000, v69
	v_add_f32_e32 v55, v55, v56
	v_lshlrev_b32_e32 v56, 16, v70
	v_add_f32_e32 v56, v44, v56
	v_and_b32_e32 v44, 0xffff0000, v70
	v_add_f32_e32 v57, v45, v44
	v_lshlrev_b32_e32 v44, 16, v71
	v_add_f32_e32 v58, v46, v44
	v_and_b32_e32 v44, 0xffff0000, v71
	v_add_f32_e32 v47, v47, v44
	v_cvt_pk_bf16_f32 v44, v52, v53
	v_cvt_pk_bf16_f32 v45, v54, v55
	v_cvt_pk_bf16_f32 v46, v56, v57
	v_cvt_pk_bf16_f32 v47, v58, v47
	global_store_dwordx4 v[60:61], v[44:47], off offset:256 nt
	s_nop 1
	v_lshlrev_b32_e32 v44, 16, v72
	v_add_f32_e32 v44, v48, v44
	v_lshlrev_b32_e32 v48, 16, v74
	v_and_b32_e32 v45, 0xffff0000, v72
	v_add_f32_e32 v48, v40, v48
	v_and_b32_e32 v40, 0xffff0000, v74
	v_add_f32_e32 v45, v49, v45
	v_lshlrev_b32_e32 v46, 16, v73
	v_add_f32_e32 v49, v41, v40
	v_lshlrev_b32_e32 v40, 16, v75
	v_add_f32_e32 v46, v50, v46
	v_and_b32_e32 v47, 0xffff0000, v73
	v_add_f32_e32 v50, v42, v40
	v_and_b32_e32 v40, 0xffff0000, v75
	v_add_f32_e32 v47, v51, v47
	v_add_f32_e32 v43, v43, v40
	v_cvt_pk_bf16_f32 v40, v44, v45
	v_lshl_add_u64 v[44:45], s[22:23], 0, v[98:99]
	v_cvt_pk_bf16_f32 v41, v46, v47
	v_cvt_pk_bf16_f32 v42, v48, v49
	v_cvt_pk_bf16_f32 v43, v50, v43
	v_lshl_add_u64 v[44:45], v[44:45], 0, v[144:145]
	global_store_dwordx4 v[44:45], v[40:43], off nt
	s_nop 1
	v_lshlrev_b32_e32 v40, 16, v76
	v_add_f32_e32 v36, v36, v40
	v_and_b32_e32 v40, 0xffff0000, v76
	v_add_f32_e32 v37, v37, v40
	v_lshlrev_b32_e32 v40, 16, v77
	v_add_f32_e32 v38, v38, v40
	v_and_b32_e32 v40, 0xffff0000, v77
	v_add_f32_e32 v39, v39, v40
	v_lshlrev_b32_e32 v40, 16, v78
	v_add_f32_e32 v40, v28, v40
	v_and_b32_e32 v28, 0xffff0000, v78
	v_add_f32_e32 v41, v29, v28
	v_lshlrev_b32_e32 v28, 16, v79
	v_add_f32_e32 v42, v30, v28
	v_and_b32_e32 v28, 0xffff0000, v79
	v_add_f32_e32 v31, v31, v28
	v_cvt_pk_bf16_f32 v28, v36, v37
	v_cvt_pk_bf16_f32 v29, v38, v39
	v_cvt_pk_bf16_f32 v30, v40, v41
	v_cvt_pk_bf16_f32 v31, v42, v31
	global_store_dwordx4 v[44:45], v[28:31], off offset:256 nt
	s_nop 1
	v_lshlrev_b32_e32 v28, 16, v80
	v_add_f32_e32 v28, v32, v28
	v_lshlrev_b32_e32 v32, 16, v82
	v_and_b32_e32 v29, 0xffff0000, v80
	v_add_f32_e32 v32, v24, v32
	v_and_b32_e32 v24, 0xffff0000, v82
	v_add_f32_e32 v29, v33, v29
	v_lshlrev_b32_e32 v30, 16, v81
	v_add_f32_e32 v33, v25, v24
	v_lshlrev_b32_e32 v24, 16, v83
	v_add_f32_e32 v30, v34, v30
	v_and_b32_e32 v31, 0xffff0000, v81
	v_add_f32_e32 v34, v26, v24
	v_and_b32_e32 v24, 0xffff0000, v83
	v_add_f32_e32 v31, v35, v31
	v_add_f32_e32 v27, v27, v24
	v_cvt_pk_bf16_f32 v24, v28, v29
	v_lshl_add_u64 v[28:29], s[22:23], 0, v[100:101]
	v_cvt_pk_bf16_f32 v25, v30, v31
	v_cvt_pk_bf16_f32 v26, v32, v33
	v_cvt_pk_bf16_f32 v27, v34, v27
	v_lshl_add_u64 v[28:29], v[28:29], 0, v[144:145]
	global_store_dwordx4 v[28:29], v[24:27], off nt
	s_nop 1
	v_lshlrev_b32_e32 v24, 16, v84
	v_add_f32_e32 v20, v20, v24
	v_and_b32_e32 v24, 0xffff0000, v84
	v_add_f32_e32 v21, v21, v24
	v_lshlrev_b32_e32 v24, 16, v85
	v_add_f32_e32 v22, v22, v24
	v_and_b32_e32 v24, 0xffff0000, v85
	v_add_f32_e32 v23, v23, v24
	v_lshlrev_b32_e32 v24, 16, v86
	v_add_f32_e32 v24, v12, v24
	v_and_b32_e32 v12, 0xffff0000, v86
	v_add_f32_e32 v25, v13, v12
	v_lshlrev_b32_e32 v12, 16, v87
	v_add_f32_e32 v26, v14, v12
	v_and_b32_e32 v12, 0xffff0000, v87
	v_add_f32_e32 v15, v15, v12
	v_cvt_pk_bf16_f32 v12, v20, v21
	v_cvt_pk_bf16_f32 v13, v22, v23
	v_cvt_pk_bf16_f32 v14, v24, v25
	v_cvt_pk_bf16_f32 v15, v26, v15
	global_store_dwordx4 v[28:29], v[12:15], off offset:256 nt
	s_nop 1
	v_lshlrev_b32_e32 v12, 16, v88
	v_add_f32_e32 v12, v16, v12
	v_lshlrev_b32_e32 v16, 16, v90
	v_and_b32_e32 v13, 0xffff0000, v88
	v_add_f32_e32 v16, v8, v16
	v_and_b32_e32 v8, 0xffff0000, v90
	v_add_f32_e32 v13, v17, v13
	v_lshlrev_b32_e32 v14, 16, v89
	v_add_f32_e32 v17, v9, v8
	v_lshlrev_b32_e32 v8, 16, v91
	v_add_f32_e32 v14, v18, v14
	v_and_b32_e32 v15, 0xffff0000, v89
	v_add_f32_e32 v18, v10, v8
	v_and_b32_e32 v8, 0xffff0000, v91
	v_add_f32_e32 v15, v19, v15
	v_add_f32_e32 v11, v11, v8
	v_cvt_pk_bf16_f32 v8, v12, v13
	v_lshl_add_u64 v[12:13], s[22:23], 0, v[102:103]
	v_cvt_pk_bf16_f32 v9, v14, v15
	v_cvt_pk_bf16_f32 v10, v16, v17
	v_cvt_pk_bf16_f32 v11, v18, v11
	v_lshl_add_u64 v[12:13], v[12:13], 0, v[144:145]
	global_store_dwordx4 v[12:13], v[8:11], off nt
	s_nop 1
	v_lshlrev_b32_e32 v8, 16, v92
	v_add_f32_e32 v4, v4, v8
	v_and_b32_e32 v8, 0xffff0000, v92
	v_add_f32_e32 v5, v5, v8
	v_lshlrev_b32_e32 v8, 16, v93
	v_add_f32_e32 v6, v6, v8
	v_and_b32_e32 v8, 0xffff0000, v93
	v_add_f32_e32 v7, v7, v8
	v_lshlrev_b32_e32 v8, 16, v94
	v_add_f32_e32 v8, v0, v8
	v_and_b32_e32 v0, 0xffff0000, v94
	v_add_f32_e32 v9, v1, v0
	v_lshlrev_b32_e32 v0, 16, v95
	v_add_f32_e32 v10, v2, v0
	v_and_b32_e32 v0, 0xffff0000, v95
	v_add_f32_e32 v3, v3, v0
	v_cvt_pk_bf16_f32 v0, v4, v5
	v_cvt_pk_bf16_f32 v1, v6, v7
	v_cvt_pk_bf16_f32 v2, v8, v9
	v_cvt_pk_bf16_f32 v3, v10, v3
	global_store_dwordx4 v[12:13], v[0:3], off offset:256 nt
	s_cbranch_vccz .LBB0_931
	s_waitcnt vmcnt(0)
	s_cmpk_gt_u32 s3, 0xff
	s_cbranch_scc1 .LBB0_942
	s_barrier
